# rmsnorm-2 fused: wo epilogue emits bf16(x1*g) + per-row partial sums of squares, 1/rms applied after the linear maps (pq epilogue, PEER U pass); norm2 phase and its grid barrier removed
# speedup vs baseline: 1.0686x; 1.0117x over previous
; template <int WM, class AF, class BF>
; DI void gemm512(f32x16 (&acc)[WM][2], AF arow, int a_kstep, BF brow, int b_kstep, int KT, char* smem) {
;     ...
; #pragma unroll 1
;   for (int kt = 0; kt < KT; kt += 2) {
;     GEMM_STEP(A0, B0, A1, B1, ra0, rb0, ra1, rb1, kt + 2)
;     if (kt + 1 < KT) GEMM_STEP(A1, B1, A0, B0, ra1, rb1, ra0, rb0, kt + 3)
;   }
.LBB0_866:
	ds_read_b128 v[160:163], v220
	ds_read_b128 v[164:167], v219 offset:36864
	ds_read_b128 v[168:171], v219 offset:36896
	ds_read_b128 v[172:175], v220 offset:32
	ds_read_b128 v[176:179], v219 offset:41472
	ds_read_b128 v[180:183], v219 offset:41504
	s_add_i32 s16, s15, 2
	s_waitcnt lgkmcnt(4)
	v_mfma_f32_32x32x16_bf16 v[112:127], v[160:163], v[164:167], v[112:127]
	s_cmp_lt_u32 s15, 14
	s_cselect_b64 s[22:23], -1, 0
	s_and_b64 vcc, s[22:23], exec
	s_cselect_b32 s4, s14, 0x3c0
	s_lshl_b64 s[22:23], s[4:5], 1
	s_min_u32 s4, s15, 12
	s_lshl_b32 s4, s4, 7
	s_waitcnt lgkmcnt(1)
	v_mfma_f32_32x32x16_bf16 v[96:111], v[160:163], v[176:179], v[96:111]
	ds_read_b128 v[160:163], v220 offset:4608
	ds_read_b128 v[184:187], v220 offset:4640
	v_lshl_add_u64 v[240:241], v[206:207], 0, s[4:5]
	v_lshl_add_u64 v[242:243], v[208:209], 0, s[4:5]
	s_addk_i32 s14, 0x80
	s_mov_b32 s15, s16
	s_waitcnt lgkmcnt(1)
	v_mfma_f32_32x32x16_bf16 v[80:95], v[160:163], v[164:167], v[80:95]
	v_mfma_f32_32x32x16_bf16 v[64:79], v[160:163], v[176:179], v[64:79]
	ds_read_b128 v[160:163], v220 offset:9216
	ds_read_b128 v[188:191], v220 offset:9248
	s_waitcnt lgkmcnt(1)
	v_mfma_f32_32x32x16_bf16 v[48:63], v[160:163], v[164:167], v[48:63]
	v_mfma_f32_32x32x16_bf16 v[32:47], v[160:163], v[176:179], v[32:47]
	ds_read_b128 v[160:163], v220 offset:13824
	ds_read_b128 v[232:235], v220 offset:13856
	s_waitcnt lgkmcnt(1)
	v_mfma_f32_32x32x16_bf16 v[16:31], v[160:163], v[164:167], v[16:31]
	v_mfma_f32_32x32x16_bf16 v[0:15], v[160:163], v[176:179], v[0:15]
	v_mfma_f32_32x32x16_bf16 v[112:127], v[172:175], v[168:171], v[112:127]
	v_mfma_f32_32x32x16_bf16 v[96:111], v[172:175], v[180:183], v[96:111]
	v_mfma_f32_32x32x16_bf16 v[80:95], v[184:187], v[168:171], v[80:95]
	v_mfma_f32_32x32x16_bf16 v[64:79], v[184:187], v[180:183], v[64:79]
	v_mfma_f32_32x32x16_bf16 v[48:63], v[188:191], v[168:171], v[48:63]
	s_waitcnt lgkmcnt(0)
	v_mfma_f32_32x32x16_bf16 v[16:31], v[232:235], v[168:171], v[16:31]
	ds_read_b128 v[160:163], v220 offset:64
	ds_read_b128 v[164:167], v219 offset:36928
	ds_read_b128 v[176:179], v219 offset:36960
	ds_read_b128 v[168:171], v220 offset:96
	v_mfma_f32_32x32x16_bf16 v[0:15], v[232:235], v[180:183], v[0:15]
	ds_read_b128 v[172:175], v219 offset:41536
	ds_read_b128 v[232:235], v219 offset:41568
	v_mfma_f32_32x32x16_bf16 v[32:47], v[188:191], v[180:183], v[32:47]
	s_waitcnt lgkmcnt(4)
	v_mfma_f32_32x32x16_bf16 v[112:127], v[160:163], v[164:167], v[112:127]
	s_waitcnt lgkmcnt(1)
	v_mfma_f32_32x32x16_bf16 v[96:111], v[160:163], v[172:175], v[96:111]
	ds_read_b128 v[160:163], v220 offset:4672
	ds_read_b128 v[180:183], v220 offset:4704
	s_waitcnt lgkmcnt(1)
	v_mfma_f32_32x32x16_bf16 v[80:95], v[160:163], v[164:167], v[80:95]
	v_mfma_f32_32x32x16_bf16 v[64:79], v[160:163], v[172:175], v[64:79]
	ds_read_b128 v[160:163], v220 offset:9280
	ds_read_b128 v[184:187], v220 offset:9312
	s_waitcnt lgkmcnt(1)
	v_mfma_f32_32x32x16_bf16 v[48:63], v[160:163], v[164:167], v[48:63]
	v_mfma_f32_32x32x16_bf16 v[32:47], v[160:163], v[172:175], v[32:47]
	ds_read_b128 v[160:163], v220 offset:13888
	ds_read_b128 v[236:239], v220 offset:13920
	s_waitcnt vmcnt(7)
	ds_write_b128 v223, v[128:131]
	s_waitcnt vmcnt(5)
	ds_write_b128 v224, v[136:139]
	s_waitcnt vmcnt(4)
	ds_write_b128 v225, v[140:143]
	s_waitcnt vmcnt(3)
	ds_write_b128 v226, v[144:147]
	ds_write_b128 v227, v[132:135]
	s_waitcnt vmcnt(2)
	ds_write_b128 v228, v[148:151]
	s_waitcnt vmcnt(1)
	ds_write_b128 v229, v[152:155]
	s_waitcnt vmcnt(0)
	ds_write_b128 v230, v[156:159]
	v_lshl_add_u64 v[128:129], v[194:195], 0, s[22:23]
	v_lshl_add_u64 v[130:131], v[196:197], 0, s[22:23]
	v_lshl_add_u64 v[132:133], v[198:199], 0, s[22:23]
	v_lshl_add_u64 v[134:135], v[200:201], 0, s[22:23]
	s_waitcnt lgkmcnt(9)
	v_mfma_f32_32x32x16_bf16 v[16:31], v[160:163], v[164:167], v[16:31]
	v_lshl_add_u64 v[136:137], v[202:203], 0, s[22:23]
	v_lshl_add_u64 v[138:139], v[204:205], 0, s[22:23]
	v_lshl_add_u64 v[140:141], v[206:207], 0, s[22:23]
	v_lshl_add_u64 v[142:143], v[208:209], 0, s[22:23]
	v_mfma_f32_32x32x16_bf16 v[112:127], v[168:171], v[176:179], v[112:127]
	v_mfma_f32_32x32x16_bf16 v[96:111], v[168:171], v[232:235], v[96:111]
	v_mfma_f32_32x32x16_bf16 v[0:15], v[160:163], v[172:175], v[0:15]
	global_load_dwordx4 v[160:163], v[128:129], off
	global_load_dwordx4 v[164:167], v[130:131], off
	global_load_dwordx4 v[168:171], v[132:133], off
	global_load_dwordx4 v[172:175], v[134:135], off
	v_mfma_f32_32x32x16_bf16 v[80:95], v[180:183], v[176:179], v[80:95]
	v_mfma_f32_32x32x16_bf16 v[64:79], v[180:183], v[232:235], v[64:79]
	v_mfma_f32_32x32x16_bf16 v[48:63], v[184:187], v[176:179], v[48:63]
	v_mfma_f32_32x32x16_bf16 v[32:47], v[184:187], v[232:235], v[32:47]
	s_waitcnt lgkmcnt(8)
	v_mfma_f32_32x32x16_bf16 v[16:31], v[236:239], v[176:179], v[16:31]
	global_load_dwordx4 v[176:179], v[136:137], off
	global_load_dwordx4 v[180:183], v[138:139], off
	global_load_dwordx4 v[184:187], v[140:141], off
	global_load_dwordx4 v[188:191], v[142:143], off
	s_waitcnt lgkmcnt(0)
	s_barrier
; template <int WM, class AF, class BF>
; DI void gemm512(f32x16 (&acc)[WM][2], AF arow, int a_kstep, BF brow, int b_kstep, int KT, char* smem) {
;     ...
; #pragma unroll 1
;   for (int kt = 0; kt < KT; kt += 2) {
;     GEMM_STEP(A0, B0, A1, B1, ra0, rb0, ra1, rb1, kt + 2)
;     if (kt + 1 < KT) GEMM_STEP(A1, B1, A0, B0, ra1, rb1, ra0, rb0, kt + 3)
;   }
	ds_read_b128 v[128:131], v222
	ds_read_b128 v[132:135], v221
	ds_read_b128 v[136:139], v221 offset:32
	ds_read_b128 v[140:143], v222 offset:32
	ds_read_b128 v[144:147], v221 offset:4608
	ds_read_b128 v[148:151], v221 offset:4640
	s_waitcnt lgkmcnt(4)
	v_mfma_f32_32x32x16_bf16 v[112:127], v[128:131], v[132:135], v[112:127]
	s_waitcnt lgkmcnt(1)
	v_mfma_f32_32x32x16_bf16 v[96:111], v[128:131], v[144:147], v[96:111]
	ds_read_b128 v[128:131], v222 offset:4608
	ds_read_b128 v[152:155], v222 offset:4640
	v_mfma_f32_32x32x16_bf16 v[0:15], v[236:239], v[232:235], v[0:15]
	s_waitcnt lgkmcnt(1)
	v_mfma_f32_32x32x16_bf16 v[80:95], v[128:131], v[132:135], v[80:95]
	v_mfma_f32_32x32x16_bf16 v[64:79], v[128:131], v[144:147], v[64:79]
	ds_read_b128 v[128:131], v222 offset:9216
	ds_read_b128 v[156:159], v222 offset:9248
	s_waitcnt lgkmcnt(1)
	v_mfma_f32_32x32x16_bf16 v[48:63], v[128:131], v[132:135], v[48:63]
	v_mfma_f32_32x32x16_bf16 v[32:47], v[128:131], v[144:147], v[32:47]
	ds_read_b128 v[128:131], v222 offset:13824
	ds_read_b128 v[232:235], v222 offset:13856
	s_waitcnt lgkmcnt(1)
	v_mfma_f32_32x32x16_bf16 v[16:31], v[128:131], v[132:135], v[16:31]
	v_mfma_f32_32x32x16_bf16 v[0:15], v[128:131], v[144:147], v[0:15]
	v_mfma_f32_32x32x16_bf16 v[112:127], v[140:143], v[136:139], v[112:127]
	v_mfma_f32_32x32x16_bf16 v[96:111], v[140:143], v[148:151], v[96:111]
	v_mfma_f32_32x32x16_bf16 v[80:95], v[152:155], v[136:139], v[80:95]
	v_mfma_f32_32x32x16_bf16 v[64:79], v[152:155], v[148:151], v[64:79]
	v_lshl_add_u64 v[152:153], v[202:203], 0, s[4:5]
	v_lshl_add_u64 v[154:155], v[204:205], 0, s[4:5]
	v_mfma_f32_32x32x16_bf16 v[48:63], v[156:159], v[136:139], v[48:63]
	v_mfma_f32_32x32x16_bf16 v[32:47], v[156:159], v[148:151], v[32:47]
	s_waitcnt lgkmcnt(0)
	v_mfma_f32_32x32x16_bf16 v[16:31], v[232:235], v[136:139], v[16:31]
	ds_read_b128 v[128:131], v222 offset:64
	ds_read_b128 v[132:135], v221 offset:64
	ds_read_b128 v[156:159], v221 offset:96
	ds_read_b128 v[136:139], v222 offset:96
	v_mfma_f32_32x32x16_bf16 v[0:15], v[232:235], v[148:151], v[0:15]
	ds_read_b128 v[140:143], v221 offset:4672
	ds_read_b128 v[232:235], v221 offset:4704
	s_waitcnt lgkmcnt(4)
	v_mfma_f32_32x32x16_bf16 v[112:127], v[128:131], v[132:135], v[112:127]
	s_waitcnt lgkmcnt(1)
	v_mfma_f32_32x32x16_bf16 v[96:111], v[128:131], v[140:143], v[96:111]
	ds_read_b128 v[128:131], v222 offset:4672
	ds_read_b128 v[144:147], v222 offset:4704
	s_waitcnt lgkmcnt(1)
	v_mfma_f32_32x32x16_bf16 v[80:95], v[128:131], v[132:135], v[80:95]
	v_mfma_f32_32x32x16_bf16 v[64:79], v[128:131], v[140:143], v[64:79]
	ds_read_b128 v[128:131], v222 offset:9280
	ds_read_b128 v[148:151], v222 offset:9312
	s_waitcnt lgkmcnt(1)
	v_mfma_f32_32x32x16_bf16 v[48:63], v[128:131], v[132:135], v[48:63]
	v_mfma_f32_32x32x16_bf16 v[32:47], v[128:131], v[140:143], v[32:47]
	ds_read_b128 v[128:131], v222 offset:13888
	ds_read_b128 v[236:239], v222 offset:13920
	s_waitcnt lgkmcnt(1)
	v_mfma_f32_32x32x16_bf16 v[16:31], v[128:131], v[132:135], v[16:31]
	v_lshl_add_u64 v[132:133], v[196:197], 0, s[4:5]
	v_lshl_add_u64 v[134:135], v[198:199], 0, s[4:5]
	v_mfma_f32_32x32x16_bf16 v[0:15], v[128:131], v[140:143], v[0:15]
	v_lshl_add_u64 v[128:129], v[194:195], 0, s[4:5]
	v_mfma_f32_32x32x16_bf16 v[80:95], v[144:147], v[156:159], v[80:95]
	v_mfma_f32_32x32x16_bf16 v[64:79], v[144:147], v[232:235], v[64:79]
	v_lshl_add_u64 v[144:145], v[200:201], 0, s[4:5]
	v_mfma_f32_32x32x16_bf16 v[112:127], v[136:139], v[156:159], v[112:127]
	v_mfma_f32_32x32x16_bf16 v[96:111], v[136:139], v[232:235], v[96:111]
	v_mfma_f32_32x32x16_bf16 v[48:63], v[148:151], v[156:159], v[48:63]
	v_mfma_f32_32x32x16_bf16 v[32:47], v[148:151], v[232:235], v[32:47]
	global_load_dwordx4 v[128:131], v[128:129], off offset:384
	s_nop 0
	global_load_dwordx4 v[136:139], v[132:133], off offset:384
	global_load_dwordx4 v[140:143], v[134:135], off offset:384
	s_nop 0
	global_load_dwordx4 v[144:147], v[144:145], off offset:384
	s_nop 0
	global_load_dwordx4 v[132:135], v[152:153], off offset:384
	global_load_dwordx4 v[148:151], v[154:155], off offset:384
	s_nop 0
	global_load_dwordx4 v[152:155], v[240:241], off offset:384
	s_waitcnt lgkmcnt(0)
	v_mfma_f32_32x32x16_bf16 v[16:31], v[236:239], v[156:159], v[16:31]
	global_load_dwordx4 v[156:159], v[242:243], off offset:384
	s_waitcnt vmcnt(15)
	ds_write_b128 v192, v[160:163]
	s_waitcnt vmcnt(14)
	ds_write_b128 v216, v[164:167]
	s_waitcnt vmcnt(13)
	ds_write_b128 v217, v[168:171]
	s_waitcnt vmcnt(12)
	ds_write_b128 v218, v[172:175]
	s_waitcnt vmcnt(11)
	ds_write_b128 v192, v[176:179] offset:36864
	s_waitcnt vmcnt(10)
	ds_write_b128 v216, v[180:183] offset:36864
	s_waitcnt vmcnt(9)
	ds_write_b128 v217, v[184:187] offset:36864
	s_waitcnt vmcnt(8)
	ds_write_b128 v218, v[188:191] offset:36864
	s_waitcnt lgkmcnt(0)
	s_barrier
	v_mfma_f32_32x32x16_bf16 v[0:15], v[236:239], v[232:235], v[0:15]
	s_cbranch_vccnz .LBB0_866
	s_waitcnt vmcnt(0)
	s_mov_b32 s22, s12
	s_mov_b32 s24, s13
	v_readlane_b32 s80, v253, 0
	v_readlane_b32 s81, v253, 1
	s_add_i32 s11, s11, 1
	s_mul_i32 s4, s11, s51
	s_add_i32 s4, s4, s50
	s_barrier
; template <int NR>
; DI void rms_rows(const float* __restrict__ xr, const float* __restrict__ g, u16* __restrict__ dst, int lane) {
;     ...
;     for (int i = 0; i < 4; ++i) ss += v[r][i].x * v[r][i].x + v[r][i].y * v[r][i].y + v[r][i].z * v[r][i].z + v[r][i].w * v[r][i].w;
;     ss = wave_sum(ss);
;     const float rr = rsqrtf(ss * (1.f / 1024.f) + 1e-6f);
; #pragma unroll
;     for (int i = 0; i < 4; ++i) {
;       uint2 o;
;       o.x = pack2(v[r][i].x * rr * gg[i].x, v[r][i].y * rr * gg[i].y);
;       o.y = pack2(v[r][i].z * rr * gg[i].z, v[r][i].w * rr * gg[i].w);
;       *(uint2*)(dst + (size_t)r * 1024 + lane * 4 + 256 * i) = o;
; DI void phase_wo(const Params& p, char* smem) {
;     ...
; #pragma unroll
;     for (int i = 0; i < 4; ++i)
; #pragma unroll
;       for (int j = 0; j < 2; ++j)
; #pragma unroll
;         for (int q4 = 0; q4 < 4; ++q4) {
;           const int f = n0 + wm * 128 + i * 32 + q4 * 8 + hh * 4;
;           const size_t t = m0 + wn * 64 + j * 32 + lr;
;           float4 xv = *(const float4*)(p.x + t * 1024 + f);
;           xv.x += acc[i][j][q4 * 4 + 0]; xv.y += acc[i][j][q4 * 4 + 1];
;           xv.z += acc[i][j][q4 * 4 + 2]; xv.w += acc[i][j][q4 * 4 + 3];
;           *(float4*)(X1 + t * 1024 + f) = xv;
;         }
	v_mbcnt_lo_u32_b32 v176, -1, 0
	v_mbcnt_hi_u32_b32 v176, -1, v176
	v_lshrrev_b32_e32 v177, 6, v211
	v_and_b32_e32 v178, 31, v176
	v_lshrrev_b32_e32 v179, 5, v176
	v_and_b32_e32 v180, 3, v177
	v_lshrrev_b32_e32 v181, 2, v177
	v_mul_u32_u24_e32 v182, 16896, v177
	v_mul_u32_u24_e32 v183, 528, v178
	v_lshl_add_u32 v183, v179, 4, v183
	v_add3_u32 v183, v183, v182, 64
	v_mul_u32_u24_e32 v184, 528, v179
	v_lshl_add_u32 v184, v178, 4, v184
	v_add3_u32 v184, v184, v182, 64
	v_lshl_add_u32 v185, v180, 6, v179
	v_add_u32_e32 v185, s22, v185
	v_lshlrev_b32_e32 v185, 12, v185
	v_lshlrev_b32_e32 v186, 9, v181
	v_lshl_add_u32 v186, v178, 4, v186
	s_lshl_b32 s26, s24, 2
	v_add3_u32 v185, v185, v186, s26
	v_mov_b32_e32 v187, v185
	v_readlane_b32 s82, v253, 34
	v_readlane_b32 s83, v253, 35
	v_readlane_b32 s84, v253, 48
	v_readlane_b32 s85, v253, 49
	v_add_u32_e32 v224, s26, v186
	v_lshrrev_b32_e32 v204, 1, v185
	s_add_u32 s86, s84, 0x9a80200
	s_addc_u32 s87, s85, 0
	s_add_u32 s84, s84, 0x7200200
	s_addc_u32 s85, s85, 0
	global_load_dwordx4 v[188:191], v224, s[82:83]
	v_and_b32_e32 v205, 15, v176
	v_lshlrev_b32_e32 v205, 1, v205
	v_add_u32_e32 v205, v205, v179
	v_lshl_add_u32 v205, v180, 6, v205
	v_add_u32_e32 v205, s22, v205
	v_lshlrev_b32_e32 v205, 5, v205
	s_lshr_b32 s27, s24, 8
	s_lshl_b32 s27, s27, 3
	v_lshl_add_u32 v205, v181, 2, v205
	v_add_u32_e32 v205, s27, v205
	ds_write_b128 v183, v[112:115] offset:0
	ds_write_b128 v183, v[116:119] offset:32
	ds_write_b128 v183, v[120:123] offset:64
	ds_write_b128 v183, v[124:127] offset:96
	ds_write_b128 v183, v[80:83] offset:128
	ds_write_b128 v183, v[84:87] offset:160
	ds_write_b128 v183, v[88:91] offset:192
	ds_write_b128 v183, v[92:95] offset:224
	ds_write_b128 v183, v[48:51] offset:256
	ds_write_b128 v183, v[52:55] offset:288
	ds_write_b128 v183, v[56:59] offset:320
	ds_write_b128 v183, v[60:63] offset:352
	ds_write_b128 v183, v[16:19] offset:384
	ds_write_b128 v183, v[20:23] offset:416
	ds_write_b128 v183, v[24:27] offset:448
	ds_write_b128 v183, v[28:31] offset:480
	global_load_dwordx4 v[144:147], v185, s[80:81]
	v_add_u32_e32 v185, 0x2000, v185
	global_load_dwordx4 v[148:151], v185, s[80:81]
	v_add_u32_e32 v185, 0x2000, v185
	global_load_dwordx4 v[152:155], v185, s[80:81]
	v_add_u32_e32 v185, 0x2000, v185
	global_load_dwordx4 v[156:159], v185, s[80:81]
	v_add_u32_e32 v185, 0x2000, v185
	global_load_dwordx4 v[160:163], v185, s[80:81]
	v_add_u32_e32 v185, 0x2000, v185
	global_load_dwordx4 v[164:167], v185, s[80:81]
	v_add_u32_e32 v185, 0x2000, v185
	global_load_dwordx4 v[168:171], v185, s[80:81]
	v_add_u32_e32 v185, 0x2000, v185
	global_load_dwordx4 v[172:175], v185, s[80:81]
	v_add_u32_e32 v185, 0x2000, v185
	ds_read_b128 v[128:131], v184 offset:0
	ds_read_b128 v[132:135], v184 offset:1056
	ds_read_b128 v[136:139], v184 offset:2112
	ds_read_b128 v[140:143], v184 offset:3168
	s_waitcnt vmcnt(4) lgkmcnt(0)
	v_pk_add_f32 v[128:129], v[128:129], v[144:145]
	v_pk_add_f32 v[130:131], v[130:131], v[146:147]
	v_pk_add_f32 v[132:133], v[132:133], v[148:149]
	v_pk_add_f32 v[134:135], v[134:135], v[150:151]
	v_pk_add_f32 v[136:137], v[136:137], v[152:153]
	v_pk_add_f32 v[138:139], v[138:139], v[154:155]
	v_pk_add_f32 v[140:141], v[140:141], v[156:157]
	v_pk_add_f32 v[142:143], v[142:143], v[158:159]
	global_store_dwordx4 v187, v[128:131], s[76:77]
	v_add_u32_e32 v187, 0x2000, v187
	global_store_dwordx4 v187, v[132:135], s[76:77]
	v_add_u32_e32 v187, 0x2000, v187
	global_store_dwordx4 v187, v[136:139], s[76:77]
	v_add_u32_e32 v187, 0x2000, v187
	global_store_dwordx4 v187, v[140:143], s[76:77]
	v_add_u32_e32 v187, 0x2000, v187
	v_mul_f32_e32 v194, v128, v128
	v_mul_f32_e32 v195, v132, v132
	v_mul_f32_e32 v196, v136, v136
	v_mul_f32_e32 v197, v140, v140
	v_fmac_f32_e32 v194, v129, v129
	v_fmac_f32_e32 v195, v133, v133
	v_fmac_f32_e32 v196, v137, v137
	v_fmac_f32_e32 v197, v141, v141
	v_fmac_f32_e32 v194, v130, v130
	v_fmac_f32_e32 v195, v134, v134
	v_fmac_f32_e32 v196, v138, v138
	v_fmac_f32_e32 v197, v142, v142
	v_fmac_f32_e32 v194, v131, v131
	v_fmac_f32_e32 v195, v135, v135
	v_fmac_f32_e32 v196, v139, v139
	v_fmac_f32_e32 v197, v143, v143
	v_pk_mul_f32 v[198:199], v[128:129], v[188:189]
	v_pk_mul_f32 v[200:201], v[130:131], v[190:191]
	v_add_f32_dpp v194, v194, v194 row_ror:8 row_mask:0xf bank_mask:0xf
	v_cvt_pk_bf16_f32 v216, v198, v199
	v_cvt_pk_bf16_f32 v217, v200, v201
	global_store_dwordx2 v204, v[216:217], s[84:85]
	v_add_u32_e32 v204, 0x1000, v204
	v_pk_mul_f32 v[198:199], v[132:133], v[188:189]
	v_pk_mul_f32 v[200:201], v[134:135], v[190:191]
	v_add_f32_dpp v195, v195, v195 row_ror:8 row_mask:0xf bank_mask:0xf
	v_cvt_pk_bf16_f32 v218, v198, v199
	v_cvt_pk_bf16_f32 v219, v200, v201
	global_store_dwordx2 v204, v[218:219], s[84:85]
	v_add_u32_e32 v204, 0x1000, v204
	v_pk_mul_f32 v[198:199], v[136:137], v[188:189]
	v_pk_mul_f32 v[200:201], v[138:139], v[190:191]
	v_add_f32_dpp v196, v196, v196 row_ror:8 row_mask:0xf bank_mask:0xf
	v_cvt_pk_bf16_f32 v220, v198, v199
	v_cvt_pk_bf16_f32 v221, v200, v201
	global_store_dwordx2 v204, v[220:221], s[84:85]
	v_add_u32_e32 v204, 0x1000, v204
	v_pk_mul_f32 v[198:199], v[140:141], v[188:189]
	v_pk_mul_f32 v[200:201], v[142:143], v[190:191]
	v_add_f32_dpp v197, v197, v197 row_ror:8 row_mask:0xf bank_mask:0xf
	v_cvt_pk_bf16_f32 v222, v198, v199
	v_cvt_pk_bf16_f32 v223, v200, v201
	global_store_dwordx2 v204, v[222:223], s[84:85]
	v_add_u32_e32 v204, 0x1000, v204
	v_add_f32_dpp v194, v194, v194 row_ror:4 row_mask:0xf bank_mask:0xf
	v_add_f32_dpp v195, v195, v195 row_ror:4 row_mask:0xf bank_mask:0xf
	v_add_f32_dpp v196, v196, v196 row_ror:4 row_mask:0xf bank_mask:0xf
; template <int NR>
; DI void rms_rows(const float* __restrict__ xr, const float* __restrict__ g, u16* __restrict__ dst, int lane) {
;     ...
;     for (int i = 0; i < 4; ++i) ss += v[r][i].x * v[r][i].x + v[r][i].y * v[r][i].y + v[r][i].z * v[r][i].z + v[r][i].w * v[r][i].w;
;     ss = wave_sum(ss);
;     const float rr = rsqrtf(ss * (1.f / 1024.f) + 1e-6f);
; #pragma unroll
;     for (int i = 0; i < 4; ++i) {
;       uint2 o;
;       o.x = pack2(v[r][i].x * rr * gg[i].x, v[r][i].y * rr * gg[i].y);
;       o.y = pack2(v[r][i].z * rr * gg[i].z, v[r][i].w * rr * gg[i].w);
;       *(uint2*)(dst + (size_t)r * 1024 + lane * 4 + 256 * i) = o;
; DI void phase_wo(const Params& p, char* smem) {
;     ...
; #pragma unroll
;     for (int i = 0; i < 4; ++i)
; #pragma unroll
;       for (int j = 0; j < 2; ++j)
; #pragma unroll
;         for (int q4 = 0; q4 < 4; ++q4) {
;           const int f = n0 + wm * 128 + i * 32 + q4 * 8 + hh * 4;
;           const size_t t = m0 + wn * 64 + j * 32 + lr;
;           float4 xv = *(const float4*)(p.x + t * 1024 + f);
;           xv.x += acc[i][j][q4 * 4 + 0]; xv.y += acc[i][j][q4 * 4 + 1];
;           xv.z += acc[i][j][q4 * 4 + 2]; xv.w += acc[i][j][q4 * 4 + 3];
;           *(float4*)(X1 + t * 1024 + f) = xv;
;         }
	v_add_f32_dpp v197, v197, v197 row_ror:4 row_mask:0xf bank_mask:0xf
	v_add_f32_dpp v194, v194, v194 row_ror:2 row_mask:0xf bank_mask:0xf
	v_add_f32_dpp v195, v195, v195 row_ror:2 row_mask:0xf bank_mask:0xf
	v_add_f32_dpp v196, v196, v196 row_ror:2 row_mask:0xf bank_mask:0xf
	v_add_f32_dpp v197, v197, v197 row_ror:2 row_mask:0xf bank_mask:0xf
	v_add_f32_dpp v194, v194, v194 row_ror:1 row_mask:0xf bank_mask:0xf
	v_add_f32_dpp v195, v195, v195 row_ror:1 row_mask:0xf bank_mask:0xf
	v_add_f32_dpp v196, v196, v196 row_ror:1 row_mask:0xf bank_mask:0xf
	v_add_f32_dpp v197, v197, v197 row_ror:1 row_mask:0xf bank_mask:0xf
	v_add_f32_dpp v194, v194, v194 row_bcast:15 row_mask:0xa bank_mask:0xf
	v_add_f32_dpp v195, v195, v195 row_bcast:15 row_mask:0xa bank_mask:0xf
	v_add_f32_dpp v196, v196, v196 row_bcast:15 row_mask:0xa bank_mask:0xf
	v_add_f32_dpp v197, v197, v197 row_bcast:15 row_mask:0xa bank_mask:0xf
	s_mov_b32 s90, 0x10000
	s_mov_b32 s91, 0x10000
	v_cndmask_b32_e64 v202, v202, v194, s[90:91]
	s_mov_b32 s90, 0x20000
	s_mov_b32 s91, 0x20000
	v_cndmask_b32_e64 v202, v202, v195, s[90:91]
	s_mov_b32 s90, 0x40000
	s_mov_b32 s91, 0x40000
	v_cndmask_b32_e64 v202, v202, v196, s[90:91]
	s_mov_b32 s90, 0x80000
	s_mov_b32 s91, 0x80000
	v_cndmask_b32_e64 v202, v202, v197, s[90:91]
	global_load_dwordx4 v[144:147], v185, s[80:81]
	v_add_u32_e32 v185, 0x2000, v185
	global_load_dwordx4 v[148:151], v185, s[80:81]
	v_add_u32_e32 v185, 0x2000, v185
	global_load_dwordx4 v[152:155], v185, s[80:81]
	v_add_u32_e32 v185, 0x2000, v185
	global_load_dwordx4 v[156:159], v185, s[80:81]
	v_add_u32_e32 v185, 0x2000, v185
	ds_read_b128 v[128:131], v184 offset:4224
	ds_read_b128 v[132:135], v184 offset:5280
	ds_read_b128 v[136:139], v184 offset:6336
	ds_read_b128 v[140:143], v184 offset:7392
	s_waitcnt vmcnt(12) lgkmcnt(0)
	v_pk_add_f32 v[128:129], v[128:129], v[160:161]
	v_pk_add_f32 v[130:131], v[130:131], v[162:163]
	v_pk_add_f32 v[132:133], v[132:133], v[164:165]
	v_pk_add_f32 v[134:135], v[134:135], v[166:167]
	v_pk_add_f32 v[136:137], v[136:137], v[168:169]
	v_pk_add_f32 v[138:139], v[138:139], v[170:171]
	v_pk_add_f32 v[140:141], v[140:141], v[172:173]
	v_pk_add_f32 v[142:143], v[142:143], v[174:175]
	global_store_dwordx4 v187, v[128:131], s[76:77]
	v_add_u32_e32 v187, 0x2000, v187
	global_store_dwordx4 v187, v[132:135], s[76:77]
	v_add_u32_e32 v187, 0x2000, v187
	global_store_dwordx4 v187, v[136:139], s[76:77]
	v_add_u32_e32 v187, 0x2000, v187
	global_store_dwordx4 v187, v[140:143], s[76:77]
	v_add_u32_e32 v187, 0x2000, v187
	v_mul_f32_e32 v194, v128, v128
	v_mul_f32_e32 v195, v132, v132
	v_mul_f32_e32 v196, v136, v136
	v_mul_f32_e32 v197, v140, v140
	v_fmac_f32_e32 v194, v129, v129
	v_fmac_f32_e32 v195, v133, v133
	v_fmac_f32_e32 v196, v137, v137
	v_fmac_f32_e32 v197, v141, v141
	v_fmac_f32_e32 v194, v130, v130
	v_fmac_f32_e32 v195, v134, v134
	v_fmac_f32_e32 v196, v138, v138
	v_fmac_f32_e32 v197, v142, v142
	v_fmac_f32_e32 v194, v131, v131
	v_fmac_f32_e32 v195, v135, v135
	v_fmac_f32_e32 v196, v139, v139
	v_fmac_f32_e32 v197, v143, v143
	v_pk_mul_f32 v[198:199], v[128:129], v[188:189]
	v_pk_mul_f32 v[200:201], v[130:131], v[190:191]
	v_add_f32_dpp v194, v194, v194 row_ror:8 row_mask:0xf bank_mask:0xf
	v_cvt_pk_bf16_f32 v216, v198, v199
	v_cvt_pk_bf16_f32 v217, v200, v201
	global_store_dwordx2 v204, v[216:217], s[84:85]
	v_add_u32_e32 v204, 0x1000, v204
	v_pk_mul_f32 v[198:199], v[132:133], v[188:189]
	v_pk_mul_f32 v[200:201], v[134:135], v[190:191]
	v_add_f32_dpp v195, v195, v195 row_ror:8 row_mask:0xf bank_mask:0xf
	v_cvt_pk_bf16_f32 v218, v198, v199
	v_cvt_pk_bf16_f32 v219, v200, v201
	global_store_dwordx2 v204, v[218:219], s[84:85]
	v_add_u32_e32 v204, 0x1000, v204
	v_pk_mul_f32 v[198:199], v[136:137], v[188:189]
	v_pk_mul_f32 v[200:201], v[138:139], v[190:191]
	v_add_f32_dpp v196, v196, v196 row_ror:8 row_mask:0xf bank_mask:0xf
	v_cvt_pk_bf16_f32 v220, v198, v199
	v_cvt_pk_bf16_f32 v221, v200, v201
	global_store_dwordx2 v204, v[220:221], s[84:85]
	v_add_u32_e32 v204, 0x1000, v204
	v_pk_mul_f32 v[198:199], v[140:141], v[188:189]
	v_pk_mul_f32 v[200:201], v[142:143], v[190:191]
	v_add_f32_dpp v197, v197, v197 row_ror:8 row_mask:0xf bank_mask:0xf
	v_cvt_pk_bf16_f32 v222, v198, v199
	v_cvt_pk_bf16_f32 v223, v200, v201
	global_store_dwordx2 v204, v[222:223], s[84:85]
	v_add_u32_e32 v204, 0x1000, v204
	v_add_f32_dpp v194, v194, v194 row_ror:4 row_mask:0xf bank_mask:0xf
	v_add_f32_dpp v195, v195, v195 row_ror:4 row_mask:0xf bank_mask:0xf
	v_add_f32_dpp v196, v196, v196 row_ror:4 row_mask:0xf bank_mask:0xf
	v_add_f32_dpp v197, v197, v197 row_ror:4 row_mask:0xf bank_mask:0xf
	v_add_f32_dpp v194, v194, v194 row_ror:2 row_mask:0xf bank_mask:0xf
	v_add_f32_dpp v195, v195, v195 row_ror:2 row_mask:0xf bank_mask:0xf
	v_add_f32_dpp v196, v196, v196 row_ror:2 row_mask:0xf bank_mask:0xf
	v_add_f32_dpp v197, v197, v197 row_ror:2 row_mask:0xf bank_mask:0xf
	v_add_f32_dpp v194, v194, v194 row_ror:1 row_mask:0xf bank_mask:0xf
	v_add_f32_dpp v195, v195, v195 row_ror:1 row_mask:0xf bank_mask:0xf
	v_add_f32_dpp v196, v196, v196 row_ror:1 row_mask:0xf bank_mask:0xf
	v_add_f32_dpp v197, v197, v197 row_ror:1 row_mask:0xf bank_mask:0xf
	v_add_f32_dpp v194, v194, v194 row_bcast:15 row_mask:0xa bank_mask:0xf
	v_add_f32_dpp v195, v195, v195 row_bcast:15 row_mask:0xa bank_mask:0xf
	v_add_f32_dpp v196, v196, v196 row_bcast:15 row_mask:0xa bank_mask:0xf
	v_add_f32_dpp v197, v197, v197 row_bcast:15 row_mask:0xa bank_mask:0xf
	s_mov_b32 s90, 0x100000
	s_mov_b32 s91, 0x100000
	v_cndmask_b32_e64 v202, v202, v194, s[90:91]
	s_mov_b32 s90, 0x200000
	s_mov_b32 s91, 0x200000
	v_cndmask_b32_e64 v202, v202, v195, s[90:91]
	s_mov_b32 s90, 0x400000
	s_mov_b32 s91, 0x400000
	v_cndmask_b32_e64 v202, v202, v196, s[90:91]
	s_mov_b32 s90, 0x800000
	s_mov_b32 s91, 0x800000
	v_cndmask_b32_e64 v202, v202, v197, s[90:91]
	global_load_dwordx4 v[160:163], v185, s[80:81]
	v_add_u32_e32 v185, 0x2000, v185
	global_load_dwordx4 v[164:167], v185, s[80:81]
	v_add_u32_e32 v185, 0x2000, v185
	global_load_dwordx4 v[168:171], v185, s[80:81]
	v_add_u32_e32 v185, 0x2000, v185
	global_load_dwordx4 v[172:175], v185, s[80:81]
	v_add_u32_e32 v185, 0x2000, v185
	ds_read_b128 v[128:131], v184 offset:8448
	ds_read_b128 v[132:135], v184 offset:9504
	ds_read_b128 v[136:139], v184 offset:10560
	ds_read_b128 v[140:143], v184 offset:11616
	s_waitcnt vmcnt(12) lgkmcnt(0)
; template <int NR>
; DI void rms_rows(const float* __restrict__ xr, const float* __restrict__ g, u16* __restrict__ dst, int lane) {
;     ...
;     for (int i = 0; i < 4; ++i) ss += v[r][i].x * v[r][i].x + v[r][i].y * v[r][i].y + v[r][i].z * v[r][i].z + v[r][i].w * v[r][i].w;
;     ss = wave_sum(ss);
;     const float rr = rsqrtf(ss * (1.f / 1024.f) + 1e-6f);
; #pragma unroll
;     for (int i = 0; i < 4; ++i) {
;       uint2 o;
;       o.x = pack2(v[r][i].x * rr * gg[i].x, v[r][i].y * rr * gg[i].y);
;       o.y = pack2(v[r][i].z * rr * gg[i].z, v[r][i].w * rr * gg[i].w);
;       *(uint2*)(dst + (size_t)r * 1024 + lane * 4 + 256 * i) = o;
; DI void phase_wo(const Params& p, char* smem) {
;     ...
; #pragma unroll
;     for (int i = 0; i < 4; ++i)
; #pragma unroll
;       for (int j = 0; j < 2; ++j)
; #pragma unroll
;         for (int q4 = 0; q4 < 4; ++q4) {
;           const int f = n0 + wm * 128 + i * 32 + q4 * 8 + hh * 4;
;           const size_t t = m0 + wn * 64 + j * 32 + lr;
;           float4 xv = *(const float4*)(p.x + t * 1024 + f);
;           xv.x += acc[i][j][q4 * 4 + 0]; xv.y += acc[i][j][q4 * 4 + 1];
;           xv.z += acc[i][j][q4 * 4 + 2]; xv.w += acc[i][j][q4 * 4 + 3];
;           *(float4*)(X1 + t * 1024 + f) = xv;
;         }
	v_pk_add_f32 v[128:129], v[128:129], v[144:145]
	v_pk_add_f32 v[130:131], v[130:131], v[146:147]
	v_pk_add_f32 v[132:133], v[132:133], v[148:149]
	v_pk_add_f32 v[134:135], v[134:135], v[150:151]
	v_pk_add_f32 v[136:137], v[136:137], v[152:153]
	v_pk_add_f32 v[138:139], v[138:139], v[154:155]
	v_pk_add_f32 v[140:141], v[140:141], v[156:157]
	v_pk_add_f32 v[142:143], v[142:143], v[158:159]
	global_store_dwordx4 v187, v[128:131], s[76:77]
	v_add_u32_e32 v187, 0x2000, v187
	global_store_dwordx4 v187, v[132:135], s[76:77]
	v_add_u32_e32 v187, 0x2000, v187
	global_store_dwordx4 v187, v[136:139], s[76:77]
	v_add_u32_e32 v187, 0x2000, v187
	global_store_dwordx4 v187, v[140:143], s[76:77]
	v_add_u32_e32 v187, 0x2000, v187
	v_mul_f32_e32 v194, v128, v128
	v_mul_f32_e32 v195, v132, v132
	v_mul_f32_e32 v196, v136, v136
	v_mul_f32_e32 v197, v140, v140
	v_fmac_f32_e32 v194, v129, v129
	v_fmac_f32_e32 v195, v133, v133
	v_fmac_f32_e32 v196, v137, v137
	v_fmac_f32_e32 v197, v141, v141
	v_fmac_f32_e32 v194, v130, v130
	v_fmac_f32_e32 v195, v134, v134
	v_fmac_f32_e32 v196, v138, v138
	v_fmac_f32_e32 v197, v142, v142
	v_fmac_f32_e32 v194, v131, v131
	v_fmac_f32_e32 v195, v135, v135
	v_fmac_f32_e32 v196, v139, v139
	v_fmac_f32_e32 v197, v143, v143
	v_pk_mul_f32 v[198:199], v[128:129], v[188:189]
	v_pk_mul_f32 v[200:201], v[130:131], v[190:191]
	v_add_f32_dpp v194, v194, v194 row_ror:8 row_mask:0xf bank_mask:0xf
	v_cvt_pk_bf16_f32 v216, v198, v199
	v_cvt_pk_bf16_f32 v217, v200, v201
	global_store_dwordx2 v204, v[216:217], s[84:85]
	v_add_u32_e32 v204, 0x1000, v204
	v_pk_mul_f32 v[198:199], v[132:133], v[188:189]
	v_pk_mul_f32 v[200:201], v[134:135], v[190:191]
	v_add_f32_dpp v195, v195, v195 row_ror:8 row_mask:0xf bank_mask:0xf
	v_cvt_pk_bf16_f32 v218, v198, v199
	v_cvt_pk_bf16_f32 v219, v200, v201
	global_store_dwordx2 v204, v[218:219], s[84:85]
	v_add_u32_e32 v204, 0x1000, v204
	v_pk_mul_f32 v[198:199], v[136:137], v[188:189]
	v_pk_mul_f32 v[200:201], v[138:139], v[190:191]
	v_add_f32_dpp v196, v196, v196 row_ror:8 row_mask:0xf bank_mask:0xf
	v_cvt_pk_bf16_f32 v220, v198, v199
	v_cvt_pk_bf16_f32 v221, v200, v201
	global_store_dwordx2 v204, v[220:221], s[84:85]
	v_add_u32_e32 v204, 0x1000, v204
	v_pk_mul_f32 v[198:199], v[140:141], v[188:189]
	v_pk_mul_f32 v[200:201], v[142:143], v[190:191]
	v_add_f32_dpp v197, v197, v197 row_ror:8 row_mask:0xf bank_mask:0xf
	v_cvt_pk_bf16_f32 v222, v198, v199
	v_cvt_pk_bf16_f32 v223, v200, v201
	global_store_dwordx2 v204, v[222:223], s[84:85]
	v_add_u32_e32 v204, 0x1000, v204
	v_add_f32_dpp v194, v194, v194 row_ror:4 row_mask:0xf bank_mask:0xf
	v_add_f32_dpp v195, v195, v195 row_ror:4 row_mask:0xf bank_mask:0xf
	v_add_f32_dpp v196, v196, v196 row_ror:4 row_mask:0xf bank_mask:0xf
	v_add_f32_dpp v197, v197, v197 row_ror:4 row_mask:0xf bank_mask:0xf
	v_add_f32_dpp v194, v194, v194 row_ror:2 row_mask:0xf bank_mask:0xf
	v_add_f32_dpp v195, v195, v195 row_ror:2 row_mask:0xf bank_mask:0xf
	v_add_f32_dpp v196, v196, v196 row_ror:2 row_mask:0xf bank_mask:0xf
	v_add_f32_dpp v197, v197, v197 row_ror:2 row_mask:0xf bank_mask:0xf
	v_add_f32_dpp v194, v194, v194 row_ror:1 row_mask:0xf bank_mask:0xf
	v_add_f32_dpp v195, v195, v195 row_ror:1 row_mask:0xf bank_mask:0xf
	v_add_f32_dpp v196, v196, v196 row_ror:1 row_mask:0xf bank_mask:0xf
	v_add_f32_dpp v197, v197, v197 row_ror:1 row_mask:0xf bank_mask:0xf
	v_add_f32_dpp v194, v194, v194 row_bcast:15 row_mask:0xa bank_mask:0xf
	v_add_f32_dpp v195, v195, v195 row_bcast:15 row_mask:0xa bank_mask:0xf
	v_add_f32_dpp v196, v196, v196 row_bcast:15 row_mask:0xa bank_mask:0xf
	v_add_f32_dpp v197, v197, v197 row_bcast:15 row_mask:0xa bank_mask:0xf
	s_mov_b32 s90, 0x1000000
	s_mov_b32 s91, 0x1000000
	v_cndmask_b32_e64 v202, v202, v194, s[90:91]
	s_mov_b32 s90, 0x2000000
	s_mov_b32 s91, 0x2000000
	v_cndmask_b32_e64 v202, v202, v195, s[90:91]
	s_mov_b32 s90, 0x4000000
	s_mov_b32 s91, 0x4000000
	v_cndmask_b32_e64 v202, v202, v196, s[90:91]
	s_mov_b32 s90, 0x8000000
	s_mov_b32 s91, 0x8000000
	v_cndmask_b32_e64 v202, v202, v197, s[90:91]
	global_load_dwordx4 v[144:147], v185, s[80:81]
	v_add_u32_e32 v185, 0x2000, v185
	global_load_dwordx4 v[148:151], v185, s[80:81]
	v_add_u32_e32 v185, 0x2000, v185
	global_load_dwordx4 v[152:155], v185, s[80:81]
	v_add_u32_e32 v185, 0x2000, v185
	global_load_dwordx4 v[156:159], v185, s[80:81]
	v_add_u32_e32 v185, 0x2000, v185
	ds_read_b128 v[128:131], v184 offset:12672
	ds_read_b128 v[132:135], v184 offset:13728
	ds_read_b128 v[136:139], v184 offset:14784
	ds_read_b128 v[140:143], v184 offset:15840
	s_waitcnt vmcnt(12) lgkmcnt(0)
; template <int NR>
; DI void rms_rows(const float* __restrict__ xr, const float* __restrict__ g, u16* __restrict__ dst, int lane) {
;     ...
;     for (int i = 0; i < 4; ++i) ss += v[r][i].x * v[r][i].x + v[r][i].y * v[r][i].y + v[r][i].z * v[r][i].z + v[r][i].w * v[r][i].w;
;     ss = wave_sum(ss);
;     const float rr = rsqrtf(ss * (1.f / 1024.f) + 1e-6f);
; #pragma unroll
;     for (int i = 0; i < 4; ++i) {
;       uint2 o;
;       o.x = pack2(v[r][i].x * rr * gg[i].x, v[r][i].y * rr * gg[i].y);
;       o.y = pack2(v[r][i].z * rr * gg[i].z, v[r][i].w * rr * gg[i].w);
;       *(uint2*)(dst + (size_t)r * 1024 + lane * 4 + 256 * i) = o;
; DI void phase_wo(const Params& p, char* smem) {
;     ...
; #pragma unroll
;     for (int i = 0; i < 4; ++i)
; #pragma unroll
;       for (int j = 0; j < 2; ++j)
; #pragma unroll
;         for (int q4 = 0; q4 < 4; ++q4) {
;           const int f = n0 + wm * 128 + i * 32 + q4 * 8 + hh * 4;
;           const size_t t = m0 + wn * 64 + j * 32 + lr;
;           float4 xv = *(const float4*)(p.x + t * 1024 + f);
;           xv.x += acc[i][j][q4 * 4 + 0]; xv.y += acc[i][j][q4 * 4 + 1];
;           xv.z += acc[i][j][q4 * 4 + 2]; xv.w += acc[i][j][q4 * 4 + 3];
;           *(float4*)(X1 + t * 1024 + f) = xv;
;         }
	v_pk_add_f32 v[128:129], v[128:129], v[160:161]
	v_pk_add_f32 v[130:131], v[130:131], v[162:163]
	v_pk_add_f32 v[132:133], v[132:133], v[164:165]
	v_pk_add_f32 v[134:135], v[134:135], v[166:167]
	v_pk_add_f32 v[136:137], v[136:137], v[168:169]
	v_pk_add_f32 v[138:139], v[138:139], v[170:171]
	v_pk_add_f32 v[140:141], v[140:141], v[172:173]
	v_pk_add_f32 v[142:143], v[142:143], v[174:175]
	global_store_dwordx4 v187, v[128:131], s[76:77]
	v_add_u32_e32 v187, 0x2000, v187
	global_store_dwordx4 v187, v[132:135], s[76:77]
	v_add_u32_e32 v187, 0x2000, v187
	global_store_dwordx4 v187, v[136:139], s[76:77]
	v_add_u32_e32 v187, 0x2000, v187
	global_store_dwordx4 v187, v[140:143], s[76:77]
	v_add_u32_e32 v187, 0x2000, v187
	v_mul_f32_e32 v194, v128, v128
	v_mul_f32_e32 v195, v132, v132
	v_mul_f32_e32 v196, v136, v136
	v_mul_f32_e32 v197, v140, v140
	v_fmac_f32_e32 v194, v129, v129
	v_fmac_f32_e32 v195, v133, v133
	v_fmac_f32_e32 v196, v137, v137
	v_fmac_f32_e32 v197, v141, v141
	v_fmac_f32_e32 v194, v130, v130
	v_fmac_f32_e32 v195, v134, v134
	v_fmac_f32_e32 v196, v138, v138
	v_fmac_f32_e32 v197, v142, v142
	v_fmac_f32_e32 v194, v131, v131
	v_fmac_f32_e32 v195, v135, v135
	v_fmac_f32_e32 v196, v139, v139
	v_fmac_f32_e32 v197, v143, v143
	v_pk_mul_f32 v[198:199], v[128:129], v[188:189]
	v_pk_mul_f32 v[200:201], v[130:131], v[190:191]
	v_add_f32_dpp v194, v194, v194 row_ror:8 row_mask:0xf bank_mask:0xf
	v_cvt_pk_bf16_f32 v216, v198, v199
	v_cvt_pk_bf16_f32 v217, v200, v201
	global_store_dwordx2 v204, v[216:217], s[84:85]
	v_add_u32_e32 v204, 0x1000, v204
	v_pk_mul_f32 v[198:199], v[132:133], v[188:189]
	v_pk_mul_f32 v[200:201], v[134:135], v[190:191]
	v_add_f32_dpp v195, v195, v195 row_ror:8 row_mask:0xf bank_mask:0xf
	v_cvt_pk_bf16_f32 v218, v198, v199
	v_cvt_pk_bf16_f32 v219, v200, v201
	global_store_dwordx2 v204, v[218:219], s[84:85]
	v_add_u32_e32 v204, 0x1000, v204
	v_pk_mul_f32 v[198:199], v[136:137], v[188:189]
	v_pk_mul_f32 v[200:201], v[138:139], v[190:191]
	v_add_f32_dpp v196, v196, v196 row_ror:8 row_mask:0xf bank_mask:0xf
	v_cvt_pk_bf16_f32 v220, v198, v199
	v_cvt_pk_bf16_f32 v221, v200, v201
	global_store_dwordx2 v204, v[220:221], s[84:85]
	v_add_u32_e32 v204, 0x1000, v204
	v_pk_mul_f32 v[198:199], v[140:141], v[188:189]
	v_pk_mul_f32 v[200:201], v[142:143], v[190:191]
	v_add_f32_dpp v197, v197, v197 row_ror:8 row_mask:0xf bank_mask:0xf
	v_cvt_pk_bf16_f32 v222, v198, v199
	v_cvt_pk_bf16_f32 v223, v200, v201
	global_store_dwordx2 v204, v[222:223], s[84:85]
	v_add_u32_e32 v204, 0x1000, v204
	v_add_f32_dpp v194, v194, v194 row_ror:4 row_mask:0xf bank_mask:0xf
	v_add_f32_dpp v195, v195, v195 row_ror:4 row_mask:0xf bank_mask:0xf
	v_add_f32_dpp v196, v196, v196 row_ror:4 row_mask:0xf bank_mask:0xf
	v_add_f32_dpp v197, v197, v197 row_ror:4 row_mask:0xf bank_mask:0xf
	v_add_f32_dpp v194, v194, v194 row_ror:2 row_mask:0xf bank_mask:0xf
	v_add_f32_dpp v195, v195, v195 row_ror:2 row_mask:0xf bank_mask:0xf
	v_add_f32_dpp v196, v196, v196 row_ror:2 row_mask:0xf bank_mask:0xf
	v_add_f32_dpp v197, v197, v197 row_ror:2 row_mask:0xf bank_mask:0xf
	v_add_f32_dpp v194, v194, v194 row_ror:1 row_mask:0xf bank_mask:0xf
	v_add_f32_dpp v195, v195, v195 row_ror:1 row_mask:0xf bank_mask:0xf
	v_add_f32_dpp v196, v196, v196 row_ror:1 row_mask:0xf bank_mask:0xf
	v_add_f32_dpp v197, v197, v197 row_ror:1 row_mask:0xf bank_mask:0xf
	v_add_f32_dpp v194, v194, v194 row_bcast:15 row_mask:0xa bank_mask:0xf
	v_add_f32_dpp v195, v195, v195 row_bcast:15 row_mask:0xa bank_mask:0xf
	v_add_f32_dpp v196, v196, v196 row_bcast:15 row_mask:0xa bank_mask:0xf
	v_add_f32_dpp v197, v197, v197 row_bcast:15 row_mask:0xa bank_mask:0xf
	s_mov_b32 s90, 0x10000000
	s_mov_b32 s91, 0x10000000
	v_cndmask_b32_e64 v202, v202, v194, s[90:91]
	s_mov_b32 s90, 0x20000000
	s_mov_b32 s91, 0x20000000
	v_cndmask_b32_e64 v202, v202, v195, s[90:91]
	s_mov_b32 s90, 0x40000000
	s_mov_b32 s91, 0x40000000
	v_cndmask_b32_e64 v202, v202, v196, s[90:91]
	s_mov_b32 s90, 0x80000000
	s_mov_b32 s91, 0x80000000
	v_cndmask_b32_e64 v202, v202, v197, s[90:91]
	ds_write_b128 v183, v[96:99] offset:0
	ds_write_b128 v183, v[100:103] offset:32
	ds_write_b128 v183, v[104:107] offset:64
	ds_write_b128 v183, v[108:111] offset:96
	ds_write_b128 v183, v[64:67] offset:128
	ds_write_b128 v183, v[68:71] offset:160
	ds_write_b128 v183, v[72:75] offset:192
	ds_write_b128 v183, v[76:79] offset:224
	ds_write_b128 v183, v[32:35] offset:256
	ds_write_b128 v183, v[36:39] offset:288
	ds_write_b128 v183, v[40:43] offset:320
	ds_write_b128 v183, v[44:47] offset:352
	ds_write_b128 v183, v[0:3] offset:384
	ds_write_b128 v183, v[4:7] offset:416
	ds_write_b128 v183, v[8:11] offset:448
	ds_write_b128 v183, v[12:15] offset:480
	global_load_dwordx4 v[160:163], v185, s[80:81]
	v_add_u32_e32 v185, 0x2000, v185
	global_load_dwordx4 v[164:167], v185, s[80:81]
	v_add_u32_e32 v185, 0x2000, v185
	global_load_dwordx4 v[168:171], v185, s[80:81]
	v_add_u32_e32 v185, 0x2000, v185
	global_load_dwordx4 v[172:175], v185, s[80:81]
	v_add_u32_e32 v185, 0x2000, v185
	ds_read_b128 v[128:131], v184 offset:0
	ds_read_b128 v[132:135], v184 offset:1056
	ds_read_b128 v[136:139], v184 offset:2112
	ds_read_b128 v[140:143], v184 offset:3168
	s_waitcnt vmcnt(12) lgkmcnt(0)
; template <int NR>
; DI void rms_rows(const float* __restrict__ xr, const float* __restrict__ g, u16* __restrict__ dst, int lane) {
;     ...
;     for (int i = 0; i < 4; ++i) ss += v[r][i].x * v[r][i].x + v[r][i].y * v[r][i].y + v[r][i].z * v[r][i].z + v[r][i].w * v[r][i].w;
;     ss = wave_sum(ss);
;     const float rr = rsqrtf(ss * (1.f / 1024.f) + 1e-6f);
; #pragma unroll
;     for (int i = 0; i < 4; ++i) {
;       uint2 o;
;       o.x = pack2(v[r][i].x * rr * gg[i].x, v[r][i].y * rr * gg[i].y);
;       o.y = pack2(v[r][i].z * rr * gg[i].z, v[r][i].w * rr * gg[i].w);
;       *(uint2*)(dst + (size_t)r * 1024 + lane * 4 + 256 * i) = o;
; DI void phase_wo(const Params& p, char* smem) {
;     ...
; #pragma unroll
;     for (int i = 0; i < 4; ++i)
; #pragma unroll
;       for (int j = 0; j < 2; ++j)
; #pragma unroll
;         for (int q4 = 0; q4 < 4; ++q4) {
;           const int f = n0 + wm * 128 + i * 32 + q4 * 8 + hh * 4;
;           const size_t t = m0 + wn * 64 + j * 32 + lr;
;           float4 xv = *(const float4*)(p.x + t * 1024 + f);
;           xv.x += acc[i][j][q4 * 4 + 0]; xv.y += acc[i][j][q4 * 4 + 1];
;           xv.z += acc[i][j][q4 * 4 + 2]; xv.w += acc[i][j][q4 * 4 + 3];
;           *(float4*)(X1 + t * 1024 + f) = xv;
;         }
	v_pk_add_f32 v[128:129], v[128:129], v[144:145]
	v_pk_add_f32 v[130:131], v[130:131], v[146:147]
	v_pk_add_f32 v[132:133], v[132:133], v[148:149]
	v_pk_add_f32 v[134:135], v[134:135], v[150:151]
	v_pk_add_f32 v[136:137], v[136:137], v[152:153]
	v_pk_add_f32 v[138:139], v[138:139], v[154:155]
	v_pk_add_f32 v[140:141], v[140:141], v[156:157]
	v_pk_add_f32 v[142:143], v[142:143], v[158:159]
	global_store_dwordx4 v187, v[128:131], s[76:77]
	v_add_u32_e32 v187, 0x2000, v187
	global_store_dwordx4 v187, v[132:135], s[76:77]
	v_add_u32_e32 v187, 0x2000, v187
	global_store_dwordx4 v187, v[136:139], s[76:77]
	v_add_u32_e32 v187, 0x2000, v187
	global_store_dwordx4 v187, v[140:143], s[76:77]
	v_add_u32_e32 v187, 0x2000, v187
	v_mul_f32_e32 v194, v128, v128
	v_mul_f32_e32 v195, v132, v132
	v_mul_f32_e32 v196, v136, v136
	v_mul_f32_e32 v197, v140, v140
	v_fmac_f32_e32 v194, v129, v129
	v_fmac_f32_e32 v195, v133, v133
	v_fmac_f32_e32 v196, v137, v137
	v_fmac_f32_e32 v197, v141, v141
	v_fmac_f32_e32 v194, v130, v130
	v_fmac_f32_e32 v195, v134, v134
	v_fmac_f32_e32 v196, v138, v138
	v_fmac_f32_e32 v197, v142, v142
	v_fmac_f32_e32 v194, v131, v131
	v_fmac_f32_e32 v195, v135, v135
	v_fmac_f32_e32 v196, v139, v139
	v_fmac_f32_e32 v197, v143, v143
	v_pk_mul_f32 v[198:199], v[128:129], v[188:189]
	v_pk_mul_f32 v[200:201], v[130:131], v[190:191]
	v_add_f32_dpp v194, v194, v194 row_ror:8 row_mask:0xf bank_mask:0xf
	v_cvt_pk_bf16_f32 v216, v198, v199
	v_cvt_pk_bf16_f32 v217, v200, v201
	global_store_dwordx2 v204, v[216:217], s[84:85]
	v_add_u32_e32 v204, 0x1000, v204
	v_pk_mul_f32 v[198:199], v[132:133], v[188:189]
	v_pk_mul_f32 v[200:201], v[134:135], v[190:191]
	v_add_f32_dpp v195, v195, v195 row_ror:8 row_mask:0xf bank_mask:0xf
	v_cvt_pk_bf16_f32 v218, v198, v199
	v_cvt_pk_bf16_f32 v219, v200, v201
	global_store_dwordx2 v204, v[218:219], s[84:85]
	v_add_u32_e32 v204, 0x1000, v204
	v_pk_mul_f32 v[198:199], v[136:137], v[188:189]
	v_pk_mul_f32 v[200:201], v[138:139], v[190:191]
	v_add_f32_dpp v196, v196, v196 row_ror:8 row_mask:0xf bank_mask:0xf
	v_cvt_pk_bf16_f32 v220, v198, v199
	v_cvt_pk_bf16_f32 v221, v200, v201
	global_store_dwordx2 v204, v[220:221], s[84:85]
	v_add_u32_e32 v204, 0x1000, v204
	v_pk_mul_f32 v[198:199], v[140:141], v[188:189]
	v_pk_mul_f32 v[200:201], v[142:143], v[190:191]
	v_add_f32_dpp v197, v197, v197 row_ror:8 row_mask:0xf bank_mask:0xf
	v_cvt_pk_bf16_f32 v222, v198, v199
	v_cvt_pk_bf16_f32 v223, v200, v201
	global_store_dwordx2 v204, v[222:223], s[84:85]
	v_add_u32_e32 v204, 0x1000, v204
	v_add_f32_dpp v194, v194, v194 row_ror:4 row_mask:0xf bank_mask:0xf
	v_add_f32_dpp v195, v195, v195 row_ror:4 row_mask:0xf bank_mask:0xf
	v_add_f32_dpp v196, v196, v196 row_ror:4 row_mask:0xf bank_mask:0xf
	v_add_f32_dpp v197, v197, v197 row_ror:4 row_mask:0xf bank_mask:0xf
	v_add_f32_dpp v194, v194, v194 row_ror:2 row_mask:0xf bank_mask:0xf
	v_add_f32_dpp v195, v195, v195 row_ror:2 row_mask:0xf bank_mask:0xf
	v_add_f32_dpp v196, v196, v196 row_ror:2 row_mask:0xf bank_mask:0xf
	v_add_f32_dpp v197, v197, v197 row_ror:2 row_mask:0xf bank_mask:0xf
	v_add_f32_dpp v194, v194, v194 row_ror:1 row_mask:0xf bank_mask:0xf
	v_add_f32_dpp v195, v195, v195 row_ror:1 row_mask:0xf bank_mask:0xf
	v_add_f32_dpp v196, v196, v196 row_ror:1 row_mask:0xf bank_mask:0xf
	v_add_f32_dpp v197, v197, v197 row_ror:1 row_mask:0xf bank_mask:0xf
	v_add_f32_dpp v194, v194, v194 row_bcast:15 row_mask:0xa bank_mask:0xf
	v_add_f32_dpp v195, v195, v195 row_bcast:15 row_mask:0xa bank_mask:0xf
	v_add_f32_dpp v196, v196, v196 row_bcast:15 row_mask:0xa bank_mask:0xf
	v_add_f32_dpp v197, v197, v197 row_bcast:15 row_mask:0xa bank_mask:0xf
	s_mov_b32 s90, 0x10000
	s_mov_b32 s91, 0x10000
	v_cndmask_b32_e64 v203, v203, v194, s[90:91]
	s_mov_b32 s90, 0x20000
	s_mov_b32 s91, 0x20000
	v_cndmask_b32_e64 v203, v203, v195, s[90:91]
	s_mov_b32 s90, 0x40000
	s_mov_b32 s91, 0x40000
	v_cndmask_b32_e64 v203, v203, v196, s[90:91]
	s_mov_b32 s90, 0x80000
	s_mov_b32 s91, 0x80000
	v_cndmask_b32_e64 v203, v203, v197, s[90:91]
	global_load_dwordx4 v[144:147], v185, s[80:81]
	v_add_u32_e32 v185, 0x2000, v185
	global_load_dwordx4 v[148:151], v185, s[80:81]
	v_add_u32_e32 v185, 0x2000, v185
	global_load_dwordx4 v[152:155], v185, s[80:81]
	v_add_u32_e32 v185, 0x2000, v185
	global_load_dwordx4 v[156:159], v185, s[80:81]
	v_add_u32_e32 v185, 0x2000, v185
	ds_read_b128 v[128:131], v184 offset:4224
	ds_read_b128 v[132:135], v184 offset:5280
	ds_read_b128 v[136:139], v184 offset:6336
	ds_read_b128 v[140:143], v184 offset:7392
	s_waitcnt vmcnt(12) lgkmcnt(0)
; template <int NR>
; DI void rms_rows(const float* __restrict__ xr, const float* __restrict__ g, u16* __restrict__ dst, int lane) {
;     ...
;     for (int i = 0; i < 4; ++i) ss += v[r][i].x * v[r][i].x + v[r][i].y * v[r][i].y + v[r][i].z * v[r][i].z + v[r][i].w * v[r][i].w;
;     ss = wave_sum(ss);
;     const float rr = rsqrtf(ss * (1.f / 1024.f) + 1e-6f);
; #pragma unroll
;     for (int i = 0; i < 4; ++i) {
;       uint2 o;
;       o.x = pack2(v[r][i].x * rr * gg[i].x, v[r][i].y * rr * gg[i].y);
;       o.y = pack2(v[r][i].z * rr * gg[i].z, v[r][i].w * rr * gg[i].w);
;       *(uint2*)(dst + (size_t)r * 1024 + lane * 4 + 256 * i) = o;
; DI void phase_wo(const Params& p, char* smem) {
;     ...
; #pragma unroll
;     for (int i = 0; i < 4; ++i)
; #pragma unroll
;       for (int j = 0; j < 2; ++j)
; #pragma unroll
;         for (int q4 = 0; q4 < 4; ++q4) {
;           const int f = n0 + wm * 128 + i * 32 + q4 * 8 + hh * 4;
;           const size_t t = m0 + wn * 64 + j * 32 + lr;
;           float4 xv = *(const float4*)(p.x + t * 1024 + f);
;           xv.x += acc[i][j][q4 * 4 + 0]; xv.y += acc[i][j][q4 * 4 + 1];
;           xv.z += acc[i][j][q4 * 4 + 2]; xv.w += acc[i][j][q4 * 4 + 3];
;           *(float4*)(X1 + t * 1024 + f) = xv;
;         }
	v_pk_add_f32 v[128:129], v[128:129], v[160:161]
	v_pk_add_f32 v[130:131], v[130:131], v[162:163]
	v_pk_add_f32 v[132:133], v[132:133], v[164:165]
	v_pk_add_f32 v[134:135], v[134:135], v[166:167]
	v_pk_add_f32 v[136:137], v[136:137], v[168:169]
	v_pk_add_f32 v[138:139], v[138:139], v[170:171]
	v_pk_add_f32 v[140:141], v[140:141], v[172:173]
	v_pk_add_f32 v[142:143], v[142:143], v[174:175]
	global_store_dwordx4 v187, v[128:131], s[76:77]
	v_add_u32_e32 v187, 0x2000, v187
	global_store_dwordx4 v187, v[132:135], s[76:77]
	v_add_u32_e32 v187, 0x2000, v187
	global_store_dwordx4 v187, v[136:139], s[76:77]
	v_add_u32_e32 v187, 0x2000, v187
	global_store_dwordx4 v187, v[140:143], s[76:77]
	v_add_u32_e32 v187, 0x2000, v187
	v_mul_f32_e32 v194, v128, v128
	v_mul_f32_e32 v195, v132, v132
	v_mul_f32_e32 v196, v136, v136
	v_mul_f32_e32 v197, v140, v140
	v_fmac_f32_e32 v194, v129, v129
	v_fmac_f32_e32 v195, v133, v133
	v_fmac_f32_e32 v196, v137, v137
	v_fmac_f32_e32 v197, v141, v141
	v_fmac_f32_e32 v194, v130, v130
	v_fmac_f32_e32 v195, v134, v134
	v_fmac_f32_e32 v196, v138, v138
	v_fmac_f32_e32 v197, v142, v142
	v_fmac_f32_e32 v194, v131, v131
	v_fmac_f32_e32 v195, v135, v135
	v_fmac_f32_e32 v196, v139, v139
	v_fmac_f32_e32 v197, v143, v143
	v_pk_mul_f32 v[198:199], v[128:129], v[188:189]
	v_pk_mul_f32 v[200:201], v[130:131], v[190:191]
	v_add_f32_dpp v194, v194, v194 row_ror:8 row_mask:0xf bank_mask:0xf
	v_cvt_pk_bf16_f32 v216, v198, v199
	v_cvt_pk_bf16_f32 v217, v200, v201
	global_store_dwordx2 v204, v[216:217], s[84:85]
	v_add_u32_e32 v204, 0x1000, v204
	v_pk_mul_f32 v[198:199], v[132:133], v[188:189]
	v_pk_mul_f32 v[200:201], v[134:135], v[190:191]
	v_add_f32_dpp v195, v195, v195 row_ror:8 row_mask:0xf bank_mask:0xf
	v_cvt_pk_bf16_f32 v218, v198, v199
	v_cvt_pk_bf16_f32 v219, v200, v201
	global_store_dwordx2 v204, v[218:219], s[84:85]
	v_add_u32_e32 v204, 0x1000, v204
	v_pk_mul_f32 v[198:199], v[136:137], v[188:189]
	v_pk_mul_f32 v[200:201], v[138:139], v[190:191]
	v_add_f32_dpp v196, v196, v196 row_ror:8 row_mask:0xf bank_mask:0xf
	v_cvt_pk_bf16_f32 v220, v198, v199
	v_cvt_pk_bf16_f32 v221, v200, v201
	global_store_dwordx2 v204, v[220:221], s[84:85]
	v_add_u32_e32 v204, 0x1000, v204
	v_pk_mul_f32 v[198:199], v[140:141], v[188:189]
	v_pk_mul_f32 v[200:201], v[142:143], v[190:191]
	v_add_f32_dpp v197, v197, v197 row_ror:8 row_mask:0xf bank_mask:0xf
	v_cvt_pk_bf16_f32 v222, v198, v199
	v_cvt_pk_bf16_f32 v223, v200, v201
	global_store_dwordx2 v204, v[222:223], s[84:85]
	v_add_u32_e32 v204, 0x1000, v204
	v_add_f32_dpp v194, v194, v194 row_ror:4 row_mask:0xf bank_mask:0xf
	v_add_f32_dpp v195, v195, v195 row_ror:4 row_mask:0xf bank_mask:0xf
	v_add_f32_dpp v196, v196, v196 row_ror:4 row_mask:0xf bank_mask:0xf
	v_add_f32_dpp v197, v197, v197 row_ror:4 row_mask:0xf bank_mask:0xf
	v_add_f32_dpp v194, v194, v194 row_ror:2 row_mask:0xf bank_mask:0xf
	v_add_f32_dpp v195, v195, v195 row_ror:2 row_mask:0xf bank_mask:0xf
	v_add_f32_dpp v196, v196, v196 row_ror:2 row_mask:0xf bank_mask:0xf
	v_add_f32_dpp v197, v197, v197 row_ror:2 row_mask:0xf bank_mask:0xf
	v_add_f32_dpp v194, v194, v194 row_ror:1 row_mask:0xf bank_mask:0xf
	v_add_f32_dpp v195, v195, v195 row_ror:1 row_mask:0xf bank_mask:0xf
	v_add_f32_dpp v196, v196, v196 row_ror:1 row_mask:0xf bank_mask:0xf
	v_add_f32_dpp v197, v197, v197 row_ror:1 row_mask:0xf bank_mask:0xf
	v_add_f32_dpp v194, v194, v194 row_bcast:15 row_mask:0xa bank_mask:0xf
	v_add_f32_dpp v195, v195, v195 row_bcast:15 row_mask:0xa bank_mask:0xf
	v_add_f32_dpp v196, v196, v196 row_bcast:15 row_mask:0xa bank_mask:0xf
	v_add_f32_dpp v197, v197, v197 row_bcast:15 row_mask:0xa bank_mask:0xf
	s_mov_b32 s90, 0x100000
	s_mov_b32 s91, 0x100000
	v_cndmask_b32_e64 v203, v203, v194, s[90:91]
	s_mov_b32 s90, 0x200000
	s_mov_b32 s91, 0x200000
	v_cndmask_b32_e64 v203, v203, v195, s[90:91]
	s_mov_b32 s90, 0x400000
	s_mov_b32 s91, 0x400000
	v_cndmask_b32_e64 v203, v203, v196, s[90:91]
	s_mov_b32 s90, 0x800000
	s_mov_b32 s91, 0x800000
	v_cndmask_b32_e64 v203, v203, v197, s[90:91]
	global_load_dwordx4 v[160:163], v185, s[80:81]
	v_add_u32_e32 v185, 0x2000, v185
	global_load_dwordx4 v[164:167], v185, s[80:81]
	v_add_u32_e32 v185, 0x2000, v185
	global_load_dwordx4 v[168:171], v185, s[80:81]
	v_add_u32_e32 v185, 0x2000, v185
	global_load_dwordx4 v[172:175], v185, s[80:81]
	v_add_u32_e32 v185, 0x2000, v185
	ds_read_b128 v[128:131], v184 offset:8448
	ds_read_b128 v[132:135], v184 offset:9504
	ds_read_b128 v[136:139], v184 offset:10560
	ds_read_b128 v[140:143], v184 offset:11616
	s_waitcnt vmcnt(12) lgkmcnt(0)
; template <int NR>
; DI void rms_rows(const float* __restrict__ xr, const float* __restrict__ g, u16* __restrict__ dst, int lane) {
;     ...
;     for (int i = 0; i < 4; ++i) ss += v[r][i].x * v[r][i].x + v[r][i].y * v[r][i].y + v[r][i].z * v[r][i].z + v[r][i].w * v[r][i].w;
;     ss = wave_sum(ss);
;     const float rr = rsqrtf(ss * (1.f / 1024.f) + 1e-6f);
; #pragma unroll
;     for (int i = 0; i < 4; ++i) {
;       uint2 o;
;       o.x = pack2(v[r][i].x * rr * gg[i].x, v[r][i].y * rr * gg[i].y);
;       o.y = pack2(v[r][i].z * rr * gg[i].z, v[r][i].w * rr * gg[i].w);
;       *(uint2*)(dst + (size_t)r * 1024 + lane * 4 + 256 * i) = o;
; DI void phase_wo(const Params& p, char* smem) {
;     ...
; #pragma unroll
;     for (int i = 0; i < 4; ++i)
; #pragma unroll
;       for (int j = 0; j < 2; ++j)
; #pragma unroll
;         for (int q4 = 0; q4 < 4; ++q4) {
;           const int f = n0 + wm * 128 + i * 32 + q4 * 8 + hh * 4;
;           const size_t t = m0 + wn * 64 + j * 32 + lr;
;           float4 xv = *(const float4*)(p.x + t * 1024 + f);
;           xv.x += acc[i][j][q4 * 4 + 0]; xv.y += acc[i][j][q4 * 4 + 1];
;           xv.z += acc[i][j][q4 * 4 + 2]; xv.w += acc[i][j][q4 * 4 + 3];
;           *(float4*)(X1 + t * 1024 + f) = xv;
;         }
	v_pk_add_f32 v[128:129], v[128:129], v[144:145]
	v_pk_add_f32 v[130:131], v[130:131], v[146:147]
	v_pk_add_f32 v[132:133], v[132:133], v[148:149]
	v_pk_add_f32 v[134:135], v[134:135], v[150:151]
	v_pk_add_f32 v[136:137], v[136:137], v[152:153]
	v_pk_add_f32 v[138:139], v[138:139], v[154:155]
	v_pk_add_f32 v[140:141], v[140:141], v[156:157]
	v_pk_add_f32 v[142:143], v[142:143], v[158:159]
	global_store_dwordx4 v187, v[128:131], s[76:77]
	v_add_u32_e32 v187, 0x2000, v187
	global_store_dwordx4 v187, v[132:135], s[76:77]
	v_add_u32_e32 v187, 0x2000, v187
	global_store_dwordx4 v187, v[136:139], s[76:77]
	v_add_u32_e32 v187, 0x2000, v187
	global_store_dwordx4 v187, v[140:143], s[76:77]
	v_add_u32_e32 v187, 0x2000, v187
	v_mul_f32_e32 v194, v128, v128
	v_mul_f32_e32 v195, v132, v132
	v_mul_f32_e32 v196, v136, v136
	v_mul_f32_e32 v197, v140, v140
	v_fmac_f32_e32 v194, v129, v129
	v_fmac_f32_e32 v195, v133, v133
	v_fmac_f32_e32 v196, v137, v137
	v_fmac_f32_e32 v197, v141, v141
	v_fmac_f32_e32 v194, v130, v130
	v_fmac_f32_e32 v195, v134, v134
	v_fmac_f32_e32 v196, v138, v138
	v_fmac_f32_e32 v197, v142, v142
	v_fmac_f32_e32 v194, v131, v131
	v_fmac_f32_e32 v195, v135, v135
	v_fmac_f32_e32 v196, v139, v139
	v_fmac_f32_e32 v197, v143, v143
	v_pk_mul_f32 v[198:199], v[128:129], v[188:189]
	v_pk_mul_f32 v[200:201], v[130:131], v[190:191]
	v_add_f32_dpp v194, v194, v194 row_ror:8 row_mask:0xf bank_mask:0xf
	v_cvt_pk_bf16_f32 v216, v198, v199
	v_cvt_pk_bf16_f32 v217, v200, v201
	global_store_dwordx2 v204, v[216:217], s[84:85]
	v_add_u32_e32 v204, 0x1000, v204
	v_pk_mul_f32 v[198:199], v[132:133], v[188:189]
	v_pk_mul_f32 v[200:201], v[134:135], v[190:191]
	v_add_f32_dpp v195, v195, v195 row_ror:8 row_mask:0xf bank_mask:0xf
	v_cvt_pk_bf16_f32 v218, v198, v199
	v_cvt_pk_bf16_f32 v219, v200, v201
	global_store_dwordx2 v204, v[218:219], s[84:85]
	v_add_u32_e32 v204, 0x1000, v204
	v_pk_mul_f32 v[198:199], v[136:137], v[188:189]
	v_pk_mul_f32 v[200:201], v[138:139], v[190:191]
	v_add_f32_dpp v196, v196, v196 row_ror:8 row_mask:0xf bank_mask:0xf
	v_cvt_pk_bf16_f32 v220, v198, v199
	v_cvt_pk_bf16_f32 v221, v200, v201
	global_store_dwordx2 v204, v[220:221], s[84:85]
	v_add_u32_e32 v204, 0x1000, v204
	v_pk_mul_f32 v[198:199], v[140:141], v[188:189]
	v_pk_mul_f32 v[200:201], v[142:143], v[190:191]
	v_add_f32_dpp v197, v197, v197 row_ror:8 row_mask:0xf bank_mask:0xf
	v_cvt_pk_bf16_f32 v222, v198, v199
	v_cvt_pk_bf16_f32 v223, v200, v201
	global_store_dwordx2 v204, v[222:223], s[84:85]
	v_add_u32_e32 v204, 0x1000, v204
	v_add_f32_dpp v194, v194, v194 row_ror:4 row_mask:0xf bank_mask:0xf
	v_add_f32_dpp v195, v195, v195 row_ror:4 row_mask:0xf bank_mask:0xf
	v_add_f32_dpp v196, v196, v196 row_ror:4 row_mask:0xf bank_mask:0xf
	v_add_f32_dpp v197, v197, v197 row_ror:4 row_mask:0xf bank_mask:0xf
	v_add_f32_dpp v194, v194, v194 row_ror:2 row_mask:0xf bank_mask:0xf
	v_add_f32_dpp v195, v195, v195 row_ror:2 row_mask:0xf bank_mask:0xf
	v_add_f32_dpp v196, v196, v196 row_ror:2 row_mask:0xf bank_mask:0xf
	v_add_f32_dpp v197, v197, v197 row_ror:2 row_mask:0xf bank_mask:0xf
	v_add_f32_dpp v194, v194, v194 row_ror:1 row_mask:0xf bank_mask:0xf
	v_add_f32_dpp v195, v195, v195 row_ror:1 row_mask:0xf bank_mask:0xf
	v_add_f32_dpp v196, v196, v196 row_ror:1 row_mask:0xf bank_mask:0xf
	v_add_f32_dpp v197, v197, v197 row_ror:1 row_mask:0xf bank_mask:0xf
	v_add_f32_dpp v194, v194, v194 row_bcast:15 row_mask:0xa bank_mask:0xf
	v_add_f32_dpp v195, v195, v195 row_bcast:15 row_mask:0xa bank_mask:0xf
	v_add_f32_dpp v196, v196, v196 row_bcast:15 row_mask:0xa bank_mask:0xf
	v_add_f32_dpp v197, v197, v197 row_bcast:15 row_mask:0xa bank_mask:0xf
	s_mov_b32 s90, 0x1000000
	s_mov_b32 s91, 0x1000000
	v_cndmask_b32_e64 v203, v203, v194, s[90:91]
	s_mov_b32 s90, 0x2000000
	s_mov_b32 s91, 0x2000000
	v_cndmask_b32_e64 v203, v203, v195, s[90:91]
	s_mov_b32 s90, 0x4000000
	s_mov_b32 s91, 0x4000000
	v_cndmask_b32_e64 v203, v203, v196, s[90:91]
	s_mov_b32 s90, 0x8000000
	s_mov_b32 s91, 0x8000000
	v_cndmask_b32_e64 v203, v203, v197, s[90:91]
	ds_read_b128 v[128:131], v184 offset:12672
	ds_read_b128 v[132:135], v184 offset:13728
	ds_read_b128 v[136:139], v184 offset:14784
	ds_read_b128 v[140:143], v184 offset:15840
	s_waitcnt vmcnt(8) lgkmcnt(0)
; template <int NR>
; DI void rms_rows(const float* __restrict__ xr, const float* __restrict__ g, u16* __restrict__ dst, int lane) {
;     ...
;     for (int i = 0; i < 4; ++i) ss += v[r][i].x * v[r][i].x + v[r][i].y * v[r][i].y + v[r][i].z * v[r][i].z + v[r][i].w * v[r][i].w;
;     ss = wave_sum(ss);
;     const float rr = rsqrtf(ss * (1.f / 1024.f) + 1e-6f);
; #pragma unroll
;     for (int i = 0; i < 4; ++i) {
;       uint2 o;
;       o.x = pack2(v[r][i].x * rr * gg[i].x, v[r][i].y * rr * gg[i].y);
;       o.y = pack2(v[r][i].z * rr * gg[i].z, v[r][i].w * rr * gg[i].w);
;       *(uint2*)(dst + (size_t)r * 1024 + lane * 4 + 256 * i) = o;
; DI void phase_wo(const Params& p, char* smem) {
;     ...
; #pragma unroll
;     for (int i = 0; i < 4; ++i)
; #pragma unroll
;       for (int j = 0; j < 2; ++j)
; #pragma unroll
;         for (int q4 = 0; q4 < 4; ++q4) {
;           const int f = n0 + wm * 128 + i * 32 + q4 * 8 + hh * 4;
;           const size_t t = m0 + wn * 64 + j * 32 + lr;
;           float4 xv = *(const float4*)(p.x + t * 1024 + f);
;           xv.x += acc[i][j][q4 * 4 + 0]; xv.y += acc[i][j][q4 * 4 + 1];
;           xv.z += acc[i][j][q4 * 4 + 2]; xv.w += acc[i][j][q4 * 4 + 3];
;           *(float4*)(X1 + t * 1024 + f) = xv;
;         }
	v_pk_add_f32 v[128:129], v[128:129], v[160:161]
	v_pk_add_f32 v[130:131], v[130:131], v[162:163]
	v_pk_add_f32 v[132:133], v[132:133], v[164:165]
	v_pk_add_f32 v[134:135], v[134:135], v[166:167]
	v_pk_add_f32 v[136:137], v[136:137], v[168:169]
	v_pk_add_f32 v[138:139], v[138:139], v[170:171]
	v_pk_add_f32 v[140:141], v[140:141], v[172:173]
	v_pk_add_f32 v[142:143], v[142:143], v[174:175]
	global_store_dwordx4 v187, v[128:131], s[76:77]
	v_add_u32_e32 v187, 0x2000, v187
	global_store_dwordx4 v187, v[132:135], s[76:77]
	v_add_u32_e32 v187, 0x2000, v187
	global_store_dwordx4 v187, v[136:139], s[76:77]
	v_add_u32_e32 v187, 0x2000, v187
	global_store_dwordx4 v187, v[140:143], s[76:77]
	v_add_u32_e32 v187, 0x2000, v187
	v_mul_f32_e32 v194, v128, v128
	v_mul_f32_e32 v195, v132, v132
	v_mul_f32_e32 v196, v136, v136
	v_mul_f32_e32 v197, v140, v140
	v_fmac_f32_e32 v194, v129, v129
	v_fmac_f32_e32 v195, v133, v133
	v_fmac_f32_e32 v196, v137, v137
	v_fmac_f32_e32 v197, v141, v141
	v_fmac_f32_e32 v194, v130, v130
	v_fmac_f32_e32 v195, v134, v134
	v_fmac_f32_e32 v196, v138, v138
	v_fmac_f32_e32 v197, v142, v142
	v_fmac_f32_e32 v194, v131, v131
	v_fmac_f32_e32 v195, v135, v135
	v_fmac_f32_e32 v196, v139, v139
	v_fmac_f32_e32 v197, v143, v143
	v_pk_mul_f32 v[198:199], v[128:129], v[188:189]
	v_pk_mul_f32 v[200:201], v[130:131], v[190:191]
	v_add_f32_dpp v194, v194, v194 row_ror:8 row_mask:0xf bank_mask:0xf
	v_cvt_pk_bf16_f32 v216, v198, v199
	v_cvt_pk_bf16_f32 v217, v200, v201
	global_store_dwordx2 v204, v[216:217], s[84:85]
	v_add_u32_e32 v204, 0x1000, v204
	v_pk_mul_f32 v[198:199], v[132:133], v[188:189]
	v_pk_mul_f32 v[200:201], v[134:135], v[190:191]
	v_add_f32_dpp v195, v195, v195 row_ror:8 row_mask:0xf bank_mask:0xf
	v_cvt_pk_bf16_f32 v218, v198, v199
	v_cvt_pk_bf16_f32 v219, v200, v201
	global_store_dwordx2 v204, v[218:219], s[84:85]
	v_add_u32_e32 v204, 0x1000, v204
	v_pk_mul_f32 v[198:199], v[136:137], v[188:189]
	v_pk_mul_f32 v[200:201], v[138:139], v[190:191]
	v_add_f32_dpp v196, v196, v196 row_ror:8 row_mask:0xf bank_mask:0xf
	v_cvt_pk_bf16_f32 v220, v198, v199
	v_cvt_pk_bf16_f32 v221, v200, v201
	global_store_dwordx2 v204, v[220:221], s[84:85]
	v_add_u32_e32 v204, 0x1000, v204
	v_pk_mul_f32 v[198:199], v[140:141], v[188:189]
	v_pk_mul_f32 v[200:201], v[142:143], v[190:191]
	v_add_f32_dpp v197, v197, v197 row_ror:8 row_mask:0xf bank_mask:0xf
	v_cvt_pk_bf16_f32 v222, v198, v199
	v_cvt_pk_bf16_f32 v223, v200, v201
	global_store_dwordx2 v204, v[222:223], s[84:85]
	v_add_u32_e32 v204, 0x1000, v204
	v_add_f32_dpp v194, v194, v194 row_ror:4 row_mask:0xf bank_mask:0xf
	v_add_f32_dpp v195, v195, v195 row_ror:4 row_mask:0xf bank_mask:0xf
	v_add_f32_dpp v196, v196, v196 row_ror:4 row_mask:0xf bank_mask:0xf
	v_add_f32_dpp v197, v197, v197 row_ror:4 row_mask:0xf bank_mask:0xf
	v_add_f32_dpp v194, v194, v194 row_ror:2 row_mask:0xf bank_mask:0xf
	v_add_f32_dpp v195, v195, v195 row_ror:2 row_mask:0xf bank_mask:0xf
	v_add_f32_dpp v196, v196, v196 row_ror:2 row_mask:0xf bank_mask:0xf
	v_add_f32_dpp v197, v197, v197 row_ror:2 row_mask:0xf bank_mask:0xf
	v_add_f32_dpp v194, v194, v194 row_ror:1 row_mask:0xf bank_mask:0xf
	v_add_f32_dpp v195, v195, v195 row_ror:1 row_mask:0xf bank_mask:0xf
	v_add_f32_dpp v196, v196, v196 row_ror:1 row_mask:0xf bank_mask:0xf
	v_add_f32_dpp v197, v197, v197 row_ror:1 row_mask:0xf bank_mask:0xf
	v_add_f32_dpp v194, v194, v194 row_bcast:15 row_mask:0xa bank_mask:0xf
	v_add_f32_dpp v195, v195, v195 row_bcast:15 row_mask:0xa bank_mask:0xf
	v_add_f32_dpp v196, v196, v196 row_bcast:15 row_mask:0xa bank_mask:0xf
	v_add_f32_dpp v197, v197, v197 row_bcast:15 row_mask:0xa bank_mask:0xf
	s_mov_b32 s90, 0x10000000
	s_mov_b32 s91, 0x10000000
	v_cndmask_b32_e64 v203, v203, v194, s[90:91]
	s_mov_b32 s90, 0x20000000
	s_mov_b32 s91, 0x20000000
	v_cndmask_b32_e64 v203, v203, v195, s[90:91]
	s_mov_b32 s90, 0x40000000
	s_mov_b32 s91, 0x40000000
	v_cndmask_b32_e64 v203, v203, v196, s[90:91]
	s_mov_b32 s90, 0x80000000
	s_mov_b32 s91, 0x80000000
	v_cndmask_b32_e64 v203, v203, v197, s[90:91]
	s_mov_b32 exec_lo, 0xffff0000
	s_mov_b32 exec_hi, 0xffff0000
	global_store_dword v205, v202, s[86:87]
	global_store_dword v205, v203, s[86:87] offset:1024
	s_mov_b64 exec, -1
	s_cmp_lt_u32 s4, 32
	s_cbranch_scc1 .LBB0_865
	s_mov_b32 s88, s17

; DI int my_tid() { int t = threadIdx.x & 255; asm volatile("" : "+v"(t)); return t; }
; DI int vb_id() { return (int)blockIdx.x + half_id() * (int)gridDim.x; }
; DI int vb_n() { return (int)gridDim.x * 2; }
; DI void phase_norm2(const Params& p) {
;   const int tid = my_tid(); const int lane = tid & 63, wave = tid >> 6;
;   u16* XN2 = (u16*)(p.ws + WS_Q);
;   for (int it = vb_id(); it < 1024; it += vb_n()) {
;     int row = it * 16 + wave * 4;
;     rms_rows<4>(p.out + (size_t)row * 1024, p.g_ffn, XN2 + (size_t)row * 1024, lane);
;   }
; }
.LBB0_921:
	s_or_b64 exec, exec, s[2:3]
	v_readfirstlane_b32 s2, v211
	s_lshr_b32 s2, s2, 8
	s_mul_i32 s2, s2, s60
	s_add_i32 s3, s2, s55
	v_mov_b32_e32 v16, v210
	s_cmpk_gt_i32 s3, 0x3ff
	s_waitcnt lgkmcnt(0)
	s_barrier
	s_branch .Ln2_skip
	v_lshlrev_b32_e32 v0, 2, v16
	v_and_b32_e32 v0, 0xfc, v0
	v_lshlrev_b32_e32 v18, 1, v0
	v_mov_b32_e32 v19, 0
	v_lshl_add_u64 v[20:21], s[78:79], 0, v[18:19]
	v_lshlrev_b32_e32 v18, 2, v0
	global_load_dwordx4 v[0:3], v18, s[64:65]
	global_load_dwordx4 v[4:7], v18, s[64:65] offset:1024
	global_load_dwordx4 v[8:11], v18, s[64:65] offset:2048
	global_load_dwordx4 v[12:15], v18, s[64:65] offset:3072
	v_mbcnt_hi_u32_b32 v17, -1, v212
	v_and_b32_e32 v22, 64, v17
	v_add_u32_e32 v22, 64, v22
	v_xor_b32_e32 v23, 32, v17
	v_cmp_lt_i32_e32 vcc, v23, v22
	v_ashrrev_i32_e32 v16, 4, v16
	v_and_b32_e32 v16, -4, v16
	v_cndmask_b32_e32 v23, v17, v23, vcc
	v_lshlrev_b32_e32 v66, 2, v23
	v_xor_b32_e32 v23, 16, v17
	v_cmp_lt_i32_e32 vcc, v23, v22
	s_mov_b64 s[4:5], 0x7200200
	s_mov_b32 s10, 0x358637bd
	v_cndmask_b32_e32 v23, v17, v23, vcc
	v_lshlrev_b32_e32 v67, 2, v23
	v_xor_b32_e32 v23, 8, v17
	v_cmp_lt_i32_e32 vcc, v23, v22
	v_lshl_add_u64 v[56:57], v[20:21], 0, s[4:5]
	v_lshl_add_u64 v[58:59], s[76:77], 0, v[18:19]
	v_cndmask_b32_e32 v23, v17, v23, vcc
	v_lshlrev_b32_e32 v68, 2, v23
	v_xor_b32_e32 v23, 4, v17
	v_cmp_lt_i32_e32 vcc, v23, v22
	v_lshl_add_u32 v60, s3, 4, v16
	s_lshl_b32 s4, s60, 5
	v_cndmask_b32_e32 v23, v17, v23, vcc
	v_lshlrev_b32_e32 v69, 2, v23
	v_xor_b32_e32 v23, 2, v17
	v_cmp_lt_i32_e32 vcc, v23, v22
	s_movk_i32 s5, 0x1000
	s_mov_b32 s2, 0x3a800000
	v_cndmask_b32_e32 v23, v17, v23, vcc
	v_lshlrev_b32_e32 v70, 2, v23
	v_xor_b32_e32 v23, 1, v17
	v_cmp_lt_i32_e32 vcc, v23, v22
	s_mov_b32 s6, 0x800000
	s_movk_i32 s7, 0x2000
	v_cndmask_b32_e32 v17, v17, v23, vcc
	v_lshlrev_b32_e32 v71, 2, v17
	s_movk_i32 s8, 0x3000
	v_mov_b64_e32 v[62:63], s[10:11]

; template <int WM, class AF, class BF>
; DI void gemm512(f32x16 (&acc)[WM][2], AF arow, int a_kstep, BF brow, int b_kstep, int KT, char* smem) {
;     ...
; #pragma unroll
;   for (int i = 0; i < NA; ++i) {
;     int c = tid + 512 * i;
;     int row = c >> 3, kc = (c & 7) * 8;
;     ap[i] = arow(row) + kc;
;     soa[i] = row * 72 + kc;
;   }
; #pragma unroll
;   for (int i = 0; i < 4; ++i) {
;     int c = tid + 512 * i;
;     int row = c >> 3, kc = (c & 7) * 8;
;     bp[i] = brow(row) + kc;
;     sob[i] = row * 72 + kc;
;   }
;   u32x4 ra0[NA], rb0[4], ra1[NA], rb1[4];
; #pragma unroll
;   for (int i = 0; i < NA; ++i) ra0[i] = *(const u32x4*)ap[i];
; #pragma unroll
;   for (int i = 0; i < 4; ++i) rb0[i] = *(const u32x4*)bp[i];
;   {
;     const int s1 = (KT > 1) ? 1 : 0;
; #pragma unroll
;     for (int i = 0; i < NA; ++i) ra1[i] = *(const u32x4*)(ap[i] + s1 * a_kstep);
; #pragma unroll
;     for (int i = 0; i < 4; ++i) rb1[i] = *(const u32x4*)(bp[i] + s1 * b_kstep);
;   }
; DI void phase_pq(const Params& p, char* smem) {
;     ...
;   for (int kk = 0;; ++kk) {
;     int mt, nt;
;     if (!xcd_tile(kk, 8, 8, mt, nt)) break;
;     const int m0 = mt * 256, n0 = nt * 256;
;     f32x16 acc[4][2];
;     zero_acc<4>(acc);
;     gemm512<4>(acc, [&](int r) { return WT + (size_t)(n0 + r) * 1024; }, 64, [&](int r) { return XN2 + (size_t)(m0 + r) * 1024; }, 64, 16, smem);
.Ln2_skip:
	s_add_u32 s16, s78, 0x7200200
	s_addc_u32 s17, s79, 0
	v_mov_b32_e32 v0, v211
	s_andn2_b64 vcc, exec, s[0:1]
	s_waitcnt lgkmcnt(0)
	s_barrier
	s_cbranch_vccnz .LBB0_981
	s_add_u32 s0, s78, 0xd00000
	s_addc_u32 s1, s79, 0
	s_lshl_b32 s2, s55, 3
	v_lshrrev_b32_e32 v2, 3, v0
	s_and_b32 s6, s2, 56
	v_ashrrev_i32_e32 v1, 1, v0
	v_and_b32_e32 v2, 4, v2
	s_movk_i32 s2, 0xff80
	v_and_or_b32 v214, v1, s2, v2
	v_and_b32_e32 v215, 0xdf, v0
	s_mov_b32 s3, 0
	v_mov_b32_e32 v193, 0
	s_movk_i32 s7, 0x48
	s_mov_b32 s8, 0x1fffff80
	s_add_i32 s9, 32, 0x1b000
	s_add_i32 s10, 32, 0x12000
	s_mov_b64 s[4:5], 0x20000
	s_mov_b32 s2, s50
	s_mov_b32 s11, 0
.LBB0_978:
	s_and_b32 s12, s2, 7
	s_lshl_b32 s2, s2, 5
	v_mov_b32_e32 v32, v211
	s_and_b32 s13, s2, 0x700
	s_or_b32 s12, s12, s6
	v_lshlrev_b32_e32 v0, 3, v32
	v_ashrrev_i32_e32 v34, 3, v32
	v_and_b32_e32 v33, 56, v0
	v_add_u32_e32 v2, s13, v34
	v_lshlrev_b32_e32 v192, 1, v33
	v_ashrrev_i32_e32 v3, 31, v2
	v_lshl_add_u64 v[0:1], s[0:1], 0, v[192:193]
	v_lshlrev_b64 v[2:3], 11, v[2:3]
	v_lshl_add_u64 v[194:195], v[0:1], 0, v[2:3]
	v_add_u32_e32 v2, 0x200, v32
	v_ashrrev_i32_e32 v35, 3, v2
	v_add_u32_e32 v2, s13, v35
	v_ashrrev_i32_e32 v3, 31, v2
	v_lshlrev_b64 v[2:3], 11, v[2:3]
	v_lshl_add_u64 v[196:197], v[0:1], 0, v[2:3]
	v_add_u32_e32 v2, 0x400, v32
	v_ashrrev_i32_e32 v36, 3, v2
	v_add_u32_e32 v2, s13, v36
	v_ashrrev_i32_e32 v3, 31, v2
	v_lshlrev_b64 v[2:3], 11, v[2:3]
	v_lshl_add_u64 v[198:199], v[0:1], 0, v[2:3]
	v_add_u32_e32 v2, 0x600, v32
	v_ashrrev_i32_e32 v37, 3, v2
	v_add_u32_e32 v2, s13, v37
	v_ashrrev_i32_e32 v3, 31, v2
	s_lshl_b32 s12, s12, 8
	v_readlane_b32 s80, v253, 48
	v_readlane_b32 s81, v253, 49
	v_mbcnt_lo_u32_b32 v244, -1, 0
	v_mbcnt_hi_u32_b32 v244, -1, v244
	v_bfe_u32 v245, v211, 6, 2
	v_and_b32_e32 v246, 31, v244
	v_lshrrev_b32_e32 v247, 5, v244
	v_lshl_add_u32 v231, v245, 6, v246
	v_add_u32_e32 v231, s12, v231
	v_lshlrev_b32_e32 v231, 5, v231
	v_lshl_add_u32 v231, v247, 4, v231
	s_add_u32 s80, s80, 0x9a80200
	s_addc_u32 s81, s81, 0
	global_load_dwordx4 v[244:247], v231, s[80:81]
	global_load_dwordx4 v[248:251], v231, s[80:81] offset:1024
	v_lshlrev_b64 v[2:3], 11, v[2:3]
	v_lshl_add_u64 v[200:201], v[0:1], 0, v[2:3]
	v_add_u32_e32 v2, s12, v34
	v_ashrrev_i32_e32 v3, 31, v2
	v_lshl_add_u64 v[0:1], s[16:17], 0, v[192:193]
	v_lshlrev_b64 v[2:3], 11, v[2:3]
	v_lshl_add_u64 v[202:203], v[0:1], 0, v[2:3]
	v_add_u32_e32 v2, s12, v35
	v_ashrrev_i32_e32 v3, 31, v2
	v_lshlrev_b64 v[2:3], 11, v[2:3]
	v_lshl_add_u64 v[204:205], v[0:1], 0, v[2:3]
	v_add_u32_e32 v2, s12, v36
	v_ashrrev_i32_e32 v3, 31, v2
	v_lshlrev_b64 v[2:3], 11, v[2:3]
	v_lshl_add_u64 v[206:207], v[0:1], 0, v[2:3]
	v_add_u32_e32 v2, s12, v37
	v_ashrrev_i32_e32 v3, 31, v2
	v_lshlrev_b64 v[2:3], 11, v[2:3]
	v_lshl_add_u64 v[208:209], v[0:1], 0, v[2:3]
	global_load_dwordx4 v[0:3], v[194:195], off
	global_load_dwordx4 v[4:7], v[196:197], off
	global_load_dwordx4 v[8:11], v[198:199], off
	global_load_dwordx4 v[12:15], v[200:201], off
	global_load_dwordx4 v[16:19], v[202:203], off
	global_load_dwordx4 v[20:23], v[204:205], off
	global_load_dwordx4 v[24:27], v[206:207], off
	global_load_dwordx4 v[28:31], v[208:209], off
	global_load_dwordx4 v[128:131], v[194:195], off offset:128
	global_load_dwordx4 v[132:135], v[202:203], off offset:128
	global_load_dwordx4 v[136:139], v[196:197], off offset:128
	global_load_dwordx4 v[140:143], v[198:199], off offset:128
	global_load_dwordx4 v[144:147], v[200:201], off offset:128
	global_load_dwordx4 v[148:151], v[204:205], off offset:128
	global_load_dwordx4 v[152:155], v[206:207], off offset:128
	global_load_dwordx4 v[156:159], v[208:209], off offset:128
	v_mul_lo_u32 v34, v34, s7
	v_mul_lo_u32 v35, v35, s7
	v_mul_lo_u32 v36, v36, s7
	v_mul_lo_u32 v37, v37, s7
	v_add_lshl_u32 v34, v34, v33, 1
	v_add_u32_e32 v192, 32, v34
	v_add_lshl_u32 v35, v35, v33, 1
	v_add_lshl_u32 v36, v36, v33, 1
	v_add_lshl_u32 v33, v37, v33, 1
	v_add_u32_e32 v216, 32, v35
	v_add_u32_e32 v217, 32, v36
	v_add_u32_e32 v218, 32, v33
	s_waitcnt vmcnt(63) expcnt(7) lgkmcnt(15)
	s_barrier
	v_add_u32_e32 v223, s10, v34
	v_add_u32_e32 v224, s10, v35
	v_add_u32_e32 v225, s10, v36
	v_add_u32_e32 v226, s10, v33
	v_add_u32_e32 v227, s9, v34
	v_add_u32_e32 v228, s9, v35
	v_add_u32_e32 v229, s9, v36
	v_add_u32_e32 v230, s9, v33
	s_movk_i32 s14, 0x80
	s_mov_b32 s15, s3
	v_mov_b32_e32 v33, v193
	v_mov_b32_e32 v34, v193
	v_mov_b32_e32 v35, v193
	v_mov_b32_e32 v36, v193
	v_mov_b32_e32 v37, v193
	v_mov_b32_e32 v38, v193
	v_mov_b32_e32 v39, v193
	v_mov_b32_e32 v40, v193
	v_mov_b32_e32 v41, v193
	v_mov_b32_e32 v42, v193
	v_mov_b32_e32 v43, v193
	v_mov_b32_e32 v44, v193
	v_mov_b32_e32 v45, v193
	v_mov_b32_e32 v46, v193
	v_mov_b32_e32 v47, v193
	v_mov_b32_e32 v48, 0
	v_mov_b32_e32 v49, v193
	v_mov_b32_e32 v50, v193
	v_mov_b32_e32 v51, v193
	v_mov_b32_e32 v52, v193
	v_mov_b32_e32 v53, v193
	v_mov_b32_e32 v54, v193
	v_mov_b32_e32 v55, v193
	v_mov_b32_e32 v56, v193
	v_mov_b32_e32 v57, v193
	v_mov_b32_e32 v58, v193
	v_mov_b32_e32 v59, v193
	v_mov_b32_e32 v60, v193
	v_mov_b32_e32 v61, v193
	v_mov_b32_e32 v62, v193
	v_mov_b32_e32 v63, v193
	v_mov_b32_e32 v64, 0
	v_mov_b32_e32 v65, v193
	v_mov_b32_e32 v66, v193
	s_waitcnt vmcnt(15)
	ds_write_b128 v192, v[0:3]
	s_waitcnt vmcnt(14)
	ds_write_b128 v216, v[4:7]
	s_waitcnt vmcnt(13)
	ds_write_b128 v217, v[8:11]
	s_waitcnt vmcnt(12)
	ds_write_b128 v218, v[12:15]
	s_waitcnt vmcnt(11)
	ds_write_b128 v192, v[16:19] offset:36864
	s_waitcnt vmcnt(10)
	ds_write_b128 v216, v[20:23] offset:36864
	s_waitcnt vmcnt(9)
	ds_write_b128 v217, v[24:27] offset:36864
	s_waitcnt vmcnt(8)
; template <int WM, class AF, class BF>
; DI void gemm512(f32x16 (&acc)[WM][2], AF arow, int a_kstep, BF brow, int b_kstep, int KT, char* smem) {
;     ...
;   u16* A0 = (u16*)smem;
;   u16* B0 = A0 + AM * 72;
;   u16* A1 = B0 + 256 * 72;
;   u16* B1 = A1 + AM * 72;
;   __syncthreads();
; #pragma unroll
;   for (int i = 0; i < NA; ++i) *(u32x4*)(A0 + soa[i]) = ra0[i];
; #pragma unroll
;   for (int i = 0; i < 4; ++i) *(u32x4*)(B0 + sob[i]) = rb0[i];
;   __syncthreads();
;   const int fa = (wm * WM * 32 + lr) * 72 + hh * 8, fb = (wn * 64 + lr) * 72 + hh * 8;
	ds_write_b128 v218, v[28:31] offset:36864
	v_and_b32_e32 v0, 31, v32
	v_lshrrev_b32_e32 v1, 1, v32
	v_and_or_b32 v0, v1, s8, v0
	v_lshrrev_b32_e32 v1, 2, v32
	v_and_b32_e32 v2, 0xdf, v32
	v_mul_lo_u32 v0, v0, s7
	v_and_b32_e32 v1, 8, v1
	v_mul_u32_u24_e32 v2, 0x48, v2
	v_add_lshl_u32 v2, v2, v1, 1
	v_add_lshl_u32 v0, v0, v1, 1
	v_add_u32_e32 v219, 32, v2
	v_add_u32_e32 v220, 32, v0
	v_add_u32_e32 v221, s9, v2
	v_add_u32_e32 v222, s10, v0
	v_mov_b32_e32 v0, 0
	v_mov_b32_e32 v1, v193
	v_mov_b32_e32 v2, v193
	v_mov_b32_e32 v3, v193
	v_mov_b32_e32 v4, v193
	v_mov_b32_e32 v5, v193
	v_mov_b32_e32 v6, v193
	v_mov_b32_e32 v7, v193
	v_mov_b32_e32 v8, v193
	v_mov_b32_e32 v9, v193
	v_mov_b32_e32 v10, v193
	v_mov_b32_e32 v11, v193
	v_mov_b32_e32 v12, v193
	v_mov_b32_e32 v13, v193
	v_mov_b32_e32 v14, v193
	v_mov_b32_e32 v15, v193
	v_mov_b32_e32 v16, 0
	v_mov_b32_e32 v17, v193
	v_mov_b32_e32 v18, v193
	v_mov_b32_e32 v19, v193
	v_mov_b32_e32 v20, v193
	v_mov_b32_e32 v21, v193
	v_mov_b32_e32 v22, v193
	v_mov_b32_e32 v23, v193
	v_mov_b32_e32 v24, v193
	v_mov_b32_e32 v25, v193
	v_mov_b32_e32 v26, v193
	v_mov_b32_e32 v27, v193
	v_mov_b32_e32 v28, v193
	v_mov_b32_e32 v29, v193
	v_mov_b32_e32 v30, v193
	v_mov_b32_e32 v31, v193
	v_mov_b32_e32 v32, 0
	v_mov_b32_e32 v67, v193
	v_mov_b32_e32 v68, v193
	v_mov_b32_e32 v69, v193
	v_mov_b32_e32 v70, v193
	v_mov_b32_e32 v71, v193
	v_mov_b32_e32 v72, v193
	v_mov_b32_e32 v73, v193
	v_mov_b32_e32 v74, v193
	v_mov_b32_e32 v75, v193
	v_mov_b32_e32 v76, v193
	v_mov_b32_e32 v77, v193
	v_mov_b32_e32 v78, v193
	v_mov_b32_e32 v79, v193
	v_mov_b32_e32 v80, 0
	v_mov_b32_e32 v81, v193
	v_mov_b32_e32 v82, v193
	v_mov_b32_e32 v83, v193
	v_mov_b32_e32 v84, v193
	v_mov_b32_e32 v85, v193
	v_mov_b32_e32 v86, v193
	v_mov_b32_e32 v87, v193
	v_mov_b32_e32 v88, v193
	v_mov_b32_e32 v89, v193
	v_mov_b32_e32 v90, v193
	v_mov_b32_e32 v91, v193
	v_mov_b32_e32 v92, v193
	v_mov_b32_e32 v93, v193
	v_mov_b32_e32 v94, v193
	v_mov_b32_e32 v95, v193
	v_mov_b32_e32 v96, 0
	v_mov_b32_e32 v97, v193
	v_mov_b32_e32 v98, v193
	v_mov_b32_e32 v99, v193
	v_mov_b32_e32 v100, v193
	v_mov_b32_e32 v101, v193
	v_mov_b32_e32 v102, v193
	v_mov_b32_e32 v103, v193
	v_mov_b32_e32 v104, v193
	v_mov_b32_e32 v105, v193
	v_mov_b32_e32 v106, v193
	v_mov_b32_e32 v107, v193
	v_mov_b32_e32 v108, v193
	v_mov_b32_e32 v109, v193
	v_mov_b32_e32 v110, v193
	v_mov_b32_e32 v111, v193
	v_mov_b32_e32 v112, 0
	v_mov_b32_e32 v113, v193
	v_mov_b32_e32 v114, v193
	v_mov_b32_e32 v115, v193
	v_mov_b32_e32 v116, v193
	v_mov_b32_e32 v117, v193
	v_mov_b32_e32 v118, v193
	v_mov_b32_e32 v119, v193
	v_mov_b32_e32 v120, v193
	v_mov_b32_e32 v121, v193
	v_mov_b32_e32 v122, v193
	v_mov_b32_e32 v123, v193
	v_mov_b32_e32 v124, v193
	v_mov_b32_e32 v125, v193
	v_mov_b32_e32 v126, v193
	v_mov_b32_e32 v127, v193
	s_waitcnt lgkmcnt(0)
	s_barrier
.LBB0_979:
	ds_read_b128 v[160:163], v220
	ds_read_b128 v[164:167], v219 offset:36864
	ds_read_b128 v[168:171], v219 offset:36896
	ds_read_b128 v[172:175], v220 offset:32
	ds_read_b128 v[176:179], v219 offset:41472
	ds_read_b128 v[180:183], v219 offset:41504
	s_add_i32 s22, s15, 2
	s_waitcnt lgkmcnt(4)
	v_mfma_f32_32x32x16_bf16 v[112:127], v[160:163], v[164:167], v[112:127]
	s_cmp_lt_u32 s15, 14
	s_cselect_b64 s[24:25], -1, 0
	s_and_b64 vcc, s[24:25], exec
	s_cselect_b32 s2, s14, 0x3c0
	s_lshl_b64 s[24:25], s[2:3], 1
	s_min_u32 s2, s15, 12
	s_lshl_b32 s2, s2, 7
	s_waitcnt lgkmcnt(1)
	v_mfma_f32_32x32x16_bf16 v[96:111], v[160:163], v[176:179], v[96:111]
	ds_read_b128 v[160:163], v220 offset:4608
	ds_read_b128 v[184:187], v220 offset:4640
	v_lshl_add_u64 v[240:241], v[206:207], 0, s[2:3]
	v_lshl_add_u64 v[242:243], v[208:209], 0, s[2:3]
	s_addk_i32 s14, 0x80
	s_mov_b32 s15, s22
	s_waitcnt lgkmcnt(1)
	v_mfma_f32_32x32x16_bf16 v[80:95], v[160:163], v[164:167], v[80:95]
	v_mfma_f32_32x32x16_bf16 v[64:79], v[160:163], v[176:179], v[64:79]
	ds_read_b128 v[160:163], v220 offset:9216
	ds_read_b128 v[188:191], v220 offset:9248
	s_waitcnt lgkmcnt(1)
	v_mfma_f32_32x32x16_bf16 v[48:63], v[160:163], v[164:167], v[48:63]
	v_mfma_f32_32x32x16_bf16 v[32:47], v[160:163], v[176:179], v[32:47]
	ds_read_b128 v[160:163], v220 offset:13824
	ds_read_b128 v[232:235], v220 offset:13856
	s_waitcnt lgkmcnt(1)
	v_mfma_f32_32x32x16_bf16 v[16:31], v[160:163], v[164:167], v[16:31]
	v_mfma_f32_32x32x16_bf16 v[0:15], v[160:163], v[176:179], v[0:15]
	v_mfma_f32_32x32x16_bf16 v[112:127], v[172:175], v[168:171], v[112:127]
	v_mfma_f32_32x32x16_bf16 v[96:111], v[172:175], v[180:183], v[96:111]
	v_mfma_f32_32x32x16_bf16 v[80:95], v[184:187], v[168:171], v[80:95]
	v_mfma_f32_32x32x16_bf16 v[64:79], v[184:187], v[180:183], v[64:79]
	v_mfma_f32_32x32x16_bf16 v[48:63], v[188:191], v[168:171], v[48:63]
	s_waitcnt lgkmcnt(0)
	v_mfma_f32_32x32x16_bf16 v[16:31], v[232:235], v[168:171], v[16:31]
	ds_read_b128 v[160:163], v220 offset:64
	ds_read_b128 v[164:167], v219 offset:36928
	ds_read_b128 v[176:179], v219 offset:36960
	ds_read_b128 v[168:171], v220 offset:96
	v_mfma_f32_32x32x16_bf16 v[0:15], v[232:235], v[180:183], v[0:15]
	ds_read_b128 v[172:175], v219 offset:41536
	ds_read_b128 v[232:235], v219 offset:41568
	v_mfma_f32_32x32x16_bf16 v[32:47], v[188:191], v[180:183], v[32:47]
	s_waitcnt lgkmcnt(4)
	v_mfma_f32_32x32x16_bf16 v[112:127], v[160:163], v[164:167], v[112:127]
	s_waitcnt lgkmcnt(1)
	v_mfma_f32_32x32x16_bf16 v[96:111], v[160:163], v[172:175], v[96:111]
	ds_read_b128 v[160:163], v220 offset:4672
	ds_read_b128 v[180:183], v220 offset:4704
	s_waitcnt lgkmcnt(1)
	v_mfma_f32_32x32x16_bf16 v[80:95], v[160:163], v[164:167], v[80:95]
	v_mfma_f32_32x32x16_bf16 v[64:79], v[160:163], v[172:175], v[64:79]
	ds_read_b128 v[160:163], v220 offset:9280
	ds_read_b128 v[184:187], v220 offset:9312
	s_waitcnt lgkmcnt(1)
; template <int WM, class AF, class BF>
; DI void gemm512(f32x16 (&acc)[WM][2], AF arow, int a_kstep, BF brow, int b_kstep, int KT, char* smem) {
;     ...
; #pragma unroll 1
;   for (int kt = 0; kt < KT; kt += 2) {
;     GEMM_STEP(A0, B0, A1, B1, ra0, rb0, ra1, rb1, kt + 2)
;     if (kt + 1 < KT) GEMM_STEP(A1, B1, A0, B0, ra1, rb1, ra0, rb0, kt + 3)
	v_mfma_f32_32x32x16_bf16 v[48:63], v[160:163], v[164:167], v[48:63]
	v_mfma_f32_32x32x16_bf16 v[32:47], v[160:163], v[172:175], v[32:47]
	ds_read_b128 v[160:163], v220 offset:13888
	ds_read_b128 v[236:239], v220 offset:13920
	s_waitcnt vmcnt(7)
	ds_write_b128 v223, v[128:131]
	s_waitcnt vmcnt(5)
	ds_write_b128 v224, v[136:139]
	s_waitcnt vmcnt(4)
	ds_write_b128 v225, v[140:143]
	s_waitcnt vmcnt(3)
	ds_write_b128 v226, v[144:147]
	ds_write_b128 v227, v[132:135]
	s_waitcnt vmcnt(2)
	ds_write_b128 v228, v[148:151]
	s_waitcnt vmcnt(1)
	ds_write_b128 v229, v[152:155]
	s_waitcnt vmcnt(0)
	ds_write_b128 v230, v[156:159]
	v_lshl_add_u64 v[128:129], v[194:195], 0, s[24:25]
	v_lshl_add_u64 v[130:131], v[196:197], 0, s[24:25]
	v_lshl_add_u64 v[132:133], v[198:199], 0, s[24:25]
	v_lshl_add_u64 v[134:135], v[200:201], 0, s[24:25]
	s_waitcnt lgkmcnt(9)
	v_mfma_f32_32x32x16_bf16 v[16:31], v[160:163], v[164:167], v[16:31]
	v_lshl_add_u64 v[136:137], v[202:203], 0, s[24:25]
	v_lshl_add_u64 v[138:139], v[204:205], 0, s[24:25]
	v_lshl_add_u64 v[140:141], v[206:207], 0, s[24:25]
	v_lshl_add_u64 v[142:143], v[208:209], 0, s[24:25]
	v_mfma_f32_32x32x16_bf16 v[112:127], v[168:171], v[176:179], v[112:127]
	v_mfma_f32_32x32x16_bf16 v[96:111], v[168:171], v[232:235], v[96:111]
	v_mfma_f32_32x32x16_bf16 v[0:15], v[160:163], v[172:175], v[0:15]
	global_load_dwordx4 v[160:163], v[128:129], off
	global_load_dwordx4 v[164:167], v[130:131], off
	global_load_dwordx4 v[168:171], v[132:133], off
	global_load_dwordx4 v[172:175], v[134:135], off
	v_mfma_f32_32x32x16_bf16 v[80:95], v[180:183], v[176:179], v[80:95]
	v_mfma_f32_32x32x16_bf16 v[64:79], v[180:183], v[232:235], v[64:79]
	v_mfma_f32_32x32x16_bf16 v[48:63], v[184:187], v[176:179], v[48:63]
	v_mfma_f32_32x32x16_bf16 v[32:47], v[184:187], v[232:235], v[32:47]
	s_waitcnt lgkmcnt(8)
	v_mfma_f32_32x32x16_bf16 v[16:31], v[236:239], v[176:179], v[16:31]
	global_load_dwordx4 v[176:179], v[136:137], off
	global_load_dwordx4 v[180:183], v[138:139], off
	global_load_dwordx4 v[184:187], v[140:141], off
	global_load_dwordx4 v[188:191], v[142:143], off
	s_waitcnt lgkmcnt(0)
	s_barrier
	ds_read_b128 v[128:131], v222
	ds_read_b128 v[132:135], v221
	ds_read_b128 v[136:139], v221 offset:32
	ds_read_b128 v[140:143], v222 offset:32
	ds_read_b128 v[144:147], v221 offset:4608
	ds_read_b128 v[148:151], v221 offset:4640
	s_waitcnt lgkmcnt(4)
	v_mfma_f32_32x32x16_bf16 v[112:127], v[128:131], v[132:135], v[112:127]
	s_waitcnt lgkmcnt(1)
	v_mfma_f32_32x32x16_bf16 v[96:111], v[128:131], v[144:147], v[96:111]
	ds_read_b128 v[128:131], v222 offset:4608
	ds_read_b128 v[152:155], v222 offset:4640
	v_mfma_f32_32x32x16_bf16 v[0:15], v[236:239], v[232:235], v[0:15]
	s_waitcnt lgkmcnt(1)
	v_mfma_f32_32x32x16_bf16 v[80:95], v[128:131], v[132:135], v[80:95]
	v_mfma_f32_32x32x16_bf16 v[64:79], v[128:131], v[144:147], v[64:79]
	ds_read_b128 v[128:131], v222 offset:9216
	ds_read_b128 v[156:159], v222 offset:9248
	s_waitcnt lgkmcnt(1)
	v_mfma_f32_32x32x16_bf16 v[48:63], v[128:131], v[132:135], v[48:63]
	v_mfma_f32_32x32x16_bf16 v[32:47], v[128:131], v[144:147], v[32:47]
	ds_read_b128 v[128:131], v222 offset:13824
	ds_read_b128 v[232:235], v222 offset:13856
	s_waitcnt lgkmcnt(1)
	v_mfma_f32_32x32x16_bf16 v[16:31], v[128:131], v[132:135], v[16:31]
	v_mfma_f32_32x32x16_bf16 v[0:15], v[128:131], v[144:147], v[0:15]
	v_mfma_f32_32x32x16_bf16 v[112:127], v[140:143], v[136:139], v[112:127]
	v_mfma_f32_32x32x16_bf16 v[96:111], v[140:143], v[148:151], v[96:111]
	v_mfma_f32_32x32x16_bf16 v[80:95], v[152:155], v[136:139], v[80:95]
	v_mfma_f32_32x32x16_bf16 v[64:79], v[152:155], v[148:151], v[64:79]
	v_lshl_add_u64 v[152:153], v[202:203], 0, s[2:3]
	v_lshl_add_u64 v[154:155], v[204:205], 0, s[2:3]
	v_mfma_f32_32x32x16_bf16 v[48:63], v[156:159], v[136:139], v[48:63]
	v_mfma_f32_32x32x16_bf16 v[32:47], v[156:159], v[148:151], v[32:47]
	s_waitcnt lgkmcnt(0)
	v_mfma_f32_32x32x16_bf16 v[16:31], v[232:235], v[136:139], v[16:31]
	ds_read_b128 v[128:131], v222 offset:64
	ds_read_b128 v[132:135], v221 offset:64
	ds_read_b128 v[156:159], v221 offset:96
	ds_read_b128 v[136:139], v222 offset:96
	v_mfma_f32_32x32x16_bf16 v[0:15], v[232:235], v[148:151], v[0:15]
	ds_read_b128 v[140:143], v221 offset:4672
	ds_read_b128 v[232:235], v221 offset:4704
	s_waitcnt lgkmcnt(4)
	v_mfma_f32_32x32x16_bf16 v[112:127], v[128:131], v[132:135], v[112:127]
	s_waitcnt lgkmcnt(1)
	v_mfma_f32_32x32x16_bf16 v[96:111], v[128:131], v[140:143], v[96:111]
	ds_read_b128 v[128:131], v222 offset:4672
	ds_read_b128 v[144:147], v222 offset:4704
	s_waitcnt lgkmcnt(1)
	v_mfma_f32_32x32x16_bf16 v[80:95], v[128:131], v[132:135], v[80:95]
	v_mfma_f32_32x32x16_bf16 v[64:79], v[128:131], v[140:143], v[64:79]
	ds_read_b128 v[128:131], v222 offset:9280
	ds_read_b128 v[148:151], v222 offset:9312
	s_waitcnt lgkmcnt(1)
	v_mfma_f32_32x32x16_bf16 v[48:63], v[128:131], v[132:135], v[48:63]
	v_mfma_f32_32x32x16_bf16 v[32:47], v[128:131], v[140:143], v[32:47]
	ds_read_b128 v[128:131], v222 offset:13888
	ds_read_b128 v[236:239], v222 offset:13920
	s_waitcnt lgkmcnt(1)
	v_mfma_f32_32x32x16_bf16 v[16:31], v[128:131], v[132:135], v[16:31]
	v_lshl_add_u64 v[132:133], v[196:197], 0, s[2:3]
	v_lshl_add_u64 v[134:135], v[198:199], 0, s[2:3]
	v_mfma_f32_32x32x16_bf16 v[0:15], v[128:131], v[140:143], v[0:15]
	v_lshl_add_u64 v[128:129], v[194:195], 0, s[2:3]
	v_mfma_f32_32x32x16_bf16 v[80:95], v[144:147], v[156:159], v[80:95]
	v_mfma_f32_32x32x16_bf16 v[64:79], v[144:147], v[232:235], v[64:79]
	v_lshl_add_u64 v[144:145], v[200:201], 0, s[2:3]
	v_mfma_f32_32x32x16_bf16 v[112:127], v[136:139], v[156:159], v[112:127]
	v_mfma_f32_32x32x16_bf16 v[96:111], v[136:139], v[232:235], v[96:111]
	v_mfma_f32_32x32x16_bf16 v[48:63], v[148:151], v[156:159], v[48:63]
	v_mfma_f32_32x32x16_bf16 v[32:47], v[148:151], v[232:235], v[32:47]
	global_load_dwordx4 v[128:131], v[128:129], off offset:384
	s_nop 0
	global_load_dwordx4 v[136:139], v[132:133], off offset:384
	global_load_dwordx4 v[140:143], v[134:135], off offset:384
	s_nop 0
	global_load_dwordx4 v[144:147], v[144:145], off offset:384
	s_nop 0
	global_load_dwordx4 v[132:135], v[152:153], off offset:384
	global_load_dwordx4 v[148:151], v[154:155], off offset:384
	s_nop 0
	global_load_dwordx4 v[152:155], v[240:241], off offset:384
	s_waitcnt lgkmcnt(0)
	v_mfma_f32_32x32x16_bf16 v[16:31], v[236:239], v[156:159], v[16:31]
	global_load_dwordx4 v[156:159], v[242:243], off offset:384
	s_waitcnt vmcnt(15)
	ds_write_b128 v192, v[160:163]
	s_waitcnt vmcnt(14)
	ds_write_b128 v216, v[164:167]
	s_waitcnt vmcnt(13)
	ds_write_b128 v217, v[168:171]
	s_waitcnt vmcnt(12)
	ds_write_b128 v218, v[172:175]
	s_waitcnt vmcnt(11)
	ds_write_b128 v192, v[176:179] offset:36864
	s_waitcnt vmcnt(10)
	ds_write_b128 v216, v[180:183] offset:36864
	s_waitcnt vmcnt(9)
	ds_write_b128 v217, v[184:187] offset:36864
	s_waitcnt vmcnt(8)
	ds_write_b128 v218, v[188:191] offset:36864
	s_waitcnt lgkmcnt(0)
	s_barrier
; template <int NR>
; DI void rms_rows(const float* __restrict__ xr, const float* __restrict__ g, u16* __restrict__ dst, int lane) {
;     ...
;     for (int i = 0; i < 4; ++i) ss += v[r][i].x * v[r][i].x + v[r][i].y * v[r][i].y + v[r][i].z * v[r][i].z + v[r][i].w * v[r][i].w;
;     ss = wave_sum(ss);
;     const float rr = rsqrtf(ss * (1.f / 1024.f) + 1e-6f);
; DI void phase_pq(const Params& p, char* smem) {
;     ...
; #pragma unroll
;     for (int i = 0; i < 4; ++i)
; #pragma unroll
;       for (int j = 0; j < 2; ++j)
; #pragma unroll
;         for (int q4 = 0; q4 < 4; ++q4) {
;           const int f = n0 + wm * 128 + i * 32 + q4 * 8 + hh * 4;
;           const size_t t = m0 + wn * 64 + j * 32 + lr;
;           uint2 o;
;           o.x = pack2(acc[i][j][q4 * 4 + 0], acc[i][j][q4 * 4 + 1]);
;           o.y = pack2(acc[i][j][q4 * 4 + 2], acc[i][j][q4 * 4 + 3]);
;           *(uint2*)(PQ + t * 2048 + f) = o;
	v_mfma_f32_32x32x16_bf16 v[0:15], v[236:239], v[232:235], v[0:15]
	s_cbranch_vccnz .LBB0_979
	s_waitcnt vmcnt(0)
	s_add_i32 s11, s11, 1
	s_mul_i32 s2, s11, s51
	s_add_i32 s2, s2, s50
	v_pk_add_f32 v[244:245], v[244:245], v[246:247]
	v_pk_add_f32 v[248:249], v[248:249], v[250:251]
	v_mov_b32_e32 v128, 0x358637bd
	v_add_f32_e32 v244, v244, v245
	v_add_f32_e32 v248, v248, v249
	s_nop 0
	v_mov_b32_e32 v246, v244
	v_mov_b32_e32 v250, v248
	s_nop 1
	v_permlane32_swap_b32_e32 v244, v246
	v_permlane32_swap_b32_e32 v248, v250
	s_nop 1
	v_add_f32_e32 v244, v244, v246
	v_add_f32_e32 v248, v248, v250
	v_fmamk_f32 v244, v244, 0x3a800000, v128
	v_fmamk_f32 v248, v248, 0x3a800000, v128
	v_rsq_f32_e32 v244, v244
	v_rsq_f32_e32 v248, v248
	s_nop 0
	v_pk_mul_f32 v[112:113], v[112:113], v[244:245] op_sel_hi:[1,0]
	v_pk_mul_f32 v[114:115], v[114:115], v[244:245] op_sel_hi:[1,0]
	v_pk_mul_f32 v[116:117], v[116:117], v[244:245] op_sel_hi:[1,0]
	v_pk_mul_f32 v[118:119], v[118:119], v[244:245] op_sel_hi:[1,0]
	v_pk_mul_f32 v[120:121], v[120:121], v[244:245] op_sel_hi:[1,0]
	v_pk_mul_f32 v[122:123], v[122:123], v[244:245] op_sel_hi:[1,0]
	v_pk_mul_f32 v[124:125], v[124:125], v[244:245] op_sel_hi:[1,0]
	v_pk_mul_f32 v[126:127], v[126:127], v[244:245] op_sel_hi:[1,0]
	v_pk_mul_f32 v[96:97], v[96:97], v[248:249] op_sel_hi:[1,0]
	v_pk_mul_f32 v[98:99], v[98:99], v[248:249] op_sel_hi:[1,0]
	v_pk_mul_f32 v[100:101], v[100:101], v[248:249] op_sel_hi:[1,0]
	v_pk_mul_f32 v[102:103], v[102:103], v[248:249] op_sel_hi:[1,0]
	v_pk_mul_f32 v[104:105], v[104:105], v[248:249] op_sel_hi:[1,0]
	v_pk_mul_f32 v[106:107], v[106:107], v[248:249] op_sel_hi:[1,0]
	v_pk_mul_f32 v[108:109], v[108:109], v[248:249] op_sel_hi:[1,0]
	v_pk_mul_f32 v[110:111], v[110:111], v[248:249] op_sel_hi:[1,0]
	v_pk_mul_f32 v[80:81], v[80:81], v[244:245] op_sel_hi:[1,0]
	v_pk_mul_f32 v[82:83], v[82:83], v[244:245] op_sel_hi:[1,0]
	v_pk_mul_f32 v[84:85], v[84:85], v[244:245] op_sel_hi:[1,0]
	v_pk_mul_f32 v[86:87], v[86:87], v[244:245] op_sel_hi:[1,0]
	v_pk_mul_f32 v[88:89], v[88:89], v[244:245] op_sel_hi:[1,0]
	v_pk_mul_f32 v[90:91], v[90:91], v[244:245] op_sel_hi:[1,0]
	v_pk_mul_f32 v[92:93], v[92:93], v[244:245] op_sel_hi:[1,0]
	v_pk_mul_f32 v[94:95], v[94:95], v[244:245] op_sel_hi:[1,0]
	v_pk_mul_f32 v[64:65], v[64:65], v[248:249] op_sel_hi:[1,0]
	v_pk_mul_f32 v[66:67], v[66:67], v[248:249] op_sel_hi:[1,0]
	v_pk_mul_f32 v[68:69], v[68:69], v[248:249] op_sel_hi:[1,0]
	v_pk_mul_f32 v[70:71], v[70:71], v[248:249] op_sel_hi:[1,0]
	v_pk_mul_f32 v[72:73], v[72:73], v[248:249] op_sel_hi:[1,0]
	v_pk_mul_f32 v[74:75], v[74:75], v[248:249] op_sel_hi:[1,0]
	v_pk_mul_f32 v[76:77], v[76:77], v[248:249] op_sel_hi:[1,0]
	v_pk_mul_f32 v[78:79], v[78:79], v[248:249] op_sel_hi:[1,0]
	v_pk_mul_f32 v[48:49], v[48:49], v[244:245] op_sel_hi:[1,0]
	v_pk_mul_f32 v[50:51], v[50:51], v[244:245] op_sel_hi:[1,0]
	v_pk_mul_f32 v[52:53], v[52:53], v[244:245] op_sel_hi:[1,0]
	v_pk_mul_f32 v[54:55], v[54:55], v[244:245] op_sel_hi:[1,0]
	v_pk_mul_f32 v[56:57], v[56:57], v[244:245] op_sel_hi:[1,0]
	v_pk_mul_f32 v[58:59], v[58:59], v[244:245] op_sel_hi:[1,0]
	v_pk_mul_f32 v[60:61], v[60:61], v[244:245] op_sel_hi:[1,0]
	v_pk_mul_f32 v[62:63], v[62:63], v[244:245] op_sel_hi:[1,0]
	v_pk_mul_f32 v[32:33], v[32:33], v[248:249] op_sel_hi:[1,0]
	v_pk_mul_f32 v[34:35], v[34:35], v[248:249] op_sel_hi:[1,0]
	v_pk_mul_f32 v[36:37], v[36:37], v[248:249] op_sel_hi:[1,0]
	v_pk_mul_f32 v[38:39], v[38:39], v[248:249] op_sel_hi:[1,0]
	v_pk_mul_f32 v[40:41], v[40:41], v[248:249] op_sel_hi:[1,0]
	v_pk_mul_f32 v[42:43], v[42:43], v[248:249] op_sel_hi:[1,0]
	v_pk_mul_f32 v[44:45], v[44:45], v[248:249] op_sel_hi:[1,0]
	v_pk_mul_f32 v[46:47], v[46:47], v[248:249] op_sel_hi:[1,0]
	v_pk_mul_f32 v[16:17], v[16:17], v[244:245] op_sel_hi:[1,0]
	v_pk_mul_f32 v[18:19], v[18:19], v[244:245] op_sel_hi:[1,0]
	v_pk_mul_f32 v[20:21], v[20:21], v[244:245] op_sel_hi:[1,0]
	v_pk_mul_f32 v[22:23], v[22:23], v[244:245] op_sel_hi:[1,0]
	v_pk_mul_f32 v[24:25], v[24:25], v[244:245] op_sel_hi:[1,0]
	v_pk_mul_f32 v[26:27], v[26:27], v[244:245] op_sel_hi:[1,0]
	v_pk_mul_f32 v[28:29], v[28:29], v[244:245] op_sel_hi:[1,0]
	v_pk_mul_f32 v[30:31], v[30:31], v[244:245] op_sel_hi:[1,0]
	v_pk_mul_f32 v[0:1], v[0:1], v[248:249] op_sel_hi:[1,0]
	v_pk_mul_f32 v[2:3], v[2:3], v[248:249] op_sel_hi:[1,0]
	v_pk_mul_f32 v[4:5], v[4:5], v[248:249] op_sel_hi:[1,0]
	v_pk_mul_f32 v[6:7], v[6:7], v[248:249] op_sel_hi:[1,0]
	v_pk_mul_f32 v[8:9], v[8:9], v[248:249] op_sel_hi:[1,0]
	v_pk_mul_f32 v[10:11], v[10:11], v[248:249] op_sel_hi:[1,0]
	v_pk_mul_f32 v[12:13], v[12:13], v[248:249] op_sel_hi:[1,0]
	v_pk_mul_f32 v[14:15], v[14:15], v[248:249] op_sel_hi:[1,0]
	v_cvt_pk_bf16_f32 v112, v112, v113
	v_cvt_pk_bf16_f32 v113, v114, v115
	v_cvt_pk_bf16_f32 v114, v116, v117
	v_cvt_pk_bf16_f32 v115, v118, v119
	v_cvt_pk_bf16_f32 v116, v120, v121
	v_cvt_pk_bf16_f32 v117, v122, v123
	v_cvt_pk_bf16_f32 v118, v124, v125
	v_cvt_pk_bf16_f32 v119, v126, v127
	v_cvt_pk_bf16_f32 v96, v96, v97
	v_cvt_pk_bf16_f32 v97, v98, v99
	v_cvt_pk_bf16_f32 v98, v100, v101
	v_cvt_pk_bf16_f32 v99, v102, v103
	v_cvt_pk_bf16_f32 v100, v104, v105
	v_cvt_pk_bf16_f32 v101, v106, v107
	v_cvt_pk_bf16_f32 v102, v108, v109
	v_cvt_pk_bf16_f32 v103, v110, v111
	v_cvt_pk_bf16_f32 v80, v80, v81
	v_cvt_pk_bf16_f32 v81, v82, v83
	v_cvt_pk_bf16_f32 v82, v84, v85
	v_cvt_pk_bf16_f32 v83, v86, v87
	v_cvt_pk_bf16_f32 v84, v88, v89
	v_cvt_pk_bf16_f32 v85, v90, v91
	v_cvt_pk_bf16_f32 v86, v92, v93
	v_cvt_pk_bf16_f32 v87, v94, v95
	v_cvt_pk_bf16_f32 v64, v64, v65
	v_cvt_pk_bf16_f32 v65, v66, v67
	v_cvt_pk_bf16_f32 v66, v68, v69
	v_cvt_pk_bf16_f32 v67, v70, v71
	v_cvt_pk_bf16_f32 v68, v72, v73
	v_cvt_pk_bf16_f32 v69, v74, v75
	v_cvt_pk_bf16_f32 v70, v76, v77
	v_cvt_pk_bf16_f32 v71, v78, v79
	v_cvt_pk_bf16_f32 v48, v48, v49
	v_cvt_pk_bf16_f32 v49, v50, v51
	v_cvt_pk_bf16_f32 v50, v52, v53
	v_cvt_pk_bf16_f32 v51, v54, v55
	v_cvt_pk_bf16_f32 v52, v56, v57
	v_cvt_pk_bf16_f32 v53, v58, v59
	v_cvt_pk_bf16_f32 v54, v60, v61
	v_cvt_pk_bf16_f32 v55, v62, v63
	v_cvt_pk_bf16_f32 v32, v32, v33
	v_cvt_pk_bf16_f32 v33, v34, v35
	v_cvt_pk_bf16_f32 v34, v36, v37
	v_cvt_pk_bf16_f32 v35, v38, v39
	v_cvt_pk_bf16_f32 v36, v40, v41
	v_cvt_pk_bf16_f32 v37, v42, v43
	v_cvt_pk_bf16_f32 v38, v44, v45
	v_cvt_pk_bf16_f32 v39, v46, v47
	v_cvt_pk_bf16_f32 v16, v16, v17
	v_cvt_pk_bf16_f32 v17, v18, v19
	v_cvt_pk_bf16_f32 v18, v20, v21
	v_cvt_pk_bf16_f32 v19, v22, v23
	v_cvt_pk_bf16_f32 v20, v24, v25
	v_cvt_pk_bf16_f32 v21, v26, v27
	v_cvt_pk_bf16_f32 v22, v28, v29
	v_cvt_pk_bf16_f32 v23, v30, v31
	v_cvt_pk_bf16_f32 v0, v0, v1
	v_cvt_pk_bf16_f32 v1, v2, v3
	v_cvt_pk_bf16_f32 v2, v4, v5
	v_cvt_pk_bf16_f32 v3, v6, v7
	v_cvt_pk_bf16_f32 v4, v8, v9
	v_cvt_pk_bf16_f32 v5, v10, v11
	v_cvt_pk_bf16_f32 v6, v12, v13
	v_cvt_pk_bf16_f32 v7, v14, v15
	s_barrier
; DI void phase_pq(const Params& p, char* smem) {
;     ...
; #pragma unroll
;     for (int i = 0; i < 4; ++i)
; #pragma unroll
;       for (int j = 0; j < 2; ++j)
; #pragma unroll
;         for (int q4 = 0; q4 < 4; ++q4) {
;           const int f = n0 + wm * 128 + i * 32 + q4 * 8 + hh * 4;
;           const size_t t = m0 + wn * 64 + j * 32 + lr;
;           uint2 o;
;           o.x = pack2(acc[i][j][q4 * 4 + 0], acc[i][j][q4 * 4 + 1]);
;           o.y = pack2(acc[i][j][q4 * 4 + 2], acc[i][j][q4 * 4 + 3]);
;           *(uint2*)(PQ + t * 2048 + f) = o;
;         }
	v_mbcnt_lo_u32_b32 v128, -1, 0
	v_mbcnt_hi_u32_b32 v128, -1, v128
	v_lshrrev_b32_e32 v129, 6, v211
	v_and_b32_e32 v130, 31, v128
	v_lshrrev_b32_e32 v131, 5, v128
	v_and_b32_e32 v132, 3, v129
	v_lshrrev_b32_e32 v133, 2, v129
	v_lshl_add_u32 v134, v132, 6, v130
	v_mul_u32_u24_e32 v134, 528, v134
	v_lshlrev_b32_e32 v135, 8, v133
	v_lshl_add_u32 v135, v131, 3, v135
	v_add3_u32 v134, v134, v135, 64
	ds_write_b64 v134, v[112:113] offset:0
	ds_write_b64 v134, v[114:115] offset:16
	ds_write_b64 v134, v[116:117] offset:32
	ds_write_b64 v134, v[118:119] offset:48
	ds_write_b64 v134, v[96:97] offset:16896
	ds_write_b64 v134, v[98:99] offset:16912
	ds_write_b64 v134, v[100:101] offset:16928
	ds_write_b64 v134, v[102:103] offset:16944
	ds_write_b64 v134, v[80:81] offset:64
	ds_write_b64 v134, v[82:83] offset:80
	ds_write_b64 v134, v[84:85] offset:96
	ds_write_b64 v134, v[86:87] offset:112
	ds_write_b64 v134, v[64:65] offset:16960
	ds_write_b64 v134, v[66:67] offset:16976
	ds_write_b64 v134, v[68:69] offset:16992
	ds_write_b64 v134, v[70:71] offset:17008
	ds_write_b64 v134, v[48:49] offset:128
	ds_write_b64 v134, v[50:51] offset:144
	ds_write_b64 v134, v[52:53] offset:160
	ds_write_b64 v134, v[54:55] offset:176
	ds_write_b64 v134, v[32:33] offset:17024
	ds_write_b64 v134, v[34:35] offset:17040
	ds_write_b64 v134, v[36:37] offset:17056
	ds_write_b64 v134, v[38:39] offset:17072
	ds_write_b64 v134, v[16:17] offset:192
	ds_write_b64 v134, v[18:19] offset:208
	ds_write_b64 v134, v[20:21] offset:224
	ds_write_b64 v134, v[22:23] offset:240
	ds_write_b64 v134, v[0:1] offset:17088
	ds_write_b64 v134, v[2:3] offset:17104
	ds_write_b64 v134, v[4:5] offset:17120
	ds_write_b64 v134, v[6:7] offset:17136
	s_waitcnt lgkmcnt(0)
	s_barrier
	v_lshl_add_u32 v136, v129, 5, v131
	v_mul_u32_u24_e32 v137, 528, v136
	v_lshl_add_u32 v137, v130, 4, v137
	v_add_u32_e32 v137, 64, v137
	v_add_u32_e32 v136, s12, v136
	v_lshlrev_b32_e32 v136, 12, v136
	v_lshl_add_u32 v136, v130, 4, v136
	s_lshl_b32 s22, s13, 1
	v_add_u32_e32 v136, s22, v136
	ds_read_b128 v[0:3], v137 offset:0
	ds_read_b128 v[4:7], v137 offset:1056
	ds_read_b128 v[8:11], v137 offset:2112
	ds_read_b128 v[12:15], v137 offset:3168
	ds_read_b128 v[16:19], v137 offset:4224
	ds_read_b128 v[20:23], v137 offset:5280
	ds_read_b128 v[24:27], v137 offset:6336
	ds_read_b128 v[28:31], v137 offset:7392
	ds_read_b128 v[32:35], v137 offset:8448
	ds_read_b128 v[36:39], v137 offset:9504
	ds_read_b128 v[40:43], v137 offset:10560
	ds_read_b128 v[44:47], v137 offset:11616
	ds_read_b128 v[48:51], v137 offset:12672
	ds_read_b128 v[52:55], v137 offset:13728
	ds_read_b128 v[56:59], v137 offset:14784
	ds_read_b128 v[60:63], v137 offset:15840
	s_waitcnt lgkmcnt(15)
	global_store_dwordx4 v136, v[0:3], s[20:21]
	v_add_u32_e32 v136, 0x2000, v136
	s_waitcnt lgkmcnt(14)
	global_store_dwordx4 v136, v[4:7], s[20:21]
	v_add_u32_e32 v136, 0x2000, v136
	s_waitcnt lgkmcnt(13)
	global_store_dwordx4 v136, v[8:11], s[20:21]
	v_add_u32_e32 v136, 0x2000, v136
	s_waitcnt lgkmcnt(12)
	global_store_dwordx4 v136, v[12:15], s[20:21]
	v_add_u32_e32 v136, 0x2000, v136
	s_waitcnt lgkmcnt(11)
	global_store_dwordx4 v136, v[16:19], s[20:21]
	v_add_u32_e32 v136, 0x2000, v136
	s_waitcnt lgkmcnt(10)
	global_store_dwordx4 v136, v[20:23], s[20:21]
	v_add_u32_e32 v136, 0x2000, v136
	s_waitcnt lgkmcnt(9)
	global_store_dwordx4 v136, v[24:27], s[20:21]
	v_add_u32_e32 v136, 0x2000, v136
	s_waitcnt lgkmcnt(8)
	global_store_dwordx4 v136, v[28:31], s[20:21]
	v_add_u32_e32 v136, 0x2000, v136
	s_waitcnt lgkmcnt(7)
	global_store_dwordx4 v136, v[32:35], s[20:21]
	v_add_u32_e32 v136, 0x2000, v136
	s_waitcnt lgkmcnt(6)
	global_store_dwordx4 v136, v[36:39], s[20:21]
	v_add_u32_e32 v136, 0x2000, v136
	s_waitcnt lgkmcnt(5)
	global_store_dwordx4 v136, v[40:43], s[20:21]
	v_add_u32_e32 v136, 0x2000, v136
	s_waitcnt lgkmcnt(4)
	global_store_dwordx4 v136, v[44:47], s[20:21]
	v_add_u32_e32 v136, 0x2000, v136
	s_waitcnt lgkmcnt(3)
	global_store_dwordx4 v136, v[48:51], s[20:21]
	v_add_u32_e32 v136, 0x2000, v136
	s_waitcnt lgkmcnt(2)
	global_store_dwordx4 v136, v[52:55], s[20:21]
	v_add_u32_e32 v136, 0x2000, v136
	s_waitcnt lgkmcnt(1)
	global_store_dwordx4 v136, v[56:59], s[20:21]
	v_add_u32_e32 v136, 0x2000, v136
	s_waitcnt lgkmcnt(0)
	global_store_dwordx4 v136, v[60:63], s[20:21]
	v_add_u32_e32 v136, 0x2000, v136
	s_cmp_lt_u32 s2, 64
	s_cbranch_scc1 .LBB0_978

; template <bool STORE>
; DI void peer_item(const Params& p, int item, char* smem) {
;     ...
; #pragma unroll 2
;     for (int k = 0; k < 128; k += 8) {
;       u32x4 uq[8];
;       const int emine = e_s[tl * 128 + k + (lane >> 3)];
;       const float gmine = g_s[tl * 128 + k + (lane >> 3)];
;       const float su = SU[emine], sv = SV[emine];
; #pragma unroll
;       for (int u = 0; u < 8; ++u) {
;         int e = e_s[tl * 128 + k + u];
;         uq[u] = *(const u32x4*)(U8 + (size_t)e * 1024 + lane * 16);
;       }
;       float part[8];
; #pragma unroll
;       for (int u = 0; u < 8; ++u) {
;         float d = 0.f;
; #pragma unroll
;         for (int i = 0; i < 4; ++i) {
;           f32x2_t lo = __builtin_amdgcn_cvt_pk_f32_fp8((int)uq[u][i], false);
;           f32x2_t hi = __builtin_amdgcn_cvt_pk_f32_fp8((int)uq[u][i], true);
;           d += xf[4 * i] * lo.x + xf[4 * i + 1] * lo.y + xf[4 * i + 2] * hi.x + xf[4 * i + 3] * hi.y;
;         }
;         part[u] = d;
;       }
;       float q4[4], r2[2], h;
; #pragma unroll
;       for (int j = 0; j < 4; ++j) {
;         float mine = b5 ? part[j + 4] : part[j];
;         float other = b5 ? part[j] : part[j + 4];
;         q4[j] = mine + __shfl_xor(other, 32);
;       }
; #pragma unroll
;       for (int j = 0; j < 2; ++j) {
;         float mine = b4 ? q4[j + 2] : q4[j];
;         float other = b4 ? q4[j] : q4[j + 2];
;         r2[j] = mine + __shfl_xor(other, 16);
;       }
;       {
;         float mine = b3 ? r2[1] : r2[0];
;         float other = b3 ? r2[0] : r2[1];
;         h = mine + __shfl_xor(other, 8);
;       }
;       h += __shfl_xor(h, 4);
;       h += __shfl_xor(h, 2);
;       h += __shfl_xor(h, 1);
.Lup_k:
	v_readlane_b32 s48, v130, s72
	v_readlane_b32 s49, v130, s73
	v_readlane_b32 s50, v130, s74
	v_readlane_b32 s51, v130, s75
	v_readlane_b32 s52, v130, s76
	v_readlane_b32 s53, v130, s77
	v_readlane_b32 s54, v130, s78
	v_readlane_b32 s55, v130, s79
	s_add_u32 s32, s0, s48
	s_addc_u32 s33, s1, 0
	s_add_u32 s34, s0, s49
	s_addc_u32 s35, s1, 0
	s_add_u32 s36, s0, s50
	s_addc_u32 s37, s1, 0
	s_add_u32 s38, s0, s51
	s_addc_u32 s39, s1, 0
	s_add_u32 s40, s0, s52
	s_addc_u32 s41, s1, 0
	s_add_u32 s42, s0, s53
	s_addc_u32 s43, s1, 0
	s_add_u32 s44, s0, s54
	s_addc_u32 s45, s1, 0
	s_add_u32 s46, s0, s55
	s_addc_u32 s47, s1, 0
	global_load_dwordx4 v[176:179], v234, s[32:33]
	global_load_dwordx4 v[180:183], v234, s[34:35]
	global_load_dwordx4 v[184:187], v234, s[36:37]
	global_load_dwordx4 v[188:191], v234, s[38:39]
	global_load_dwordx4 v[192:195], v234, s[40:41]
	global_load_dwordx4 v[196:199], v234, s[42:43]
	global_load_dwordx4 v[200:203], v234, s[44:45]
	global_load_dwordx4 v[204:207], v234, s[46:47]
	s_waitcnt vmcnt(8)
	v_cvt_pk_f32_fp8_e32 v[214:215], v144
	v_cvt_pk_f32_fp8_sdwa v[216:217], v144 src0_sel:WORD_1
	v_cvt_pk_f32_fp8_e32 v[218:219], v145
	v_cvt_pk_f32_fp8_sdwa v[220:221], v145 src0_sel:WORD_1
	v_pk_mul_f32 v[222:223], v[0:1], v[214:215]
	v_pk_mul_f32 v[224:225], v[2:3], v[216:217]
	v_cvt_pk_f32_fp8_e32 v[214:215], v146
	v_cvt_pk_f32_fp8_sdwa v[216:217], v146 src0_sel:WORD_1
	v_pk_fma_f32 v[222:223], v[4:5], v[218:219], v[222:223]
	v_pk_fma_f32 v[224:225], v[6:7], v[220:221], v[224:225]
	v_cvt_pk_f32_fp8_e32 v[218:219], v147
	v_cvt_pk_f32_fp8_sdwa v[220:221], v147 src0_sel:WORD_1
	v_pk_fma_f32 v[222:223], v[8:9], v[214:215], v[222:223]
	v_pk_fma_f32 v[224:225], v[10:11], v[216:217], v[224:225]
	v_pk_fma_f32 v[222:223], v[12:13], v[218:219], v[222:223]
	v_pk_fma_f32 v[224:225], v[14:15], v[220:221], v[224:225]
	v_pk_add_f32 v[222:223], v[222:223], v[224:225]
	s_nop 0
	v_add_f32_e32 v226, v222, v223
	v_cvt_pk_f32_fp8_e32 v[214:215], v148
	v_cvt_pk_f32_fp8_sdwa v[216:217], v148 src0_sel:WORD_1
	v_cvt_pk_f32_fp8_e32 v[218:219], v149
	v_cvt_pk_f32_fp8_sdwa v[220:221], v149 src0_sel:WORD_1
	v_pk_mul_f32 v[222:223], v[0:1], v[214:215]
	v_pk_mul_f32 v[224:225], v[2:3], v[216:217]
	v_cvt_pk_f32_fp8_e32 v[214:215], v150
	v_cvt_pk_f32_fp8_sdwa v[216:217], v150 src0_sel:WORD_1
	v_pk_fma_f32 v[222:223], v[4:5], v[218:219], v[222:223]
	v_pk_fma_f32 v[224:225], v[6:7], v[220:221], v[224:225]
	v_cvt_pk_f32_fp8_e32 v[218:219], v151
	v_cvt_pk_f32_fp8_sdwa v[220:221], v151 src0_sel:WORD_1
	v_pk_fma_f32 v[222:223], v[8:9], v[214:215], v[222:223]
	v_pk_fma_f32 v[224:225], v[10:11], v[216:217], v[224:225]
	v_pk_fma_f32 v[222:223], v[12:13], v[218:219], v[222:223]
	v_pk_fma_f32 v[224:225], v[14:15], v[220:221], v[224:225]
	v_pk_add_f32 v[222:223], v[222:223], v[224:225]
	s_nop 0
	v_add_f32_e32 v227, v222, v223
	v_cvt_pk_f32_fp8_e32 v[214:215], v152
	v_cvt_pk_f32_fp8_sdwa v[216:217], v152 src0_sel:WORD_1
	v_cvt_pk_f32_fp8_e32 v[218:219], v153
	v_cvt_pk_f32_fp8_sdwa v[220:221], v153 src0_sel:WORD_1
	v_pk_mul_f32 v[222:223], v[0:1], v[214:215]
	v_pk_mul_f32 v[224:225], v[2:3], v[216:217]
	v_cvt_pk_f32_fp8_e32 v[214:215], v154
	v_cvt_pk_f32_fp8_sdwa v[216:217], v154 src0_sel:WORD_1
	v_pk_fma_f32 v[222:223], v[4:5], v[218:219], v[222:223]
	v_pk_fma_f32 v[224:225], v[6:7], v[220:221], v[224:225]
	v_cvt_pk_f32_fp8_e32 v[218:219], v155
	v_cvt_pk_f32_fp8_sdwa v[220:221], v155 src0_sel:WORD_1
	v_pk_fma_f32 v[222:223], v[8:9], v[214:215], v[222:223]
	v_pk_fma_f32 v[224:225], v[10:11], v[216:217], v[224:225]
	v_pk_fma_f32 v[222:223], v[12:13], v[218:219], v[222:223]
	v_pk_fma_f32 v[224:225], v[14:15], v[220:221], v[224:225]
	v_pk_add_f32 v[222:223], v[222:223], v[224:225]
	s_nop 0
	v_add_f32_e32 v228, v222, v223
	v_cvt_pk_f32_fp8_e32 v[214:215], v156
	v_cvt_pk_f32_fp8_sdwa v[216:217], v156 src0_sel:WORD_1
	v_cvt_pk_f32_fp8_e32 v[218:219], v157
	v_cvt_pk_f32_fp8_sdwa v[220:221], v157 src0_sel:WORD_1
	v_pk_mul_f32 v[222:223], v[0:1], v[214:215]
	v_pk_mul_f32 v[224:225], v[2:3], v[216:217]
	v_cvt_pk_f32_fp8_e32 v[214:215], v158
	v_cvt_pk_f32_fp8_sdwa v[216:217], v158 src0_sel:WORD_1
	v_pk_fma_f32 v[222:223], v[4:5], v[218:219], v[222:223]
	v_pk_fma_f32 v[224:225], v[6:7], v[220:221], v[224:225]
	v_cvt_pk_f32_fp8_e32 v[218:219], v159
	v_cvt_pk_f32_fp8_sdwa v[220:221], v159 src0_sel:WORD_1
	v_pk_fma_f32 v[222:223], v[8:9], v[214:215], v[222:223]
	v_pk_fma_f32 v[224:225], v[10:11], v[216:217], v[224:225]
	v_pk_fma_f32 v[222:223], v[12:13], v[218:219], v[222:223]
	v_pk_fma_f32 v[224:225], v[14:15], v[220:221], v[224:225]
	v_pk_add_f32 v[222:223], v[222:223], v[224:225]
	s_nop 0
	v_add_f32_e32 v229, v222, v223
	v_cvt_pk_f32_fp8_e32 v[214:215], v160
	v_cvt_pk_f32_fp8_sdwa v[216:217], v160 src0_sel:WORD_1
	v_cvt_pk_f32_fp8_e32 v[218:219], v161
	v_cvt_pk_f32_fp8_sdwa v[220:221], v161 src0_sel:WORD_1
	v_pk_mul_f32 v[222:223], v[0:1], v[214:215]
	v_pk_mul_f32 v[224:225], v[2:3], v[216:217]
	v_cvt_pk_f32_fp8_e32 v[214:215], v162
	v_cvt_pk_f32_fp8_sdwa v[216:217], v162 src0_sel:WORD_1
	v_pk_fma_f32 v[222:223], v[4:5], v[218:219], v[222:223]
	v_pk_fma_f32 v[224:225], v[6:7], v[220:221], v[224:225]
	v_cvt_pk_f32_fp8_e32 v[218:219], v163
	v_cvt_pk_f32_fp8_sdwa v[220:221], v163 src0_sel:WORD_1
	v_pk_fma_f32 v[222:223], v[8:9], v[214:215], v[222:223]
	v_pk_fma_f32 v[224:225], v[10:11], v[216:217], v[224:225]
	v_pk_fma_f32 v[222:223], v[12:13], v[218:219], v[222:223]
	v_pk_fma_f32 v[224:225], v[14:15], v[220:221], v[224:225]
	v_pk_add_f32 v[222:223], v[222:223], v[224:225]
	s_nop 0
	v_add_f32_e32 v230, v222, v223
	v_cvt_pk_f32_fp8_e32 v[214:215], v164
; template <bool STORE>
; DI void peer_item(const Params& p, int item, char* smem) {
;     ...
; #pragma unroll 2
;     for (int k = 0; k < 128; k += 8) {
;       u32x4 uq[8];
;       const int emine = e_s[tl * 128 + k + (lane >> 3)];
;       const float gmine = g_s[tl * 128 + k + (lane >> 3)];
;       const float su = SU[emine], sv = SV[emine];
; #pragma unroll
;       for (int u = 0; u < 8; ++u) {
;         int e = e_s[tl * 128 + k + u];
;         uq[u] = *(const u32x4*)(U8 + (size_t)e * 1024 + lane * 16);
;       }
;       float part[8];
; #pragma unroll
;       for (int u = 0; u < 8; ++u) {
;         float d = 0.f;
; #pragma unroll
;         for (int i = 0; i < 4; ++i) {
;           f32x2_t lo = __builtin_amdgcn_cvt_pk_f32_fp8((int)uq[u][i], false);
;           f32x2_t hi = __builtin_amdgcn_cvt_pk_f32_fp8((int)uq[u][i], true);
;           d += xf[4 * i] * lo.x + xf[4 * i + 1] * lo.y + xf[4 * i + 2] * hi.x + xf[4 * i + 3] * hi.y;
;         }
;         part[u] = d;
;       }
;       float q4[4], r2[2], h;
; #pragma unroll
;       for (int j = 0; j < 4; ++j) {
;         float mine = b5 ? part[j + 4] : part[j];
;         float other = b5 ? part[j] : part[j + 4];
;         q4[j] = mine + __shfl_xor(other, 32);
;       }
; #pragma unroll
;       for (int j = 0; j < 2; ++j) {
;         float mine = b4 ? q4[j + 2] : q4[j];
;         float other = b4 ? q4[j] : q4[j + 2];
;         r2[j] = mine + __shfl_xor(other, 16);
;       }
;       {
;         float mine = b3 ? r2[1] : r2[0];
;         float other = b3 ? r2[0] : r2[1];
;         h = mine + __shfl_xor(other, 8);
;       }
;       h += __shfl_xor(h, 4);
;       h += __shfl_xor(h, 2);
;       h += __shfl_xor(h, 1);
	v_cvt_pk_f32_fp8_sdwa v[216:217], v164 src0_sel:WORD_1
	v_cvt_pk_f32_fp8_e32 v[218:219], v165
	v_cvt_pk_f32_fp8_sdwa v[220:221], v165 src0_sel:WORD_1
	v_pk_mul_f32 v[222:223], v[0:1], v[214:215]
	v_pk_mul_f32 v[224:225], v[2:3], v[216:217]
	v_cvt_pk_f32_fp8_e32 v[214:215], v166
	v_cvt_pk_f32_fp8_sdwa v[216:217], v166 src0_sel:WORD_1
	v_pk_fma_f32 v[222:223], v[4:5], v[218:219], v[222:223]
	v_pk_fma_f32 v[224:225], v[6:7], v[220:221], v[224:225]
	v_cvt_pk_f32_fp8_e32 v[218:219], v167
	v_cvt_pk_f32_fp8_sdwa v[220:221], v167 src0_sel:WORD_1
	v_pk_fma_f32 v[222:223], v[8:9], v[214:215], v[222:223]
	v_pk_fma_f32 v[224:225], v[10:11], v[216:217], v[224:225]
	v_pk_fma_f32 v[222:223], v[12:13], v[218:219], v[222:223]
	v_pk_fma_f32 v[224:225], v[14:15], v[220:221], v[224:225]
	v_pk_add_f32 v[222:223], v[222:223], v[224:225]
	s_nop 0
	v_add_f32_e32 v231, v222, v223
	v_cvt_pk_f32_fp8_e32 v[214:215], v168
	v_cvt_pk_f32_fp8_sdwa v[216:217], v168 src0_sel:WORD_1
	v_cvt_pk_f32_fp8_e32 v[218:219], v169
	v_cvt_pk_f32_fp8_sdwa v[220:221], v169 src0_sel:WORD_1
	v_pk_mul_f32 v[222:223], v[0:1], v[214:215]
	v_pk_mul_f32 v[224:225], v[2:3], v[216:217]
	v_cvt_pk_f32_fp8_e32 v[214:215], v170
	v_cvt_pk_f32_fp8_sdwa v[216:217], v170 src0_sel:WORD_1
	v_pk_fma_f32 v[222:223], v[4:5], v[218:219], v[222:223]
	v_pk_fma_f32 v[224:225], v[6:7], v[220:221], v[224:225]
	v_cvt_pk_f32_fp8_e32 v[218:219], v171
	v_cvt_pk_f32_fp8_sdwa v[220:221], v171 src0_sel:WORD_1
	v_pk_fma_f32 v[222:223], v[8:9], v[214:215], v[222:223]
	v_pk_fma_f32 v[224:225], v[10:11], v[216:217], v[224:225]
	v_pk_fma_f32 v[222:223], v[12:13], v[218:219], v[222:223]
	v_pk_fma_f32 v[224:225], v[14:15], v[220:221], v[224:225]
	v_pk_add_f32 v[222:223], v[222:223], v[224:225]
	s_nop 0
	v_add_f32_e32 v232, v222, v223
	v_cvt_pk_f32_fp8_e32 v[214:215], v172
	v_cvt_pk_f32_fp8_sdwa v[216:217], v172 src0_sel:WORD_1
	v_cvt_pk_f32_fp8_e32 v[218:219], v173
	v_cvt_pk_f32_fp8_sdwa v[220:221], v173 src0_sel:WORD_1
	v_pk_mul_f32 v[222:223], v[0:1], v[214:215]
	v_pk_mul_f32 v[224:225], v[2:3], v[216:217]
	v_cvt_pk_f32_fp8_e32 v[214:215], v174
	v_cvt_pk_f32_fp8_sdwa v[216:217], v174 src0_sel:WORD_1
	v_pk_fma_f32 v[222:223], v[4:5], v[218:219], v[222:223]
	v_pk_fma_f32 v[224:225], v[6:7], v[220:221], v[224:225]
	v_cvt_pk_f32_fp8_e32 v[218:219], v175
	v_cvt_pk_f32_fp8_sdwa v[220:221], v175 src0_sel:WORD_1
	v_pk_fma_f32 v[222:223], v[8:9], v[214:215], v[222:223]
	v_pk_fma_f32 v[224:225], v[10:11], v[216:217], v[224:225]
	v_pk_fma_f32 v[222:223], v[12:13], v[218:219], v[222:223]
	v_pk_fma_f32 v[224:225], v[14:15], v[220:221], v[224:225]
	v_pk_add_f32 v[222:223], v[222:223], v[224:225]
	s_nop 0
	v_add_f32_e32 v233, v222, v223
	v_permlane32_swap_b32_e32 v226, v230
	v_permlane32_swap_b32_e32 v227, v231
	v_permlane32_swap_b32_e32 v228, v232
	v_permlane32_swap_b32_e32 v229, v233
	v_add_f32_e32 v226, v226, v230
	v_add_f32_e32 v228, v228, v232
	v_add_f32_e32 v227, v227, v231
	v_add_f32_e32 v229, v229, v233
	s_nop 1
	v_permlane16_swap_b32_e32 v226, v228
	v_permlane16_swap_b32_e32 v227, v229
	v_add_f32_e32 v226, v226, v228
	v_add_f32_e32 v227, v227, v229
	s_nop 0
	v_cndmask_b32_e64 v230, v226, v227, s[24:25]
	v_cndmask_b32_e64 v231, v227, v226, s[24:25]
	s_nop 1
	v_add_f32_dpp v232, v231, v230 row_ror:8 row_mask:0xf bank_mask:0xf
	s_nop 1
	v_add_f32_dpp v233, v232, v232 quad_perm:[1,0,3,2] row_mask:0xf bank_mask:0xf
	s_nop 1
	v_add_f32_dpp v232, v233, v233 quad_perm:[2,3,0,1] row_mask:0xf bank_mask:0xf
	s_nop 1
	v_add_f32_dpp v233, v232, v232 row_half_mirror row_mask:0xf bank_mask:0xf
	ds_write_b32 v235, v233 offset:32768
	v_readlane_b32 s48, v132, s72
	v_readlane_b32 s49, v132, s73
	v_readlane_b32 s50, v132, s74
	v_readlane_b32 s51, v132, s75
	v_readlane_b32 s52, v132, s76
	v_readlane_b32 s53, v132, s77
	v_readlane_b32 s54, v132, s78
	v_readlane_b32 s55, v132, s79
	s_add_u32 s32, s0, s48
	s_addc_u32 s33, s1, 0
	s_add_u32 s34, s0, s49
	s_addc_u32 s35, s1, 0
	s_add_u32 s36, s0, s50
	s_addc_u32 s37, s1, 0
	s_add_u32 s38, s0, s51
	s_addc_u32 s39, s1, 0
	s_add_u32 s40, s0, s52
	s_addc_u32 s41, s1, 0
	s_add_u32 s42, s0, s53
	s_addc_u32 s43, s1, 0
	s_add_u32 s44, s0, s54
	s_addc_u32 s45, s1, 0
	s_add_u32 s46, s0, s55
	s_addc_u32 s47, s1, 0
	global_load_dwordx4 v[144:147], v234, s[32:33]
	global_load_dwordx4 v[148:151], v234, s[34:35]
	global_load_dwordx4 v[152:155], v234, s[36:37]
	global_load_dwordx4 v[156:159], v234, s[38:39]
	global_load_dwordx4 v[160:163], v234, s[40:41]
	global_load_dwordx4 v[164:167], v234, s[42:43]
	global_load_dwordx4 v[168:171], v234, s[44:45]
	global_load_dwordx4 v[172:175], v234, s[46:47]
	s_waitcnt vmcnt(8)
; template <bool STORE>
; DI void peer_item(const Params& p, int item, char* smem) {
;     ...
; #pragma unroll 2
;     for (int k = 0; k < 128; k += 8) {
;       u32x4 uq[8];
;       const int emine = e_s[tl * 128 + k + (lane >> 3)];
;       const float gmine = g_s[tl * 128 + k + (lane >> 3)];
;       const float su = SU[emine], sv = SV[emine];
; #pragma unroll
;       for (int u = 0; u < 8; ++u) {
;         int e = e_s[tl * 128 + k + u];
;         uq[u] = *(const u32x4*)(U8 + (size_t)e * 1024 + lane * 16);
;       }
;       float part[8];
; #pragma unroll
;       for (int u = 0; u < 8; ++u) {
;         float d = 0.f;
; #pragma unroll
;         for (int i = 0; i < 4; ++i) {
;           f32x2_t lo = __builtin_amdgcn_cvt_pk_f32_fp8((int)uq[u][i], false);
;           f32x2_t hi = __builtin_amdgcn_cvt_pk_f32_fp8((int)uq[u][i], true);
;           d += xf[4 * i] * lo.x + xf[4 * i + 1] * lo.y + xf[4 * i + 2] * hi.x + xf[4 * i + 3] * hi.y;
;         }
;         part[u] = d;
;       }
;       float q4[4], r2[2], h;
; #pragma unroll
;       for (int j = 0; j < 4; ++j) {
;         float mine = b5 ? part[j + 4] : part[j];
;         float other = b5 ? part[j] : part[j + 4];
;         q4[j] = mine + __shfl_xor(other, 32);
;       }
; #pragma unroll
;       for (int j = 0; j < 2; ++j) {
;         float mine = b4 ? q4[j + 2] : q4[j];
;         float other = b4 ? q4[j] : q4[j + 2];
;         r2[j] = mine + __shfl_xor(other, 16);
;       }
;       {
;         float mine = b3 ? r2[1] : r2[0];
;         float other = b3 ? r2[0] : r2[1];
;         h = mine + __shfl_xor(other, 8);
;       }
;       h += __shfl_xor(h, 4);
;       h += __shfl_xor(h, 2);
;       h += __shfl_xor(h, 1);
	v_cvt_pk_f32_fp8_e32 v[214:215], v176
	v_cvt_pk_f32_fp8_sdwa v[216:217], v176 src0_sel:WORD_1
	v_cvt_pk_f32_fp8_e32 v[218:219], v177
	v_cvt_pk_f32_fp8_sdwa v[220:221], v177 src0_sel:WORD_1
	v_pk_mul_f32 v[222:223], v[16:17], v[214:215]
	v_pk_mul_f32 v[224:225], v[18:19], v[216:217]
	v_cvt_pk_f32_fp8_e32 v[214:215], v178
	v_cvt_pk_f32_fp8_sdwa v[216:217], v178 src0_sel:WORD_1
	v_pk_fma_f32 v[222:223], v[20:21], v[218:219], v[222:223]
	v_pk_fma_f32 v[224:225], v[22:23], v[220:221], v[224:225]
	v_cvt_pk_f32_fp8_e32 v[218:219], v179
	v_cvt_pk_f32_fp8_sdwa v[220:221], v179 src0_sel:WORD_1
	v_pk_fma_f32 v[222:223], v[24:25], v[214:215], v[222:223]
	v_pk_fma_f32 v[224:225], v[26:27], v[216:217], v[224:225]
	v_pk_fma_f32 v[222:223], v[28:29], v[218:219], v[222:223]
	v_pk_fma_f32 v[224:225], v[30:31], v[220:221], v[224:225]
	v_pk_add_f32 v[222:223], v[222:223], v[224:225]
	s_nop 0
	v_add_f32_e32 v226, v222, v223
	v_cvt_pk_f32_fp8_e32 v[214:215], v180
	v_cvt_pk_f32_fp8_sdwa v[216:217], v180 src0_sel:WORD_1
	v_cvt_pk_f32_fp8_e32 v[218:219], v181
	v_cvt_pk_f32_fp8_sdwa v[220:221], v181 src0_sel:WORD_1
	v_pk_mul_f32 v[222:223], v[16:17], v[214:215]
	v_pk_mul_f32 v[224:225], v[18:19], v[216:217]
	v_cvt_pk_f32_fp8_e32 v[214:215], v182
	v_cvt_pk_f32_fp8_sdwa v[216:217], v182 src0_sel:WORD_1
	v_pk_fma_f32 v[222:223], v[20:21], v[218:219], v[222:223]
	v_pk_fma_f32 v[224:225], v[22:23], v[220:221], v[224:225]
	v_cvt_pk_f32_fp8_e32 v[218:219], v183
	v_cvt_pk_f32_fp8_sdwa v[220:221], v183 src0_sel:WORD_1
	v_pk_fma_f32 v[222:223], v[24:25], v[214:215], v[222:223]
	v_pk_fma_f32 v[224:225], v[26:27], v[216:217], v[224:225]
	v_pk_fma_f32 v[222:223], v[28:29], v[218:219], v[222:223]
	v_pk_fma_f32 v[224:225], v[30:31], v[220:221], v[224:225]
	v_pk_add_f32 v[222:223], v[222:223], v[224:225]
	s_nop 0
	v_add_f32_e32 v227, v222, v223
	v_cvt_pk_f32_fp8_e32 v[214:215], v184
	v_cvt_pk_f32_fp8_sdwa v[216:217], v184 src0_sel:WORD_1
	v_cvt_pk_f32_fp8_e32 v[218:219], v185
	v_cvt_pk_f32_fp8_sdwa v[220:221], v185 src0_sel:WORD_1
	v_pk_mul_f32 v[222:223], v[16:17], v[214:215]
	v_pk_mul_f32 v[224:225], v[18:19], v[216:217]
	v_cvt_pk_f32_fp8_e32 v[214:215], v186
	v_cvt_pk_f32_fp8_sdwa v[216:217], v186 src0_sel:WORD_1
	v_pk_fma_f32 v[222:223], v[20:21], v[218:219], v[222:223]
	v_pk_fma_f32 v[224:225], v[22:23], v[220:221], v[224:225]
	v_cvt_pk_f32_fp8_e32 v[218:219], v187
	v_cvt_pk_f32_fp8_sdwa v[220:221], v187 src0_sel:WORD_1
	v_pk_fma_f32 v[222:223], v[24:25], v[214:215], v[222:223]
	v_pk_fma_f32 v[224:225], v[26:27], v[216:217], v[224:225]
	v_pk_fma_f32 v[222:223], v[28:29], v[218:219], v[222:223]
	v_pk_fma_f32 v[224:225], v[30:31], v[220:221], v[224:225]
	v_pk_add_f32 v[222:223], v[222:223], v[224:225]
	s_nop 0
	v_add_f32_e32 v228, v222, v223
	v_cvt_pk_f32_fp8_e32 v[214:215], v188
	v_cvt_pk_f32_fp8_sdwa v[216:217], v188 src0_sel:WORD_1
	v_cvt_pk_f32_fp8_e32 v[218:219], v189
	v_cvt_pk_f32_fp8_sdwa v[220:221], v189 src0_sel:WORD_1
	v_pk_mul_f32 v[222:223], v[16:17], v[214:215]
	v_pk_mul_f32 v[224:225], v[18:19], v[216:217]
	v_cvt_pk_f32_fp8_e32 v[214:215], v190
	v_cvt_pk_f32_fp8_sdwa v[216:217], v190 src0_sel:WORD_1
	v_pk_fma_f32 v[222:223], v[20:21], v[218:219], v[222:223]
	v_pk_fma_f32 v[224:225], v[22:23], v[220:221], v[224:225]
	v_cvt_pk_f32_fp8_e32 v[218:219], v191
	v_cvt_pk_f32_fp8_sdwa v[220:221], v191 src0_sel:WORD_1
	v_pk_fma_f32 v[222:223], v[24:25], v[214:215], v[222:223]
	v_pk_fma_f32 v[224:225], v[26:27], v[216:217], v[224:225]
	v_pk_fma_f32 v[222:223], v[28:29], v[218:219], v[222:223]
	v_pk_fma_f32 v[224:225], v[30:31], v[220:221], v[224:225]
	v_pk_add_f32 v[222:223], v[222:223], v[224:225]
	s_nop 0
	v_add_f32_e32 v229, v222, v223
	v_cvt_pk_f32_fp8_e32 v[214:215], v192
	v_cvt_pk_f32_fp8_sdwa v[216:217], v192 src0_sel:WORD_1
	v_cvt_pk_f32_fp8_e32 v[218:219], v193
	v_cvt_pk_f32_fp8_sdwa v[220:221], v193 src0_sel:WORD_1
	v_pk_mul_f32 v[222:223], v[16:17], v[214:215]
	v_pk_mul_f32 v[224:225], v[18:19], v[216:217]
	v_cvt_pk_f32_fp8_e32 v[214:215], v194
	v_cvt_pk_f32_fp8_sdwa v[216:217], v194 src0_sel:WORD_1
	v_pk_fma_f32 v[222:223], v[20:21], v[218:219], v[222:223]
	v_pk_fma_f32 v[224:225], v[22:23], v[220:221], v[224:225]
	v_cvt_pk_f32_fp8_e32 v[218:219], v195
	v_cvt_pk_f32_fp8_sdwa v[220:221], v195 src0_sel:WORD_1
	v_pk_fma_f32 v[222:223], v[24:25], v[214:215], v[222:223]
	v_pk_fma_f32 v[224:225], v[26:27], v[216:217], v[224:225]
	v_pk_fma_f32 v[222:223], v[28:29], v[218:219], v[222:223]
	v_pk_fma_f32 v[224:225], v[30:31], v[220:221], v[224:225]
	v_pk_add_f32 v[222:223], v[222:223], v[224:225]
	s_nop 0
	v_add_f32_e32 v230, v222, v223
	v_cvt_pk_f32_fp8_e32 v[214:215], v196
	v_cvt_pk_f32_fp8_sdwa v[216:217], v196 src0_sel:WORD_1
	v_cvt_pk_f32_fp8_e32 v[218:219], v197
	v_cvt_pk_f32_fp8_sdwa v[220:221], v197 src0_sel:WORD_1
	v_pk_mul_f32 v[222:223], v[16:17], v[214:215]
	v_pk_mul_f32 v[224:225], v[18:19], v[216:217]
	v_cvt_pk_f32_fp8_e32 v[214:215], v198
	v_cvt_pk_f32_fp8_sdwa v[216:217], v198 src0_sel:WORD_1
	v_pk_fma_f32 v[222:223], v[20:21], v[218:219], v[222:223]
	v_pk_fma_f32 v[224:225], v[22:23], v[220:221], v[224:225]
	v_cvt_pk_f32_fp8_e32 v[218:219], v199
	v_cvt_pk_f32_fp8_sdwa v[220:221], v199 src0_sel:WORD_1
	v_pk_fma_f32 v[222:223], v[24:25], v[214:215], v[222:223]
	v_pk_fma_f32 v[224:225], v[26:27], v[216:217], v[224:225]
	v_pk_fma_f32 v[222:223], v[28:29], v[218:219], v[222:223]
	v_pk_fma_f32 v[224:225], v[30:31], v[220:221], v[224:225]
	v_pk_add_f32 v[222:223], v[222:223], v[224:225]
	s_nop 0
	v_add_f32_e32 v231, v222, v223
	v_cvt_pk_f32_fp8_e32 v[214:215], v200
	v_cvt_pk_f32_fp8_sdwa v[216:217], v200 src0_sel:WORD_1
	v_cvt_pk_f32_fp8_e32 v[218:219], v201
; template <bool STORE>
; DI void peer_item(const Params& p, int item, char* smem) {
;     ...
; #pragma unroll 2
;     for (int k = 0; k < 128; k += 8) {
;       u32x4 uq[8];
;       const int emine = e_s[tl * 128 + k + (lane >> 3)];
;       const float gmine = g_s[tl * 128 + k + (lane >> 3)];
;       const float su = SU[emine], sv = SV[emine];
; #pragma unroll
;       for (int u = 0; u < 8; ++u) {
;         int e = e_s[tl * 128 + k + u];
;         uq[u] = *(const u32x4*)(U8 + (size_t)e * 1024 + lane * 16);
;       }
;       float part[8];
; #pragma unroll
;       for (int u = 0; u < 8; ++u) {
;         float d = 0.f;
; #pragma unroll
;         for (int i = 0; i < 4; ++i) {
;           f32x2_t lo = __builtin_amdgcn_cvt_pk_f32_fp8((int)uq[u][i], false);
;           f32x2_t hi = __builtin_amdgcn_cvt_pk_f32_fp8((int)uq[u][i], true);
;           d += xf[4 * i] * lo.x + xf[4 * i + 1] * lo.y + xf[4 * i + 2] * hi.x + xf[4 * i + 3] * hi.y;
;         }
;         part[u] = d;
;       }
;       float q4[4], r2[2], h;
; #pragma unroll
;       for (int j = 0; j < 4; ++j) {
;         float mine = b5 ? part[j + 4] : part[j];
;         float other = b5 ? part[j] : part[j + 4];
;         q4[j] = mine + __shfl_xor(other, 32);
;       }
; #pragma unroll
;       for (int j = 0; j < 2; ++j) {
;         float mine = b4 ? q4[j + 2] : q4[j];
;         float other = b4 ? q4[j] : q4[j + 2];
;         r2[j] = mine + __shfl_xor(other, 16);
;       }
;       {
;         float mine = b3 ? r2[1] : r2[0];
;         float other = b3 ? r2[0] : r2[1];
;         h = mine + __shfl_xor(other, 8);
;       }
;       h += __shfl_xor(h, 4);
;       h += __shfl_xor(h, 2);
;       h += __shfl_xor(h, 1);
	v_cvt_pk_f32_fp8_sdwa v[220:221], v201 src0_sel:WORD_1
	v_pk_mul_f32 v[222:223], v[16:17], v[214:215]
	v_pk_mul_f32 v[224:225], v[18:19], v[216:217]
	v_cvt_pk_f32_fp8_e32 v[214:215], v202
	v_cvt_pk_f32_fp8_sdwa v[216:217], v202 src0_sel:WORD_1
	v_pk_fma_f32 v[222:223], v[20:21], v[218:219], v[222:223]
	v_pk_fma_f32 v[224:225], v[22:23], v[220:221], v[224:225]
	v_cvt_pk_f32_fp8_e32 v[218:219], v203
	v_cvt_pk_f32_fp8_sdwa v[220:221], v203 src0_sel:WORD_1
	v_pk_fma_f32 v[222:223], v[24:25], v[214:215], v[222:223]
	v_pk_fma_f32 v[224:225], v[26:27], v[216:217], v[224:225]
	v_pk_fma_f32 v[222:223], v[28:29], v[218:219], v[222:223]
	v_pk_fma_f32 v[224:225], v[30:31], v[220:221], v[224:225]
	v_pk_add_f32 v[222:223], v[222:223], v[224:225]
	s_nop 0
	v_add_f32_e32 v232, v222, v223
	v_cvt_pk_f32_fp8_e32 v[214:215], v204
	v_cvt_pk_f32_fp8_sdwa v[216:217], v204 src0_sel:WORD_1
	v_cvt_pk_f32_fp8_e32 v[218:219], v205
	v_cvt_pk_f32_fp8_sdwa v[220:221], v205 src0_sel:WORD_1
	v_pk_mul_f32 v[222:223], v[16:17], v[214:215]
	v_pk_mul_f32 v[224:225], v[18:19], v[216:217]
	v_cvt_pk_f32_fp8_e32 v[214:215], v206
	v_cvt_pk_f32_fp8_sdwa v[216:217], v206 src0_sel:WORD_1
	v_pk_fma_f32 v[222:223], v[20:21], v[218:219], v[222:223]
	v_pk_fma_f32 v[224:225], v[22:23], v[220:221], v[224:225]
	v_cvt_pk_f32_fp8_e32 v[218:219], v207
	v_cvt_pk_f32_fp8_sdwa v[220:221], v207 src0_sel:WORD_1
	v_pk_fma_f32 v[222:223], v[24:25], v[214:215], v[222:223]
	v_pk_fma_f32 v[224:225], v[26:27], v[216:217], v[224:225]
	v_pk_fma_f32 v[222:223], v[28:29], v[218:219], v[222:223]
	v_pk_fma_f32 v[224:225], v[30:31], v[220:221], v[224:225]
	v_pk_add_f32 v[222:223], v[222:223], v[224:225]
	s_nop 0
	v_add_f32_e32 v233, v222, v223
	v_permlane32_swap_b32_e32 v226, v230
	v_permlane32_swap_b32_e32 v227, v231
	v_permlane32_swap_b32_e32 v228, v232
	v_permlane32_swap_b32_e32 v229, v233
	v_add_f32_e32 v226, v226, v230
	v_add_f32_e32 v228, v228, v232
	v_add_f32_e32 v227, v227, v231
	v_add_f32_e32 v229, v229, v233
	s_nop 1
	v_permlane16_swap_b32_e32 v226, v228
	v_permlane16_swap_b32_e32 v227, v229
	v_add_f32_e32 v226, v226, v228
	v_add_f32_e32 v227, v227, v229
	s_nop 0
	v_cndmask_b32_e64 v230, v226, v227, s[24:25]
	v_cndmask_b32_e64 v231, v227, v226, s[24:25]
	s_nop 1
	v_add_f32_dpp v232, v231, v230 row_ror:8 row_mask:0xf bank_mask:0xf
	s_nop 1
	v_add_f32_dpp v233, v232, v232 quad_perm:[1,0,3,2] row_mask:0xf bank_mask:0xf
	s_nop 1
	v_add_f32_dpp v232, v233, v233 quad_perm:[2,3,0,1] row_mask:0xf bank_mask:0xf
	s_nop 1
	v_add_f32_dpp v233, v232, v232 row_half_mirror row_mask:0xf bank_mask:0xf
	ds_write_b32 v235, v233 offset:33280
	v_readlane_b32 s48, v134, s72
	v_readlane_b32 s49, v134, s73
	v_readlane_b32 s50, v134, s74
	v_readlane_b32 s51, v134, s75
	v_readlane_b32 s52, v134, s76
	v_readlane_b32 s53, v134, s77
	v_readlane_b32 s54, v134, s78
	v_readlane_b32 s55, v134, s79
	s_add_u32 s32, s0, s48
	s_addc_u32 s33, s1, 0
	s_add_u32 s34, s0, s49
	s_addc_u32 s35, s1, 0
	s_add_u32 s36, s0, s50
	s_addc_u32 s37, s1, 0
	s_add_u32 s38, s0, s51
	s_addc_u32 s39, s1, 0
	s_add_u32 s40, s0, s52
	s_addc_u32 s41, s1, 0
	s_add_u32 s42, s0, s53
	s_addc_u32 s43, s1, 0
	s_add_u32 s44, s0, s54
	s_addc_u32 s45, s1, 0
	s_add_u32 s46, s0, s55
	s_addc_u32 s47, s1, 0
	global_load_dwordx4 v[176:179], v234, s[32:33]
	global_load_dwordx4 v[180:183], v234, s[34:35]
	global_load_dwordx4 v[184:187], v234, s[36:37]
	global_load_dwordx4 v[188:191], v234, s[38:39]
	global_load_dwordx4 v[192:195], v234, s[40:41]
	global_load_dwordx4 v[196:199], v234, s[42:43]
	global_load_dwordx4 v[200:203], v234, s[44:45]
	global_load_dwordx4 v[204:207], v234, s[46:47]
	s_waitcnt vmcnt(8)
	v_cvt_pk_f32_fp8_e32 v[214:215], v144
	v_cvt_pk_f32_fp8_sdwa v[216:217], v144 src0_sel:WORD_1
	v_cvt_pk_f32_fp8_e32 v[218:219], v145
	v_cvt_pk_f32_fp8_sdwa v[220:221], v145 src0_sel:WORD_1
	v_pk_mul_f32 v[222:223], v[32:33], v[214:215]
	v_pk_mul_f32 v[224:225], v[34:35], v[216:217]
	v_cvt_pk_f32_fp8_e32 v[214:215], v146
	v_cvt_pk_f32_fp8_sdwa v[216:217], v146 src0_sel:WORD_1
	v_pk_fma_f32 v[222:223], v[36:37], v[218:219], v[222:223]
	v_pk_fma_f32 v[224:225], v[38:39], v[220:221], v[224:225]
	v_cvt_pk_f32_fp8_e32 v[218:219], v147
	v_cvt_pk_f32_fp8_sdwa v[220:221], v147 src0_sel:WORD_1
	v_pk_fma_f32 v[222:223], v[40:41], v[214:215], v[222:223]
	v_pk_fma_f32 v[224:225], v[42:43], v[216:217], v[224:225]
	v_pk_fma_f32 v[222:223], v[44:45], v[218:219], v[222:223]
	v_pk_fma_f32 v[224:225], v[46:47], v[220:221], v[224:225]
	v_pk_add_f32 v[222:223], v[222:223], v[224:225]
	s_nop 0
	v_add_f32_e32 v226, v222, v223
	v_cvt_pk_f32_fp8_e32 v[214:215], v148
	v_cvt_pk_f32_fp8_sdwa v[216:217], v148 src0_sel:WORD_1
	v_cvt_pk_f32_fp8_e32 v[218:219], v149
	v_cvt_pk_f32_fp8_sdwa v[220:221], v149 src0_sel:WORD_1
	v_pk_mul_f32 v[222:223], v[32:33], v[214:215]
	v_pk_mul_f32 v[224:225], v[34:35], v[216:217]
	v_cvt_pk_f32_fp8_e32 v[214:215], v150
	v_cvt_pk_f32_fp8_sdwa v[216:217], v150 src0_sel:WORD_1
	v_pk_fma_f32 v[222:223], v[36:37], v[218:219], v[222:223]
	v_pk_fma_f32 v[224:225], v[38:39], v[220:221], v[224:225]
	v_cvt_pk_f32_fp8_e32 v[218:219], v151
	v_cvt_pk_f32_fp8_sdwa v[220:221], v151 src0_sel:WORD_1
	v_pk_fma_f32 v[222:223], v[40:41], v[214:215], v[222:223]
	v_pk_fma_f32 v[224:225], v[42:43], v[216:217], v[224:225]
	v_pk_fma_f32 v[222:223], v[44:45], v[218:219], v[222:223]
	v_pk_fma_f32 v[224:225], v[46:47], v[220:221], v[224:225]
	v_pk_add_f32 v[222:223], v[222:223], v[224:225]
	s_nop 0
	v_add_f32_e32 v227, v222, v223
	v_cvt_pk_f32_fp8_e32 v[214:215], v152
	v_cvt_pk_f32_fp8_sdwa v[216:217], v152 src0_sel:WORD_1
	v_cvt_pk_f32_fp8_e32 v[218:219], v153
	v_cvt_pk_f32_fp8_sdwa v[220:221], v153 src0_sel:WORD_1
; template <bool STORE>
; DI void peer_item(const Params& p, int item, char* smem) {
;     ...
; #pragma unroll 2
;     for (int k = 0; k < 128; k += 8) {
;       u32x4 uq[8];
;       const int emine = e_s[tl * 128 + k + (lane >> 3)];
;       const float gmine = g_s[tl * 128 + k + (lane >> 3)];
;       const float su = SU[emine], sv = SV[emine];
; #pragma unroll
;       for (int u = 0; u < 8; ++u) {
;         int e = e_s[tl * 128 + k + u];
;         uq[u] = *(const u32x4*)(U8 + (size_t)e * 1024 + lane * 16);
;       }
;       float part[8];
; #pragma unroll
;       for (int u = 0; u < 8; ++u) {
;         float d = 0.f;
; #pragma unroll
;         for (int i = 0; i < 4; ++i) {
;           f32x2_t lo = __builtin_amdgcn_cvt_pk_f32_fp8((int)uq[u][i], false);
;           f32x2_t hi = __builtin_amdgcn_cvt_pk_f32_fp8((int)uq[u][i], true);
;           d += xf[4 * i] * lo.x + xf[4 * i + 1] * lo.y + xf[4 * i + 2] * hi.x + xf[4 * i + 3] * hi.y;
;         }
;         part[u] = d;
;       }
;       float q4[4], r2[2], h;
; #pragma unroll
;       for (int j = 0; j < 4; ++j) {
;         float mine = b5 ? part[j + 4] : part[j];
;         float other = b5 ? part[j] : part[j + 4];
;         q4[j] = mine + __shfl_xor(other, 32);
;       }
; #pragma unroll
;       for (int j = 0; j < 2; ++j) {
;         float mine = b4 ? q4[j + 2] : q4[j];
;         float other = b4 ? q4[j] : q4[j + 2];
;         r2[j] = mine + __shfl_xor(other, 16);
;       }
;       {
;         float mine = b3 ? r2[1] : r2[0];
;         float other = b3 ? r2[0] : r2[1];
;         h = mine + __shfl_xor(other, 8);
;       }
;       h += __shfl_xor(h, 4);
;       h += __shfl_xor(h, 2);
;       h += __shfl_xor(h, 1);
	v_pk_mul_f32 v[222:223], v[32:33], v[214:215]
	v_pk_mul_f32 v[224:225], v[34:35], v[216:217]
	v_cvt_pk_f32_fp8_e32 v[214:215], v154
	v_cvt_pk_f32_fp8_sdwa v[216:217], v154 src0_sel:WORD_1
	v_pk_fma_f32 v[222:223], v[36:37], v[218:219], v[222:223]
	v_pk_fma_f32 v[224:225], v[38:39], v[220:221], v[224:225]
	v_cvt_pk_f32_fp8_e32 v[218:219], v155
	v_cvt_pk_f32_fp8_sdwa v[220:221], v155 src0_sel:WORD_1
	v_pk_fma_f32 v[222:223], v[40:41], v[214:215], v[222:223]
	v_pk_fma_f32 v[224:225], v[42:43], v[216:217], v[224:225]
	v_pk_fma_f32 v[222:223], v[44:45], v[218:219], v[222:223]
	v_pk_fma_f32 v[224:225], v[46:47], v[220:221], v[224:225]
	v_pk_add_f32 v[222:223], v[222:223], v[224:225]
	s_nop 0
	v_add_f32_e32 v228, v222, v223
	v_cvt_pk_f32_fp8_e32 v[214:215], v156
	v_cvt_pk_f32_fp8_sdwa v[216:217], v156 src0_sel:WORD_1
	v_cvt_pk_f32_fp8_e32 v[218:219], v157
	v_cvt_pk_f32_fp8_sdwa v[220:221], v157 src0_sel:WORD_1
	v_pk_mul_f32 v[222:223], v[32:33], v[214:215]
	v_pk_mul_f32 v[224:225], v[34:35], v[216:217]
	v_cvt_pk_f32_fp8_e32 v[214:215], v158
	v_cvt_pk_f32_fp8_sdwa v[216:217], v158 src0_sel:WORD_1
	v_pk_fma_f32 v[222:223], v[36:37], v[218:219], v[222:223]
	v_pk_fma_f32 v[224:225], v[38:39], v[220:221], v[224:225]
	v_cvt_pk_f32_fp8_e32 v[218:219], v159
	v_cvt_pk_f32_fp8_sdwa v[220:221], v159 src0_sel:WORD_1
	v_pk_fma_f32 v[222:223], v[40:41], v[214:215], v[222:223]
	v_pk_fma_f32 v[224:225], v[42:43], v[216:217], v[224:225]
	v_pk_fma_f32 v[222:223], v[44:45], v[218:219], v[222:223]
	v_pk_fma_f32 v[224:225], v[46:47], v[220:221], v[224:225]
	v_pk_add_f32 v[222:223], v[222:223], v[224:225]
	s_nop 0
	v_add_f32_e32 v229, v222, v223
	v_cvt_pk_f32_fp8_e32 v[214:215], v160
	v_cvt_pk_f32_fp8_sdwa v[216:217], v160 src0_sel:WORD_1
	v_cvt_pk_f32_fp8_e32 v[218:219], v161
	v_cvt_pk_f32_fp8_sdwa v[220:221], v161 src0_sel:WORD_1
	v_pk_mul_f32 v[222:223], v[32:33], v[214:215]
	v_pk_mul_f32 v[224:225], v[34:35], v[216:217]
	v_cvt_pk_f32_fp8_e32 v[214:215], v162
	v_cvt_pk_f32_fp8_sdwa v[216:217], v162 src0_sel:WORD_1
	v_pk_fma_f32 v[222:223], v[36:37], v[218:219], v[222:223]
	v_pk_fma_f32 v[224:225], v[38:39], v[220:221], v[224:225]
	v_cvt_pk_f32_fp8_e32 v[218:219], v163
	v_cvt_pk_f32_fp8_sdwa v[220:221], v163 src0_sel:WORD_1
	v_pk_fma_f32 v[222:223], v[40:41], v[214:215], v[222:223]
	v_pk_fma_f32 v[224:225], v[42:43], v[216:217], v[224:225]
	v_pk_fma_f32 v[222:223], v[44:45], v[218:219], v[222:223]
	v_pk_fma_f32 v[224:225], v[46:47], v[220:221], v[224:225]
	v_pk_add_f32 v[222:223], v[222:223], v[224:225]
	s_nop 0
	v_add_f32_e32 v230, v222, v223
	v_cvt_pk_f32_fp8_e32 v[214:215], v164
	v_cvt_pk_f32_fp8_sdwa v[216:217], v164 src0_sel:WORD_1
	v_cvt_pk_f32_fp8_e32 v[218:219], v165
	v_cvt_pk_f32_fp8_sdwa v[220:221], v165 src0_sel:WORD_1
	v_pk_mul_f32 v[222:223], v[32:33], v[214:215]
	v_pk_mul_f32 v[224:225], v[34:35], v[216:217]
	v_cvt_pk_f32_fp8_e32 v[214:215], v166
	v_cvt_pk_f32_fp8_sdwa v[216:217], v166 src0_sel:WORD_1
	v_pk_fma_f32 v[222:223], v[36:37], v[218:219], v[222:223]
	v_pk_fma_f32 v[224:225], v[38:39], v[220:221], v[224:225]
	v_cvt_pk_f32_fp8_e32 v[218:219], v167
	v_cvt_pk_f32_fp8_sdwa v[220:221], v167 src0_sel:WORD_1
	v_pk_fma_f32 v[222:223], v[40:41], v[214:215], v[222:223]
	v_pk_fma_f32 v[224:225], v[42:43], v[216:217], v[224:225]
	v_pk_fma_f32 v[222:223], v[44:45], v[218:219], v[222:223]
	v_pk_fma_f32 v[224:225], v[46:47], v[220:221], v[224:225]
	v_pk_add_f32 v[222:223], v[222:223], v[224:225]
	s_nop 0
	v_add_f32_e32 v231, v222, v223
	v_cvt_pk_f32_fp8_e32 v[214:215], v168
	v_cvt_pk_f32_fp8_sdwa v[216:217], v168 src0_sel:WORD_1
	v_cvt_pk_f32_fp8_e32 v[218:219], v169
	v_cvt_pk_f32_fp8_sdwa v[220:221], v169 src0_sel:WORD_1
	v_pk_mul_f32 v[222:223], v[32:33], v[214:215]
	v_pk_mul_f32 v[224:225], v[34:35], v[216:217]
	v_cvt_pk_f32_fp8_e32 v[214:215], v170
	v_cvt_pk_f32_fp8_sdwa v[216:217], v170 src0_sel:WORD_1
	v_pk_fma_f32 v[222:223], v[36:37], v[218:219], v[222:223]
	v_pk_fma_f32 v[224:225], v[38:39], v[220:221], v[224:225]
	v_cvt_pk_f32_fp8_e32 v[218:219], v171
	v_cvt_pk_f32_fp8_sdwa v[220:221], v171 src0_sel:WORD_1
	v_pk_fma_f32 v[222:223], v[40:41], v[214:215], v[222:223]
	v_pk_fma_f32 v[224:225], v[42:43], v[216:217], v[224:225]
	v_pk_fma_f32 v[222:223], v[44:45], v[218:219], v[222:223]
	v_pk_fma_f32 v[224:225], v[46:47], v[220:221], v[224:225]
	v_pk_add_f32 v[222:223], v[222:223], v[224:225]
	s_nop 0
	v_add_f32_e32 v232, v222, v223
	v_cvt_pk_f32_fp8_e32 v[214:215], v172
	v_cvt_pk_f32_fp8_sdwa v[216:217], v172 src0_sel:WORD_1
	v_cvt_pk_f32_fp8_e32 v[218:219], v173
	v_cvt_pk_f32_fp8_sdwa v[220:221], v173 src0_sel:WORD_1
	v_pk_mul_f32 v[222:223], v[32:33], v[214:215]
	v_pk_mul_f32 v[224:225], v[34:35], v[216:217]
	v_cvt_pk_f32_fp8_e32 v[214:215], v174
	v_cvt_pk_f32_fp8_sdwa v[216:217], v174 src0_sel:WORD_1
	v_pk_fma_f32 v[222:223], v[36:37], v[218:219], v[222:223]
	v_pk_fma_f32 v[224:225], v[38:39], v[220:221], v[224:225]
	v_cvt_pk_f32_fp8_e32 v[218:219], v175
	v_cvt_pk_f32_fp8_sdwa v[220:221], v175 src0_sel:WORD_1
	v_pk_fma_f32 v[222:223], v[40:41], v[214:215], v[222:223]
	v_pk_fma_f32 v[224:225], v[42:43], v[216:217], v[224:225]
	v_pk_fma_f32 v[222:223], v[44:45], v[218:219], v[222:223]
	v_pk_fma_f32 v[224:225], v[46:47], v[220:221], v[224:225]
	v_pk_add_f32 v[222:223], v[222:223], v[224:225]
	s_nop 0
	v_add_f32_e32 v233, v222, v223
	v_permlane32_swap_b32_e32 v226, v230
	v_permlane32_swap_b32_e32 v227, v231
	v_permlane32_swap_b32_e32 v228, v232
	v_permlane32_swap_b32_e32 v229, v233
	v_add_f32_e32 v226, v226, v230
	v_add_f32_e32 v228, v228, v232
	v_add_f32_e32 v227, v227, v231
	v_add_f32_e32 v229, v229, v233
	s_nop 1
	v_permlane16_swap_b32_e32 v226, v228
; template <bool STORE>
; DI void peer_item(const Params& p, int item, char* smem) {
;     ...
; #pragma unroll 2
;     for (int k = 0; k < 128; k += 8) {
;       u32x4 uq[8];
;       const int emine = e_s[tl * 128 + k + (lane >> 3)];
;       const float gmine = g_s[tl * 128 + k + (lane >> 3)];
;       const float su = SU[emine], sv = SV[emine];
; #pragma unroll
;       for (int u = 0; u < 8; ++u) {
;         int e = e_s[tl * 128 + k + u];
;         uq[u] = *(const u32x4*)(U8 + (size_t)e * 1024 + lane * 16);
;       }
;       float part[8];
; #pragma unroll
;       for (int u = 0; u < 8; ++u) {
;         float d = 0.f;
; #pragma unroll
;         for (int i = 0; i < 4; ++i) {
;           f32x2_t lo = __builtin_amdgcn_cvt_pk_f32_fp8((int)uq[u][i], false);
;           f32x2_t hi = __builtin_amdgcn_cvt_pk_f32_fp8((int)uq[u][i], true);
;           d += xf[4 * i] * lo.x + xf[4 * i + 1] * lo.y + xf[4 * i + 2] * hi.x + xf[4 * i + 3] * hi.y;
;         }
;         part[u] = d;
;       }
;       float q4[4], r2[2], h;
; #pragma unroll
;       for (int j = 0; j < 4; ++j) {
;         float mine = b5 ? part[j + 4] : part[j];
;         float other = b5 ? part[j] : part[j + 4];
;         q4[j] = mine + __shfl_xor(other, 32);
;       }
; #pragma unroll
;       for (int j = 0; j < 2; ++j) {
;         float mine = b4 ? q4[j + 2] : q4[j];
;         float other = b4 ? q4[j] : q4[j + 2];
;         r2[j] = mine + __shfl_xor(other, 16);
;       }
;       {
;         float mine = b3 ? r2[1] : r2[0];
;         float other = b3 ? r2[0] : r2[1];
;         h = mine + __shfl_xor(other, 8);
;       }
;       h += __shfl_xor(h, 4);
;       h += __shfl_xor(h, 2);
;       h += __shfl_xor(h, 1);
	v_permlane16_swap_b32_e32 v227, v229
	v_add_f32_e32 v226, v226, v228
	v_add_f32_e32 v227, v227, v229
	s_nop 0
	v_cndmask_b32_e64 v230, v226, v227, s[24:25]
	v_cndmask_b32_e64 v231, v227, v226, s[24:25]
	s_nop 1
	v_add_f32_dpp v232, v231, v230 row_ror:8 row_mask:0xf bank_mask:0xf
	s_nop 1
	v_add_f32_dpp v233, v232, v232 quad_perm:[1,0,3,2] row_mask:0xf bank_mask:0xf
	s_nop 1
	v_add_f32_dpp v232, v233, v233 quad_perm:[2,3,0,1] row_mask:0xf bank_mask:0xf
	s_nop 1
	v_add_f32_dpp v233, v232, v232 row_half_mirror row_mask:0xf bank_mask:0xf
	ds_write_b32 v235, v233 offset:33792
	v_readlane_b32 s48, v136, s72
	v_readlane_b32 s49, v136, s73
	v_readlane_b32 s50, v136, s74
	v_readlane_b32 s51, v136, s75
	v_readlane_b32 s52, v136, s76
	v_readlane_b32 s53, v136, s77
	v_readlane_b32 s54, v136, s78
	v_readlane_b32 s55, v136, s79
	s_add_u32 s32, s0, s48
	s_addc_u32 s33, s1, 0
	s_add_u32 s34, s0, s49
	s_addc_u32 s35, s1, 0
	s_add_u32 s36, s0, s50
	s_addc_u32 s37, s1, 0
	s_add_u32 s38, s0, s51
	s_addc_u32 s39, s1, 0
	s_add_u32 s40, s0, s52
	s_addc_u32 s41, s1, 0
	s_add_u32 s42, s0, s53
	s_addc_u32 s43, s1, 0
	s_add_u32 s44, s0, s54
	s_addc_u32 s45, s1, 0
	s_add_u32 s46, s0, s55
	s_addc_u32 s47, s1, 0
	global_load_dwordx4 v[144:147], v234, s[32:33]
	global_load_dwordx4 v[148:151], v234, s[34:35]
	global_load_dwordx4 v[152:155], v234, s[36:37]
	global_load_dwordx4 v[156:159], v234, s[38:39]
	global_load_dwordx4 v[160:163], v234, s[40:41]
	global_load_dwordx4 v[164:167], v234, s[42:43]
	global_load_dwordx4 v[168:171], v234, s[44:45]
	global_load_dwordx4 v[172:175], v234, s[46:47]
	s_waitcnt vmcnt(8)
	v_cvt_pk_f32_fp8_e32 v[214:215], v176
	v_cvt_pk_f32_fp8_sdwa v[216:217], v176 src0_sel:WORD_1
	v_cvt_pk_f32_fp8_e32 v[218:219], v177
	v_cvt_pk_f32_fp8_sdwa v[220:221], v177 src0_sel:WORD_1
	v_pk_mul_f32 v[222:223], v[48:49], v[214:215]
	v_pk_mul_f32 v[224:225], v[50:51], v[216:217]
	v_cvt_pk_f32_fp8_e32 v[214:215], v178
	v_cvt_pk_f32_fp8_sdwa v[216:217], v178 src0_sel:WORD_1
	v_pk_fma_f32 v[222:223], v[52:53], v[218:219], v[222:223]
	v_pk_fma_f32 v[224:225], v[54:55], v[220:221], v[224:225]
	v_cvt_pk_f32_fp8_e32 v[218:219], v179
	v_cvt_pk_f32_fp8_sdwa v[220:221], v179 src0_sel:WORD_1
	v_pk_fma_f32 v[222:223], v[56:57], v[214:215], v[222:223]
	v_pk_fma_f32 v[224:225], v[58:59], v[216:217], v[224:225]
	v_pk_fma_f32 v[222:223], v[60:61], v[218:219], v[222:223]
	v_pk_fma_f32 v[224:225], v[62:63], v[220:221], v[224:225]
	v_pk_add_f32 v[222:223], v[222:223], v[224:225]
	s_nop 0
	v_add_f32_e32 v226, v222, v223
	v_cvt_pk_f32_fp8_e32 v[214:215], v180
	v_cvt_pk_f32_fp8_sdwa v[216:217], v180 src0_sel:WORD_1
	v_cvt_pk_f32_fp8_e32 v[218:219], v181
	v_cvt_pk_f32_fp8_sdwa v[220:221], v181 src0_sel:WORD_1
	v_pk_mul_f32 v[222:223], v[48:49], v[214:215]
	v_pk_mul_f32 v[224:225], v[50:51], v[216:217]
	v_cvt_pk_f32_fp8_e32 v[214:215], v182
	v_cvt_pk_f32_fp8_sdwa v[216:217], v182 src0_sel:WORD_1
	v_pk_fma_f32 v[222:223], v[52:53], v[218:219], v[222:223]
	v_pk_fma_f32 v[224:225], v[54:55], v[220:221], v[224:225]
	v_cvt_pk_f32_fp8_e32 v[218:219], v183
	v_cvt_pk_f32_fp8_sdwa v[220:221], v183 src0_sel:WORD_1
	v_pk_fma_f32 v[222:223], v[56:57], v[214:215], v[222:223]
	v_pk_fma_f32 v[224:225], v[58:59], v[216:217], v[224:225]
	v_pk_fma_f32 v[222:223], v[60:61], v[218:219], v[222:223]
	v_pk_fma_f32 v[224:225], v[62:63], v[220:221], v[224:225]
	v_pk_add_f32 v[222:223], v[222:223], v[224:225]
	s_nop 0
	v_add_f32_e32 v227, v222, v223
	v_cvt_pk_f32_fp8_e32 v[214:215], v184
	v_cvt_pk_f32_fp8_sdwa v[216:217], v184 src0_sel:WORD_1
	v_cvt_pk_f32_fp8_e32 v[218:219], v185
	v_cvt_pk_f32_fp8_sdwa v[220:221], v185 src0_sel:WORD_1
	v_pk_mul_f32 v[222:223], v[48:49], v[214:215]
	v_pk_mul_f32 v[224:225], v[50:51], v[216:217]
	v_cvt_pk_f32_fp8_e32 v[214:215], v186
	v_cvt_pk_f32_fp8_sdwa v[216:217], v186 src0_sel:WORD_1
	v_pk_fma_f32 v[222:223], v[52:53], v[218:219], v[222:223]
	v_pk_fma_f32 v[224:225], v[54:55], v[220:221], v[224:225]
	v_cvt_pk_f32_fp8_e32 v[218:219], v187
	v_cvt_pk_f32_fp8_sdwa v[220:221], v187 src0_sel:WORD_1
	v_pk_fma_f32 v[222:223], v[56:57], v[214:215], v[222:223]
	v_pk_fma_f32 v[224:225], v[58:59], v[216:217], v[224:225]
	v_pk_fma_f32 v[222:223], v[60:61], v[218:219], v[222:223]
	v_pk_fma_f32 v[224:225], v[62:63], v[220:221], v[224:225]
	v_pk_add_f32 v[222:223], v[222:223], v[224:225]
	s_nop 0
	v_add_f32_e32 v228, v222, v223
	v_cvt_pk_f32_fp8_e32 v[214:215], v188
	v_cvt_pk_f32_fp8_sdwa v[216:217], v188 src0_sel:WORD_1
	v_cvt_pk_f32_fp8_e32 v[218:219], v189
	v_cvt_pk_f32_fp8_sdwa v[220:221], v189 src0_sel:WORD_1
	v_pk_mul_f32 v[222:223], v[48:49], v[214:215]
	v_pk_mul_f32 v[224:225], v[50:51], v[216:217]
	v_cvt_pk_f32_fp8_e32 v[214:215], v190
	v_cvt_pk_f32_fp8_sdwa v[216:217], v190 src0_sel:WORD_1
	v_pk_fma_f32 v[222:223], v[52:53], v[218:219], v[222:223]
	v_pk_fma_f32 v[224:225], v[54:55], v[220:221], v[224:225]
	v_cvt_pk_f32_fp8_e32 v[218:219], v191
	v_cvt_pk_f32_fp8_sdwa v[220:221], v191 src0_sel:WORD_1
	v_pk_fma_f32 v[222:223], v[56:57], v[214:215], v[222:223]
	v_pk_fma_f32 v[224:225], v[58:59], v[216:217], v[224:225]
	v_pk_fma_f32 v[222:223], v[60:61], v[218:219], v[222:223]
	v_pk_fma_f32 v[224:225], v[62:63], v[220:221], v[224:225]
	v_pk_add_f32 v[222:223], v[222:223], v[224:225]
	s_nop 0
	v_add_f32_e32 v229, v222, v223
	v_cvt_pk_f32_fp8_e32 v[214:215], v192
	v_cvt_pk_f32_fp8_sdwa v[216:217], v192 src0_sel:WORD_1
	v_cvt_pk_f32_fp8_e32 v[218:219], v193
	v_cvt_pk_f32_fp8_sdwa v[220:221], v193 src0_sel:WORD_1
	v_pk_mul_f32 v[222:223], v[48:49], v[214:215]
	v_pk_mul_f32 v[224:225], v[50:51], v[216:217]
	v_cvt_pk_f32_fp8_e32 v[214:215], v194
	v_cvt_pk_f32_fp8_sdwa v[216:217], v194 src0_sel:WORD_1
; template <bool STORE>
; DI void peer_item(const Params& p, int item, char* smem) {
;     ...
; #pragma unroll 2
;     for (int k = 0; k < 128; k += 8) {
;       u32x4 uq[8];
;       const int emine = e_s[tl * 128 + k + (lane >> 3)];
;       const float gmine = g_s[tl * 128 + k + (lane >> 3)];
;       const float su = SU[emine], sv = SV[emine];
; #pragma unroll
;       for (int u = 0; u < 8; ++u) {
;         int e = e_s[tl * 128 + k + u];
;         uq[u] = *(const u32x4*)(U8 + (size_t)e * 1024 + lane * 16);
;       }
;       float part[8];
; #pragma unroll
;       for (int u = 0; u < 8; ++u) {
;         float d = 0.f;
; #pragma unroll
;         for (int i = 0; i < 4; ++i) {
;           f32x2_t lo = __builtin_amdgcn_cvt_pk_f32_fp8((int)uq[u][i], false);
;           f32x2_t hi = __builtin_amdgcn_cvt_pk_f32_fp8((int)uq[u][i], true);
;           d += xf[4 * i] * lo.x + xf[4 * i + 1] * lo.y + xf[4 * i + 2] * hi.x + xf[4 * i + 3] * hi.y;
;         }
;         part[u] = d;
;       }
;       float q4[4], r2[2], h;
; #pragma unroll
;       for (int j = 0; j < 4; ++j) {
;         float mine = b5 ? part[j + 4] : part[j];
;         float other = b5 ? part[j] : part[j + 4];
;         q4[j] = mine + __shfl_xor(other, 32);
;       }
; #pragma unroll
;       for (int j = 0; j < 2; ++j) {
;         float mine = b4 ? q4[j + 2] : q4[j];
;         float other = b4 ? q4[j] : q4[j + 2];
;         r2[j] = mine + __shfl_xor(other, 16);
;       }
;       {
;         float mine = b3 ? r2[1] : r2[0];
;         float other = b3 ? r2[0] : r2[1];
;         h = mine + __shfl_xor(other, 8);
;       }
;       h += __shfl_xor(h, 4);
;       h += __shfl_xor(h, 2);
;       h += __shfl_xor(h, 1);
	v_pk_fma_f32 v[222:223], v[52:53], v[218:219], v[222:223]
	v_pk_fma_f32 v[224:225], v[54:55], v[220:221], v[224:225]
	v_cvt_pk_f32_fp8_e32 v[218:219], v195
	v_cvt_pk_f32_fp8_sdwa v[220:221], v195 src0_sel:WORD_1
	v_pk_fma_f32 v[222:223], v[56:57], v[214:215], v[222:223]
	v_pk_fma_f32 v[224:225], v[58:59], v[216:217], v[224:225]
	v_pk_fma_f32 v[222:223], v[60:61], v[218:219], v[222:223]
	v_pk_fma_f32 v[224:225], v[62:63], v[220:221], v[224:225]
	v_pk_add_f32 v[222:223], v[222:223], v[224:225]
	s_nop 0
	v_add_f32_e32 v230, v222, v223
	v_cvt_pk_f32_fp8_e32 v[214:215], v196
	v_cvt_pk_f32_fp8_sdwa v[216:217], v196 src0_sel:WORD_1
	v_cvt_pk_f32_fp8_e32 v[218:219], v197
	v_cvt_pk_f32_fp8_sdwa v[220:221], v197 src0_sel:WORD_1
	v_pk_mul_f32 v[222:223], v[48:49], v[214:215]
	v_pk_mul_f32 v[224:225], v[50:51], v[216:217]
	v_cvt_pk_f32_fp8_e32 v[214:215], v198
	v_cvt_pk_f32_fp8_sdwa v[216:217], v198 src0_sel:WORD_1
	v_pk_fma_f32 v[222:223], v[52:53], v[218:219], v[222:223]
	v_pk_fma_f32 v[224:225], v[54:55], v[220:221], v[224:225]
	v_cvt_pk_f32_fp8_e32 v[218:219], v199
	v_cvt_pk_f32_fp8_sdwa v[220:221], v199 src0_sel:WORD_1
	v_pk_fma_f32 v[222:223], v[56:57], v[214:215], v[222:223]
	v_pk_fma_f32 v[224:225], v[58:59], v[216:217], v[224:225]
	v_pk_fma_f32 v[222:223], v[60:61], v[218:219], v[222:223]
	v_pk_fma_f32 v[224:225], v[62:63], v[220:221], v[224:225]
	v_pk_add_f32 v[222:223], v[222:223], v[224:225]
	s_nop 0
	v_add_f32_e32 v231, v222, v223
	v_cvt_pk_f32_fp8_e32 v[214:215], v200
	v_cvt_pk_f32_fp8_sdwa v[216:217], v200 src0_sel:WORD_1
	v_cvt_pk_f32_fp8_e32 v[218:219], v201
	v_cvt_pk_f32_fp8_sdwa v[220:221], v201 src0_sel:WORD_1
	v_pk_mul_f32 v[222:223], v[48:49], v[214:215]
	v_pk_mul_f32 v[224:225], v[50:51], v[216:217]
	v_cvt_pk_f32_fp8_e32 v[214:215], v202
	v_cvt_pk_f32_fp8_sdwa v[216:217], v202 src0_sel:WORD_1
	v_pk_fma_f32 v[222:223], v[52:53], v[218:219], v[222:223]
	v_pk_fma_f32 v[224:225], v[54:55], v[220:221], v[224:225]
	v_cvt_pk_f32_fp8_e32 v[218:219], v203
	v_cvt_pk_f32_fp8_sdwa v[220:221], v203 src0_sel:WORD_1
	v_pk_fma_f32 v[222:223], v[56:57], v[214:215], v[222:223]
	v_pk_fma_f32 v[224:225], v[58:59], v[216:217], v[224:225]
	v_pk_fma_f32 v[222:223], v[60:61], v[218:219], v[222:223]
	v_pk_fma_f32 v[224:225], v[62:63], v[220:221], v[224:225]
	v_pk_add_f32 v[222:223], v[222:223], v[224:225]
	s_nop 0
	v_add_f32_e32 v232, v222, v223
	v_cvt_pk_f32_fp8_e32 v[214:215], v204
	v_cvt_pk_f32_fp8_sdwa v[216:217], v204 src0_sel:WORD_1
	v_cvt_pk_f32_fp8_e32 v[218:219], v205
	v_cvt_pk_f32_fp8_sdwa v[220:221], v205 src0_sel:WORD_1
	v_pk_mul_f32 v[222:223], v[48:49], v[214:215]
	v_pk_mul_f32 v[224:225], v[50:51], v[216:217]
	v_cvt_pk_f32_fp8_e32 v[214:215], v206
	v_cvt_pk_f32_fp8_sdwa v[216:217], v206 src0_sel:WORD_1
	v_pk_fma_f32 v[222:223], v[52:53], v[218:219], v[222:223]
	v_pk_fma_f32 v[224:225], v[54:55], v[220:221], v[224:225]
	v_cvt_pk_f32_fp8_e32 v[218:219], v207
	v_cvt_pk_f32_fp8_sdwa v[220:221], v207 src0_sel:WORD_1
	v_pk_fma_f32 v[222:223], v[56:57], v[214:215], v[222:223]
	v_pk_fma_f32 v[224:225], v[58:59], v[216:217], v[224:225]
	v_pk_fma_f32 v[222:223], v[60:61], v[218:219], v[222:223]
	v_pk_fma_f32 v[224:225], v[62:63], v[220:221], v[224:225]
	v_pk_add_f32 v[222:223], v[222:223], v[224:225]
	s_nop 0
	v_add_f32_e32 v233, v222, v223
	v_permlane32_swap_b32_e32 v226, v230
	v_permlane32_swap_b32_e32 v227, v231
	v_permlane32_swap_b32_e32 v228, v232
	v_permlane32_swap_b32_e32 v229, v233
	v_add_f32_e32 v226, v226, v230
	v_add_f32_e32 v228, v228, v232
	v_add_f32_e32 v227, v227, v231
	v_add_f32_e32 v229, v229, v233
	s_nop 1
	v_permlane16_swap_b32_e32 v226, v228
	v_permlane16_swap_b32_e32 v227, v229
	v_add_f32_e32 v226, v226, v228
	v_add_f32_e32 v227, v227, v229
	s_nop 0
	v_cndmask_b32_e64 v230, v226, v227, s[24:25]
	v_cndmask_b32_e64 v231, v227, v226, s[24:25]
	s_nop 1
	v_add_f32_dpp v232, v231, v230 row_ror:8 row_mask:0xf bank_mask:0xf
	s_nop 1
	v_add_f32_dpp v233, v232, v232 quad_perm:[1,0,3,2] row_mask:0xf bank_mask:0xf
	s_nop 1
	v_add_f32_dpp v232, v233, v233 quad_perm:[2,3,0,1] row_mask:0xf bank_mask:0xf
	s_nop 1
	v_add_f32_dpp v233, v232, v232 row_half_mirror row_mask:0xf bank_mask:0xf
	ds_write_b32 v235, v233 offset:34304
	v_readlane_b32 s48, v138, s72
	v_readlane_b32 s49, v138, s73
	v_readlane_b32 s50, v138, s74
	v_readlane_b32 s51, v138, s75
	v_readlane_b32 s52, v138, s76
	v_readlane_b32 s53, v138, s77
	v_readlane_b32 s54, v138, s78
	v_readlane_b32 s55, v138, s79
	s_add_u32 s32, s0, s48
	s_addc_u32 s33, s1, 0
	s_add_u32 s34, s0, s49
	s_addc_u32 s35, s1, 0
	s_add_u32 s36, s0, s50
	s_addc_u32 s37, s1, 0
	s_add_u32 s38, s0, s51
	s_addc_u32 s39, s1, 0
	s_add_u32 s40, s0, s52
	s_addc_u32 s41, s1, 0
	s_add_u32 s42, s0, s53
	s_addc_u32 s43, s1, 0
	s_add_u32 s44, s0, s54
	s_addc_u32 s45, s1, 0
	s_add_u32 s46, s0, s55
	s_addc_u32 s47, s1, 0
	global_load_dwordx4 v[176:179], v234, s[32:33]
	global_load_dwordx4 v[180:183], v234, s[34:35]
	global_load_dwordx4 v[184:187], v234, s[36:37]
	global_load_dwordx4 v[188:191], v234, s[38:39]
	global_load_dwordx4 v[192:195], v234, s[40:41]
	global_load_dwordx4 v[196:199], v234, s[42:43]
	global_load_dwordx4 v[200:203], v234, s[44:45]
	global_load_dwordx4 v[204:207], v234, s[46:47]
	s_waitcnt vmcnt(8)
; template <bool STORE>
; DI void peer_item(const Params& p, int item, char* smem) {
;     ...
; #pragma unroll 2
;     for (int k = 0; k < 128; k += 8) {
;       u32x4 uq[8];
;       const int emine = e_s[tl * 128 + k + (lane >> 3)];
;       const float gmine = g_s[tl * 128 + k + (lane >> 3)];
;       const float su = SU[emine], sv = SV[emine];
; #pragma unroll
;       for (int u = 0; u < 8; ++u) {
;         int e = e_s[tl * 128 + k + u];
;         uq[u] = *(const u32x4*)(U8 + (size_t)e * 1024 + lane * 16);
;       }
;       float part[8];
; #pragma unroll
;       for (int u = 0; u < 8; ++u) {
;         float d = 0.f;
; #pragma unroll
;         for (int i = 0; i < 4; ++i) {
;           f32x2_t lo = __builtin_amdgcn_cvt_pk_f32_fp8((int)uq[u][i], false);
;           f32x2_t hi = __builtin_amdgcn_cvt_pk_f32_fp8((int)uq[u][i], true);
;           d += xf[4 * i] * lo.x + xf[4 * i + 1] * lo.y + xf[4 * i + 2] * hi.x + xf[4 * i + 3] * hi.y;
;         }
;         part[u] = d;
;       }
;       float q4[4], r2[2], h;
; #pragma unroll
;       for (int j = 0; j < 4; ++j) {
;         float mine = b5 ? part[j + 4] : part[j];
;         float other = b5 ? part[j] : part[j + 4];
;         q4[j] = mine + __shfl_xor(other, 32);
;       }
; #pragma unroll
;       for (int j = 0; j < 2; ++j) {
;         float mine = b4 ? q4[j + 2] : q4[j];
;         float other = b4 ? q4[j] : q4[j + 2];
;         r2[j] = mine + __shfl_xor(other, 16);
;       }
;       {
;         float mine = b3 ? r2[1] : r2[0];
;         float other = b3 ? r2[0] : r2[1];
;         h = mine + __shfl_xor(other, 8);
;       }
;       h += __shfl_xor(h, 4);
;       h += __shfl_xor(h, 2);
;       h += __shfl_xor(h, 1);
	v_cvt_pk_f32_fp8_e32 v[214:215], v144
	v_cvt_pk_f32_fp8_sdwa v[216:217], v144 src0_sel:WORD_1
	v_cvt_pk_f32_fp8_e32 v[218:219], v145
	v_cvt_pk_f32_fp8_sdwa v[220:221], v145 src0_sel:WORD_1
	v_pk_mul_f32 v[222:223], v[64:65], v[214:215]
	v_pk_mul_f32 v[224:225], v[66:67], v[216:217]
	v_cvt_pk_f32_fp8_e32 v[214:215], v146
	v_cvt_pk_f32_fp8_sdwa v[216:217], v146 src0_sel:WORD_1
	v_pk_fma_f32 v[222:223], v[68:69], v[218:219], v[222:223]
	v_pk_fma_f32 v[224:225], v[70:71], v[220:221], v[224:225]
	v_cvt_pk_f32_fp8_e32 v[218:219], v147
	v_cvt_pk_f32_fp8_sdwa v[220:221], v147 src0_sel:WORD_1
	v_pk_fma_f32 v[222:223], v[72:73], v[214:215], v[222:223]
	v_pk_fma_f32 v[224:225], v[74:75], v[216:217], v[224:225]
	v_pk_fma_f32 v[222:223], v[76:77], v[218:219], v[222:223]
	v_pk_fma_f32 v[224:225], v[78:79], v[220:221], v[224:225]
	v_pk_add_f32 v[222:223], v[222:223], v[224:225]
	s_nop 0
	v_add_f32_e32 v226, v222, v223
	v_cvt_pk_f32_fp8_e32 v[214:215], v148
	v_cvt_pk_f32_fp8_sdwa v[216:217], v148 src0_sel:WORD_1
	v_cvt_pk_f32_fp8_e32 v[218:219], v149
	v_cvt_pk_f32_fp8_sdwa v[220:221], v149 src0_sel:WORD_1
	v_pk_mul_f32 v[222:223], v[64:65], v[214:215]
	v_pk_mul_f32 v[224:225], v[66:67], v[216:217]
	v_cvt_pk_f32_fp8_e32 v[214:215], v150
	v_cvt_pk_f32_fp8_sdwa v[216:217], v150 src0_sel:WORD_1
	v_pk_fma_f32 v[222:223], v[68:69], v[218:219], v[222:223]
	v_pk_fma_f32 v[224:225], v[70:71], v[220:221], v[224:225]
	v_cvt_pk_f32_fp8_e32 v[218:219], v151
	v_cvt_pk_f32_fp8_sdwa v[220:221], v151 src0_sel:WORD_1
	v_pk_fma_f32 v[222:223], v[72:73], v[214:215], v[222:223]
	v_pk_fma_f32 v[224:225], v[74:75], v[216:217], v[224:225]
	v_pk_fma_f32 v[222:223], v[76:77], v[218:219], v[222:223]
	v_pk_fma_f32 v[224:225], v[78:79], v[220:221], v[224:225]
	v_pk_add_f32 v[222:223], v[222:223], v[224:225]
	s_nop 0
	v_add_f32_e32 v227, v222, v223
	v_cvt_pk_f32_fp8_e32 v[214:215], v152
	v_cvt_pk_f32_fp8_sdwa v[216:217], v152 src0_sel:WORD_1
	v_cvt_pk_f32_fp8_e32 v[218:219], v153
	v_cvt_pk_f32_fp8_sdwa v[220:221], v153 src0_sel:WORD_1
	v_pk_mul_f32 v[222:223], v[64:65], v[214:215]
	v_pk_mul_f32 v[224:225], v[66:67], v[216:217]
	v_cvt_pk_f32_fp8_e32 v[214:215], v154
	v_cvt_pk_f32_fp8_sdwa v[216:217], v154 src0_sel:WORD_1
	v_pk_fma_f32 v[222:223], v[68:69], v[218:219], v[222:223]
	v_pk_fma_f32 v[224:225], v[70:71], v[220:221], v[224:225]
	v_cvt_pk_f32_fp8_e32 v[218:219], v155
	v_cvt_pk_f32_fp8_sdwa v[220:221], v155 src0_sel:WORD_1
	v_pk_fma_f32 v[222:223], v[72:73], v[214:215], v[222:223]
	v_pk_fma_f32 v[224:225], v[74:75], v[216:217], v[224:225]
	v_pk_fma_f32 v[222:223], v[76:77], v[218:219], v[222:223]
	v_pk_fma_f32 v[224:225], v[78:79], v[220:221], v[224:225]
	v_pk_add_f32 v[222:223], v[222:223], v[224:225]
	s_nop 0
	v_add_f32_e32 v228, v222, v223
	v_cvt_pk_f32_fp8_e32 v[214:215], v156
	v_cvt_pk_f32_fp8_sdwa v[216:217], v156 src0_sel:WORD_1
	v_cvt_pk_f32_fp8_e32 v[218:219], v157
	v_cvt_pk_f32_fp8_sdwa v[220:221], v157 src0_sel:WORD_1
	v_pk_mul_f32 v[222:223], v[64:65], v[214:215]
	v_pk_mul_f32 v[224:225], v[66:67], v[216:217]
	v_cvt_pk_f32_fp8_e32 v[214:215], v158
	v_cvt_pk_f32_fp8_sdwa v[216:217], v158 src0_sel:WORD_1
	v_pk_fma_f32 v[222:223], v[68:69], v[218:219], v[222:223]
	v_pk_fma_f32 v[224:225], v[70:71], v[220:221], v[224:225]
	v_cvt_pk_f32_fp8_e32 v[218:219], v159
	v_cvt_pk_f32_fp8_sdwa v[220:221], v159 src0_sel:WORD_1
	v_pk_fma_f32 v[222:223], v[72:73], v[214:215], v[222:223]
	v_pk_fma_f32 v[224:225], v[74:75], v[216:217], v[224:225]
	v_pk_fma_f32 v[222:223], v[76:77], v[218:219], v[222:223]
	v_pk_fma_f32 v[224:225], v[78:79], v[220:221], v[224:225]
	v_pk_add_f32 v[222:223], v[222:223], v[224:225]
	s_nop 0
	v_add_f32_e32 v229, v222, v223
	v_cvt_pk_f32_fp8_e32 v[214:215], v160
	v_cvt_pk_f32_fp8_sdwa v[216:217], v160 src0_sel:WORD_1
	v_cvt_pk_f32_fp8_e32 v[218:219], v161
	v_cvt_pk_f32_fp8_sdwa v[220:221], v161 src0_sel:WORD_1
	v_pk_mul_f32 v[222:223], v[64:65], v[214:215]
	v_pk_mul_f32 v[224:225], v[66:67], v[216:217]
	v_cvt_pk_f32_fp8_e32 v[214:215], v162
	v_cvt_pk_f32_fp8_sdwa v[216:217], v162 src0_sel:WORD_1
	v_pk_fma_f32 v[222:223], v[68:69], v[218:219], v[222:223]
	v_pk_fma_f32 v[224:225], v[70:71], v[220:221], v[224:225]
	v_cvt_pk_f32_fp8_e32 v[218:219], v163
	v_cvt_pk_f32_fp8_sdwa v[220:221], v163 src0_sel:WORD_1
	v_pk_fma_f32 v[222:223], v[72:73], v[214:215], v[222:223]
	v_pk_fma_f32 v[224:225], v[74:75], v[216:217], v[224:225]
	v_pk_fma_f32 v[222:223], v[76:77], v[218:219], v[222:223]
	v_pk_fma_f32 v[224:225], v[78:79], v[220:221], v[224:225]
	v_pk_add_f32 v[222:223], v[222:223], v[224:225]
	s_nop 0
	v_add_f32_e32 v230, v222, v223
	v_cvt_pk_f32_fp8_e32 v[214:215], v164
	v_cvt_pk_f32_fp8_sdwa v[216:217], v164 src0_sel:WORD_1
	v_cvt_pk_f32_fp8_e32 v[218:219], v165
	v_cvt_pk_f32_fp8_sdwa v[220:221], v165 src0_sel:WORD_1
	v_pk_mul_f32 v[222:223], v[64:65], v[214:215]
	v_pk_mul_f32 v[224:225], v[66:67], v[216:217]
	v_cvt_pk_f32_fp8_e32 v[214:215], v166
	v_cvt_pk_f32_fp8_sdwa v[216:217], v166 src0_sel:WORD_1
	v_pk_fma_f32 v[222:223], v[68:69], v[218:219], v[222:223]
	v_pk_fma_f32 v[224:225], v[70:71], v[220:221], v[224:225]
	v_cvt_pk_f32_fp8_e32 v[218:219], v167
	v_cvt_pk_f32_fp8_sdwa v[220:221], v167 src0_sel:WORD_1
	v_pk_fma_f32 v[222:223], v[72:73], v[214:215], v[222:223]
	v_pk_fma_f32 v[224:225], v[74:75], v[216:217], v[224:225]
	v_pk_fma_f32 v[222:223], v[76:77], v[218:219], v[222:223]
	v_pk_fma_f32 v[224:225], v[78:79], v[220:221], v[224:225]
	v_pk_add_f32 v[222:223], v[222:223], v[224:225]
	s_nop 0
	v_add_f32_e32 v231, v222, v223
	v_cvt_pk_f32_fp8_e32 v[214:215], v168
	v_cvt_pk_f32_fp8_sdwa v[216:217], v168 src0_sel:WORD_1
	v_cvt_pk_f32_fp8_e32 v[218:219], v169
; template <bool STORE>
; DI void peer_item(const Params& p, int item, char* smem) {
;     ...
; #pragma unroll 2
;     for (int k = 0; k < 128; k += 8) {
;       u32x4 uq[8];
;       const int emine = e_s[tl * 128 + k + (lane >> 3)];
;       const float gmine = g_s[tl * 128 + k + (lane >> 3)];
;       const float su = SU[emine], sv = SV[emine];
; #pragma unroll
;       for (int u = 0; u < 8; ++u) {
;         int e = e_s[tl * 128 + k + u];
;         uq[u] = *(const u32x4*)(U8 + (size_t)e * 1024 + lane * 16);
;       }
;       float part[8];
; #pragma unroll
;       for (int u = 0; u < 8; ++u) {
;         float d = 0.f;
; #pragma unroll
;         for (int i = 0; i < 4; ++i) {
;           f32x2_t lo = __builtin_amdgcn_cvt_pk_f32_fp8((int)uq[u][i], false);
;           f32x2_t hi = __builtin_amdgcn_cvt_pk_f32_fp8((int)uq[u][i], true);
;           d += xf[4 * i] * lo.x + xf[4 * i + 1] * lo.y + xf[4 * i + 2] * hi.x + xf[4 * i + 3] * hi.y;
;         }
;         part[u] = d;
;       }
;       float q4[4], r2[2], h;
; #pragma unroll
;       for (int j = 0; j < 4; ++j) {
;         float mine = b5 ? part[j + 4] : part[j];
;         float other = b5 ? part[j] : part[j + 4];
;         q4[j] = mine + __shfl_xor(other, 32);
;       }
; #pragma unroll
;       for (int j = 0; j < 2; ++j) {
;         float mine = b4 ? q4[j + 2] : q4[j];
;         float other = b4 ? q4[j] : q4[j + 2];
;         r2[j] = mine + __shfl_xor(other, 16);
;       }
;       {
;         float mine = b3 ? r2[1] : r2[0];
;         float other = b3 ? r2[0] : r2[1];
;         h = mine + __shfl_xor(other, 8);
;       }
;       h += __shfl_xor(h, 4);
;       h += __shfl_xor(h, 2);
;       h += __shfl_xor(h, 1);
	v_cvt_pk_f32_fp8_sdwa v[220:221], v169 src0_sel:WORD_1
	v_pk_mul_f32 v[222:223], v[64:65], v[214:215]
	v_pk_mul_f32 v[224:225], v[66:67], v[216:217]
	v_cvt_pk_f32_fp8_e32 v[214:215], v170
	v_cvt_pk_f32_fp8_sdwa v[216:217], v170 src0_sel:WORD_1
	v_pk_fma_f32 v[222:223], v[68:69], v[218:219], v[222:223]
	v_pk_fma_f32 v[224:225], v[70:71], v[220:221], v[224:225]
	v_cvt_pk_f32_fp8_e32 v[218:219], v171
	v_cvt_pk_f32_fp8_sdwa v[220:221], v171 src0_sel:WORD_1
	v_pk_fma_f32 v[222:223], v[72:73], v[214:215], v[222:223]
	v_pk_fma_f32 v[224:225], v[74:75], v[216:217], v[224:225]
	v_pk_fma_f32 v[222:223], v[76:77], v[218:219], v[222:223]
	v_pk_fma_f32 v[224:225], v[78:79], v[220:221], v[224:225]
	v_pk_add_f32 v[222:223], v[222:223], v[224:225]
	s_nop 0
	v_add_f32_e32 v232, v222, v223
	v_cvt_pk_f32_fp8_e32 v[214:215], v172
	v_cvt_pk_f32_fp8_sdwa v[216:217], v172 src0_sel:WORD_1
	v_cvt_pk_f32_fp8_e32 v[218:219], v173
	v_cvt_pk_f32_fp8_sdwa v[220:221], v173 src0_sel:WORD_1
	v_pk_mul_f32 v[222:223], v[64:65], v[214:215]
	v_pk_mul_f32 v[224:225], v[66:67], v[216:217]
	v_cvt_pk_f32_fp8_e32 v[214:215], v174
	v_cvt_pk_f32_fp8_sdwa v[216:217], v174 src0_sel:WORD_1
	v_pk_fma_f32 v[222:223], v[68:69], v[218:219], v[222:223]
	v_pk_fma_f32 v[224:225], v[70:71], v[220:221], v[224:225]
	v_cvt_pk_f32_fp8_e32 v[218:219], v175
	v_cvt_pk_f32_fp8_sdwa v[220:221], v175 src0_sel:WORD_1
	v_pk_fma_f32 v[222:223], v[72:73], v[214:215], v[222:223]
	v_pk_fma_f32 v[224:225], v[74:75], v[216:217], v[224:225]
	v_pk_fma_f32 v[222:223], v[76:77], v[218:219], v[222:223]
	v_pk_fma_f32 v[224:225], v[78:79], v[220:221], v[224:225]
	v_pk_add_f32 v[222:223], v[222:223], v[224:225]
	s_nop 0
	v_add_f32_e32 v233, v222, v223
	v_permlane32_swap_b32_e32 v226, v230
	v_permlane32_swap_b32_e32 v227, v231
	v_permlane32_swap_b32_e32 v228, v232
	v_permlane32_swap_b32_e32 v229, v233
	v_add_f32_e32 v226, v226, v230
	v_add_f32_e32 v228, v228, v232
	v_add_f32_e32 v227, v227, v231
	v_add_f32_e32 v229, v229, v233
	s_nop 1
	v_permlane16_swap_b32_e32 v226, v228
	v_permlane16_swap_b32_e32 v227, v229
	v_add_f32_e32 v226, v226, v228
	v_add_f32_e32 v227, v227, v229
	s_nop 0
	v_cndmask_b32_e64 v230, v226, v227, s[24:25]
	v_cndmask_b32_e64 v231, v227, v226, s[24:25]
	s_nop 1
	v_add_f32_dpp v232, v231, v230 row_ror:8 row_mask:0xf bank_mask:0xf
	s_nop 1
	v_add_f32_dpp v233, v232, v232 quad_perm:[1,0,3,2] row_mask:0xf bank_mask:0xf
	s_nop 1
	v_add_f32_dpp v232, v233, v233 quad_perm:[2,3,0,1] row_mask:0xf bank_mask:0xf
	s_nop 1
	v_add_f32_dpp v233, v232, v232 row_half_mirror row_mask:0xf bank_mask:0xf
	ds_write_b32 v235, v233 offset:34816
	v_readlane_b32 s48, v140, s72
	v_readlane_b32 s49, v140, s73
	v_readlane_b32 s50, v140, s74
	v_readlane_b32 s51, v140, s75
	v_readlane_b32 s52, v140, s76
	v_readlane_b32 s53, v140, s77
	v_readlane_b32 s54, v140, s78
	v_readlane_b32 s55, v140, s79
	s_add_u32 s32, s0, s48
	s_addc_u32 s33, s1, 0
	s_add_u32 s34, s0, s49
	s_addc_u32 s35, s1, 0
	s_add_u32 s36, s0, s50
	s_addc_u32 s37, s1, 0
	s_add_u32 s38, s0, s51
	s_addc_u32 s39, s1, 0
	s_add_u32 s40, s0, s52
	s_addc_u32 s41, s1, 0
	s_add_u32 s42, s0, s53
	s_addc_u32 s43, s1, 0
	s_add_u32 s44, s0, s54
	s_addc_u32 s45, s1, 0
	s_add_u32 s46, s0, s55
	s_addc_u32 s47, s1, 0
	global_load_dwordx4 v[144:147], v234, s[32:33]
	global_load_dwordx4 v[148:151], v234, s[34:35]
	global_load_dwordx4 v[152:155], v234, s[36:37]
	global_load_dwordx4 v[156:159], v234, s[38:39]
	global_load_dwordx4 v[160:163], v234, s[40:41]
	global_load_dwordx4 v[164:167], v234, s[42:43]
	global_load_dwordx4 v[168:171], v234, s[44:45]
	global_load_dwordx4 v[172:175], v234, s[46:47]
	s_waitcnt vmcnt(8)
	v_cvt_pk_f32_fp8_e32 v[214:215], v176
	v_cvt_pk_f32_fp8_sdwa v[216:217], v176 src0_sel:WORD_1
	v_cvt_pk_f32_fp8_e32 v[218:219], v177
	v_cvt_pk_f32_fp8_sdwa v[220:221], v177 src0_sel:WORD_1
	v_pk_mul_f32 v[222:223], v[80:81], v[214:215]
	v_pk_mul_f32 v[224:225], v[82:83], v[216:217]
	v_cvt_pk_f32_fp8_e32 v[214:215], v178
	v_cvt_pk_f32_fp8_sdwa v[216:217], v178 src0_sel:WORD_1
	v_pk_fma_f32 v[222:223], v[84:85], v[218:219], v[222:223]
	v_pk_fma_f32 v[224:225], v[86:87], v[220:221], v[224:225]
	v_cvt_pk_f32_fp8_e32 v[218:219], v179
	v_cvt_pk_f32_fp8_sdwa v[220:221], v179 src0_sel:WORD_1
	v_pk_fma_f32 v[222:223], v[88:89], v[214:215], v[222:223]
	v_pk_fma_f32 v[224:225], v[90:91], v[216:217], v[224:225]
	v_pk_fma_f32 v[222:223], v[92:93], v[218:219], v[222:223]
	v_pk_fma_f32 v[224:225], v[94:95], v[220:221], v[224:225]
	v_pk_add_f32 v[222:223], v[222:223], v[224:225]
	s_nop 0
	v_add_f32_e32 v226, v222, v223
	v_cvt_pk_f32_fp8_e32 v[214:215], v180
	v_cvt_pk_f32_fp8_sdwa v[216:217], v180 src0_sel:WORD_1
	v_cvt_pk_f32_fp8_e32 v[218:219], v181
	v_cvt_pk_f32_fp8_sdwa v[220:221], v181 src0_sel:WORD_1
	v_pk_mul_f32 v[222:223], v[80:81], v[214:215]
	v_pk_mul_f32 v[224:225], v[82:83], v[216:217]
	v_cvt_pk_f32_fp8_e32 v[214:215], v182
	v_cvt_pk_f32_fp8_sdwa v[216:217], v182 src0_sel:WORD_1
	v_pk_fma_f32 v[222:223], v[84:85], v[218:219], v[222:223]
	v_pk_fma_f32 v[224:225], v[86:87], v[220:221], v[224:225]
	v_cvt_pk_f32_fp8_e32 v[218:219], v183
	v_cvt_pk_f32_fp8_sdwa v[220:221], v183 src0_sel:WORD_1
	v_pk_fma_f32 v[222:223], v[88:89], v[214:215], v[222:223]
	v_pk_fma_f32 v[224:225], v[90:91], v[216:217], v[224:225]
	v_pk_fma_f32 v[222:223], v[92:93], v[218:219], v[222:223]
	v_pk_fma_f32 v[224:225], v[94:95], v[220:221], v[224:225]
	v_pk_add_f32 v[222:223], v[222:223], v[224:225]
	s_nop 0
	v_add_f32_e32 v227, v222, v223
	v_cvt_pk_f32_fp8_e32 v[214:215], v184
	v_cvt_pk_f32_fp8_sdwa v[216:217], v184 src0_sel:WORD_1
	v_cvt_pk_f32_fp8_e32 v[218:219], v185
	v_cvt_pk_f32_fp8_sdwa v[220:221], v185 src0_sel:WORD_1
; template <bool STORE>
; DI void peer_item(const Params& p, int item, char* smem) {
;     ...
; #pragma unroll 2
;     for (int k = 0; k < 128; k += 8) {
;       u32x4 uq[8];
;       const int emine = e_s[tl * 128 + k + (lane >> 3)];
;       const float gmine = g_s[tl * 128 + k + (lane >> 3)];
;       const float su = SU[emine], sv = SV[emine];
; #pragma unroll
;       for (int u = 0; u < 8; ++u) {
;         int e = e_s[tl * 128 + k + u];
;         uq[u] = *(const u32x4*)(U8 + (size_t)e * 1024 + lane * 16);
;       }
;       float part[8];
; #pragma unroll
;       for (int u = 0; u < 8; ++u) {
;         float d = 0.f;
; #pragma unroll
;         for (int i = 0; i < 4; ++i) {
;           f32x2_t lo = __builtin_amdgcn_cvt_pk_f32_fp8((int)uq[u][i], false);
;           f32x2_t hi = __builtin_amdgcn_cvt_pk_f32_fp8((int)uq[u][i], true);
;           d += xf[4 * i] * lo.x + xf[4 * i + 1] * lo.y + xf[4 * i + 2] * hi.x + xf[4 * i + 3] * hi.y;
;         }
;         part[u] = d;
;       }
;       float q4[4], r2[2], h;
; #pragma unroll
;       for (int j = 0; j < 4; ++j) {
;         float mine = b5 ? part[j + 4] : part[j];
;         float other = b5 ? part[j] : part[j + 4];
;         q4[j] = mine + __shfl_xor(other, 32);
;       }
; #pragma unroll
;       for (int j = 0; j < 2; ++j) {
;         float mine = b4 ? q4[j + 2] : q4[j];
;         float other = b4 ? q4[j] : q4[j + 2];
;         r2[j] = mine + __shfl_xor(other, 16);
;       }
;       {
;         float mine = b3 ? r2[1] : r2[0];
;         float other = b3 ? r2[0] : r2[1];
;         h = mine + __shfl_xor(other, 8);
;       }
;       h += __shfl_xor(h, 4);
;       h += __shfl_xor(h, 2);
;       h += __shfl_xor(h, 1);
	v_pk_mul_f32 v[222:223], v[80:81], v[214:215]
	v_pk_mul_f32 v[224:225], v[82:83], v[216:217]
	v_cvt_pk_f32_fp8_e32 v[214:215], v186
	v_cvt_pk_f32_fp8_sdwa v[216:217], v186 src0_sel:WORD_1
	v_pk_fma_f32 v[222:223], v[84:85], v[218:219], v[222:223]
	v_pk_fma_f32 v[224:225], v[86:87], v[220:221], v[224:225]
	v_cvt_pk_f32_fp8_e32 v[218:219], v187
	v_cvt_pk_f32_fp8_sdwa v[220:221], v187 src0_sel:WORD_1
	v_pk_fma_f32 v[222:223], v[88:89], v[214:215], v[222:223]
	v_pk_fma_f32 v[224:225], v[90:91], v[216:217], v[224:225]
	v_pk_fma_f32 v[222:223], v[92:93], v[218:219], v[222:223]
	v_pk_fma_f32 v[224:225], v[94:95], v[220:221], v[224:225]
	v_pk_add_f32 v[222:223], v[222:223], v[224:225]
	s_nop 0
	v_add_f32_e32 v228, v222, v223
	v_cvt_pk_f32_fp8_e32 v[214:215], v188
	v_cvt_pk_f32_fp8_sdwa v[216:217], v188 src0_sel:WORD_1
	v_cvt_pk_f32_fp8_e32 v[218:219], v189
	v_cvt_pk_f32_fp8_sdwa v[220:221], v189 src0_sel:WORD_1
	v_pk_mul_f32 v[222:223], v[80:81], v[214:215]
	v_pk_mul_f32 v[224:225], v[82:83], v[216:217]
	v_cvt_pk_f32_fp8_e32 v[214:215], v190
	v_cvt_pk_f32_fp8_sdwa v[216:217], v190 src0_sel:WORD_1
	v_pk_fma_f32 v[222:223], v[84:85], v[218:219], v[222:223]
	v_pk_fma_f32 v[224:225], v[86:87], v[220:221], v[224:225]
	v_cvt_pk_f32_fp8_e32 v[218:219], v191
	v_cvt_pk_f32_fp8_sdwa v[220:221], v191 src0_sel:WORD_1
	v_pk_fma_f32 v[222:223], v[88:89], v[214:215], v[222:223]
	v_pk_fma_f32 v[224:225], v[90:91], v[216:217], v[224:225]
	v_pk_fma_f32 v[222:223], v[92:93], v[218:219], v[222:223]
	v_pk_fma_f32 v[224:225], v[94:95], v[220:221], v[224:225]
	v_pk_add_f32 v[222:223], v[222:223], v[224:225]
	s_nop 0
	v_add_f32_e32 v229, v222, v223
	v_cvt_pk_f32_fp8_e32 v[214:215], v192
	v_cvt_pk_f32_fp8_sdwa v[216:217], v192 src0_sel:WORD_1
	v_cvt_pk_f32_fp8_e32 v[218:219], v193
	v_cvt_pk_f32_fp8_sdwa v[220:221], v193 src0_sel:WORD_1
	v_pk_mul_f32 v[222:223], v[80:81], v[214:215]
	v_pk_mul_f32 v[224:225], v[82:83], v[216:217]
	v_cvt_pk_f32_fp8_e32 v[214:215], v194
	v_cvt_pk_f32_fp8_sdwa v[216:217], v194 src0_sel:WORD_1
	v_pk_fma_f32 v[222:223], v[84:85], v[218:219], v[222:223]
	v_pk_fma_f32 v[224:225], v[86:87], v[220:221], v[224:225]
	v_cvt_pk_f32_fp8_e32 v[218:219], v195
	v_cvt_pk_f32_fp8_sdwa v[220:221], v195 src0_sel:WORD_1
	v_pk_fma_f32 v[222:223], v[88:89], v[214:215], v[222:223]
	v_pk_fma_f32 v[224:225], v[90:91], v[216:217], v[224:225]
	v_pk_fma_f32 v[222:223], v[92:93], v[218:219], v[222:223]
	v_pk_fma_f32 v[224:225], v[94:95], v[220:221], v[224:225]
	v_pk_add_f32 v[222:223], v[222:223], v[224:225]
	s_nop 0
	v_add_f32_e32 v230, v222, v223
	v_cvt_pk_f32_fp8_e32 v[214:215], v196
	v_cvt_pk_f32_fp8_sdwa v[216:217], v196 src0_sel:WORD_1
	v_cvt_pk_f32_fp8_e32 v[218:219], v197
	v_cvt_pk_f32_fp8_sdwa v[220:221], v197 src0_sel:WORD_1
	v_pk_mul_f32 v[222:223], v[80:81], v[214:215]
	v_pk_mul_f32 v[224:225], v[82:83], v[216:217]
	v_cvt_pk_f32_fp8_e32 v[214:215], v198
	v_cvt_pk_f32_fp8_sdwa v[216:217], v198 src0_sel:WORD_1
	v_pk_fma_f32 v[222:223], v[84:85], v[218:219], v[222:223]
	v_pk_fma_f32 v[224:225], v[86:87], v[220:221], v[224:225]
	v_cvt_pk_f32_fp8_e32 v[218:219], v199
	v_cvt_pk_f32_fp8_sdwa v[220:221], v199 src0_sel:WORD_1
	v_pk_fma_f32 v[222:223], v[88:89], v[214:215], v[222:223]
	v_pk_fma_f32 v[224:225], v[90:91], v[216:217], v[224:225]
	v_pk_fma_f32 v[222:223], v[92:93], v[218:219], v[222:223]
	v_pk_fma_f32 v[224:225], v[94:95], v[220:221], v[224:225]
	v_pk_add_f32 v[222:223], v[222:223], v[224:225]
	s_nop 0
	v_add_f32_e32 v231, v222, v223
	v_cvt_pk_f32_fp8_e32 v[214:215], v200
	v_cvt_pk_f32_fp8_sdwa v[216:217], v200 src0_sel:WORD_1
	v_cvt_pk_f32_fp8_e32 v[218:219], v201
	v_cvt_pk_f32_fp8_sdwa v[220:221], v201 src0_sel:WORD_1
	v_pk_mul_f32 v[222:223], v[80:81], v[214:215]
	v_pk_mul_f32 v[224:225], v[82:83], v[216:217]
	v_cvt_pk_f32_fp8_e32 v[214:215], v202
	v_cvt_pk_f32_fp8_sdwa v[216:217], v202 src0_sel:WORD_1
	v_pk_fma_f32 v[222:223], v[84:85], v[218:219], v[222:223]
	v_pk_fma_f32 v[224:225], v[86:87], v[220:221], v[224:225]
	v_cvt_pk_f32_fp8_e32 v[218:219], v203
	v_cvt_pk_f32_fp8_sdwa v[220:221], v203 src0_sel:WORD_1
	v_pk_fma_f32 v[222:223], v[88:89], v[214:215], v[222:223]
	v_pk_fma_f32 v[224:225], v[90:91], v[216:217], v[224:225]
	v_pk_fma_f32 v[222:223], v[92:93], v[218:219], v[222:223]
	v_pk_fma_f32 v[224:225], v[94:95], v[220:221], v[224:225]
	v_pk_add_f32 v[222:223], v[222:223], v[224:225]
	s_nop 0
	v_add_f32_e32 v232, v222, v223
	v_cvt_pk_f32_fp8_e32 v[214:215], v204
	v_cvt_pk_f32_fp8_sdwa v[216:217], v204 src0_sel:WORD_1
	v_cvt_pk_f32_fp8_e32 v[218:219], v205
	v_cvt_pk_f32_fp8_sdwa v[220:221], v205 src0_sel:WORD_1
	v_pk_mul_f32 v[222:223], v[80:81], v[214:215]
	v_pk_mul_f32 v[224:225], v[82:83], v[216:217]
	v_cvt_pk_f32_fp8_e32 v[214:215], v206
	v_cvt_pk_f32_fp8_sdwa v[216:217], v206 src0_sel:WORD_1
	v_pk_fma_f32 v[222:223], v[84:85], v[218:219], v[222:223]
	v_pk_fma_f32 v[224:225], v[86:87], v[220:221], v[224:225]
	v_cvt_pk_f32_fp8_e32 v[218:219], v207
	v_cvt_pk_f32_fp8_sdwa v[220:221], v207 src0_sel:WORD_1
	v_pk_fma_f32 v[222:223], v[88:89], v[214:215], v[222:223]
	v_pk_fma_f32 v[224:225], v[90:91], v[216:217], v[224:225]
	v_pk_fma_f32 v[222:223], v[92:93], v[218:219], v[222:223]
	v_pk_fma_f32 v[224:225], v[94:95], v[220:221], v[224:225]
	v_pk_add_f32 v[222:223], v[222:223], v[224:225]
	s_nop 0
	v_add_f32_e32 v233, v222, v223
	v_permlane32_swap_b32_e32 v226, v230
	v_permlane32_swap_b32_e32 v227, v231
	v_permlane32_swap_b32_e32 v228, v232
	v_permlane32_swap_b32_e32 v229, v233
	v_add_f32_e32 v226, v226, v230
	v_add_f32_e32 v228, v228, v232
	v_add_f32_e32 v227, v227, v231
	v_add_f32_e32 v229, v229, v233
	s_nop 1
	v_permlane16_swap_b32_e32 v226, v228
; template <bool STORE>
; DI void peer_item(const Params& p, int item, char* smem) {
;     ...
; #pragma unroll 2
;     for (int k = 0; k < 128; k += 8) {
;       u32x4 uq[8];
;       const int emine = e_s[tl * 128 + k + (lane >> 3)];
;       const float gmine = g_s[tl * 128 + k + (lane >> 3)];
;       const float su = SU[emine], sv = SV[emine];
; #pragma unroll
;       for (int u = 0; u < 8; ++u) {
;         int e = e_s[tl * 128 + k + u];
;         uq[u] = *(const u32x4*)(U8 + (size_t)e * 1024 + lane * 16);
;       }
;       float part[8];
; #pragma unroll
;       for (int u = 0; u < 8; ++u) {
;         float d = 0.f;
; #pragma unroll
;         for (int i = 0; i < 4; ++i) {
;           f32x2_t lo = __builtin_amdgcn_cvt_pk_f32_fp8((int)uq[u][i], false);
;           f32x2_t hi = __builtin_amdgcn_cvt_pk_f32_fp8((int)uq[u][i], true);
;           d += xf[4 * i] * lo.x + xf[4 * i + 1] * lo.y + xf[4 * i + 2] * hi.x + xf[4 * i + 3] * hi.y;
;         }
;         part[u] = d;
;       }
;       float q4[4], r2[2], h;
; #pragma unroll
;       for (int j = 0; j < 4; ++j) {
;         float mine = b5 ? part[j + 4] : part[j];
;         float other = b5 ? part[j] : part[j + 4];
;         q4[j] = mine + __shfl_xor(other, 32);
;       }
; #pragma unroll
;       for (int j = 0; j < 2; ++j) {
;         float mine = b4 ? q4[j + 2] : q4[j];
;         float other = b4 ? q4[j] : q4[j + 2];
;         r2[j] = mine + __shfl_xor(other, 16);
;       }
;       {
;         float mine = b3 ? r2[1] : r2[0];
;         float other = b3 ? r2[0] : r2[1];
;         h = mine + __shfl_xor(other, 8);
;       }
;       h += __shfl_xor(h, 4);
;       h += __shfl_xor(h, 2);
;       h += __shfl_xor(h, 1);
	v_permlane16_swap_b32_e32 v227, v229
	v_add_f32_e32 v226, v226, v228
	v_add_f32_e32 v227, v227, v229
	s_nop 0
	v_cndmask_b32_e64 v230, v226, v227, s[24:25]
	v_cndmask_b32_e64 v231, v227, v226, s[24:25]
	s_nop 1
	v_add_f32_dpp v232, v231, v230 row_ror:8 row_mask:0xf bank_mask:0xf
	s_nop 1
	v_add_f32_dpp v233, v232, v232 quad_perm:[1,0,3,2] row_mask:0xf bank_mask:0xf
	s_nop 1
	v_add_f32_dpp v232, v233, v233 quad_perm:[2,3,0,1] row_mask:0xf bank_mask:0xf
	s_nop 1
	v_add_f32_dpp v233, v232, v232 row_half_mirror row_mask:0xf bank_mask:0xf
	ds_write_b32 v235, v233 offset:35328
	v_readlane_b32 s48, v142, s72
	v_readlane_b32 s49, v142, s73
	v_readlane_b32 s50, v142, s74
	v_readlane_b32 s51, v142, s75
	v_readlane_b32 s52, v142, s76
	v_readlane_b32 s53, v142, s77
	v_readlane_b32 s54, v142, s78
	v_readlane_b32 s55, v142, s79
	s_add_u32 s32, s0, s48
	s_addc_u32 s33, s1, 0
	s_add_u32 s34, s0, s49
	s_addc_u32 s35, s1, 0
	s_add_u32 s36, s0, s50
	s_addc_u32 s37, s1, 0
	s_add_u32 s38, s0, s51
	s_addc_u32 s39, s1, 0
	s_add_u32 s40, s0, s52
	s_addc_u32 s41, s1, 0
	s_add_u32 s42, s0, s53
	s_addc_u32 s43, s1, 0
	s_add_u32 s44, s0, s54
	s_addc_u32 s45, s1, 0
	s_add_u32 s46, s0, s55
	s_addc_u32 s47, s1, 0
	global_load_dwordx4 v[176:179], v234, s[32:33]
	global_load_dwordx4 v[180:183], v234, s[34:35]
	global_load_dwordx4 v[184:187], v234, s[36:37]
	global_load_dwordx4 v[188:191], v234, s[38:39]
	global_load_dwordx4 v[192:195], v234, s[40:41]
	global_load_dwordx4 v[196:199], v234, s[42:43]
	global_load_dwordx4 v[200:203], v234, s[44:45]
	global_load_dwordx4 v[204:207], v234, s[46:47]
	s_waitcnt vmcnt(8)
	v_cvt_pk_f32_fp8_e32 v[214:215], v144
	v_cvt_pk_f32_fp8_sdwa v[216:217], v144 src0_sel:WORD_1
	v_cvt_pk_f32_fp8_e32 v[218:219], v145
	v_cvt_pk_f32_fp8_sdwa v[220:221], v145 src0_sel:WORD_1
	v_pk_mul_f32 v[222:223], v[96:97], v[214:215]
	v_pk_mul_f32 v[224:225], v[98:99], v[216:217]
	v_cvt_pk_f32_fp8_e32 v[214:215], v146
	v_cvt_pk_f32_fp8_sdwa v[216:217], v146 src0_sel:WORD_1
	v_pk_fma_f32 v[222:223], v[100:101], v[218:219], v[222:223]
	v_pk_fma_f32 v[224:225], v[102:103], v[220:221], v[224:225]
	v_cvt_pk_f32_fp8_e32 v[218:219], v147
	v_cvt_pk_f32_fp8_sdwa v[220:221], v147 src0_sel:WORD_1
	v_pk_fma_f32 v[222:223], v[104:105], v[214:215], v[222:223]
	v_pk_fma_f32 v[224:225], v[106:107], v[216:217], v[224:225]
	v_pk_fma_f32 v[222:223], v[108:109], v[218:219], v[222:223]
	v_pk_fma_f32 v[224:225], v[110:111], v[220:221], v[224:225]
	v_pk_add_f32 v[222:223], v[222:223], v[224:225]
	s_nop 0
	v_add_f32_e32 v226, v222, v223
	v_cvt_pk_f32_fp8_e32 v[214:215], v148
	v_cvt_pk_f32_fp8_sdwa v[216:217], v148 src0_sel:WORD_1
	v_cvt_pk_f32_fp8_e32 v[218:219], v149
	v_cvt_pk_f32_fp8_sdwa v[220:221], v149 src0_sel:WORD_1
	v_pk_mul_f32 v[222:223], v[96:97], v[214:215]
	v_pk_mul_f32 v[224:225], v[98:99], v[216:217]
	v_cvt_pk_f32_fp8_e32 v[214:215], v150
	v_cvt_pk_f32_fp8_sdwa v[216:217], v150 src0_sel:WORD_1
	v_pk_fma_f32 v[222:223], v[100:101], v[218:219], v[222:223]
	v_pk_fma_f32 v[224:225], v[102:103], v[220:221], v[224:225]
	v_cvt_pk_f32_fp8_e32 v[218:219], v151
	v_cvt_pk_f32_fp8_sdwa v[220:221], v151 src0_sel:WORD_1
	v_pk_fma_f32 v[222:223], v[104:105], v[214:215], v[222:223]
	v_pk_fma_f32 v[224:225], v[106:107], v[216:217], v[224:225]
	v_pk_fma_f32 v[222:223], v[108:109], v[218:219], v[222:223]
	v_pk_fma_f32 v[224:225], v[110:111], v[220:221], v[224:225]
	v_pk_add_f32 v[222:223], v[222:223], v[224:225]
	s_nop 0
	v_add_f32_e32 v227, v222, v223
	v_cvt_pk_f32_fp8_e32 v[214:215], v152
	v_cvt_pk_f32_fp8_sdwa v[216:217], v152 src0_sel:WORD_1
	v_cvt_pk_f32_fp8_e32 v[218:219], v153
	v_cvt_pk_f32_fp8_sdwa v[220:221], v153 src0_sel:WORD_1
	v_pk_mul_f32 v[222:223], v[96:97], v[214:215]
	v_pk_mul_f32 v[224:225], v[98:99], v[216:217]
	v_cvt_pk_f32_fp8_e32 v[214:215], v154
	v_cvt_pk_f32_fp8_sdwa v[216:217], v154 src0_sel:WORD_1
	v_pk_fma_f32 v[222:223], v[100:101], v[218:219], v[222:223]
	v_pk_fma_f32 v[224:225], v[102:103], v[220:221], v[224:225]
	v_cvt_pk_f32_fp8_e32 v[218:219], v155
	v_cvt_pk_f32_fp8_sdwa v[220:221], v155 src0_sel:WORD_1
	v_pk_fma_f32 v[222:223], v[104:105], v[214:215], v[222:223]
	v_pk_fma_f32 v[224:225], v[106:107], v[216:217], v[224:225]
	v_pk_fma_f32 v[222:223], v[108:109], v[218:219], v[222:223]
	v_pk_fma_f32 v[224:225], v[110:111], v[220:221], v[224:225]
	v_pk_add_f32 v[222:223], v[222:223], v[224:225]
	s_nop 0
	v_add_f32_e32 v228, v222, v223
	v_cvt_pk_f32_fp8_e32 v[214:215], v156
	v_cvt_pk_f32_fp8_sdwa v[216:217], v156 src0_sel:WORD_1
	v_cvt_pk_f32_fp8_e32 v[218:219], v157
	v_cvt_pk_f32_fp8_sdwa v[220:221], v157 src0_sel:WORD_1
	v_pk_mul_f32 v[222:223], v[96:97], v[214:215]
	v_pk_mul_f32 v[224:225], v[98:99], v[216:217]
	v_cvt_pk_f32_fp8_e32 v[214:215], v158
	v_cvt_pk_f32_fp8_sdwa v[216:217], v158 src0_sel:WORD_1
	v_pk_fma_f32 v[222:223], v[100:101], v[218:219], v[222:223]
	v_pk_fma_f32 v[224:225], v[102:103], v[220:221], v[224:225]
	v_cvt_pk_f32_fp8_e32 v[218:219], v159
	v_cvt_pk_f32_fp8_sdwa v[220:221], v159 src0_sel:WORD_1
	v_pk_fma_f32 v[222:223], v[104:105], v[214:215], v[222:223]
	v_pk_fma_f32 v[224:225], v[106:107], v[216:217], v[224:225]
	v_pk_fma_f32 v[222:223], v[108:109], v[218:219], v[222:223]
	v_pk_fma_f32 v[224:225], v[110:111], v[220:221], v[224:225]
	v_pk_add_f32 v[222:223], v[222:223], v[224:225]
	s_nop 0
	v_add_f32_e32 v229, v222, v223
	v_cvt_pk_f32_fp8_e32 v[214:215], v160
	v_cvt_pk_f32_fp8_sdwa v[216:217], v160 src0_sel:WORD_1
	v_cvt_pk_f32_fp8_e32 v[218:219], v161
	v_cvt_pk_f32_fp8_sdwa v[220:221], v161 src0_sel:WORD_1
	v_pk_mul_f32 v[222:223], v[96:97], v[214:215]
	v_pk_mul_f32 v[224:225], v[98:99], v[216:217]
	v_cvt_pk_f32_fp8_e32 v[214:215], v162
; template <bool STORE>
; DI void peer_item(const Params& p, int item, char* smem) {
;     ...
; #pragma unroll 2
;     for (int k = 0; k < 128; k += 8) {
;       u32x4 uq[8];
;       const int emine = e_s[tl * 128 + k + (lane >> 3)];
;       const float gmine = g_s[tl * 128 + k + (lane >> 3)];
;       const float su = SU[emine], sv = SV[emine];
; #pragma unroll
;       for (int u = 0; u < 8; ++u) {
;         int e = e_s[tl * 128 + k + u];
;         uq[u] = *(const u32x4*)(U8 + (size_t)e * 1024 + lane * 16);
;       }
;       float part[8];
; #pragma unroll
;       for (int u = 0; u < 8; ++u) {
;         float d = 0.f;
; #pragma unroll
;         for (int i = 0; i < 4; ++i) {
;           f32x2_t lo = __builtin_amdgcn_cvt_pk_f32_fp8((int)uq[u][i], false);
;           f32x2_t hi = __builtin_amdgcn_cvt_pk_f32_fp8((int)uq[u][i], true);
;           d += xf[4 * i] * lo.x + xf[4 * i + 1] * lo.y + xf[4 * i + 2] * hi.x + xf[4 * i + 3] * hi.y;
;         }
;         part[u] = d;
;       }
;       float q4[4], r2[2], h;
; #pragma unroll
;       for (int j = 0; j < 4; ++j) {
;         float mine = b5 ? part[j + 4] : part[j];
;         float other = b5 ? part[j] : part[j + 4];
;         q4[j] = mine + __shfl_xor(other, 32);
;       }
; #pragma unroll
;       for (int j = 0; j < 2; ++j) {
;         float mine = b4 ? q4[j + 2] : q4[j];
;         float other = b4 ? q4[j] : q4[j + 2];
;         r2[j] = mine + __shfl_xor(other, 16);
;       }
;       {
;         float mine = b3 ? r2[1] : r2[0];
;         float other = b3 ? r2[0] : r2[1];
;         h = mine + __shfl_xor(other, 8);
;       }
;       h += __shfl_xor(h, 4);
;       h += __shfl_xor(h, 2);
;       h += __shfl_xor(h, 1);
	v_cvt_pk_f32_fp8_sdwa v[216:217], v162 src0_sel:WORD_1
	v_pk_fma_f32 v[222:223], v[100:101], v[218:219], v[222:223]
	v_pk_fma_f32 v[224:225], v[102:103], v[220:221], v[224:225]
	v_cvt_pk_f32_fp8_e32 v[218:219], v163
	v_cvt_pk_f32_fp8_sdwa v[220:221], v163 src0_sel:WORD_1
	v_pk_fma_f32 v[222:223], v[104:105], v[214:215], v[222:223]
	v_pk_fma_f32 v[224:225], v[106:107], v[216:217], v[224:225]
	v_pk_fma_f32 v[222:223], v[108:109], v[218:219], v[222:223]
	v_pk_fma_f32 v[224:225], v[110:111], v[220:221], v[224:225]
	v_pk_add_f32 v[222:223], v[222:223], v[224:225]
	s_nop 0
	v_add_f32_e32 v230, v222, v223
	v_cvt_pk_f32_fp8_e32 v[214:215], v164
	v_cvt_pk_f32_fp8_sdwa v[216:217], v164 src0_sel:WORD_1
	v_cvt_pk_f32_fp8_e32 v[218:219], v165
	v_cvt_pk_f32_fp8_sdwa v[220:221], v165 src0_sel:WORD_1
	v_pk_mul_f32 v[222:223], v[96:97], v[214:215]
	v_pk_mul_f32 v[224:225], v[98:99], v[216:217]
	v_cvt_pk_f32_fp8_e32 v[214:215], v166
	v_cvt_pk_f32_fp8_sdwa v[216:217], v166 src0_sel:WORD_1
	v_pk_fma_f32 v[222:223], v[100:101], v[218:219], v[222:223]
	v_pk_fma_f32 v[224:225], v[102:103], v[220:221], v[224:225]
	v_cvt_pk_f32_fp8_e32 v[218:219], v167
	v_cvt_pk_f32_fp8_sdwa v[220:221], v167 src0_sel:WORD_1
	v_pk_fma_f32 v[222:223], v[104:105], v[214:215], v[222:223]
	v_pk_fma_f32 v[224:225], v[106:107], v[216:217], v[224:225]
	v_pk_fma_f32 v[222:223], v[108:109], v[218:219], v[222:223]
	v_pk_fma_f32 v[224:225], v[110:111], v[220:221], v[224:225]
	v_pk_add_f32 v[222:223], v[222:223], v[224:225]
	s_nop 0
	v_add_f32_e32 v231, v222, v223
	v_cvt_pk_f32_fp8_e32 v[214:215], v168
	v_cvt_pk_f32_fp8_sdwa v[216:217], v168 src0_sel:WORD_1
	v_cvt_pk_f32_fp8_e32 v[218:219], v169
	v_cvt_pk_f32_fp8_sdwa v[220:221], v169 src0_sel:WORD_1
	v_pk_mul_f32 v[222:223], v[96:97], v[214:215]
	v_pk_mul_f32 v[224:225], v[98:99], v[216:217]
	v_cvt_pk_f32_fp8_e32 v[214:215], v170
	v_cvt_pk_f32_fp8_sdwa v[216:217], v170 src0_sel:WORD_1
	v_pk_fma_f32 v[222:223], v[100:101], v[218:219], v[222:223]
	v_pk_fma_f32 v[224:225], v[102:103], v[220:221], v[224:225]
	v_cvt_pk_f32_fp8_e32 v[218:219], v171
	v_cvt_pk_f32_fp8_sdwa v[220:221], v171 src0_sel:WORD_1
	v_pk_fma_f32 v[222:223], v[104:105], v[214:215], v[222:223]
	v_pk_fma_f32 v[224:225], v[106:107], v[216:217], v[224:225]
	v_pk_fma_f32 v[222:223], v[108:109], v[218:219], v[222:223]
	v_pk_fma_f32 v[224:225], v[110:111], v[220:221], v[224:225]
	v_pk_add_f32 v[222:223], v[222:223], v[224:225]
	s_nop 0
	v_add_f32_e32 v232, v222, v223
	v_cvt_pk_f32_fp8_e32 v[214:215], v172
	v_cvt_pk_f32_fp8_sdwa v[216:217], v172 src0_sel:WORD_1
	v_cvt_pk_f32_fp8_e32 v[218:219], v173
	v_cvt_pk_f32_fp8_sdwa v[220:221], v173 src0_sel:WORD_1
	v_pk_mul_f32 v[222:223], v[96:97], v[214:215]
	v_pk_mul_f32 v[224:225], v[98:99], v[216:217]
	v_cvt_pk_f32_fp8_e32 v[214:215], v174
	v_cvt_pk_f32_fp8_sdwa v[216:217], v174 src0_sel:WORD_1
	v_pk_fma_f32 v[222:223], v[100:101], v[218:219], v[222:223]
	v_pk_fma_f32 v[224:225], v[102:103], v[220:221], v[224:225]
	v_cvt_pk_f32_fp8_e32 v[218:219], v175
	v_cvt_pk_f32_fp8_sdwa v[220:221], v175 src0_sel:WORD_1
	v_pk_fma_f32 v[222:223], v[104:105], v[214:215], v[222:223]
	v_pk_fma_f32 v[224:225], v[106:107], v[216:217], v[224:225]
	v_pk_fma_f32 v[222:223], v[108:109], v[218:219], v[222:223]
	v_pk_fma_f32 v[224:225], v[110:111], v[220:221], v[224:225]
	v_pk_add_f32 v[222:223], v[222:223], v[224:225]
	s_nop 0
	v_add_f32_e32 v233, v222, v223
	v_permlane32_swap_b32_e32 v226, v230
	v_permlane32_swap_b32_e32 v227, v231
	v_permlane32_swap_b32_e32 v228, v232
	v_permlane32_swap_b32_e32 v229, v233
	v_add_f32_e32 v226, v226, v230
	v_add_f32_e32 v228, v228, v232
	v_add_f32_e32 v227, v227, v231
	v_add_f32_e32 v229, v229, v233
	s_nop 1
	v_permlane16_swap_b32_e32 v226, v228
	v_permlane16_swap_b32_e32 v227, v229
	v_add_f32_e32 v226, v226, v228
	v_add_f32_e32 v227, v227, v229
	s_nop 0
	v_cndmask_b32_e64 v230, v226, v227, s[24:25]
	v_cndmask_b32_e64 v231, v227, v226, s[24:25]
	s_nop 1
	v_add_f32_dpp v232, v231, v230 row_ror:8 row_mask:0xf bank_mask:0xf
	s_nop 1
	v_add_f32_dpp v233, v232, v232 quad_perm:[1,0,3,2] row_mask:0xf bank_mask:0xf
	s_nop 1
	v_add_f32_dpp v232, v233, v233 quad_perm:[2,3,0,1] row_mask:0xf bank_mask:0xf
	s_nop 1
	v_add_f32_dpp v233, v232, v232 row_half_mirror row_mask:0xf bank_mask:0xf
	ds_write_b32 v235, v233 offset:35840
	v_readlane_b32 s48, v129, s72
	v_readlane_b32 s49, v129, s73
	v_readlane_b32 s50, v129, s74
	v_readlane_b32 s51, v129, s75
	v_readlane_b32 s52, v129, s76
	v_readlane_b32 s53, v129, s77
	v_readlane_b32 s54, v129, s78
	v_readlane_b32 s55, v129, s79
	s_add_u32 s32, s0, s48
	s_addc_u32 s33, s1, 0
	s_add_u32 s34, s0, s49
	s_addc_u32 s35, s1, 0
	s_add_u32 s36, s0, s50
	s_addc_u32 s37, s1, 0
	s_add_u32 s38, s0, s51
	s_addc_u32 s39, s1, 0
	s_add_u32 s40, s0, s52
	s_addc_u32 s41, s1, 0
	s_add_u32 s42, s0, s53
	s_addc_u32 s43, s1, 0
	s_add_u32 s44, s0, s54
	s_addc_u32 s45, s1, 0
	s_add_u32 s46, s0, s55
	s_addc_u32 s47, s1, 0
	global_load_dwordx4 v[144:147], v234, s[32:33]
	global_load_dwordx4 v[148:151], v234, s[34:35]
	global_load_dwordx4 v[152:155], v234, s[36:37]
	global_load_dwordx4 v[156:159], v234, s[38:39]
	global_load_dwordx4 v[160:163], v234, s[40:41]
	global_load_dwordx4 v[164:167], v234, s[42:43]
	global_load_dwordx4 v[168:171], v234, s[44:45]
	global_load_dwordx4 v[172:175], v234, s[46:47]
	s_waitcnt vmcnt(8)
; template <bool STORE>
; DI void peer_item(const Params& p, int item, char* smem) {
;     ...
; #pragma unroll 2
;     for (int k = 0; k < 128; k += 8) {
;       u32x4 uq[8];
;       const int emine = e_s[tl * 128 + k + (lane >> 3)];
;       const float gmine = g_s[tl * 128 + k + (lane >> 3)];
;       const float su = SU[emine], sv = SV[emine];
; #pragma unroll
;       for (int u = 0; u < 8; ++u) {
;         int e = e_s[tl * 128 + k + u];
;         uq[u] = *(const u32x4*)(U8 + (size_t)e * 1024 + lane * 16);
;       }
;       float part[8];
; #pragma unroll
;       for (int u = 0; u < 8; ++u) {
;         float d = 0.f;
; #pragma unroll
;         for (int i = 0; i < 4; ++i) {
;           f32x2_t lo = __builtin_amdgcn_cvt_pk_f32_fp8((int)uq[u][i], false);
;           f32x2_t hi = __builtin_amdgcn_cvt_pk_f32_fp8((int)uq[u][i], true);
;           d += xf[4 * i] * lo.x + xf[4 * i + 1] * lo.y + xf[4 * i + 2] * hi.x + xf[4 * i + 3] * hi.y;
;         }
;         part[u] = d;
;       }
;       float q4[4], r2[2], h;
; #pragma unroll
;       for (int j = 0; j < 4; ++j) {
;         float mine = b5 ? part[j + 4] : part[j];
;         float other = b5 ? part[j] : part[j + 4];
;         q4[j] = mine + __shfl_xor(other, 32);
;       }
; #pragma unroll
;       for (int j = 0; j < 2; ++j) {
;         float mine = b4 ? q4[j + 2] : q4[j];
;         float other = b4 ? q4[j] : q4[j + 2];
;         r2[j] = mine + __shfl_xor(other, 16);
;       }
;       {
;         float mine = b3 ? r2[1] : r2[0];
;         float other = b3 ? r2[0] : r2[1];
;         h = mine + __shfl_xor(other, 8);
;       }
;       h += __shfl_xor(h, 4);
;       h += __shfl_xor(h, 2);
;       h += __shfl_xor(h, 1);
	v_cvt_pk_f32_fp8_e32 v[214:215], v176
	v_cvt_pk_f32_fp8_sdwa v[216:217], v176 src0_sel:WORD_1
	v_cvt_pk_f32_fp8_e32 v[218:219], v177
	v_cvt_pk_f32_fp8_sdwa v[220:221], v177 src0_sel:WORD_1
	v_pk_mul_f32 v[222:223], v[112:113], v[214:215]
	v_pk_mul_f32 v[224:225], v[114:115], v[216:217]
	v_cvt_pk_f32_fp8_e32 v[214:215], v178
	v_cvt_pk_f32_fp8_sdwa v[216:217], v178 src0_sel:WORD_1
	v_pk_fma_f32 v[222:223], v[116:117], v[218:219], v[222:223]
	v_pk_fma_f32 v[224:225], v[118:119], v[220:221], v[224:225]
	v_cvt_pk_f32_fp8_e32 v[218:219], v179
	v_cvt_pk_f32_fp8_sdwa v[220:221], v179 src0_sel:WORD_1
	v_pk_fma_f32 v[222:223], v[120:121], v[214:215], v[222:223]
	v_pk_fma_f32 v[224:225], v[122:123], v[216:217], v[224:225]
	v_pk_fma_f32 v[222:223], v[124:125], v[218:219], v[222:223]
	v_pk_fma_f32 v[224:225], v[126:127], v[220:221], v[224:225]
	v_pk_add_f32 v[222:223], v[222:223], v[224:225]
	s_nop 0
	v_add_f32_e32 v226, v222, v223
	v_cvt_pk_f32_fp8_e32 v[214:215], v180
	v_cvt_pk_f32_fp8_sdwa v[216:217], v180 src0_sel:WORD_1
	v_cvt_pk_f32_fp8_e32 v[218:219], v181
	v_cvt_pk_f32_fp8_sdwa v[220:221], v181 src0_sel:WORD_1
	v_pk_mul_f32 v[222:223], v[112:113], v[214:215]
	v_pk_mul_f32 v[224:225], v[114:115], v[216:217]
	v_cvt_pk_f32_fp8_e32 v[214:215], v182
	v_cvt_pk_f32_fp8_sdwa v[216:217], v182 src0_sel:WORD_1
	v_pk_fma_f32 v[222:223], v[116:117], v[218:219], v[222:223]
	v_pk_fma_f32 v[224:225], v[118:119], v[220:221], v[224:225]
	v_cvt_pk_f32_fp8_e32 v[218:219], v183
	v_cvt_pk_f32_fp8_sdwa v[220:221], v183 src0_sel:WORD_1
	v_pk_fma_f32 v[222:223], v[120:121], v[214:215], v[222:223]
	v_pk_fma_f32 v[224:225], v[122:123], v[216:217], v[224:225]
	v_pk_fma_f32 v[222:223], v[124:125], v[218:219], v[222:223]
	v_pk_fma_f32 v[224:225], v[126:127], v[220:221], v[224:225]
	v_pk_add_f32 v[222:223], v[222:223], v[224:225]
	s_nop 0
	v_add_f32_e32 v227, v222, v223
	v_cvt_pk_f32_fp8_e32 v[214:215], v184
	v_cvt_pk_f32_fp8_sdwa v[216:217], v184 src0_sel:WORD_1
	v_cvt_pk_f32_fp8_e32 v[218:219], v185
	v_cvt_pk_f32_fp8_sdwa v[220:221], v185 src0_sel:WORD_1
	v_pk_mul_f32 v[222:223], v[112:113], v[214:215]
	v_pk_mul_f32 v[224:225], v[114:115], v[216:217]
	v_cvt_pk_f32_fp8_e32 v[214:215], v186
	v_cvt_pk_f32_fp8_sdwa v[216:217], v186 src0_sel:WORD_1
	v_pk_fma_f32 v[222:223], v[116:117], v[218:219], v[222:223]
	v_pk_fma_f32 v[224:225], v[118:119], v[220:221], v[224:225]
	v_cvt_pk_f32_fp8_e32 v[218:219], v187
	v_cvt_pk_f32_fp8_sdwa v[220:221], v187 src0_sel:WORD_1
	v_pk_fma_f32 v[222:223], v[120:121], v[214:215], v[222:223]
	v_pk_fma_f32 v[224:225], v[122:123], v[216:217], v[224:225]
	v_pk_fma_f32 v[222:223], v[124:125], v[218:219], v[222:223]
	v_pk_fma_f32 v[224:225], v[126:127], v[220:221], v[224:225]
	v_pk_add_f32 v[222:223], v[222:223], v[224:225]
	s_nop 0
	v_add_f32_e32 v228, v222, v223
	v_cvt_pk_f32_fp8_e32 v[214:215], v188
	v_cvt_pk_f32_fp8_sdwa v[216:217], v188 src0_sel:WORD_1
	v_cvt_pk_f32_fp8_e32 v[218:219], v189
	v_cvt_pk_f32_fp8_sdwa v[220:221], v189 src0_sel:WORD_1
	v_pk_mul_f32 v[222:223], v[112:113], v[214:215]
	v_pk_mul_f32 v[224:225], v[114:115], v[216:217]
	v_cvt_pk_f32_fp8_e32 v[214:215], v190
	v_cvt_pk_f32_fp8_sdwa v[216:217], v190 src0_sel:WORD_1
	v_pk_fma_f32 v[222:223], v[116:117], v[218:219], v[222:223]
	v_pk_fma_f32 v[224:225], v[118:119], v[220:221], v[224:225]
	v_cvt_pk_f32_fp8_e32 v[218:219], v191
	v_cvt_pk_f32_fp8_sdwa v[220:221], v191 src0_sel:WORD_1
	v_pk_fma_f32 v[222:223], v[120:121], v[214:215], v[222:223]
	v_pk_fma_f32 v[224:225], v[122:123], v[216:217], v[224:225]
	v_pk_fma_f32 v[222:223], v[124:125], v[218:219], v[222:223]
	v_pk_fma_f32 v[224:225], v[126:127], v[220:221], v[224:225]
	v_pk_add_f32 v[222:223], v[222:223], v[224:225]
	s_nop 0
	v_add_f32_e32 v229, v222, v223
	v_cvt_pk_f32_fp8_e32 v[214:215], v192
	v_cvt_pk_f32_fp8_sdwa v[216:217], v192 src0_sel:WORD_1
	v_cvt_pk_f32_fp8_e32 v[218:219], v193
	v_cvt_pk_f32_fp8_sdwa v[220:221], v193 src0_sel:WORD_1
	v_pk_mul_f32 v[222:223], v[112:113], v[214:215]
	v_pk_mul_f32 v[224:225], v[114:115], v[216:217]
	v_cvt_pk_f32_fp8_e32 v[214:215], v194
	v_cvt_pk_f32_fp8_sdwa v[216:217], v194 src0_sel:WORD_1
	v_pk_fma_f32 v[222:223], v[116:117], v[218:219], v[222:223]
	v_pk_fma_f32 v[224:225], v[118:119], v[220:221], v[224:225]
	v_cvt_pk_f32_fp8_e32 v[218:219], v195
	v_cvt_pk_f32_fp8_sdwa v[220:221], v195 src0_sel:WORD_1
	v_pk_fma_f32 v[222:223], v[120:121], v[214:215], v[222:223]
	v_pk_fma_f32 v[224:225], v[122:123], v[216:217], v[224:225]
	v_pk_fma_f32 v[222:223], v[124:125], v[218:219], v[222:223]
	v_pk_fma_f32 v[224:225], v[126:127], v[220:221], v[224:225]
	v_pk_add_f32 v[222:223], v[222:223], v[224:225]
	s_nop 0
	v_add_f32_e32 v230, v222, v223
	v_cvt_pk_f32_fp8_e32 v[214:215], v196
	v_cvt_pk_f32_fp8_sdwa v[216:217], v196 src0_sel:WORD_1
	v_cvt_pk_f32_fp8_e32 v[218:219], v197
	v_cvt_pk_f32_fp8_sdwa v[220:221], v197 src0_sel:WORD_1
	v_pk_mul_f32 v[222:223], v[112:113], v[214:215]
	v_pk_mul_f32 v[224:225], v[114:115], v[216:217]
	v_cvt_pk_f32_fp8_e32 v[214:215], v198
	v_cvt_pk_f32_fp8_sdwa v[216:217], v198 src0_sel:WORD_1
	v_pk_fma_f32 v[222:223], v[116:117], v[218:219], v[222:223]
	v_pk_fma_f32 v[224:225], v[118:119], v[220:221], v[224:225]
	v_cvt_pk_f32_fp8_e32 v[218:219], v199
	v_cvt_pk_f32_fp8_sdwa v[220:221], v199 src0_sel:WORD_1
	v_pk_fma_f32 v[222:223], v[120:121], v[214:215], v[222:223]
	v_pk_fma_f32 v[224:225], v[122:123], v[216:217], v[224:225]
	v_pk_fma_f32 v[222:223], v[124:125], v[218:219], v[222:223]
	v_pk_fma_f32 v[224:225], v[126:127], v[220:221], v[224:225]
	v_pk_add_f32 v[222:223], v[222:223], v[224:225]
	s_nop 0
	v_add_f32_e32 v231, v222, v223
	v_cvt_pk_f32_fp8_e32 v[214:215], v200
; template <bool STORE>
; DI void peer_item(const Params& p, int item, char* smem) {
;     ...
; #pragma unroll
;       for (int u = 0; u < 8; ++u) {
;         int e = e_s[tl * 128 + k + u];
;         uq[u] = *(const u32x4*)(U8 + (size_t)e * 1024 + lane * 16);
;       }
;       float part[8];
; #pragma unroll
;       for (int u = 0; u < 8; ++u) {
;         float d = 0.f;
; #pragma unroll
;         for (int i = 0; i < 4; ++i) {
;           f32x2_t lo = __builtin_amdgcn_cvt_pk_f32_fp8((int)uq[u][i], false);
;           f32x2_t hi = __builtin_amdgcn_cvt_pk_f32_fp8((int)uq[u][i], true);
;           d += xf[4 * i] * lo.x + xf[4 * i + 1] * lo.y + xf[4 * i + 2] * hi.x + xf[4 * i + 3] * hi.y;
;         }
;         part[u] = d;
;       }
;       float q4[4], r2[2], h;
; #pragma unroll
;       for (int j = 0; j < 4; ++j) {
;         float mine = b5 ? part[j + 4] : part[j];
;         float other = b5 ? part[j] : part[j + 4];
;         q4[j] = mine + __shfl_xor(other, 32);
;       }
; #pragma unroll
;       for (int j = 0; j < 2; ++j) {
;         float mine = b4 ? q4[j + 2] : q4[j];
;         float other = b4 ? q4[j] : q4[j + 2];
;         r2[j] = mine + __shfl_xor(other, 16);
;       }
;       {
;         float mine = b3 ? r2[1] : r2[0];
;         float other = b3 ? r2[0] : r2[1];
;         h = mine + __shfl_xor(other, 8);
;       }
;       h += __shfl_xor(h, 4);
;       h += __shfl_xor(h, 2);
;       h += __shfl_xor(h, 1);
	v_cvt_pk_f32_fp8_sdwa v[216:217], v200 src0_sel:WORD_1
	v_cvt_pk_f32_fp8_e32 v[218:219], v201
	v_cvt_pk_f32_fp8_sdwa v[220:221], v201 src0_sel:WORD_1
	v_pk_mul_f32 v[222:223], v[112:113], v[214:215]
	v_pk_mul_f32 v[224:225], v[114:115], v[216:217]
	v_cvt_pk_f32_fp8_e32 v[214:215], v202
	v_cvt_pk_f32_fp8_sdwa v[216:217], v202 src0_sel:WORD_1
	v_pk_fma_f32 v[222:223], v[116:117], v[218:219], v[222:223]
	v_pk_fma_f32 v[224:225], v[118:119], v[220:221], v[224:225]
	v_cvt_pk_f32_fp8_e32 v[218:219], v203
	v_cvt_pk_f32_fp8_sdwa v[220:221], v203 src0_sel:WORD_1
	v_pk_fma_f32 v[222:223], v[120:121], v[214:215], v[222:223]
	v_pk_fma_f32 v[224:225], v[122:123], v[216:217], v[224:225]
	v_pk_fma_f32 v[222:223], v[124:125], v[218:219], v[222:223]
	v_pk_fma_f32 v[224:225], v[126:127], v[220:221], v[224:225]
	v_pk_add_f32 v[222:223], v[222:223], v[224:225]
	s_nop 0
	v_add_f32_e32 v232, v222, v223
	v_cvt_pk_f32_fp8_e32 v[214:215], v204
	v_cvt_pk_f32_fp8_sdwa v[216:217], v204 src0_sel:WORD_1
	v_cvt_pk_f32_fp8_e32 v[218:219], v205
	v_cvt_pk_f32_fp8_sdwa v[220:221], v205 src0_sel:WORD_1
	v_pk_mul_f32 v[222:223], v[112:113], v[214:215]
	v_pk_mul_f32 v[224:225], v[114:115], v[216:217]
	v_cvt_pk_f32_fp8_e32 v[214:215], v206
	v_cvt_pk_f32_fp8_sdwa v[216:217], v206 src0_sel:WORD_1
	v_pk_fma_f32 v[222:223], v[116:117], v[218:219], v[222:223]
	v_pk_fma_f32 v[224:225], v[118:119], v[220:221], v[224:225]
	v_cvt_pk_f32_fp8_e32 v[218:219], v207
	v_cvt_pk_f32_fp8_sdwa v[220:221], v207 src0_sel:WORD_1
	v_pk_fma_f32 v[222:223], v[120:121], v[214:215], v[222:223]
	v_pk_fma_f32 v[224:225], v[122:123], v[216:217], v[224:225]
	v_pk_fma_f32 v[222:223], v[124:125], v[218:219], v[222:223]
	v_pk_fma_f32 v[224:225], v[126:127], v[220:221], v[224:225]
	v_pk_add_f32 v[222:223], v[222:223], v[224:225]
	s_nop 0
	v_add_f32_e32 v233, v222, v223
	v_permlane32_swap_b32_e32 v226, v230
	v_permlane32_swap_b32_e32 v227, v231
	v_permlane32_swap_b32_e32 v228, v232
	v_permlane32_swap_b32_e32 v229, v233
	v_add_f32_e32 v226, v226, v230
	v_add_f32_e32 v228, v228, v232
	v_add_f32_e32 v227, v227, v231
	v_add_f32_e32 v229, v229, v233
	s_nop 1
	v_permlane16_swap_b32_e32 v226, v228
	v_permlane16_swap_b32_e32 v227, v229
	v_add_f32_e32 v226, v226, v228
	v_add_f32_e32 v227, v227, v229
	s_nop 0
	v_cndmask_b32_e64 v230, v226, v227, s[24:25]
	v_cndmask_b32_e64 v231, v227, v226, s[24:25]
	s_nop 1
	v_add_f32_dpp v232, v231, v230 row_ror:8 row_mask:0xf bank_mask:0xf
	s_nop 1
	v_add_f32_dpp v233, v232, v232 quad_perm:[1,0,3,2] row_mask:0xf bank_mask:0xf
	s_nop 1
	v_add_f32_dpp v232, v233, v233 quad_perm:[2,3,0,1] row_mask:0xf bank_mask:0xf
	s_nop 1
	v_add_f32_dpp v233, v232, v232 row_half_mirror row_mask:0xf bank_mask:0xf
	ds_write_b32 v235, v233 offset:36352
	v_readlane_b32 s48, v131, s72
	v_readlane_b32 s49, v131, s73
	v_readlane_b32 s50, v131, s74
	v_readlane_b32 s51, v131, s75
	v_readlane_b32 s52, v131, s76
	v_readlane_b32 s53, v131, s77
	v_readlane_b32 s54, v131, s78
	v_readlane_b32 s55, v131, s79
	s_add_u32 s32, s0, s48
	s_addc_u32 s33, s1, 0
	s_add_u32 s34, s0, s49
	s_addc_u32 s35, s1, 0
	s_add_u32 s36, s0, s50
	s_addc_u32 s37, s1, 0
	s_add_u32 s38, s0, s51
	s_addc_u32 s39, s1, 0
	s_add_u32 s40, s0, s52
	s_addc_u32 s41, s1, 0
	s_add_u32 s42, s0, s53
	s_addc_u32 s43, s1, 0
	s_add_u32 s44, s0, s54
	s_addc_u32 s45, s1, 0
	s_add_u32 s46, s0, s55
	s_addc_u32 s47, s1, 0
	global_load_dwordx4 v[176:179], v234, s[32:33]
	global_load_dwordx4 v[180:183], v234, s[34:35]
	global_load_dwordx4 v[184:187], v234, s[36:37]
	global_load_dwordx4 v[188:191], v234, s[38:39]
	global_load_dwordx4 v[192:195], v234, s[40:41]
	global_load_dwordx4 v[196:199], v234, s[42:43]
	global_load_dwordx4 v[200:203], v234, s[44:45]
	global_load_dwordx4 v[204:207], v234, s[46:47]
	s_waitcnt vmcnt(8)
	v_cvt_pk_f32_fp8_e32 v[214:215], v144
	v_cvt_pk_f32_fp8_sdwa v[216:217], v144 src0_sel:WORD_1
	v_cvt_pk_f32_fp8_e32 v[218:219], v145
	v_cvt_pk_f32_fp8_sdwa v[220:221], v145 src0_sel:WORD_1
	v_pk_mul_f32 v[222:223], v[0:1], v[214:215]
	v_pk_mul_f32 v[224:225], v[2:3], v[216:217]
	v_cvt_pk_f32_fp8_e32 v[214:215], v146
	v_cvt_pk_f32_fp8_sdwa v[216:217], v146 src0_sel:WORD_1
	v_pk_fma_f32 v[222:223], v[4:5], v[218:219], v[222:223]
	v_pk_fma_f32 v[224:225], v[6:7], v[220:221], v[224:225]
	v_cvt_pk_f32_fp8_e32 v[218:219], v147
	v_cvt_pk_f32_fp8_sdwa v[220:221], v147 src0_sel:WORD_1
	v_pk_fma_f32 v[222:223], v[8:9], v[214:215], v[222:223]
	v_pk_fma_f32 v[224:225], v[10:11], v[216:217], v[224:225]
	v_pk_fma_f32 v[222:223], v[12:13], v[218:219], v[222:223]
	v_pk_fma_f32 v[224:225], v[14:15], v[220:221], v[224:225]
	v_pk_add_f32 v[222:223], v[222:223], v[224:225]
	s_nop 0
	v_add_f32_e32 v226, v222, v223
	v_cvt_pk_f32_fp8_e32 v[214:215], v148
	v_cvt_pk_f32_fp8_sdwa v[216:217], v148 src0_sel:WORD_1
	v_cvt_pk_f32_fp8_e32 v[218:219], v149
	v_cvt_pk_f32_fp8_sdwa v[220:221], v149 src0_sel:WORD_1
	v_pk_mul_f32 v[222:223], v[0:1], v[214:215]
	v_pk_mul_f32 v[224:225], v[2:3], v[216:217]
	v_cvt_pk_f32_fp8_e32 v[214:215], v150
	v_cvt_pk_f32_fp8_sdwa v[216:217], v150 src0_sel:WORD_1
	v_pk_fma_f32 v[222:223], v[4:5], v[218:219], v[222:223]
	v_pk_fma_f32 v[224:225], v[6:7], v[220:221], v[224:225]
	v_cvt_pk_f32_fp8_e32 v[218:219], v151
	v_cvt_pk_f32_fp8_sdwa v[220:221], v151 src0_sel:WORD_1
	v_pk_fma_f32 v[222:223], v[8:9], v[214:215], v[222:223]
	v_pk_fma_f32 v[224:225], v[10:11], v[216:217], v[224:225]
	v_pk_fma_f32 v[222:223], v[12:13], v[218:219], v[222:223]
	v_pk_fma_f32 v[224:225], v[14:15], v[220:221], v[224:225]
	v_pk_add_f32 v[222:223], v[222:223], v[224:225]
	s_nop 0
	v_add_f32_e32 v227, v222, v223
	v_cvt_pk_f32_fp8_e32 v[214:215], v152
; template <bool STORE>
; DI void peer_item(const Params& p, int item, char* smem) {
;     ...
; #pragma unroll
;       for (int u = 0; u < 8; ++u) {
;         float d = 0.f;
; #pragma unroll
;         for (int i = 0; i < 4; ++i) {
;           f32x2_t lo = __builtin_amdgcn_cvt_pk_f32_fp8((int)uq[u][i], false);
;           f32x2_t hi = __builtin_amdgcn_cvt_pk_f32_fp8((int)uq[u][i], true);
;           d += xf[4 * i] * lo.x + xf[4 * i + 1] * lo.y + xf[4 * i + 2] * hi.x + xf[4 * i + 3] * hi.y;
;         }
;         part[u] = d;
;       }
;       float q4[4], r2[2], h;
; #pragma unroll
;       for (int j = 0; j < 4; ++j) {
;         float mine = b5 ? part[j + 4] : part[j];
;         float other = b5 ? part[j] : part[j + 4];
;         q4[j] = mine + __shfl_xor(other, 32);
;       }
; #pragma unroll
	v_cvt_pk_f32_fp8_sdwa v[216:217], v152 src0_sel:WORD_1
	v_cvt_pk_f32_fp8_e32 v[218:219], v153
	v_cvt_pk_f32_fp8_sdwa v[220:221], v153 src0_sel:WORD_1
	v_pk_mul_f32 v[222:223], v[0:1], v[214:215]
	v_pk_mul_f32 v[224:225], v[2:3], v[216:217]
	v_cvt_pk_f32_fp8_e32 v[214:215], v154
	v_cvt_pk_f32_fp8_sdwa v[216:217], v154 src0_sel:WORD_1
	v_pk_fma_f32 v[222:223], v[4:5], v[218:219], v[222:223]
	v_pk_fma_f32 v[224:225], v[6:7], v[220:221], v[224:225]
	v_cvt_pk_f32_fp8_e32 v[218:219], v155
	v_cvt_pk_f32_fp8_sdwa v[220:221], v155 src0_sel:WORD_1
	v_pk_fma_f32 v[222:223], v[8:9], v[214:215], v[222:223]
	v_pk_fma_f32 v[224:225], v[10:11], v[216:217], v[224:225]
	v_pk_fma_f32 v[222:223], v[12:13], v[218:219], v[222:223]
	v_pk_fma_f32 v[224:225], v[14:15], v[220:221], v[224:225]
	v_pk_add_f32 v[222:223], v[222:223], v[224:225]
	s_nop 0
	v_add_f32_e32 v228, v222, v223
	v_cvt_pk_f32_fp8_e32 v[214:215], v156
	v_cvt_pk_f32_fp8_sdwa v[216:217], v156 src0_sel:WORD_1
	v_cvt_pk_f32_fp8_e32 v[218:219], v157
	v_cvt_pk_f32_fp8_sdwa v[220:221], v157 src0_sel:WORD_1
	v_pk_mul_f32 v[222:223], v[0:1], v[214:215]
	v_pk_mul_f32 v[224:225], v[2:3], v[216:217]
	v_cvt_pk_f32_fp8_e32 v[214:215], v158
	v_cvt_pk_f32_fp8_sdwa v[216:217], v158 src0_sel:WORD_1
	v_pk_fma_f32 v[222:223], v[4:5], v[218:219], v[222:223]
	v_pk_fma_f32 v[224:225], v[6:7], v[220:221], v[224:225]
	v_cvt_pk_f32_fp8_e32 v[218:219], v159
	v_cvt_pk_f32_fp8_sdwa v[220:221], v159 src0_sel:WORD_1
	v_pk_fma_f32 v[222:223], v[8:9], v[214:215], v[222:223]
	v_pk_fma_f32 v[224:225], v[10:11], v[216:217], v[224:225]
	v_pk_fma_f32 v[222:223], v[12:13], v[218:219], v[222:223]
	v_pk_fma_f32 v[224:225], v[14:15], v[220:221], v[224:225]
	v_pk_add_f32 v[222:223], v[222:223], v[224:225]
	s_nop 0
	v_add_f32_e32 v229, v222, v223
	v_cvt_pk_f32_fp8_e32 v[214:215], v160
	v_cvt_pk_f32_fp8_sdwa v[216:217], v160 src0_sel:WORD_1
	v_cvt_pk_f32_fp8_e32 v[218:219], v161
	v_cvt_pk_f32_fp8_sdwa v[220:221], v161 src0_sel:WORD_1
	v_pk_mul_f32 v[222:223], v[0:1], v[214:215]
	v_pk_mul_f32 v[224:225], v[2:3], v[216:217]
	v_cvt_pk_f32_fp8_e32 v[214:215], v162
	v_cvt_pk_f32_fp8_sdwa v[216:217], v162 src0_sel:WORD_1
	v_pk_fma_f32 v[222:223], v[4:5], v[218:219], v[222:223]
	v_pk_fma_f32 v[224:225], v[6:7], v[220:221], v[224:225]
	v_cvt_pk_f32_fp8_e32 v[218:219], v163
	v_cvt_pk_f32_fp8_sdwa v[220:221], v163 src0_sel:WORD_1
	v_pk_fma_f32 v[222:223], v[8:9], v[214:215], v[222:223]
	v_pk_fma_f32 v[224:225], v[10:11], v[216:217], v[224:225]
	v_pk_fma_f32 v[222:223], v[12:13], v[218:219], v[222:223]
	v_pk_fma_f32 v[224:225], v[14:15], v[220:221], v[224:225]
	v_pk_add_f32 v[222:223], v[222:223], v[224:225]
	s_nop 0
	v_add_f32_e32 v230, v222, v223
	v_cvt_pk_f32_fp8_e32 v[214:215], v164
	v_cvt_pk_f32_fp8_sdwa v[216:217], v164 src0_sel:WORD_1
	v_cvt_pk_f32_fp8_e32 v[218:219], v165
	v_cvt_pk_f32_fp8_sdwa v[220:221], v165 src0_sel:WORD_1
	v_pk_mul_f32 v[222:223], v[0:1], v[214:215]
	v_pk_mul_f32 v[224:225], v[2:3], v[216:217]
	v_cvt_pk_f32_fp8_e32 v[214:215], v166
	v_cvt_pk_f32_fp8_sdwa v[216:217], v166 src0_sel:WORD_1
	v_pk_fma_f32 v[222:223], v[4:5], v[218:219], v[222:223]
	v_pk_fma_f32 v[224:225], v[6:7], v[220:221], v[224:225]
	v_cvt_pk_f32_fp8_e32 v[218:219], v167
	v_cvt_pk_f32_fp8_sdwa v[220:221], v167 src0_sel:WORD_1
	v_pk_fma_f32 v[222:223], v[8:9], v[214:215], v[222:223]
	v_pk_fma_f32 v[224:225], v[10:11], v[216:217], v[224:225]
	v_pk_fma_f32 v[222:223], v[12:13], v[218:219], v[222:223]
	v_pk_fma_f32 v[224:225], v[14:15], v[220:221], v[224:225]
	v_pk_add_f32 v[222:223], v[222:223], v[224:225]
	s_nop 0
	v_add_f32_e32 v231, v222, v223
	v_cvt_pk_f32_fp8_e32 v[214:215], v168
	v_cvt_pk_f32_fp8_sdwa v[216:217], v168 src0_sel:WORD_1
	v_cvt_pk_f32_fp8_e32 v[218:219], v169
	v_cvt_pk_f32_fp8_sdwa v[220:221], v169 src0_sel:WORD_1
	v_pk_mul_f32 v[222:223], v[0:1], v[214:215]
	v_pk_mul_f32 v[224:225], v[2:3], v[216:217]
	v_cvt_pk_f32_fp8_e32 v[214:215], v170
	v_cvt_pk_f32_fp8_sdwa v[216:217], v170 src0_sel:WORD_1
	v_pk_fma_f32 v[222:223], v[4:5], v[218:219], v[222:223]
	v_pk_fma_f32 v[224:225], v[6:7], v[220:221], v[224:225]
	v_cvt_pk_f32_fp8_e32 v[218:219], v171
	v_cvt_pk_f32_fp8_sdwa v[220:221], v171 src0_sel:WORD_1
	v_pk_fma_f32 v[222:223], v[8:9], v[214:215], v[222:223]
	v_pk_fma_f32 v[224:225], v[10:11], v[216:217], v[224:225]
	v_pk_fma_f32 v[222:223], v[12:13], v[218:219], v[222:223]
	v_pk_fma_f32 v[224:225], v[14:15], v[220:221], v[224:225]
	v_pk_add_f32 v[222:223], v[222:223], v[224:225]
	s_nop 0
	v_add_f32_e32 v232, v222, v223
	v_cvt_pk_f32_fp8_e32 v[214:215], v172
	v_cvt_pk_f32_fp8_sdwa v[216:217], v172 src0_sel:WORD_1
	v_cvt_pk_f32_fp8_e32 v[218:219], v173
	v_cvt_pk_f32_fp8_sdwa v[220:221], v173 src0_sel:WORD_1
	v_pk_mul_f32 v[222:223], v[0:1], v[214:215]
	v_pk_mul_f32 v[224:225], v[2:3], v[216:217]
	v_cvt_pk_f32_fp8_e32 v[214:215], v174
	v_cvt_pk_f32_fp8_sdwa v[216:217], v174 src0_sel:WORD_1
	v_pk_fma_f32 v[222:223], v[4:5], v[218:219], v[222:223]
	v_pk_fma_f32 v[224:225], v[6:7], v[220:221], v[224:225]
	v_cvt_pk_f32_fp8_e32 v[218:219], v175
	v_cvt_pk_f32_fp8_sdwa v[220:221], v175 src0_sel:WORD_1
	v_pk_fma_f32 v[222:223], v[8:9], v[214:215], v[222:223]
	v_pk_fma_f32 v[224:225], v[10:11], v[216:217], v[224:225]
	v_pk_fma_f32 v[222:223], v[12:13], v[218:219], v[222:223]
	v_pk_fma_f32 v[224:225], v[14:15], v[220:221], v[224:225]
	v_pk_add_f32 v[222:223], v[222:223], v[224:225]
	s_nop 0
	v_add_f32_e32 v233, v222, v223
	v_permlane32_swap_b32_e32 v226, v230
	v_permlane32_swap_b32_e32 v227, v231
	v_permlane32_swap_b32_e32 v228, v232
	v_permlane32_swap_b32_e32 v229, v233
	v_add_f32_e32 v226, v226, v230
	v_add_f32_e32 v228, v228, v232
; template <bool STORE>
; DI void peer_item(const Params& p, int item, char* smem) {
;     ...
; #pragma unroll
;       for (int u = 0; u < 8; ++u) {
;         int e = e_s[tl * 128 + k + u];
;         uq[u] = *(const u32x4*)(U8 + (size_t)e * 1024 + lane * 16);
;       }
;       float part[8];
; #pragma unroll
;       for (int u = 0; u < 8; ++u) {
;         float d = 0.f;
; #pragma unroll
;         for (int i = 0; i < 4; ++i) {
;           f32x2_t lo = __builtin_amdgcn_cvt_pk_f32_fp8((int)uq[u][i], false);
;           f32x2_t hi = __builtin_amdgcn_cvt_pk_f32_fp8((int)uq[u][i], true);
;           d += xf[4 * i] * lo.x + xf[4 * i + 1] * lo.y + xf[4 * i + 2] * hi.x + xf[4 * i + 3] * hi.y;
;         }
;         part[u] = d;
;       }
;       float q4[4], r2[2], h;
; #pragma unroll
;       for (int j = 0; j < 4; ++j) {
;         float mine = b5 ? part[j + 4] : part[j];
;         float other = b5 ? part[j] : part[j + 4];
;         q4[j] = mine + __shfl_xor(other, 32);
;       }
; #pragma unroll
;       for (int j = 0; j < 2; ++j) {
;         float mine = b4 ? q4[j + 2] : q4[j];
;         float other = b4 ? q4[j] : q4[j + 2];
;         r2[j] = mine + __shfl_xor(other, 16);
;       }
;       {
;         float mine = b3 ? r2[1] : r2[0];
;         float other = b3 ? r2[0] : r2[1];
;         h = mine + __shfl_xor(other, 8);
;       }
;       h += __shfl_xor(h, 4);
;       h += __shfl_xor(h, 2);
;       h += __shfl_xor(h, 1);
	v_add_f32_e32 v227, v227, v231
	v_add_f32_e32 v229, v229, v233
	s_nop 1
	v_permlane16_swap_b32_e32 v226, v228
	v_permlane16_swap_b32_e32 v227, v229
	v_add_f32_e32 v226, v226, v228
	v_add_f32_e32 v227, v227, v229
	s_nop 0
	v_cndmask_b32_e64 v230, v226, v227, s[24:25]
	v_cndmask_b32_e64 v231, v227, v226, s[24:25]
	s_nop 1
	v_add_f32_dpp v232, v231, v230 row_ror:8 row_mask:0xf bank_mask:0xf
	s_nop 1
	v_add_f32_dpp v233, v232, v232 quad_perm:[1,0,3,2] row_mask:0xf bank_mask:0xf
	s_nop 1
	v_add_f32_dpp v232, v233, v233 quad_perm:[2,3,0,1] row_mask:0xf bank_mask:0xf
	s_nop 1
	v_add_f32_dpp v233, v232, v232 row_half_mirror row_mask:0xf bank_mask:0xf
	ds_write_b32 v235, v233 offset:32800
	v_readlane_b32 s48, v133, s72
	v_readlane_b32 s49, v133, s73
	v_readlane_b32 s50, v133, s74
	v_readlane_b32 s51, v133, s75
	v_readlane_b32 s52, v133, s76
	v_readlane_b32 s53, v133, s77
	v_readlane_b32 s54, v133, s78
	v_readlane_b32 s55, v133, s79
	s_add_u32 s32, s0, s48
	s_addc_u32 s33, s1, 0
	s_add_u32 s34, s0, s49
	s_addc_u32 s35, s1, 0
	s_add_u32 s36, s0, s50
	s_addc_u32 s37, s1, 0
	s_add_u32 s38, s0, s51
	s_addc_u32 s39, s1, 0
	s_add_u32 s40, s0, s52
	s_addc_u32 s41, s1, 0
	s_add_u32 s42, s0, s53
	s_addc_u32 s43, s1, 0
	s_add_u32 s44, s0, s54
	s_addc_u32 s45, s1, 0
	s_add_u32 s46, s0, s55
	s_addc_u32 s47, s1, 0
	global_load_dwordx4 v[144:147], v234, s[32:33]
	global_load_dwordx4 v[148:151], v234, s[34:35]
	global_load_dwordx4 v[152:155], v234, s[36:37]
	global_load_dwordx4 v[156:159], v234, s[38:39]
	global_load_dwordx4 v[160:163], v234, s[40:41]
	global_load_dwordx4 v[164:167], v234, s[42:43]
	global_load_dwordx4 v[168:171], v234, s[44:45]
	global_load_dwordx4 v[172:175], v234, s[46:47]
	s_waitcnt vmcnt(8)
	v_cvt_pk_f32_fp8_e32 v[214:215], v176
	v_cvt_pk_f32_fp8_sdwa v[216:217], v176 src0_sel:WORD_1
	v_cvt_pk_f32_fp8_e32 v[218:219], v177
	v_cvt_pk_f32_fp8_sdwa v[220:221], v177 src0_sel:WORD_1
	v_pk_mul_f32 v[222:223], v[16:17], v[214:215]
	v_pk_mul_f32 v[224:225], v[18:19], v[216:217]
	v_cvt_pk_f32_fp8_e32 v[214:215], v178
	v_cvt_pk_f32_fp8_sdwa v[216:217], v178 src0_sel:WORD_1
	v_pk_fma_f32 v[222:223], v[20:21], v[218:219], v[222:223]
	v_pk_fma_f32 v[224:225], v[22:23], v[220:221], v[224:225]
	v_cvt_pk_f32_fp8_e32 v[218:219], v179
	v_cvt_pk_f32_fp8_sdwa v[220:221], v179 src0_sel:WORD_1
	v_pk_fma_f32 v[222:223], v[24:25], v[214:215], v[222:223]
	v_pk_fma_f32 v[224:225], v[26:27], v[216:217], v[224:225]
	v_pk_fma_f32 v[222:223], v[28:29], v[218:219], v[222:223]
	v_pk_fma_f32 v[224:225], v[30:31], v[220:221], v[224:225]
	v_pk_add_f32 v[222:223], v[222:223], v[224:225]
	s_nop 0
	v_add_f32_e32 v226, v222, v223
	v_cvt_pk_f32_fp8_e32 v[214:215], v180
	v_cvt_pk_f32_fp8_sdwa v[216:217], v180 src0_sel:WORD_1
	v_cvt_pk_f32_fp8_e32 v[218:219], v181
	v_cvt_pk_f32_fp8_sdwa v[220:221], v181 src0_sel:WORD_1
	v_pk_mul_f32 v[222:223], v[16:17], v[214:215]
	v_pk_mul_f32 v[224:225], v[18:19], v[216:217]
	v_cvt_pk_f32_fp8_e32 v[214:215], v182
	v_cvt_pk_f32_fp8_sdwa v[216:217], v182 src0_sel:WORD_1
	v_pk_fma_f32 v[222:223], v[20:21], v[218:219], v[222:223]
	v_pk_fma_f32 v[224:225], v[22:23], v[220:221], v[224:225]
	v_cvt_pk_f32_fp8_e32 v[218:219], v183
	v_cvt_pk_f32_fp8_sdwa v[220:221], v183 src0_sel:WORD_1
	v_pk_fma_f32 v[222:223], v[24:25], v[214:215], v[222:223]
	v_pk_fma_f32 v[224:225], v[26:27], v[216:217], v[224:225]
	v_pk_fma_f32 v[222:223], v[28:29], v[218:219], v[222:223]
	v_pk_fma_f32 v[224:225], v[30:31], v[220:221], v[224:225]
	v_pk_add_f32 v[222:223], v[222:223], v[224:225]
	s_nop 0
	v_add_f32_e32 v227, v222, v223
	v_cvt_pk_f32_fp8_e32 v[214:215], v184
	v_cvt_pk_f32_fp8_sdwa v[216:217], v184 src0_sel:WORD_1
	v_cvt_pk_f32_fp8_e32 v[218:219], v185
	v_cvt_pk_f32_fp8_sdwa v[220:221], v185 src0_sel:WORD_1
	v_pk_mul_f32 v[222:223], v[16:17], v[214:215]
	v_pk_mul_f32 v[224:225], v[18:19], v[216:217]
	v_cvt_pk_f32_fp8_e32 v[214:215], v186
	v_cvt_pk_f32_fp8_sdwa v[216:217], v186 src0_sel:WORD_1
	v_pk_fma_f32 v[222:223], v[20:21], v[218:219], v[222:223]
	v_pk_fma_f32 v[224:225], v[22:23], v[220:221], v[224:225]
	v_cvt_pk_f32_fp8_e32 v[218:219], v187
	v_cvt_pk_f32_fp8_sdwa v[220:221], v187 src0_sel:WORD_1
	v_pk_fma_f32 v[222:223], v[24:25], v[214:215], v[222:223]
	v_pk_fma_f32 v[224:225], v[26:27], v[216:217], v[224:225]
	v_pk_fma_f32 v[222:223], v[28:29], v[218:219], v[222:223]
	v_pk_fma_f32 v[224:225], v[30:31], v[220:221], v[224:225]
	v_pk_add_f32 v[222:223], v[222:223], v[224:225]
	s_nop 0
	v_add_f32_e32 v228, v222, v223
	v_cvt_pk_f32_fp8_e32 v[214:215], v188
	v_cvt_pk_f32_fp8_sdwa v[216:217], v188 src0_sel:WORD_1
	v_cvt_pk_f32_fp8_e32 v[218:219], v189
	v_cvt_pk_f32_fp8_sdwa v[220:221], v189 src0_sel:WORD_1
	v_pk_mul_f32 v[222:223], v[16:17], v[214:215]
	v_pk_mul_f32 v[224:225], v[18:19], v[216:217]
	v_cvt_pk_f32_fp8_e32 v[214:215], v190
	v_cvt_pk_f32_fp8_sdwa v[216:217], v190 src0_sel:WORD_1
	v_pk_fma_f32 v[222:223], v[20:21], v[218:219], v[222:223]
	v_pk_fma_f32 v[224:225], v[22:23], v[220:221], v[224:225]
	v_cvt_pk_f32_fp8_e32 v[218:219], v191
	v_cvt_pk_f32_fp8_sdwa v[220:221], v191 src0_sel:WORD_1
	v_pk_fma_f32 v[222:223], v[24:25], v[214:215], v[222:223]
	v_pk_fma_f32 v[224:225], v[26:27], v[216:217], v[224:225]
	v_pk_fma_f32 v[222:223], v[28:29], v[218:219], v[222:223]
	v_pk_fma_f32 v[224:225], v[30:31], v[220:221], v[224:225]
	v_pk_add_f32 v[222:223], v[222:223], v[224:225]
	s_nop 0
	v_add_f32_e32 v229, v222, v223
	v_cvt_pk_f32_fp8_e32 v[214:215], v192
	v_cvt_pk_f32_fp8_sdwa v[216:217], v192 src0_sel:WORD_1
	v_cvt_pk_f32_fp8_e32 v[218:219], v193
	v_cvt_pk_f32_fp8_sdwa v[220:221], v193 src0_sel:WORD_1
	v_pk_mul_f32 v[222:223], v[16:17], v[214:215]
; template <bool STORE>
; DI void peer_item(const Params& p, int item, char* smem) {
;     ...
; #pragma unroll
;       for (int u = 0; u < 8; ++u) {
;         int e = e_s[tl * 128 + k + u];
;         uq[u] = *(const u32x4*)(U8 + (size_t)e * 1024 + lane * 16);
;       }
;       float part[8];
; #pragma unroll
;       for (int u = 0; u < 8; ++u) {
;         float d = 0.f;
; #pragma unroll
;         for (int i = 0; i < 4; ++i) {
;           f32x2_t lo = __builtin_amdgcn_cvt_pk_f32_fp8((int)uq[u][i], false);
;           f32x2_t hi = __builtin_amdgcn_cvt_pk_f32_fp8((int)uq[u][i], true);
;           d += xf[4 * i] * lo.x + xf[4 * i + 1] * lo.y + xf[4 * i + 2] * hi.x + xf[4 * i + 3] * hi.y;
;         }
;         part[u] = d;
;       }
;       float q4[4], r2[2], h;
; #pragma unroll
;       for (int j = 0; j < 4; ++j) {
;         float mine = b5 ? part[j + 4] : part[j];
;         float other = b5 ? part[j] : part[j + 4];
;         q4[j] = mine + __shfl_xor(other, 32);
;       }
; #pragma unroll
;       for (int j = 0; j < 2; ++j) {
;         float mine = b4 ? q4[j + 2] : q4[j];
;         float other = b4 ? q4[j] : q4[j + 2];
;         r2[j] = mine + __shfl_xor(other, 16);
;       }
;       {
;         float mine = b3 ? r2[1] : r2[0];
;         float other = b3 ? r2[0] : r2[1];
;         h = mine + __shfl_xor(other, 8);
;       }
;       h += __shfl_xor(h, 4);
;       h += __shfl_xor(h, 2);
;       h += __shfl_xor(h, 1);
	v_pk_mul_f32 v[224:225], v[18:19], v[216:217]
	v_cvt_pk_f32_fp8_e32 v[214:215], v194
	v_cvt_pk_f32_fp8_sdwa v[216:217], v194 src0_sel:WORD_1
	v_pk_fma_f32 v[222:223], v[20:21], v[218:219], v[222:223]
	v_pk_fma_f32 v[224:225], v[22:23], v[220:221], v[224:225]
	v_cvt_pk_f32_fp8_e32 v[218:219], v195
	v_cvt_pk_f32_fp8_sdwa v[220:221], v195 src0_sel:WORD_1
	v_pk_fma_f32 v[222:223], v[24:25], v[214:215], v[222:223]
	v_pk_fma_f32 v[224:225], v[26:27], v[216:217], v[224:225]
	v_pk_fma_f32 v[222:223], v[28:29], v[218:219], v[222:223]
	v_pk_fma_f32 v[224:225], v[30:31], v[220:221], v[224:225]
	v_pk_add_f32 v[222:223], v[222:223], v[224:225]
	s_nop 0
	v_add_f32_e32 v230, v222, v223
	v_cvt_pk_f32_fp8_e32 v[214:215], v196
	v_cvt_pk_f32_fp8_sdwa v[216:217], v196 src0_sel:WORD_1
	v_cvt_pk_f32_fp8_e32 v[218:219], v197
	v_cvt_pk_f32_fp8_sdwa v[220:221], v197 src0_sel:WORD_1
	v_pk_mul_f32 v[222:223], v[16:17], v[214:215]
	v_pk_mul_f32 v[224:225], v[18:19], v[216:217]
	v_cvt_pk_f32_fp8_e32 v[214:215], v198
	v_cvt_pk_f32_fp8_sdwa v[216:217], v198 src0_sel:WORD_1
	v_pk_fma_f32 v[222:223], v[20:21], v[218:219], v[222:223]
	v_pk_fma_f32 v[224:225], v[22:23], v[220:221], v[224:225]
	v_cvt_pk_f32_fp8_e32 v[218:219], v199
	v_cvt_pk_f32_fp8_sdwa v[220:221], v199 src0_sel:WORD_1
	v_pk_fma_f32 v[222:223], v[24:25], v[214:215], v[222:223]
	v_pk_fma_f32 v[224:225], v[26:27], v[216:217], v[224:225]
	v_pk_fma_f32 v[222:223], v[28:29], v[218:219], v[222:223]
	v_pk_fma_f32 v[224:225], v[30:31], v[220:221], v[224:225]
	v_pk_add_f32 v[222:223], v[222:223], v[224:225]
	s_nop 0
	v_add_f32_e32 v231, v222, v223
	v_cvt_pk_f32_fp8_e32 v[214:215], v200
	v_cvt_pk_f32_fp8_sdwa v[216:217], v200 src0_sel:WORD_1
	v_cvt_pk_f32_fp8_e32 v[218:219], v201
	v_cvt_pk_f32_fp8_sdwa v[220:221], v201 src0_sel:WORD_1
	v_pk_mul_f32 v[222:223], v[16:17], v[214:215]
	v_pk_mul_f32 v[224:225], v[18:19], v[216:217]
	v_cvt_pk_f32_fp8_e32 v[214:215], v202
	v_cvt_pk_f32_fp8_sdwa v[216:217], v202 src0_sel:WORD_1
	v_pk_fma_f32 v[222:223], v[20:21], v[218:219], v[222:223]
	v_pk_fma_f32 v[224:225], v[22:23], v[220:221], v[224:225]
	v_cvt_pk_f32_fp8_e32 v[218:219], v203
	v_cvt_pk_f32_fp8_sdwa v[220:221], v203 src0_sel:WORD_1
	v_pk_fma_f32 v[222:223], v[24:25], v[214:215], v[222:223]
	v_pk_fma_f32 v[224:225], v[26:27], v[216:217], v[224:225]
	v_pk_fma_f32 v[222:223], v[28:29], v[218:219], v[222:223]
	v_pk_fma_f32 v[224:225], v[30:31], v[220:221], v[224:225]
	v_pk_add_f32 v[222:223], v[222:223], v[224:225]
	s_nop 0
	v_add_f32_e32 v232, v222, v223
	v_cvt_pk_f32_fp8_e32 v[214:215], v204
	v_cvt_pk_f32_fp8_sdwa v[216:217], v204 src0_sel:WORD_1
	v_cvt_pk_f32_fp8_e32 v[218:219], v205
	v_cvt_pk_f32_fp8_sdwa v[220:221], v205 src0_sel:WORD_1
	v_pk_mul_f32 v[222:223], v[16:17], v[214:215]
	v_pk_mul_f32 v[224:225], v[18:19], v[216:217]
	v_cvt_pk_f32_fp8_e32 v[214:215], v206
	v_cvt_pk_f32_fp8_sdwa v[216:217], v206 src0_sel:WORD_1
	v_pk_fma_f32 v[222:223], v[20:21], v[218:219], v[222:223]
	v_pk_fma_f32 v[224:225], v[22:23], v[220:221], v[224:225]
	v_cvt_pk_f32_fp8_e32 v[218:219], v207
	v_cvt_pk_f32_fp8_sdwa v[220:221], v207 src0_sel:WORD_1
	v_pk_fma_f32 v[222:223], v[24:25], v[214:215], v[222:223]
	v_pk_fma_f32 v[224:225], v[26:27], v[216:217], v[224:225]
	v_pk_fma_f32 v[222:223], v[28:29], v[218:219], v[222:223]
	v_pk_fma_f32 v[224:225], v[30:31], v[220:221], v[224:225]
	v_pk_add_f32 v[222:223], v[222:223], v[224:225]
	s_nop 0
	v_add_f32_e32 v233, v222, v223
	v_permlane32_swap_b32_e32 v226, v230
	v_permlane32_swap_b32_e32 v227, v231
	v_permlane32_swap_b32_e32 v228, v232
	v_permlane32_swap_b32_e32 v229, v233
	v_add_f32_e32 v226, v226, v230
	v_add_f32_e32 v228, v228, v232
	v_add_f32_e32 v227, v227, v231
	v_add_f32_e32 v229, v229, v233
	s_nop 1
	v_permlane16_swap_b32_e32 v226, v228
	v_permlane16_swap_b32_e32 v227, v229
	v_add_f32_e32 v226, v226, v228
	v_add_f32_e32 v227, v227, v229
	s_nop 0
	v_cndmask_b32_e64 v230, v226, v227, s[24:25]
	v_cndmask_b32_e64 v231, v227, v226, s[24:25]
	s_nop 1
	v_add_f32_dpp v232, v231, v230 row_ror:8 row_mask:0xf bank_mask:0xf
	s_nop 1
	v_add_f32_dpp v233, v232, v232 quad_perm:[1,0,3,2] row_mask:0xf bank_mask:0xf
	s_nop 1
	v_add_f32_dpp v232, v233, v233 quad_perm:[2,3,0,1] row_mask:0xf bank_mask:0xf
	s_nop 1
	v_add_f32_dpp v233, v232, v232 row_half_mirror row_mask:0xf bank_mask:0xf
	ds_write_b32 v235, v233 offset:33312
	v_readlane_b32 s48, v135, s72
	v_readlane_b32 s49, v135, s73
	v_readlane_b32 s50, v135, s74
	v_readlane_b32 s51, v135, s75
	v_readlane_b32 s52, v135, s76
	v_readlane_b32 s53, v135, s77
	v_readlane_b32 s54, v135, s78
	v_readlane_b32 s55, v135, s79
	s_add_u32 s32, s0, s48
	s_addc_u32 s33, s1, 0
	s_add_u32 s34, s0, s49
	s_addc_u32 s35, s1, 0
	s_add_u32 s36, s0, s50
	s_addc_u32 s37, s1, 0
	s_add_u32 s38, s0, s51
	s_addc_u32 s39, s1, 0
	s_add_u32 s40, s0, s52
	s_addc_u32 s41, s1, 0
	s_add_u32 s42, s0, s53
	s_addc_u32 s43, s1, 0
	s_add_u32 s44, s0, s54
	s_addc_u32 s45, s1, 0
	s_add_u32 s46, s0, s55
	s_addc_u32 s47, s1, 0
	global_load_dwordx4 v[176:179], v234, s[32:33]
	global_load_dwordx4 v[180:183], v234, s[34:35]
	global_load_dwordx4 v[184:187], v234, s[36:37]
	global_load_dwordx4 v[188:191], v234, s[38:39]
	global_load_dwordx4 v[192:195], v234, s[40:41]
	global_load_dwordx4 v[196:199], v234, s[42:43]
	global_load_dwordx4 v[200:203], v234, s[44:45]
	global_load_dwordx4 v[204:207], v234, s[46:47]
	s_waitcnt vmcnt(8)
; template <bool STORE>
; DI void peer_item(const Params& p, int item, char* smem) {
;     ...
; #pragma unroll
;       for (int u = 0; u < 8; ++u) {
;         float d = 0.f;
; #pragma unroll
;         for (int i = 0; i < 4; ++i) {
;           f32x2_t lo = __builtin_amdgcn_cvt_pk_f32_fp8((int)uq[u][i], false);
;           f32x2_t hi = __builtin_amdgcn_cvt_pk_f32_fp8((int)uq[u][i], true);
;           d += xf[4 * i] * lo.x + xf[4 * i + 1] * lo.y + xf[4 * i + 2] * hi.x + xf[4 * i + 3] * hi.y;
;         }
;         part[u] = d;
;       }
	v_cvt_pk_f32_fp8_e32 v[214:215], v144
	v_cvt_pk_f32_fp8_sdwa v[216:217], v144 src0_sel:WORD_1
	v_cvt_pk_f32_fp8_e32 v[218:219], v145
	v_cvt_pk_f32_fp8_sdwa v[220:221], v145 src0_sel:WORD_1
	v_pk_mul_f32 v[222:223], v[32:33], v[214:215]
	v_pk_mul_f32 v[224:225], v[34:35], v[216:217]
	v_cvt_pk_f32_fp8_e32 v[214:215], v146
	v_cvt_pk_f32_fp8_sdwa v[216:217], v146 src0_sel:WORD_1
	v_pk_fma_f32 v[222:223], v[36:37], v[218:219], v[222:223]
	v_pk_fma_f32 v[224:225], v[38:39], v[220:221], v[224:225]
	v_cvt_pk_f32_fp8_e32 v[218:219], v147
	v_cvt_pk_f32_fp8_sdwa v[220:221], v147 src0_sel:WORD_1
	v_pk_fma_f32 v[222:223], v[40:41], v[214:215], v[222:223]
	v_pk_fma_f32 v[224:225], v[42:43], v[216:217], v[224:225]
	v_pk_fma_f32 v[222:223], v[44:45], v[218:219], v[222:223]
	v_pk_fma_f32 v[224:225], v[46:47], v[220:221], v[224:225]
	v_pk_add_f32 v[222:223], v[222:223], v[224:225]
	s_nop 0
	v_add_f32_e32 v226, v222, v223
	v_cvt_pk_f32_fp8_e32 v[214:215], v148
	v_cvt_pk_f32_fp8_sdwa v[216:217], v148 src0_sel:WORD_1
	v_cvt_pk_f32_fp8_e32 v[218:219], v149
	v_cvt_pk_f32_fp8_sdwa v[220:221], v149 src0_sel:WORD_1
	v_pk_mul_f32 v[222:223], v[32:33], v[214:215]
	v_pk_mul_f32 v[224:225], v[34:35], v[216:217]
	v_cvt_pk_f32_fp8_e32 v[214:215], v150
	v_cvt_pk_f32_fp8_sdwa v[216:217], v150 src0_sel:WORD_1
	v_pk_fma_f32 v[222:223], v[36:37], v[218:219], v[222:223]
	v_pk_fma_f32 v[224:225], v[38:39], v[220:221], v[224:225]
	v_cvt_pk_f32_fp8_e32 v[218:219], v151
	v_cvt_pk_f32_fp8_sdwa v[220:221], v151 src0_sel:WORD_1
	v_pk_fma_f32 v[222:223], v[40:41], v[214:215], v[222:223]
	v_pk_fma_f32 v[224:225], v[42:43], v[216:217], v[224:225]
	v_pk_fma_f32 v[222:223], v[44:45], v[218:219], v[222:223]
	v_pk_fma_f32 v[224:225], v[46:47], v[220:221], v[224:225]
	v_pk_add_f32 v[222:223], v[222:223], v[224:225]
	s_nop 0
	v_add_f32_e32 v227, v222, v223
	v_cvt_pk_f32_fp8_e32 v[214:215], v152
	v_cvt_pk_f32_fp8_sdwa v[216:217], v152 src0_sel:WORD_1
	v_cvt_pk_f32_fp8_e32 v[218:219], v153
	v_cvt_pk_f32_fp8_sdwa v[220:221], v153 src0_sel:WORD_1
	v_pk_mul_f32 v[222:223], v[32:33], v[214:215]
	v_pk_mul_f32 v[224:225], v[34:35], v[216:217]
	v_cvt_pk_f32_fp8_e32 v[214:215], v154
	v_cvt_pk_f32_fp8_sdwa v[216:217], v154 src0_sel:WORD_1
	v_pk_fma_f32 v[222:223], v[36:37], v[218:219], v[222:223]
	v_pk_fma_f32 v[224:225], v[38:39], v[220:221], v[224:225]
	v_cvt_pk_f32_fp8_e32 v[218:219], v155
	v_cvt_pk_f32_fp8_sdwa v[220:221], v155 src0_sel:WORD_1
	v_pk_fma_f32 v[222:223], v[40:41], v[214:215], v[222:223]
	v_pk_fma_f32 v[224:225], v[42:43], v[216:217], v[224:225]
	v_pk_fma_f32 v[222:223], v[44:45], v[218:219], v[222:223]
	v_pk_fma_f32 v[224:225], v[46:47], v[220:221], v[224:225]
	v_pk_add_f32 v[222:223], v[222:223], v[224:225]
	s_nop 0
	v_add_f32_e32 v228, v222, v223
	v_cvt_pk_f32_fp8_e32 v[214:215], v156
	v_cvt_pk_f32_fp8_sdwa v[216:217], v156 src0_sel:WORD_1
	v_cvt_pk_f32_fp8_e32 v[218:219], v157
	v_cvt_pk_f32_fp8_sdwa v[220:221], v157 src0_sel:WORD_1
	v_pk_mul_f32 v[222:223], v[32:33], v[214:215]
	v_pk_mul_f32 v[224:225], v[34:35], v[216:217]
	v_cvt_pk_f32_fp8_e32 v[214:215], v158
	v_cvt_pk_f32_fp8_sdwa v[216:217], v158 src0_sel:WORD_1
	v_pk_fma_f32 v[222:223], v[36:37], v[218:219], v[222:223]
	v_pk_fma_f32 v[224:225], v[38:39], v[220:221], v[224:225]
	v_cvt_pk_f32_fp8_e32 v[218:219], v159
	v_cvt_pk_f32_fp8_sdwa v[220:221], v159 src0_sel:WORD_1
	v_pk_fma_f32 v[222:223], v[40:41], v[214:215], v[222:223]
	v_pk_fma_f32 v[224:225], v[42:43], v[216:217], v[224:225]
	v_pk_fma_f32 v[222:223], v[44:45], v[218:219], v[222:223]
	v_pk_fma_f32 v[224:225], v[46:47], v[220:221], v[224:225]
	v_pk_add_f32 v[222:223], v[222:223], v[224:225]
	s_nop 0
	v_add_f32_e32 v229, v222, v223
	v_cvt_pk_f32_fp8_e32 v[214:215], v160
	v_cvt_pk_f32_fp8_sdwa v[216:217], v160 src0_sel:WORD_1
	v_cvt_pk_f32_fp8_e32 v[218:219], v161
	v_cvt_pk_f32_fp8_sdwa v[220:221], v161 src0_sel:WORD_1
	v_pk_mul_f32 v[222:223], v[32:33], v[214:215]
	v_pk_mul_f32 v[224:225], v[34:35], v[216:217]
	v_cvt_pk_f32_fp8_e32 v[214:215], v162
	v_cvt_pk_f32_fp8_sdwa v[216:217], v162 src0_sel:WORD_1
	v_pk_fma_f32 v[222:223], v[36:37], v[218:219], v[222:223]
	v_pk_fma_f32 v[224:225], v[38:39], v[220:221], v[224:225]
	v_cvt_pk_f32_fp8_e32 v[218:219], v163
	v_cvt_pk_f32_fp8_sdwa v[220:221], v163 src0_sel:WORD_1
	v_pk_fma_f32 v[222:223], v[40:41], v[214:215], v[222:223]
	v_pk_fma_f32 v[224:225], v[42:43], v[216:217], v[224:225]
	v_pk_fma_f32 v[222:223], v[44:45], v[218:219], v[222:223]
	v_pk_fma_f32 v[224:225], v[46:47], v[220:221], v[224:225]
	v_pk_add_f32 v[222:223], v[222:223], v[224:225]
	s_nop 0
	v_add_f32_e32 v230, v222, v223
	v_cvt_pk_f32_fp8_e32 v[214:215], v164
	v_cvt_pk_f32_fp8_sdwa v[216:217], v164 src0_sel:WORD_1
	v_cvt_pk_f32_fp8_e32 v[218:219], v165
	v_cvt_pk_f32_fp8_sdwa v[220:221], v165 src0_sel:WORD_1
	v_pk_mul_f32 v[222:223], v[32:33], v[214:215]
	v_pk_mul_f32 v[224:225], v[34:35], v[216:217]
	v_cvt_pk_f32_fp8_e32 v[214:215], v166
	v_cvt_pk_f32_fp8_sdwa v[216:217], v166 src0_sel:WORD_1
	v_pk_fma_f32 v[222:223], v[36:37], v[218:219], v[222:223]
	v_pk_fma_f32 v[224:225], v[38:39], v[220:221], v[224:225]
	v_cvt_pk_f32_fp8_e32 v[218:219], v167
	v_cvt_pk_f32_fp8_sdwa v[220:221], v167 src0_sel:WORD_1
	v_pk_fma_f32 v[222:223], v[40:41], v[214:215], v[222:223]
	v_pk_fma_f32 v[224:225], v[42:43], v[216:217], v[224:225]
	v_pk_fma_f32 v[222:223], v[44:45], v[218:219], v[222:223]
	v_pk_fma_f32 v[224:225], v[46:47], v[220:221], v[224:225]
	v_pk_add_f32 v[222:223], v[222:223], v[224:225]
	s_nop 0
	v_add_f32_e32 v231, v222, v223
	v_cvt_pk_f32_fp8_e32 v[214:215], v168
	v_cvt_pk_f32_fp8_sdwa v[216:217], v168 src0_sel:WORD_1
	v_cvt_pk_f32_fp8_e32 v[218:219], v169
; template <bool STORE>
; DI void peer_item(const Params& p, int item, char* smem) {
;     ...
; #pragma unroll
;       for (int u = 0; u < 8; ++u) {
;         int e = e_s[tl * 128 + k + u];
;         uq[u] = *(const u32x4*)(U8 + (size_t)e * 1024 + lane * 16);
;       }
;       float part[8];
; #pragma unroll
;       for (int u = 0; u < 8; ++u) {
;         float d = 0.f;
; #pragma unroll
;         for (int i = 0; i < 4; ++i) {
;           f32x2_t lo = __builtin_amdgcn_cvt_pk_f32_fp8((int)uq[u][i], false);
;           f32x2_t hi = __builtin_amdgcn_cvt_pk_f32_fp8((int)uq[u][i], true);
;           d += xf[4 * i] * lo.x + xf[4 * i + 1] * lo.y + xf[4 * i + 2] * hi.x + xf[4 * i + 3] * hi.y;
;         }
;         part[u] = d;
;       }
;       float q4[4], r2[2], h;
; #pragma unroll
;       for (int j = 0; j < 4; ++j) {
;         float mine = b5 ? part[j + 4] : part[j];
;         float other = b5 ? part[j] : part[j + 4];
;         q4[j] = mine + __shfl_xor(other, 32);
;       }
; #pragma unroll
;       for (int j = 0; j < 2; ++j) {
;         float mine = b4 ? q4[j + 2] : q4[j];
;         float other = b4 ? q4[j] : q4[j + 2];
;         r2[j] = mine + __shfl_xor(other, 16);
;       }
;       {
;         float mine = b3 ? r2[1] : r2[0];
;         float other = b3 ? r2[0] : r2[1];
;         h = mine + __shfl_xor(other, 8);
;       }
;       h += __shfl_xor(h, 4);
;       h += __shfl_xor(h, 2);
;       h += __shfl_xor(h, 1);
	v_cvt_pk_f32_fp8_sdwa v[220:221], v169 src0_sel:WORD_1
	v_pk_mul_f32 v[222:223], v[32:33], v[214:215]
	v_pk_mul_f32 v[224:225], v[34:35], v[216:217]
	v_cvt_pk_f32_fp8_e32 v[214:215], v170
	v_cvt_pk_f32_fp8_sdwa v[216:217], v170 src0_sel:WORD_1
	v_pk_fma_f32 v[222:223], v[36:37], v[218:219], v[222:223]
	v_pk_fma_f32 v[224:225], v[38:39], v[220:221], v[224:225]
	v_cvt_pk_f32_fp8_e32 v[218:219], v171
	v_cvt_pk_f32_fp8_sdwa v[220:221], v171 src0_sel:WORD_1
	v_pk_fma_f32 v[222:223], v[40:41], v[214:215], v[222:223]
	v_pk_fma_f32 v[224:225], v[42:43], v[216:217], v[224:225]
	v_pk_fma_f32 v[222:223], v[44:45], v[218:219], v[222:223]
	v_pk_fma_f32 v[224:225], v[46:47], v[220:221], v[224:225]
	v_pk_add_f32 v[222:223], v[222:223], v[224:225]
	s_nop 0
	v_add_f32_e32 v232, v222, v223
	v_cvt_pk_f32_fp8_e32 v[214:215], v172
	v_cvt_pk_f32_fp8_sdwa v[216:217], v172 src0_sel:WORD_1
	v_cvt_pk_f32_fp8_e32 v[218:219], v173
	v_cvt_pk_f32_fp8_sdwa v[220:221], v173 src0_sel:WORD_1
	v_pk_mul_f32 v[222:223], v[32:33], v[214:215]
	v_pk_mul_f32 v[224:225], v[34:35], v[216:217]
	v_cvt_pk_f32_fp8_e32 v[214:215], v174
	v_cvt_pk_f32_fp8_sdwa v[216:217], v174 src0_sel:WORD_1
	v_pk_fma_f32 v[222:223], v[36:37], v[218:219], v[222:223]
	v_pk_fma_f32 v[224:225], v[38:39], v[220:221], v[224:225]
	v_cvt_pk_f32_fp8_e32 v[218:219], v175
	v_cvt_pk_f32_fp8_sdwa v[220:221], v175 src0_sel:WORD_1
	v_pk_fma_f32 v[222:223], v[40:41], v[214:215], v[222:223]
	v_pk_fma_f32 v[224:225], v[42:43], v[216:217], v[224:225]
	v_pk_fma_f32 v[222:223], v[44:45], v[218:219], v[222:223]
	v_pk_fma_f32 v[224:225], v[46:47], v[220:221], v[224:225]
	v_pk_add_f32 v[222:223], v[222:223], v[224:225]
	s_nop 0
	v_add_f32_e32 v233, v222, v223
	v_permlane32_swap_b32_e32 v226, v230
	v_permlane32_swap_b32_e32 v227, v231
	v_permlane32_swap_b32_e32 v228, v232
	v_permlane32_swap_b32_e32 v229, v233
	v_add_f32_e32 v226, v226, v230
	v_add_f32_e32 v228, v228, v232
	v_add_f32_e32 v227, v227, v231
	v_add_f32_e32 v229, v229, v233
	s_nop 1
	v_permlane16_swap_b32_e32 v226, v228
	v_permlane16_swap_b32_e32 v227, v229
	v_add_f32_e32 v226, v226, v228
	v_add_f32_e32 v227, v227, v229
	s_nop 0
	v_cndmask_b32_e64 v230, v226, v227, s[24:25]
	v_cndmask_b32_e64 v231, v227, v226, s[24:25]
	s_nop 1
	v_add_f32_dpp v232, v231, v230 row_ror:8 row_mask:0xf bank_mask:0xf
	s_nop 1
	v_add_f32_dpp v233, v232, v232 quad_perm:[1,0,3,2] row_mask:0xf bank_mask:0xf
	s_nop 1
	v_add_f32_dpp v232, v233, v233 quad_perm:[2,3,0,1] row_mask:0xf bank_mask:0xf
	s_nop 1
	v_add_f32_dpp v233, v232, v232 row_half_mirror row_mask:0xf bank_mask:0xf
	ds_write_b32 v235, v233 offset:33824
	v_readlane_b32 s48, v137, s72
	v_readlane_b32 s49, v137, s73
	v_readlane_b32 s50, v137, s74
	v_readlane_b32 s51, v137, s75
	v_readlane_b32 s52, v137, s76
	v_readlane_b32 s53, v137, s77
	v_readlane_b32 s54, v137, s78
	v_readlane_b32 s55, v137, s79
	s_add_u32 s32, s0, s48
	s_addc_u32 s33, s1, 0
	s_add_u32 s34, s0, s49
	s_addc_u32 s35, s1, 0
	s_add_u32 s36, s0, s50
	s_addc_u32 s37, s1, 0
	s_add_u32 s38, s0, s51
	s_addc_u32 s39, s1, 0
	s_add_u32 s40, s0, s52
	s_addc_u32 s41, s1, 0
	s_add_u32 s42, s0, s53
	s_addc_u32 s43, s1, 0
	s_add_u32 s44, s0, s54
	s_addc_u32 s45, s1, 0
	s_add_u32 s46, s0, s55
	s_addc_u32 s47, s1, 0
	global_load_dwordx4 v[144:147], v234, s[32:33]
	global_load_dwordx4 v[148:151], v234, s[34:35]
	global_load_dwordx4 v[152:155], v234, s[36:37]
	global_load_dwordx4 v[156:159], v234, s[38:39]
	global_load_dwordx4 v[160:163], v234, s[40:41]
	global_load_dwordx4 v[164:167], v234, s[42:43]
	global_load_dwordx4 v[168:171], v234, s[44:45]
	global_load_dwordx4 v[172:175], v234, s[46:47]
	s_waitcnt vmcnt(8)
	v_cvt_pk_f32_fp8_e32 v[214:215], v176
	v_cvt_pk_f32_fp8_sdwa v[216:217], v176 src0_sel:WORD_1
	v_cvt_pk_f32_fp8_e32 v[218:219], v177
	v_cvt_pk_f32_fp8_sdwa v[220:221], v177 src0_sel:WORD_1
	v_pk_mul_f32 v[222:223], v[48:49], v[214:215]
	v_pk_mul_f32 v[224:225], v[50:51], v[216:217]
	v_cvt_pk_f32_fp8_e32 v[214:215], v178
	v_cvt_pk_f32_fp8_sdwa v[216:217], v178 src0_sel:WORD_1
	v_pk_fma_f32 v[222:223], v[52:53], v[218:219], v[222:223]
	v_pk_fma_f32 v[224:225], v[54:55], v[220:221], v[224:225]
	v_cvt_pk_f32_fp8_e32 v[218:219], v179
	v_cvt_pk_f32_fp8_sdwa v[220:221], v179 src0_sel:WORD_1
	v_pk_fma_f32 v[222:223], v[56:57], v[214:215], v[222:223]
	v_pk_fma_f32 v[224:225], v[58:59], v[216:217], v[224:225]
	v_pk_fma_f32 v[222:223], v[60:61], v[218:219], v[222:223]
	v_pk_fma_f32 v[224:225], v[62:63], v[220:221], v[224:225]
	v_pk_add_f32 v[222:223], v[222:223], v[224:225]
	s_nop 0
	v_add_f32_e32 v226, v222, v223
	v_cvt_pk_f32_fp8_e32 v[214:215], v180
	v_cvt_pk_f32_fp8_sdwa v[216:217], v180 src0_sel:WORD_1
	v_cvt_pk_f32_fp8_e32 v[218:219], v181
	v_cvt_pk_f32_fp8_sdwa v[220:221], v181 src0_sel:WORD_1
	v_pk_mul_f32 v[222:223], v[48:49], v[214:215]
	v_pk_mul_f32 v[224:225], v[50:51], v[216:217]
	v_cvt_pk_f32_fp8_e32 v[214:215], v182
	v_cvt_pk_f32_fp8_sdwa v[216:217], v182 src0_sel:WORD_1
	v_pk_fma_f32 v[222:223], v[52:53], v[218:219], v[222:223]
	v_pk_fma_f32 v[224:225], v[54:55], v[220:221], v[224:225]
	v_cvt_pk_f32_fp8_e32 v[218:219], v183
	v_cvt_pk_f32_fp8_sdwa v[220:221], v183 src0_sel:WORD_1
	v_pk_fma_f32 v[222:223], v[56:57], v[214:215], v[222:223]
	v_pk_fma_f32 v[224:225], v[58:59], v[216:217], v[224:225]
	v_pk_fma_f32 v[222:223], v[60:61], v[218:219], v[222:223]
	v_pk_fma_f32 v[224:225], v[62:63], v[220:221], v[224:225]
	v_pk_add_f32 v[222:223], v[222:223], v[224:225]
	s_nop 0
	v_add_f32_e32 v227, v222, v223
	v_cvt_pk_f32_fp8_e32 v[214:215], v184
	v_cvt_pk_f32_fp8_sdwa v[216:217], v184 src0_sel:WORD_1
	v_cvt_pk_f32_fp8_e32 v[218:219], v185
	v_cvt_pk_f32_fp8_sdwa v[220:221], v185 src0_sel:WORD_1
; template <bool STORE>
; DI void peer_item(const Params& p, int item, char* smem) {
;     ...
; #pragma unroll
;       for (int u = 0; u < 8; ++u) {
;         float d = 0.f;
; #pragma unroll
;         for (int i = 0; i < 4; ++i) {
;           f32x2_t lo = __builtin_amdgcn_cvt_pk_f32_fp8((int)uq[u][i], false);
;           f32x2_t hi = __builtin_amdgcn_cvt_pk_f32_fp8((int)uq[u][i], true);
;           d += xf[4 * i] * lo.x + xf[4 * i + 1] * lo.y + xf[4 * i + 2] * hi.x + xf[4 * i + 3] * hi.y;
;         }
;         part[u] = d;
;       }
;       float q4[4], r2[2], h;
; #pragma unroll
;       for (int j = 0; j < 4; ++j) {
;         float mine = b5 ? part[j + 4] : part[j];
;         float other = b5 ? part[j] : part[j + 4];
;         q4[j] = mine + __shfl_xor(other, 32);
;       }
	v_pk_mul_f32 v[222:223], v[48:49], v[214:215]
	v_pk_mul_f32 v[224:225], v[50:51], v[216:217]
	v_cvt_pk_f32_fp8_e32 v[214:215], v186
	v_cvt_pk_f32_fp8_sdwa v[216:217], v186 src0_sel:WORD_1
	v_pk_fma_f32 v[222:223], v[52:53], v[218:219], v[222:223]
	v_pk_fma_f32 v[224:225], v[54:55], v[220:221], v[224:225]
	v_cvt_pk_f32_fp8_e32 v[218:219], v187
	v_cvt_pk_f32_fp8_sdwa v[220:221], v187 src0_sel:WORD_1
	v_pk_fma_f32 v[222:223], v[56:57], v[214:215], v[222:223]
	v_pk_fma_f32 v[224:225], v[58:59], v[216:217], v[224:225]
	v_pk_fma_f32 v[222:223], v[60:61], v[218:219], v[222:223]
	v_pk_fma_f32 v[224:225], v[62:63], v[220:221], v[224:225]
	v_pk_add_f32 v[222:223], v[222:223], v[224:225]
	s_nop 0
	v_add_f32_e32 v228, v222, v223
	v_cvt_pk_f32_fp8_e32 v[214:215], v188
	v_cvt_pk_f32_fp8_sdwa v[216:217], v188 src0_sel:WORD_1
	v_cvt_pk_f32_fp8_e32 v[218:219], v189
	v_cvt_pk_f32_fp8_sdwa v[220:221], v189 src0_sel:WORD_1
	v_pk_mul_f32 v[222:223], v[48:49], v[214:215]
	v_pk_mul_f32 v[224:225], v[50:51], v[216:217]
	v_cvt_pk_f32_fp8_e32 v[214:215], v190
	v_cvt_pk_f32_fp8_sdwa v[216:217], v190 src0_sel:WORD_1
	v_pk_fma_f32 v[222:223], v[52:53], v[218:219], v[222:223]
	v_pk_fma_f32 v[224:225], v[54:55], v[220:221], v[224:225]
	v_cvt_pk_f32_fp8_e32 v[218:219], v191
	v_cvt_pk_f32_fp8_sdwa v[220:221], v191 src0_sel:WORD_1
	v_pk_fma_f32 v[222:223], v[56:57], v[214:215], v[222:223]
	v_pk_fma_f32 v[224:225], v[58:59], v[216:217], v[224:225]
	v_pk_fma_f32 v[222:223], v[60:61], v[218:219], v[222:223]
	v_pk_fma_f32 v[224:225], v[62:63], v[220:221], v[224:225]
	v_pk_add_f32 v[222:223], v[222:223], v[224:225]
	s_nop 0
	v_add_f32_e32 v229, v222, v223
	v_cvt_pk_f32_fp8_e32 v[214:215], v192
	v_cvt_pk_f32_fp8_sdwa v[216:217], v192 src0_sel:WORD_1
	v_cvt_pk_f32_fp8_e32 v[218:219], v193
	v_cvt_pk_f32_fp8_sdwa v[220:221], v193 src0_sel:WORD_1
	v_pk_mul_f32 v[222:223], v[48:49], v[214:215]
	v_pk_mul_f32 v[224:225], v[50:51], v[216:217]
	v_cvt_pk_f32_fp8_e32 v[214:215], v194
	v_cvt_pk_f32_fp8_sdwa v[216:217], v194 src0_sel:WORD_1
	v_pk_fma_f32 v[222:223], v[52:53], v[218:219], v[222:223]
	v_pk_fma_f32 v[224:225], v[54:55], v[220:221], v[224:225]
	v_cvt_pk_f32_fp8_e32 v[218:219], v195
	v_cvt_pk_f32_fp8_sdwa v[220:221], v195 src0_sel:WORD_1
	v_pk_fma_f32 v[222:223], v[56:57], v[214:215], v[222:223]
	v_pk_fma_f32 v[224:225], v[58:59], v[216:217], v[224:225]
	v_pk_fma_f32 v[222:223], v[60:61], v[218:219], v[222:223]
	v_pk_fma_f32 v[224:225], v[62:63], v[220:221], v[224:225]
	v_pk_add_f32 v[222:223], v[222:223], v[224:225]
	s_nop 0
	v_add_f32_e32 v230, v222, v223
	v_cvt_pk_f32_fp8_e32 v[214:215], v196
	v_cvt_pk_f32_fp8_sdwa v[216:217], v196 src0_sel:WORD_1
	v_cvt_pk_f32_fp8_e32 v[218:219], v197
	v_cvt_pk_f32_fp8_sdwa v[220:221], v197 src0_sel:WORD_1
	v_pk_mul_f32 v[222:223], v[48:49], v[214:215]
	v_pk_mul_f32 v[224:225], v[50:51], v[216:217]
	v_cvt_pk_f32_fp8_e32 v[214:215], v198
	v_cvt_pk_f32_fp8_sdwa v[216:217], v198 src0_sel:WORD_1
	v_pk_fma_f32 v[222:223], v[52:53], v[218:219], v[222:223]
	v_pk_fma_f32 v[224:225], v[54:55], v[220:221], v[224:225]
	v_cvt_pk_f32_fp8_e32 v[218:219], v199
	v_cvt_pk_f32_fp8_sdwa v[220:221], v199 src0_sel:WORD_1
	v_pk_fma_f32 v[222:223], v[56:57], v[214:215], v[222:223]
	v_pk_fma_f32 v[224:225], v[58:59], v[216:217], v[224:225]
	v_pk_fma_f32 v[222:223], v[60:61], v[218:219], v[222:223]
	v_pk_fma_f32 v[224:225], v[62:63], v[220:221], v[224:225]
	v_pk_add_f32 v[222:223], v[222:223], v[224:225]
	s_nop 0
	v_add_f32_e32 v231, v222, v223
	v_cvt_pk_f32_fp8_e32 v[214:215], v200
	v_cvt_pk_f32_fp8_sdwa v[216:217], v200 src0_sel:WORD_1
	v_cvt_pk_f32_fp8_e32 v[218:219], v201
	v_cvt_pk_f32_fp8_sdwa v[220:221], v201 src0_sel:WORD_1
	v_pk_mul_f32 v[222:223], v[48:49], v[214:215]
	v_pk_mul_f32 v[224:225], v[50:51], v[216:217]
	v_cvt_pk_f32_fp8_e32 v[214:215], v202
	v_cvt_pk_f32_fp8_sdwa v[216:217], v202 src0_sel:WORD_1
	v_pk_fma_f32 v[222:223], v[52:53], v[218:219], v[222:223]
	v_pk_fma_f32 v[224:225], v[54:55], v[220:221], v[224:225]
	v_cvt_pk_f32_fp8_e32 v[218:219], v203
	v_cvt_pk_f32_fp8_sdwa v[220:221], v203 src0_sel:WORD_1
	v_pk_fma_f32 v[222:223], v[56:57], v[214:215], v[222:223]
	v_pk_fma_f32 v[224:225], v[58:59], v[216:217], v[224:225]
	v_pk_fma_f32 v[222:223], v[60:61], v[218:219], v[222:223]
	v_pk_fma_f32 v[224:225], v[62:63], v[220:221], v[224:225]
	v_pk_add_f32 v[222:223], v[222:223], v[224:225]
	s_nop 0
	v_add_f32_e32 v232, v222, v223
	v_cvt_pk_f32_fp8_e32 v[214:215], v204
	v_cvt_pk_f32_fp8_sdwa v[216:217], v204 src0_sel:WORD_1
	v_cvt_pk_f32_fp8_e32 v[218:219], v205
	v_cvt_pk_f32_fp8_sdwa v[220:221], v205 src0_sel:WORD_1
	v_pk_mul_f32 v[222:223], v[48:49], v[214:215]
	v_pk_mul_f32 v[224:225], v[50:51], v[216:217]
	v_cvt_pk_f32_fp8_e32 v[214:215], v206
	v_cvt_pk_f32_fp8_sdwa v[216:217], v206 src0_sel:WORD_1
	v_pk_fma_f32 v[222:223], v[52:53], v[218:219], v[222:223]
	v_pk_fma_f32 v[224:225], v[54:55], v[220:221], v[224:225]
	v_cvt_pk_f32_fp8_e32 v[218:219], v207
	v_cvt_pk_f32_fp8_sdwa v[220:221], v207 src0_sel:WORD_1
	v_pk_fma_f32 v[222:223], v[56:57], v[214:215], v[222:223]
	v_pk_fma_f32 v[224:225], v[58:59], v[216:217], v[224:225]
	v_pk_fma_f32 v[222:223], v[60:61], v[218:219], v[222:223]
	v_pk_fma_f32 v[224:225], v[62:63], v[220:221], v[224:225]
	v_pk_add_f32 v[222:223], v[222:223], v[224:225]
	s_nop 0
	v_add_f32_e32 v233, v222, v223
	v_permlane32_swap_b32_e32 v226, v230
	v_permlane32_swap_b32_e32 v227, v231
	v_permlane32_swap_b32_e32 v228, v232
	v_permlane32_swap_b32_e32 v229, v233
	v_add_f32_e32 v226, v226, v230
	v_add_f32_e32 v228, v228, v232
	v_add_f32_e32 v227, v227, v231
	v_add_f32_e32 v229, v229, v233
	s_nop 1
	v_permlane16_swap_b32_e32 v226, v228
; template <bool STORE>
; DI void peer_item(const Params& p, int item, char* smem) {
;     ...
; #pragma unroll
;       for (int u = 0; u < 8; ++u) {
;         int e = e_s[tl * 128 + k + u];
;         uq[u] = *(const u32x4*)(U8 + (size_t)e * 1024 + lane * 16);
;       }
;       float part[8];
; #pragma unroll
;       for (int u = 0; u < 8; ++u) {
;         float d = 0.f;
; #pragma unroll
;         for (int i = 0; i < 4; ++i) {
;           f32x2_t lo = __builtin_amdgcn_cvt_pk_f32_fp8((int)uq[u][i], false);
;           f32x2_t hi = __builtin_amdgcn_cvt_pk_f32_fp8((int)uq[u][i], true);
;           d += xf[4 * i] * lo.x + xf[4 * i + 1] * lo.y + xf[4 * i + 2] * hi.x + xf[4 * i + 3] * hi.y;
;         }
;         part[u] = d;
;       }
;       float q4[4], r2[2], h;
; #pragma unroll
;       for (int j = 0; j < 4; ++j) {
;         float mine = b5 ? part[j + 4] : part[j];
;         float other = b5 ? part[j] : part[j + 4];
;         q4[j] = mine + __shfl_xor(other, 32);
;       }
; #pragma unroll
;       for (int j = 0; j < 2; ++j) {
;         float mine = b4 ? q4[j + 2] : q4[j];
;         float other = b4 ? q4[j] : q4[j + 2];
;         r2[j] = mine + __shfl_xor(other, 16);
;       }
;       {
;         float mine = b3 ? r2[1] : r2[0];
;         float other = b3 ? r2[0] : r2[1];
;         h = mine + __shfl_xor(other, 8);
;       }
;       h += __shfl_xor(h, 4);
;       h += __shfl_xor(h, 2);
;       h += __shfl_xor(h, 1);
	v_permlane16_swap_b32_e32 v227, v229
	v_add_f32_e32 v226, v226, v228
	v_add_f32_e32 v227, v227, v229
	s_nop 0
	v_cndmask_b32_e64 v230, v226, v227, s[24:25]
	v_cndmask_b32_e64 v231, v227, v226, s[24:25]
	s_nop 1
	v_add_f32_dpp v232, v231, v230 row_ror:8 row_mask:0xf bank_mask:0xf
	s_nop 1
	v_add_f32_dpp v233, v232, v232 quad_perm:[1,0,3,2] row_mask:0xf bank_mask:0xf
	s_nop 1
	v_add_f32_dpp v232, v233, v233 quad_perm:[2,3,0,1] row_mask:0xf bank_mask:0xf
	s_nop 1
	v_add_f32_dpp v233, v232, v232 row_half_mirror row_mask:0xf bank_mask:0xf
	ds_write_b32 v235, v233 offset:34336
	v_readlane_b32 s48, v139, s72
	v_readlane_b32 s49, v139, s73
	v_readlane_b32 s50, v139, s74
	v_readlane_b32 s51, v139, s75
	v_readlane_b32 s52, v139, s76
	v_readlane_b32 s53, v139, s77
	v_readlane_b32 s54, v139, s78
	v_readlane_b32 s55, v139, s79
	s_add_u32 s32, s0, s48
	s_addc_u32 s33, s1, 0
	s_add_u32 s34, s0, s49
	s_addc_u32 s35, s1, 0
	s_add_u32 s36, s0, s50
	s_addc_u32 s37, s1, 0
	s_add_u32 s38, s0, s51
	s_addc_u32 s39, s1, 0
	s_add_u32 s40, s0, s52
	s_addc_u32 s41, s1, 0
	s_add_u32 s42, s0, s53
	s_addc_u32 s43, s1, 0
	s_add_u32 s44, s0, s54
	s_addc_u32 s45, s1, 0
	s_add_u32 s46, s0, s55
	s_addc_u32 s47, s1, 0
	global_load_dwordx4 v[176:179], v234, s[32:33]
	global_load_dwordx4 v[180:183], v234, s[34:35]
	global_load_dwordx4 v[184:187], v234, s[36:37]
	global_load_dwordx4 v[188:191], v234, s[38:39]
	global_load_dwordx4 v[192:195], v234, s[40:41]
	global_load_dwordx4 v[196:199], v234, s[42:43]
	global_load_dwordx4 v[200:203], v234, s[44:45]
	global_load_dwordx4 v[204:207], v234, s[46:47]
	s_waitcnt vmcnt(8)
	v_cvt_pk_f32_fp8_e32 v[214:215], v144
	v_cvt_pk_f32_fp8_sdwa v[216:217], v144 src0_sel:WORD_1
	v_cvt_pk_f32_fp8_e32 v[218:219], v145
	v_cvt_pk_f32_fp8_sdwa v[220:221], v145 src0_sel:WORD_1
	v_pk_mul_f32 v[222:223], v[64:65], v[214:215]
	v_pk_mul_f32 v[224:225], v[66:67], v[216:217]
	v_cvt_pk_f32_fp8_e32 v[214:215], v146
	v_cvt_pk_f32_fp8_sdwa v[216:217], v146 src0_sel:WORD_1
	v_pk_fma_f32 v[222:223], v[68:69], v[218:219], v[222:223]
	v_pk_fma_f32 v[224:225], v[70:71], v[220:221], v[224:225]
	v_cvt_pk_f32_fp8_e32 v[218:219], v147
	v_cvt_pk_f32_fp8_sdwa v[220:221], v147 src0_sel:WORD_1
	v_pk_fma_f32 v[222:223], v[72:73], v[214:215], v[222:223]
	v_pk_fma_f32 v[224:225], v[74:75], v[216:217], v[224:225]
	v_pk_fma_f32 v[222:223], v[76:77], v[218:219], v[222:223]
	v_pk_fma_f32 v[224:225], v[78:79], v[220:221], v[224:225]
	v_pk_add_f32 v[222:223], v[222:223], v[224:225]
	s_nop 0
	v_add_f32_e32 v226, v222, v223
	v_cvt_pk_f32_fp8_e32 v[214:215], v148
	v_cvt_pk_f32_fp8_sdwa v[216:217], v148 src0_sel:WORD_1
	v_cvt_pk_f32_fp8_e32 v[218:219], v149
	v_cvt_pk_f32_fp8_sdwa v[220:221], v149 src0_sel:WORD_1
	v_pk_mul_f32 v[222:223], v[64:65], v[214:215]
	v_pk_mul_f32 v[224:225], v[66:67], v[216:217]
	v_cvt_pk_f32_fp8_e32 v[214:215], v150
	v_cvt_pk_f32_fp8_sdwa v[216:217], v150 src0_sel:WORD_1
	v_pk_fma_f32 v[222:223], v[68:69], v[218:219], v[222:223]
	v_pk_fma_f32 v[224:225], v[70:71], v[220:221], v[224:225]
	v_cvt_pk_f32_fp8_e32 v[218:219], v151
	v_cvt_pk_f32_fp8_sdwa v[220:221], v151 src0_sel:WORD_1
	v_pk_fma_f32 v[222:223], v[72:73], v[214:215], v[222:223]
	v_pk_fma_f32 v[224:225], v[74:75], v[216:217], v[224:225]
	v_pk_fma_f32 v[222:223], v[76:77], v[218:219], v[222:223]
	v_pk_fma_f32 v[224:225], v[78:79], v[220:221], v[224:225]
	v_pk_add_f32 v[222:223], v[222:223], v[224:225]
	s_nop 0
	v_add_f32_e32 v227, v222, v223
	v_cvt_pk_f32_fp8_e32 v[214:215], v152
	v_cvt_pk_f32_fp8_sdwa v[216:217], v152 src0_sel:WORD_1
	v_cvt_pk_f32_fp8_e32 v[218:219], v153
	v_cvt_pk_f32_fp8_sdwa v[220:221], v153 src0_sel:WORD_1
	v_pk_mul_f32 v[222:223], v[64:65], v[214:215]
	v_pk_mul_f32 v[224:225], v[66:67], v[216:217]
	v_cvt_pk_f32_fp8_e32 v[214:215], v154
	v_cvt_pk_f32_fp8_sdwa v[216:217], v154 src0_sel:WORD_1
	v_pk_fma_f32 v[222:223], v[68:69], v[218:219], v[222:223]
	v_pk_fma_f32 v[224:225], v[70:71], v[220:221], v[224:225]
	v_cvt_pk_f32_fp8_e32 v[218:219], v155
	v_cvt_pk_f32_fp8_sdwa v[220:221], v155 src0_sel:WORD_1
	v_pk_fma_f32 v[222:223], v[72:73], v[214:215], v[222:223]
	v_pk_fma_f32 v[224:225], v[74:75], v[216:217], v[224:225]
	v_pk_fma_f32 v[222:223], v[76:77], v[218:219], v[222:223]
	v_pk_fma_f32 v[224:225], v[78:79], v[220:221], v[224:225]
	v_pk_add_f32 v[222:223], v[222:223], v[224:225]
	s_nop 0
	v_add_f32_e32 v228, v222, v223
	v_cvt_pk_f32_fp8_e32 v[214:215], v156
	v_cvt_pk_f32_fp8_sdwa v[216:217], v156 src0_sel:WORD_1
	v_cvt_pk_f32_fp8_e32 v[218:219], v157
	v_cvt_pk_f32_fp8_sdwa v[220:221], v157 src0_sel:WORD_1
	v_pk_mul_f32 v[222:223], v[64:65], v[214:215]
	v_pk_mul_f32 v[224:225], v[66:67], v[216:217]
	v_cvt_pk_f32_fp8_e32 v[214:215], v158
	v_cvt_pk_f32_fp8_sdwa v[216:217], v158 src0_sel:WORD_1
	v_pk_fma_f32 v[222:223], v[68:69], v[218:219], v[222:223]
	v_pk_fma_f32 v[224:225], v[70:71], v[220:221], v[224:225]
	v_cvt_pk_f32_fp8_e32 v[218:219], v159
	v_cvt_pk_f32_fp8_sdwa v[220:221], v159 src0_sel:WORD_1
	v_pk_fma_f32 v[222:223], v[72:73], v[214:215], v[222:223]
	v_pk_fma_f32 v[224:225], v[74:75], v[216:217], v[224:225]
	v_pk_fma_f32 v[222:223], v[76:77], v[218:219], v[222:223]
	v_pk_fma_f32 v[224:225], v[78:79], v[220:221], v[224:225]
	v_pk_add_f32 v[222:223], v[222:223], v[224:225]
	s_nop 0
	v_add_f32_e32 v229, v222, v223
	v_cvt_pk_f32_fp8_e32 v[214:215], v160
	v_cvt_pk_f32_fp8_sdwa v[216:217], v160 src0_sel:WORD_1
	v_cvt_pk_f32_fp8_e32 v[218:219], v161
	v_cvt_pk_f32_fp8_sdwa v[220:221], v161 src0_sel:WORD_1
	v_pk_mul_f32 v[222:223], v[64:65], v[214:215]
	v_pk_mul_f32 v[224:225], v[66:67], v[216:217]
	v_cvt_pk_f32_fp8_e32 v[214:215], v162
	v_cvt_pk_f32_fp8_sdwa v[216:217], v162 src0_sel:WORD_1
; template <bool STORE>
; DI void peer_item(const Params& p, int item, char* smem) {
;     ...
; #pragma unroll
;       for (int u = 0; u < 8; ++u) {
;         int e = e_s[tl * 128 + k + u];
;         uq[u] = *(const u32x4*)(U8 + (size_t)e * 1024 + lane * 16);
;       }
;       float part[8];
; #pragma unroll
;       for (int u = 0; u < 8; ++u) {
;         float d = 0.f;
; #pragma unroll
;         for (int i = 0; i < 4; ++i) {
;           f32x2_t lo = __builtin_amdgcn_cvt_pk_f32_fp8((int)uq[u][i], false);
;           f32x2_t hi = __builtin_amdgcn_cvt_pk_f32_fp8((int)uq[u][i], true);
;           d += xf[4 * i] * lo.x + xf[4 * i + 1] * lo.y + xf[4 * i + 2] * hi.x + xf[4 * i + 3] * hi.y;
;         }
;         part[u] = d;
;       }
;       float q4[4], r2[2], h;
; #pragma unroll
;       for (int j = 0; j < 4; ++j) {
;         float mine = b5 ? part[j + 4] : part[j];
;         float other = b5 ? part[j] : part[j + 4];
;         q4[j] = mine + __shfl_xor(other, 32);
;       }
; #pragma unroll
;       for (int j = 0; j < 2; ++j) {
;         float mine = b4 ? q4[j + 2] : q4[j];
;         float other = b4 ? q4[j] : q4[j + 2];
;         r2[j] = mine + __shfl_xor(other, 16);
;       }
;       {
;         float mine = b3 ? r2[1] : r2[0];
;         float other = b3 ? r2[0] : r2[1];
;         h = mine + __shfl_xor(other, 8);
;       }
;       h += __shfl_xor(h, 4);
;       h += __shfl_xor(h, 2);
;       h += __shfl_xor(h, 1);
	v_pk_fma_f32 v[222:223], v[68:69], v[218:219], v[222:223]
	v_pk_fma_f32 v[224:225], v[70:71], v[220:221], v[224:225]
	v_cvt_pk_f32_fp8_e32 v[218:219], v163
	v_cvt_pk_f32_fp8_sdwa v[220:221], v163 src0_sel:WORD_1
	v_pk_fma_f32 v[222:223], v[72:73], v[214:215], v[222:223]
	v_pk_fma_f32 v[224:225], v[74:75], v[216:217], v[224:225]
	v_pk_fma_f32 v[222:223], v[76:77], v[218:219], v[222:223]
	v_pk_fma_f32 v[224:225], v[78:79], v[220:221], v[224:225]
	v_pk_add_f32 v[222:223], v[222:223], v[224:225]
	s_nop 0
	v_add_f32_e32 v230, v222, v223
	v_cvt_pk_f32_fp8_e32 v[214:215], v164
	v_cvt_pk_f32_fp8_sdwa v[216:217], v164 src0_sel:WORD_1
	v_cvt_pk_f32_fp8_e32 v[218:219], v165
	v_cvt_pk_f32_fp8_sdwa v[220:221], v165 src0_sel:WORD_1
	v_pk_mul_f32 v[222:223], v[64:65], v[214:215]
	v_pk_mul_f32 v[224:225], v[66:67], v[216:217]
	v_cvt_pk_f32_fp8_e32 v[214:215], v166
	v_cvt_pk_f32_fp8_sdwa v[216:217], v166 src0_sel:WORD_1
	v_pk_fma_f32 v[222:223], v[68:69], v[218:219], v[222:223]
	v_pk_fma_f32 v[224:225], v[70:71], v[220:221], v[224:225]
	v_cvt_pk_f32_fp8_e32 v[218:219], v167
	v_cvt_pk_f32_fp8_sdwa v[220:221], v167 src0_sel:WORD_1
	v_pk_fma_f32 v[222:223], v[72:73], v[214:215], v[222:223]
	v_pk_fma_f32 v[224:225], v[74:75], v[216:217], v[224:225]
	v_pk_fma_f32 v[222:223], v[76:77], v[218:219], v[222:223]
	v_pk_fma_f32 v[224:225], v[78:79], v[220:221], v[224:225]
	v_pk_add_f32 v[222:223], v[222:223], v[224:225]
	s_nop 0
	v_add_f32_e32 v231, v222, v223
	v_cvt_pk_f32_fp8_e32 v[214:215], v168
	v_cvt_pk_f32_fp8_sdwa v[216:217], v168 src0_sel:WORD_1
	v_cvt_pk_f32_fp8_e32 v[218:219], v169
	v_cvt_pk_f32_fp8_sdwa v[220:221], v169 src0_sel:WORD_1
	v_pk_mul_f32 v[222:223], v[64:65], v[214:215]
	v_pk_mul_f32 v[224:225], v[66:67], v[216:217]
	v_cvt_pk_f32_fp8_e32 v[214:215], v170
	v_cvt_pk_f32_fp8_sdwa v[216:217], v170 src0_sel:WORD_1
	v_pk_fma_f32 v[222:223], v[68:69], v[218:219], v[222:223]
	v_pk_fma_f32 v[224:225], v[70:71], v[220:221], v[224:225]
	v_cvt_pk_f32_fp8_e32 v[218:219], v171
	v_cvt_pk_f32_fp8_sdwa v[220:221], v171 src0_sel:WORD_1
	v_pk_fma_f32 v[222:223], v[72:73], v[214:215], v[222:223]
	v_pk_fma_f32 v[224:225], v[74:75], v[216:217], v[224:225]
	v_pk_fma_f32 v[222:223], v[76:77], v[218:219], v[222:223]
	v_pk_fma_f32 v[224:225], v[78:79], v[220:221], v[224:225]
	v_pk_add_f32 v[222:223], v[222:223], v[224:225]
	s_nop 0
	v_add_f32_e32 v232, v222, v223
	v_cvt_pk_f32_fp8_e32 v[214:215], v172
	v_cvt_pk_f32_fp8_sdwa v[216:217], v172 src0_sel:WORD_1
	v_cvt_pk_f32_fp8_e32 v[218:219], v173
	v_cvt_pk_f32_fp8_sdwa v[220:221], v173 src0_sel:WORD_1
	v_pk_mul_f32 v[222:223], v[64:65], v[214:215]
	v_pk_mul_f32 v[224:225], v[66:67], v[216:217]
	v_cvt_pk_f32_fp8_e32 v[214:215], v174
	v_cvt_pk_f32_fp8_sdwa v[216:217], v174 src0_sel:WORD_1
	v_pk_fma_f32 v[222:223], v[68:69], v[218:219], v[222:223]
	v_pk_fma_f32 v[224:225], v[70:71], v[220:221], v[224:225]
	v_cvt_pk_f32_fp8_e32 v[218:219], v175
	v_cvt_pk_f32_fp8_sdwa v[220:221], v175 src0_sel:WORD_1
	v_pk_fma_f32 v[222:223], v[72:73], v[214:215], v[222:223]
	v_pk_fma_f32 v[224:225], v[74:75], v[216:217], v[224:225]
	v_pk_fma_f32 v[222:223], v[76:77], v[218:219], v[222:223]
	v_pk_fma_f32 v[224:225], v[78:79], v[220:221], v[224:225]
	v_pk_add_f32 v[222:223], v[222:223], v[224:225]
	s_nop 0
	v_add_f32_e32 v233, v222, v223
	v_permlane32_swap_b32_e32 v226, v230
	v_permlane32_swap_b32_e32 v227, v231
	v_permlane32_swap_b32_e32 v228, v232
	v_permlane32_swap_b32_e32 v229, v233
	v_add_f32_e32 v226, v226, v230
	v_add_f32_e32 v228, v228, v232
	v_add_f32_e32 v227, v227, v231
	v_add_f32_e32 v229, v229, v233
	s_nop 1
	v_permlane16_swap_b32_e32 v226, v228
	v_permlane16_swap_b32_e32 v227, v229
	v_add_f32_e32 v226, v226, v228
	v_add_f32_e32 v227, v227, v229
	s_nop 0
	v_cndmask_b32_e64 v230, v226, v227, s[24:25]
	v_cndmask_b32_e64 v231, v227, v226, s[24:25]
	s_nop 1
	v_add_f32_dpp v232, v231, v230 row_ror:8 row_mask:0xf bank_mask:0xf
	s_nop 1
	v_add_f32_dpp v233, v232, v232 quad_perm:[1,0,3,2] row_mask:0xf bank_mask:0xf
	s_nop 1
	v_add_f32_dpp v232, v233, v233 quad_perm:[2,3,0,1] row_mask:0xf bank_mask:0xf
	s_nop 1
	v_add_f32_dpp v233, v232, v232 row_half_mirror row_mask:0xf bank_mask:0xf
	ds_write_b32 v235, v233 offset:34848
	v_readlane_b32 s48, v141, s72
	v_readlane_b32 s49, v141, s73
	v_readlane_b32 s50, v141, s74
	v_readlane_b32 s51, v141, s75
	v_readlane_b32 s52, v141, s76
	v_readlane_b32 s53, v141, s77
	v_readlane_b32 s54, v141, s78
	v_readlane_b32 s55, v141, s79
	s_add_u32 s32, s0, s48
	s_addc_u32 s33, s1, 0
	s_add_u32 s34, s0, s49
	s_addc_u32 s35, s1, 0
	s_add_u32 s36, s0, s50
	s_addc_u32 s37, s1, 0
	s_add_u32 s38, s0, s51
	s_addc_u32 s39, s1, 0
	s_add_u32 s40, s0, s52
	s_addc_u32 s41, s1, 0
	s_add_u32 s42, s0, s53
	s_addc_u32 s43, s1, 0
	s_add_u32 s44, s0, s54
	s_addc_u32 s45, s1, 0
	s_add_u32 s46, s0, s55
	s_addc_u32 s47, s1, 0
	global_load_dwordx4 v[144:147], v234, s[32:33]
	global_load_dwordx4 v[148:151], v234, s[34:35]
	global_load_dwordx4 v[152:155], v234, s[36:37]
	global_load_dwordx4 v[156:159], v234, s[38:39]
	global_load_dwordx4 v[160:163], v234, s[40:41]
	global_load_dwordx4 v[164:167], v234, s[42:43]
	global_load_dwordx4 v[168:171], v234, s[44:45]
	global_load_dwordx4 v[172:175], v234, s[46:47]
	s_waitcnt vmcnt(8)
; template <bool STORE>
; DI void peer_item(const Params& p, int item, char* smem) {
;     ...
; #pragma unroll
;       for (int u = 0; u < 8; ++u) {
;         float d = 0.f;
; #pragma unroll
;         for (int i = 0; i < 4; ++i) {
;           f32x2_t lo = __builtin_amdgcn_cvt_pk_f32_fp8((int)uq[u][i], false);
;           f32x2_t hi = __builtin_amdgcn_cvt_pk_f32_fp8((int)uq[u][i], true);
;           d += xf[4 * i] * lo.x + xf[4 * i + 1] * lo.y + xf[4 * i + 2] * hi.x + xf[4 * i + 3] * hi.y;
;         }
;         part[u] = d;
;       }
	v_cvt_pk_f32_fp8_e32 v[214:215], v176
	v_cvt_pk_f32_fp8_sdwa v[216:217], v176 src0_sel:WORD_1
	v_cvt_pk_f32_fp8_e32 v[218:219], v177
	v_cvt_pk_f32_fp8_sdwa v[220:221], v177 src0_sel:WORD_1
	v_pk_mul_f32 v[222:223], v[80:81], v[214:215]
	v_pk_mul_f32 v[224:225], v[82:83], v[216:217]
	v_cvt_pk_f32_fp8_e32 v[214:215], v178
	v_cvt_pk_f32_fp8_sdwa v[216:217], v178 src0_sel:WORD_1
	v_pk_fma_f32 v[222:223], v[84:85], v[218:219], v[222:223]
	v_pk_fma_f32 v[224:225], v[86:87], v[220:221], v[224:225]
	v_cvt_pk_f32_fp8_e32 v[218:219], v179
	v_cvt_pk_f32_fp8_sdwa v[220:221], v179 src0_sel:WORD_1
	v_pk_fma_f32 v[222:223], v[88:89], v[214:215], v[222:223]
	v_pk_fma_f32 v[224:225], v[90:91], v[216:217], v[224:225]
	v_pk_fma_f32 v[222:223], v[92:93], v[218:219], v[222:223]
	v_pk_fma_f32 v[224:225], v[94:95], v[220:221], v[224:225]
	v_pk_add_f32 v[222:223], v[222:223], v[224:225]
	s_nop 0
	v_add_f32_e32 v226, v222, v223
	v_cvt_pk_f32_fp8_e32 v[214:215], v180
	v_cvt_pk_f32_fp8_sdwa v[216:217], v180 src0_sel:WORD_1
	v_cvt_pk_f32_fp8_e32 v[218:219], v181
	v_cvt_pk_f32_fp8_sdwa v[220:221], v181 src0_sel:WORD_1
	v_pk_mul_f32 v[222:223], v[80:81], v[214:215]
	v_pk_mul_f32 v[224:225], v[82:83], v[216:217]
	v_cvt_pk_f32_fp8_e32 v[214:215], v182
	v_cvt_pk_f32_fp8_sdwa v[216:217], v182 src0_sel:WORD_1
	v_pk_fma_f32 v[222:223], v[84:85], v[218:219], v[222:223]
	v_pk_fma_f32 v[224:225], v[86:87], v[220:221], v[224:225]
	v_cvt_pk_f32_fp8_e32 v[218:219], v183
	v_cvt_pk_f32_fp8_sdwa v[220:221], v183 src0_sel:WORD_1
	v_pk_fma_f32 v[222:223], v[88:89], v[214:215], v[222:223]
	v_pk_fma_f32 v[224:225], v[90:91], v[216:217], v[224:225]
	v_pk_fma_f32 v[222:223], v[92:93], v[218:219], v[222:223]
	v_pk_fma_f32 v[224:225], v[94:95], v[220:221], v[224:225]
	v_pk_add_f32 v[222:223], v[222:223], v[224:225]
	s_nop 0
	v_add_f32_e32 v227, v222, v223
	v_cvt_pk_f32_fp8_e32 v[214:215], v184
	v_cvt_pk_f32_fp8_sdwa v[216:217], v184 src0_sel:WORD_1
	v_cvt_pk_f32_fp8_e32 v[218:219], v185
	v_cvt_pk_f32_fp8_sdwa v[220:221], v185 src0_sel:WORD_1
	v_pk_mul_f32 v[222:223], v[80:81], v[214:215]
	v_pk_mul_f32 v[224:225], v[82:83], v[216:217]
	v_cvt_pk_f32_fp8_e32 v[214:215], v186
	v_cvt_pk_f32_fp8_sdwa v[216:217], v186 src0_sel:WORD_1
	v_pk_fma_f32 v[222:223], v[84:85], v[218:219], v[222:223]
	v_pk_fma_f32 v[224:225], v[86:87], v[220:221], v[224:225]
	v_cvt_pk_f32_fp8_e32 v[218:219], v187
	v_cvt_pk_f32_fp8_sdwa v[220:221], v187 src0_sel:WORD_1
	v_pk_fma_f32 v[222:223], v[88:89], v[214:215], v[222:223]
	v_pk_fma_f32 v[224:225], v[90:91], v[216:217], v[224:225]
	v_pk_fma_f32 v[222:223], v[92:93], v[218:219], v[222:223]
	v_pk_fma_f32 v[224:225], v[94:95], v[220:221], v[224:225]
	v_pk_add_f32 v[222:223], v[222:223], v[224:225]
	s_nop 0
	v_add_f32_e32 v228, v222, v223
	v_cvt_pk_f32_fp8_e32 v[214:215], v188
	v_cvt_pk_f32_fp8_sdwa v[216:217], v188 src0_sel:WORD_1
	v_cvt_pk_f32_fp8_e32 v[218:219], v189
	v_cvt_pk_f32_fp8_sdwa v[220:221], v189 src0_sel:WORD_1
	v_pk_mul_f32 v[222:223], v[80:81], v[214:215]
	v_pk_mul_f32 v[224:225], v[82:83], v[216:217]
	v_cvt_pk_f32_fp8_e32 v[214:215], v190
	v_cvt_pk_f32_fp8_sdwa v[216:217], v190 src0_sel:WORD_1
	v_pk_fma_f32 v[222:223], v[84:85], v[218:219], v[222:223]
	v_pk_fma_f32 v[224:225], v[86:87], v[220:221], v[224:225]
	v_cvt_pk_f32_fp8_e32 v[218:219], v191
	v_cvt_pk_f32_fp8_sdwa v[220:221], v191 src0_sel:WORD_1
	v_pk_fma_f32 v[222:223], v[88:89], v[214:215], v[222:223]
	v_pk_fma_f32 v[224:225], v[90:91], v[216:217], v[224:225]
	v_pk_fma_f32 v[222:223], v[92:93], v[218:219], v[222:223]
	v_pk_fma_f32 v[224:225], v[94:95], v[220:221], v[224:225]
	v_pk_add_f32 v[222:223], v[222:223], v[224:225]
	s_nop 0
	v_add_f32_e32 v229, v222, v223
	v_cvt_pk_f32_fp8_e32 v[214:215], v192
	v_cvt_pk_f32_fp8_sdwa v[216:217], v192 src0_sel:WORD_1
	v_cvt_pk_f32_fp8_e32 v[218:219], v193
	v_cvt_pk_f32_fp8_sdwa v[220:221], v193 src0_sel:WORD_1
	v_pk_mul_f32 v[222:223], v[80:81], v[214:215]
	v_pk_mul_f32 v[224:225], v[82:83], v[216:217]
	v_cvt_pk_f32_fp8_e32 v[214:215], v194
	v_cvt_pk_f32_fp8_sdwa v[216:217], v194 src0_sel:WORD_1
	v_pk_fma_f32 v[222:223], v[84:85], v[218:219], v[222:223]
	v_pk_fma_f32 v[224:225], v[86:87], v[220:221], v[224:225]
	v_cvt_pk_f32_fp8_e32 v[218:219], v195
	v_cvt_pk_f32_fp8_sdwa v[220:221], v195 src0_sel:WORD_1
	v_pk_fma_f32 v[222:223], v[88:89], v[214:215], v[222:223]
	v_pk_fma_f32 v[224:225], v[90:91], v[216:217], v[224:225]
	v_pk_fma_f32 v[222:223], v[92:93], v[218:219], v[222:223]
	v_pk_fma_f32 v[224:225], v[94:95], v[220:221], v[224:225]
	v_pk_add_f32 v[222:223], v[222:223], v[224:225]
	s_nop 0
	v_add_f32_e32 v230, v222, v223
	v_cvt_pk_f32_fp8_e32 v[214:215], v196
	v_cvt_pk_f32_fp8_sdwa v[216:217], v196 src0_sel:WORD_1
	v_cvt_pk_f32_fp8_e32 v[218:219], v197
	v_cvt_pk_f32_fp8_sdwa v[220:221], v197 src0_sel:WORD_1
	v_pk_mul_f32 v[222:223], v[80:81], v[214:215]
	v_pk_mul_f32 v[224:225], v[82:83], v[216:217]
	v_cvt_pk_f32_fp8_e32 v[214:215], v198
	v_cvt_pk_f32_fp8_sdwa v[216:217], v198 src0_sel:WORD_1
	v_pk_fma_f32 v[222:223], v[84:85], v[218:219], v[222:223]
	v_pk_fma_f32 v[224:225], v[86:87], v[220:221], v[224:225]
	v_cvt_pk_f32_fp8_e32 v[218:219], v199
	v_cvt_pk_f32_fp8_sdwa v[220:221], v199 src0_sel:WORD_1
	v_pk_fma_f32 v[222:223], v[88:89], v[214:215], v[222:223]
	v_pk_fma_f32 v[224:225], v[90:91], v[216:217], v[224:225]
	v_pk_fma_f32 v[222:223], v[92:93], v[218:219], v[222:223]
	v_pk_fma_f32 v[224:225], v[94:95], v[220:221], v[224:225]
	v_pk_add_f32 v[222:223], v[222:223], v[224:225]
	s_nop 0
	v_add_f32_e32 v231, v222, v223
	v_cvt_pk_f32_fp8_e32 v[214:215], v200
	v_cvt_pk_f32_fp8_sdwa v[216:217], v200 src0_sel:WORD_1
	v_cvt_pk_f32_fp8_e32 v[218:219], v201
; template <bool STORE>
; DI void peer_item(const Params& p, int item, char* smem) {
;     ...
; #pragma unroll
;       for (int u = 0; u < 8; ++u) {
;         int e = e_s[tl * 128 + k + u];
;         uq[u] = *(const u32x4*)(U8 + (size_t)e * 1024 + lane * 16);
;       }
;       float part[8];
; #pragma unroll
;       for (int u = 0; u < 8; ++u) {
;         float d = 0.f;
; #pragma unroll
;         for (int i = 0; i < 4; ++i) {
;           f32x2_t lo = __builtin_amdgcn_cvt_pk_f32_fp8((int)uq[u][i], false);
;           f32x2_t hi = __builtin_amdgcn_cvt_pk_f32_fp8((int)uq[u][i], true);
;           d += xf[4 * i] * lo.x + xf[4 * i + 1] * lo.y + xf[4 * i + 2] * hi.x + xf[4 * i + 3] * hi.y;
;         }
;         part[u] = d;
;       }
;       float q4[4], r2[2], h;
; #pragma unroll
;       for (int j = 0; j < 4; ++j) {
;         float mine = b5 ? part[j + 4] : part[j];
;         float other = b5 ? part[j] : part[j + 4];
;         q4[j] = mine + __shfl_xor(other, 32);
;       }
; #pragma unroll
;       for (int j = 0; j < 2; ++j) {
;         float mine = b4 ? q4[j + 2] : q4[j];
;         float other = b4 ? q4[j] : q4[j + 2];
;         r2[j] = mine + __shfl_xor(other, 16);
;       }
;       {
;         float mine = b3 ? r2[1] : r2[0];
;         float other = b3 ? r2[0] : r2[1];
;         h = mine + __shfl_xor(other, 8);
;       }
;       h += __shfl_xor(h, 4);
;       h += __shfl_xor(h, 2);
;       h += __shfl_xor(h, 1);
	v_cvt_pk_f32_fp8_sdwa v[220:221], v201 src0_sel:WORD_1
	v_pk_mul_f32 v[222:223], v[80:81], v[214:215]
	v_pk_mul_f32 v[224:225], v[82:83], v[216:217]
	v_cvt_pk_f32_fp8_e32 v[214:215], v202
	v_cvt_pk_f32_fp8_sdwa v[216:217], v202 src0_sel:WORD_1
	v_pk_fma_f32 v[222:223], v[84:85], v[218:219], v[222:223]
	v_pk_fma_f32 v[224:225], v[86:87], v[220:221], v[224:225]
	v_cvt_pk_f32_fp8_e32 v[218:219], v203
	v_cvt_pk_f32_fp8_sdwa v[220:221], v203 src0_sel:WORD_1
	v_pk_fma_f32 v[222:223], v[88:89], v[214:215], v[222:223]
	v_pk_fma_f32 v[224:225], v[90:91], v[216:217], v[224:225]
	v_pk_fma_f32 v[222:223], v[92:93], v[218:219], v[222:223]
	v_pk_fma_f32 v[224:225], v[94:95], v[220:221], v[224:225]
	v_pk_add_f32 v[222:223], v[222:223], v[224:225]
	s_nop 0
	v_add_f32_e32 v232, v222, v223
	v_cvt_pk_f32_fp8_e32 v[214:215], v204
	v_cvt_pk_f32_fp8_sdwa v[216:217], v204 src0_sel:WORD_1
	v_cvt_pk_f32_fp8_e32 v[218:219], v205
	v_cvt_pk_f32_fp8_sdwa v[220:221], v205 src0_sel:WORD_1
	v_pk_mul_f32 v[222:223], v[80:81], v[214:215]
	v_pk_mul_f32 v[224:225], v[82:83], v[216:217]
	v_cvt_pk_f32_fp8_e32 v[214:215], v206
	v_cvt_pk_f32_fp8_sdwa v[216:217], v206 src0_sel:WORD_1
	v_pk_fma_f32 v[222:223], v[84:85], v[218:219], v[222:223]
	v_pk_fma_f32 v[224:225], v[86:87], v[220:221], v[224:225]
	v_cvt_pk_f32_fp8_e32 v[218:219], v207
	v_cvt_pk_f32_fp8_sdwa v[220:221], v207 src0_sel:WORD_1
	v_pk_fma_f32 v[222:223], v[88:89], v[214:215], v[222:223]
	v_pk_fma_f32 v[224:225], v[90:91], v[216:217], v[224:225]
	v_pk_fma_f32 v[222:223], v[92:93], v[218:219], v[222:223]
	v_pk_fma_f32 v[224:225], v[94:95], v[220:221], v[224:225]
	v_pk_add_f32 v[222:223], v[222:223], v[224:225]
	s_nop 0
	v_add_f32_e32 v233, v222, v223
	v_permlane32_swap_b32_e32 v226, v230
	v_permlane32_swap_b32_e32 v227, v231
	v_permlane32_swap_b32_e32 v228, v232
	v_permlane32_swap_b32_e32 v229, v233
	v_add_f32_e32 v226, v226, v230
	v_add_f32_e32 v228, v228, v232
	v_add_f32_e32 v227, v227, v231
	v_add_f32_e32 v229, v229, v233
	s_nop 1
	v_permlane16_swap_b32_e32 v226, v228
	v_permlane16_swap_b32_e32 v227, v229
	v_add_f32_e32 v226, v226, v228
	v_add_f32_e32 v227, v227, v229
	s_nop 0
	v_cndmask_b32_e64 v230, v226, v227, s[24:25]
	v_cndmask_b32_e64 v231, v227, v226, s[24:25]
	s_nop 1
	v_add_f32_dpp v232, v231, v230 row_ror:8 row_mask:0xf bank_mask:0xf
	s_nop 1
	v_add_f32_dpp v233, v232, v232 quad_perm:[1,0,3,2] row_mask:0xf bank_mask:0xf
	s_nop 1
	v_add_f32_dpp v232, v233, v233 quad_perm:[2,3,0,1] row_mask:0xf bank_mask:0xf
	s_nop 1
	v_add_f32_dpp v233, v232, v232 row_half_mirror row_mask:0xf bank_mask:0xf
	ds_write_b32 v235, v233 offset:35360
	v_readlane_b32 s48, v143, s72
	v_readlane_b32 s49, v143, s73
	v_readlane_b32 s50, v143, s74
	v_readlane_b32 s51, v143, s75
	v_readlane_b32 s52, v143, s76
	v_readlane_b32 s53, v143, s77
	v_readlane_b32 s54, v143, s78
	v_readlane_b32 s55, v143, s79
	s_add_u32 s32, s0, s48
	s_addc_u32 s33, s1, 0
	s_add_u32 s34, s0, s49
	s_addc_u32 s35, s1, 0
	s_add_u32 s36, s0, s50
	s_addc_u32 s37, s1, 0
	s_add_u32 s38, s0, s51
	s_addc_u32 s39, s1, 0
	s_add_u32 s40, s0, s52
	s_addc_u32 s41, s1, 0
	s_add_u32 s42, s0, s53
	s_addc_u32 s43, s1, 0
	s_add_u32 s44, s0, s54
	s_addc_u32 s45, s1, 0
	s_add_u32 s46, s0, s55
	s_addc_u32 s47, s1, 0
	global_load_dwordx4 v[176:179], v234, s[32:33]
	global_load_dwordx4 v[180:183], v234, s[34:35]
	global_load_dwordx4 v[184:187], v234, s[36:37]
	global_load_dwordx4 v[188:191], v234, s[38:39]
	global_load_dwordx4 v[192:195], v234, s[40:41]
	global_load_dwordx4 v[196:199], v234, s[42:43]
	global_load_dwordx4 v[200:203], v234, s[44:45]
	global_load_dwordx4 v[204:207], v234, s[46:47]
	s_waitcnt vmcnt(8)
	v_cvt_pk_f32_fp8_e32 v[214:215], v144
	v_cvt_pk_f32_fp8_sdwa v[216:217], v144 src0_sel:WORD_1
	v_cvt_pk_f32_fp8_e32 v[218:219], v145
	v_cvt_pk_f32_fp8_sdwa v[220:221], v145 src0_sel:WORD_1
	v_pk_mul_f32 v[222:223], v[96:97], v[214:215]
	v_pk_mul_f32 v[224:225], v[98:99], v[216:217]
	v_cvt_pk_f32_fp8_e32 v[214:215], v146
	v_cvt_pk_f32_fp8_sdwa v[216:217], v146 src0_sel:WORD_1
	v_pk_fma_f32 v[222:223], v[100:101], v[218:219], v[222:223]
	v_pk_fma_f32 v[224:225], v[102:103], v[220:221], v[224:225]
	v_cvt_pk_f32_fp8_e32 v[218:219], v147
	v_cvt_pk_f32_fp8_sdwa v[220:221], v147 src0_sel:WORD_1
	v_pk_fma_f32 v[222:223], v[104:105], v[214:215], v[222:223]
	v_pk_fma_f32 v[224:225], v[106:107], v[216:217], v[224:225]
	v_pk_fma_f32 v[222:223], v[108:109], v[218:219], v[222:223]
	v_pk_fma_f32 v[224:225], v[110:111], v[220:221], v[224:225]
	v_pk_add_f32 v[222:223], v[222:223], v[224:225]
	s_nop 0
	v_add_f32_e32 v226, v222, v223
	v_cvt_pk_f32_fp8_e32 v[214:215], v148
	v_cvt_pk_f32_fp8_sdwa v[216:217], v148 src0_sel:WORD_1
	v_cvt_pk_f32_fp8_e32 v[218:219], v149
	v_cvt_pk_f32_fp8_sdwa v[220:221], v149 src0_sel:WORD_1
	v_pk_mul_f32 v[222:223], v[96:97], v[214:215]
	v_pk_mul_f32 v[224:225], v[98:99], v[216:217]
	v_cvt_pk_f32_fp8_e32 v[214:215], v150
	v_cvt_pk_f32_fp8_sdwa v[216:217], v150 src0_sel:WORD_1
	v_pk_fma_f32 v[222:223], v[100:101], v[218:219], v[222:223]
	v_pk_fma_f32 v[224:225], v[102:103], v[220:221], v[224:225]
	v_cvt_pk_f32_fp8_e32 v[218:219], v151
	v_cvt_pk_f32_fp8_sdwa v[220:221], v151 src0_sel:WORD_1
	v_pk_fma_f32 v[222:223], v[104:105], v[214:215], v[222:223]
	v_pk_fma_f32 v[224:225], v[106:107], v[216:217], v[224:225]
	v_pk_fma_f32 v[222:223], v[108:109], v[218:219], v[222:223]
	v_pk_fma_f32 v[224:225], v[110:111], v[220:221], v[224:225]
	v_pk_add_f32 v[222:223], v[222:223], v[224:225]
	s_nop 0
	v_add_f32_e32 v227, v222, v223
	v_cvt_pk_f32_fp8_e32 v[214:215], v152
	v_cvt_pk_f32_fp8_sdwa v[216:217], v152 src0_sel:WORD_1
	v_cvt_pk_f32_fp8_e32 v[218:219], v153
; template <bool STORE>
; DI void peer_item(const Params& p, int item, char* smem) {
;     ...
; #pragma unroll
;       for (int u = 0; u < 8; ++u) {
;         float d = 0.f;
; #pragma unroll
;         for (int i = 0; i < 4; ++i) {
;           f32x2_t lo = __builtin_amdgcn_cvt_pk_f32_fp8((int)uq[u][i], false);
;           f32x2_t hi = __builtin_amdgcn_cvt_pk_f32_fp8((int)uq[u][i], true);
;           d += xf[4 * i] * lo.x + xf[4 * i + 1] * lo.y + xf[4 * i + 2] * hi.x + xf[4 * i + 3] * hi.y;
;         }
;         part[u] = d;
;       }
;       float q4[4], r2[2], h;
; #pragma unroll
;       for (int j = 0; j < 4; ++j) {
;         float mine = b5 ? part[j + 4] : part[j];
;         float other = b5 ? part[j] : part[j + 4];
;         q4[j] = mine + __shfl_xor(other, 32);
	v_cvt_pk_f32_fp8_sdwa v[220:221], v153 src0_sel:WORD_1
	v_pk_mul_f32 v[222:223], v[96:97], v[214:215]
	v_pk_mul_f32 v[224:225], v[98:99], v[216:217]
	v_cvt_pk_f32_fp8_e32 v[214:215], v154
	v_cvt_pk_f32_fp8_sdwa v[216:217], v154 src0_sel:WORD_1
	v_pk_fma_f32 v[222:223], v[100:101], v[218:219], v[222:223]
	v_pk_fma_f32 v[224:225], v[102:103], v[220:221], v[224:225]
	v_cvt_pk_f32_fp8_e32 v[218:219], v155
	v_cvt_pk_f32_fp8_sdwa v[220:221], v155 src0_sel:WORD_1
	v_pk_fma_f32 v[222:223], v[104:105], v[214:215], v[222:223]
	v_pk_fma_f32 v[224:225], v[106:107], v[216:217], v[224:225]
	v_pk_fma_f32 v[222:223], v[108:109], v[218:219], v[222:223]
	v_pk_fma_f32 v[224:225], v[110:111], v[220:221], v[224:225]
	v_pk_add_f32 v[222:223], v[222:223], v[224:225]
	s_nop 0
	v_add_f32_e32 v228, v222, v223
	v_cvt_pk_f32_fp8_e32 v[214:215], v156
	v_cvt_pk_f32_fp8_sdwa v[216:217], v156 src0_sel:WORD_1
	v_cvt_pk_f32_fp8_e32 v[218:219], v157
	v_cvt_pk_f32_fp8_sdwa v[220:221], v157 src0_sel:WORD_1
	v_pk_mul_f32 v[222:223], v[96:97], v[214:215]
	v_pk_mul_f32 v[224:225], v[98:99], v[216:217]
	v_cvt_pk_f32_fp8_e32 v[214:215], v158
	v_cvt_pk_f32_fp8_sdwa v[216:217], v158 src0_sel:WORD_1
	v_pk_fma_f32 v[222:223], v[100:101], v[218:219], v[222:223]
	v_pk_fma_f32 v[224:225], v[102:103], v[220:221], v[224:225]
	v_cvt_pk_f32_fp8_e32 v[218:219], v159
	v_cvt_pk_f32_fp8_sdwa v[220:221], v159 src0_sel:WORD_1
	v_pk_fma_f32 v[222:223], v[104:105], v[214:215], v[222:223]
	v_pk_fma_f32 v[224:225], v[106:107], v[216:217], v[224:225]
	v_pk_fma_f32 v[222:223], v[108:109], v[218:219], v[222:223]
	v_pk_fma_f32 v[224:225], v[110:111], v[220:221], v[224:225]
	v_pk_add_f32 v[222:223], v[222:223], v[224:225]
	s_nop 0
	v_add_f32_e32 v229, v222, v223
	v_cvt_pk_f32_fp8_e32 v[214:215], v160
	v_cvt_pk_f32_fp8_sdwa v[216:217], v160 src0_sel:WORD_1
	v_cvt_pk_f32_fp8_e32 v[218:219], v161
	v_cvt_pk_f32_fp8_sdwa v[220:221], v161 src0_sel:WORD_1
	v_pk_mul_f32 v[222:223], v[96:97], v[214:215]
	v_pk_mul_f32 v[224:225], v[98:99], v[216:217]
	v_cvt_pk_f32_fp8_e32 v[214:215], v162
	v_cvt_pk_f32_fp8_sdwa v[216:217], v162 src0_sel:WORD_1
	v_pk_fma_f32 v[222:223], v[100:101], v[218:219], v[222:223]
	v_pk_fma_f32 v[224:225], v[102:103], v[220:221], v[224:225]
	v_cvt_pk_f32_fp8_e32 v[218:219], v163
	v_cvt_pk_f32_fp8_sdwa v[220:221], v163 src0_sel:WORD_1
	v_pk_fma_f32 v[222:223], v[104:105], v[214:215], v[222:223]
	v_pk_fma_f32 v[224:225], v[106:107], v[216:217], v[224:225]
	v_pk_fma_f32 v[222:223], v[108:109], v[218:219], v[222:223]
	v_pk_fma_f32 v[224:225], v[110:111], v[220:221], v[224:225]
	v_pk_add_f32 v[222:223], v[222:223], v[224:225]
	s_nop 0
	v_add_f32_e32 v230, v222, v223
	v_cvt_pk_f32_fp8_e32 v[214:215], v164
	v_cvt_pk_f32_fp8_sdwa v[216:217], v164 src0_sel:WORD_1
	v_cvt_pk_f32_fp8_e32 v[218:219], v165
	v_cvt_pk_f32_fp8_sdwa v[220:221], v165 src0_sel:WORD_1
	v_pk_mul_f32 v[222:223], v[96:97], v[214:215]
	v_pk_mul_f32 v[224:225], v[98:99], v[216:217]
	v_cvt_pk_f32_fp8_e32 v[214:215], v166
	v_cvt_pk_f32_fp8_sdwa v[216:217], v166 src0_sel:WORD_1
	v_pk_fma_f32 v[222:223], v[100:101], v[218:219], v[222:223]
	v_pk_fma_f32 v[224:225], v[102:103], v[220:221], v[224:225]
	v_cvt_pk_f32_fp8_e32 v[218:219], v167
	v_cvt_pk_f32_fp8_sdwa v[220:221], v167 src0_sel:WORD_1
	v_pk_fma_f32 v[222:223], v[104:105], v[214:215], v[222:223]
	v_pk_fma_f32 v[224:225], v[106:107], v[216:217], v[224:225]
	v_pk_fma_f32 v[222:223], v[108:109], v[218:219], v[222:223]
	v_pk_fma_f32 v[224:225], v[110:111], v[220:221], v[224:225]
	v_pk_add_f32 v[222:223], v[222:223], v[224:225]
	s_nop 0
	v_add_f32_e32 v231, v222, v223
	v_cvt_pk_f32_fp8_e32 v[214:215], v168
	v_cvt_pk_f32_fp8_sdwa v[216:217], v168 src0_sel:WORD_1
	v_cvt_pk_f32_fp8_e32 v[218:219], v169
	v_cvt_pk_f32_fp8_sdwa v[220:221], v169 src0_sel:WORD_1
	v_pk_mul_f32 v[222:223], v[96:97], v[214:215]
	v_pk_mul_f32 v[224:225], v[98:99], v[216:217]
	v_cvt_pk_f32_fp8_e32 v[214:215], v170
	v_cvt_pk_f32_fp8_sdwa v[216:217], v170 src0_sel:WORD_1
	v_pk_fma_f32 v[222:223], v[100:101], v[218:219], v[222:223]
	v_pk_fma_f32 v[224:225], v[102:103], v[220:221], v[224:225]
	v_cvt_pk_f32_fp8_e32 v[218:219], v171
	v_cvt_pk_f32_fp8_sdwa v[220:221], v171 src0_sel:WORD_1
	v_pk_fma_f32 v[222:223], v[104:105], v[214:215], v[222:223]
	v_pk_fma_f32 v[224:225], v[106:107], v[216:217], v[224:225]
	v_pk_fma_f32 v[222:223], v[108:109], v[218:219], v[222:223]
	v_pk_fma_f32 v[224:225], v[110:111], v[220:221], v[224:225]
	v_pk_add_f32 v[222:223], v[222:223], v[224:225]
	s_nop 0
	v_add_f32_e32 v232, v222, v223
	v_cvt_pk_f32_fp8_e32 v[214:215], v172
	v_cvt_pk_f32_fp8_sdwa v[216:217], v172 src0_sel:WORD_1
	v_cvt_pk_f32_fp8_e32 v[218:219], v173
	v_cvt_pk_f32_fp8_sdwa v[220:221], v173 src0_sel:WORD_1
	v_pk_mul_f32 v[222:223], v[96:97], v[214:215]
	v_pk_mul_f32 v[224:225], v[98:99], v[216:217]
	v_cvt_pk_f32_fp8_e32 v[214:215], v174
	v_cvt_pk_f32_fp8_sdwa v[216:217], v174 src0_sel:WORD_1
	v_pk_fma_f32 v[222:223], v[100:101], v[218:219], v[222:223]
	v_pk_fma_f32 v[224:225], v[102:103], v[220:221], v[224:225]
	v_cvt_pk_f32_fp8_e32 v[218:219], v175
	v_cvt_pk_f32_fp8_sdwa v[220:221], v175 src0_sel:WORD_1
	v_pk_fma_f32 v[222:223], v[104:105], v[214:215], v[222:223]
	v_pk_fma_f32 v[224:225], v[106:107], v[216:217], v[224:225]
	v_pk_fma_f32 v[222:223], v[108:109], v[218:219], v[222:223]
	v_pk_fma_f32 v[224:225], v[110:111], v[220:221], v[224:225]
	v_pk_add_f32 v[222:223], v[222:223], v[224:225]
	s_nop 0
	v_add_f32_e32 v233, v222, v223
	v_permlane32_swap_b32_e32 v226, v230
	v_permlane32_swap_b32_e32 v227, v231
	v_permlane32_swap_b32_e32 v228, v232
	v_permlane32_swap_b32_e32 v229, v233
	v_add_f32_e32 v226, v226, v230
; template <bool STORE>
; DI void peer_item(const Params& p, int item, char* smem) {
;     ...
;     for (int k = 0; k < 128; k += 8) {
;       u32x4 uq[8];
;       const int emine = e_s[tl * 128 + k + (lane >> 3)];
;       const float gmine = g_s[tl * 128 + k + (lane >> 3)];
;       const float su = SU[emine], sv = SV[emine];
; #pragma unroll
;       for (int u = 0; u < 8; ++u) {
;         int e = e_s[tl * 128 + k + u];
;         uq[u] = *(const u32x4*)(U8 + (size_t)e * 1024 + lane * 16);
;       }
;       float part[8];
; #pragma unroll
;       for (int u = 0; u < 8; ++u) {
;         float d = 0.f;
; #pragma unroll
;         for (int i = 0; i < 4; ++i) {
;           f32x2_t lo = __builtin_amdgcn_cvt_pk_f32_fp8((int)uq[u][i], false);
;           f32x2_t hi = __builtin_amdgcn_cvt_pk_f32_fp8((int)uq[u][i], true);
;           d += xf[4 * i] * lo.x + xf[4 * i + 1] * lo.y + xf[4 * i + 2] * hi.x + xf[4 * i + 3] * hi.y;
;         }
;         part[u] = d;
;       }
;       float q4[4], r2[2], h;
; #pragma unroll
;       for (int j = 0; j < 4; ++j) {
;         float mine = b5 ? part[j + 4] : part[j];
;         float other = b5 ? part[j] : part[j + 4];
;         q4[j] = mine + __shfl_xor(other, 32);
;       }
; #pragma unroll
;       for (int j = 0; j < 2; ++j) {
;         float mine = b4 ? q4[j + 2] : q4[j];
;         float other = b4 ? q4[j] : q4[j + 2];
;         r2[j] = mine + __shfl_xor(other, 16);
;       }
;       {
;         float mine = b3 ? r2[1] : r2[0];
;         float other = b3 ? r2[0] : r2[1];
;         h = mine + __shfl_xor(other, 8);
;       }
;       h += __shfl_xor(h, 4);
;       h += __shfl_xor(h, 2);
;       h += __shfl_xor(h, 1);
	v_add_f32_e32 v228, v228, v232
	v_add_f32_e32 v227, v227, v231
	v_add_f32_e32 v229, v229, v233
	s_nop 1
	v_permlane16_swap_b32_e32 v226, v228
	v_permlane16_swap_b32_e32 v227, v229
	v_add_f32_e32 v226, v226, v228
	v_add_f32_e32 v227, v227, v229
	s_nop 0
	v_cndmask_b32_e64 v230, v226, v227, s[24:25]
	v_cndmask_b32_e64 v231, v227, v226, s[24:25]
	s_nop 1
	v_add_f32_dpp v232, v231, v230 row_ror:8 row_mask:0xf bank_mask:0xf
	s_nop 1
	v_add_f32_dpp v233, v232, v232 quad_perm:[1,0,3,2] row_mask:0xf bank_mask:0xf
	s_nop 1
	v_add_f32_dpp v232, v233, v233 quad_perm:[2,3,0,1] row_mask:0xf bank_mask:0xf
	s_nop 1
	v_add_f32_dpp v233, v232, v232 row_half_mirror row_mask:0xf bank_mask:0xf
	ds_write_b32 v235, v233 offset:35872
	s_add_u32 s72, s72, 8
	s_add_u32 s73, s73, 8
	s_add_u32 s74, s74, 8
	s_add_u32 s75, s75, 8
	s_add_u32 s76, s76, 8
	s_add_u32 s77, s77, 8
	s_add_u32 s78, s78, 8
	s_add_u32 s79, s79, 8
	s_and_b32 s72, s72, 63
	s_and_b32 s73, s73, 63
	s_and_b32 s74, s74, 63
	s_and_b32 s75, s75, 63
	s_and_b32 s76, s76, 63
	s_and_b32 s77, s77, 63
	s_and_b32 s78, s78, 63
	s_and_b32 s79, s79, 63
	v_readlane_b32 s48, v128, s72
	v_readlane_b32 s49, v128, s73
	v_readlane_b32 s50, v128, s74
	v_readlane_b32 s51, v128, s75
	v_readlane_b32 s52, v128, s76
	v_readlane_b32 s53, v128, s77
	v_readlane_b32 s54, v128, s78
	v_readlane_b32 s55, v128, s79
	s_add_u32 s32, s0, s48
	s_addc_u32 s33, s1, 0
	s_add_u32 s34, s0, s49
	s_addc_u32 s35, s1, 0
	s_add_u32 s36, s0, s50
	s_addc_u32 s37, s1, 0
	s_add_u32 s38, s0, s51
	s_addc_u32 s39, s1, 0
	s_add_u32 s40, s0, s52
	s_addc_u32 s41, s1, 0
	s_add_u32 s42, s0, s53
	s_addc_u32 s43, s1, 0
	s_add_u32 s44, s0, s54
	s_addc_u32 s45, s1, 0
	s_add_u32 s46, s0, s55
	s_addc_u32 s47, s1, 0
	global_load_dwordx4 v[144:147], v234, s[32:33]
	global_load_dwordx4 v[148:151], v234, s[34:35]
	global_load_dwordx4 v[152:155], v234, s[36:37]
	global_load_dwordx4 v[156:159], v234, s[38:39]
	global_load_dwordx4 v[160:163], v234, s[40:41]
	global_load_dwordx4 v[164:167], v234, s[42:43]
	global_load_dwordx4 v[168:171], v234, s[44:45]
	global_load_dwordx4 v[172:175], v234, s[46:47]
	s_waitcnt vmcnt(8)
	v_cvt_pk_f32_fp8_e32 v[214:215], v176
	v_cvt_pk_f32_fp8_sdwa v[216:217], v176 src0_sel:WORD_1
	v_cvt_pk_f32_fp8_e32 v[218:219], v177
	v_cvt_pk_f32_fp8_sdwa v[220:221], v177 src0_sel:WORD_1
	v_pk_mul_f32 v[222:223], v[112:113], v[214:215]
	v_pk_mul_f32 v[224:225], v[114:115], v[216:217]
	v_cvt_pk_f32_fp8_e32 v[214:215], v178
	v_cvt_pk_f32_fp8_sdwa v[216:217], v178 src0_sel:WORD_1
	v_pk_fma_f32 v[222:223], v[116:117], v[218:219], v[222:223]
	v_pk_fma_f32 v[224:225], v[118:119], v[220:221], v[224:225]
	v_cvt_pk_f32_fp8_e32 v[218:219], v179
	v_cvt_pk_f32_fp8_sdwa v[220:221], v179 src0_sel:WORD_1
	v_pk_fma_f32 v[222:223], v[120:121], v[214:215], v[222:223]
	v_pk_fma_f32 v[224:225], v[122:123], v[216:217], v[224:225]
	v_pk_fma_f32 v[222:223], v[124:125], v[218:219], v[222:223]
	v_pk_fma_f32 v[224:225], v[126:127], v[220:221], v[224:225]
	v_pk_add_f32 v[222:223], v[222:223], v[224:225]
	s_nop 0
	v_add_f32_e32 v226, v222, v223
	v_cvt_pk_f32_fp8_e32 v[214:215], v180
	v_cvt_pk_f32_fp8_sdwa v[216:217], v180 src0_sel:WORD_1
	v_cvt_pk_f32_fp8_e32 v[218:219], v181
	v_cvt_pk_f32_fp8_sdwa v[220:221], v181 src0_sel:WORD_1
	v_pk_mul_f32 v[222:223], v[112:113], v[214:215]
	v_pk_mul_f32 v[224:225], v[114:115], v[216:217]
	v_cvt_pk_f32_fp8_e32 v[214:215], v182
	v_cvt_pk_f32_fp8_sdwa v[216:217], v182 src0_sel:WORD_1
	v_pk_fma_f32 v[222:223], v[116:117], v[218:219], v[222:223]
	v_pk_fma_f32 v[224:225], v[118:119], v[220:221], v[224:225]
	v_cvt_pk_f32_fp8_e32 v[218:219], v183
	v_cvt_pk_f32_fp8_sdwa v[220:221], v183 src0_sel:WORD_1
	v_pk_fma_f32 v[222:223], v[120:121], v[214:215], v[222:223]
	v_pk_fma_f32 v[224:225], v[122:123], v[216:217], v[224:225]
	v_pk_fma_f32 v[222:223], v[124:125], v[218:219], v[222:223]
	v_pk_fma_f32 v[224:225], v[126:127], v[220:221], v[224:225]
	v_pk_add_f32 v[222:223], v[222:223], v[224:225]
	s_nop 0
	v_add_f32_e32 v227, v222, v223
	v_cvt_pk_f32_fp8_e32 v[214:215], v184
	v_cvt_pk_f32_fp8_sdwa v[216:217], v184 src0_sel:WORD_1
	v_cvt_pk_f32_fp8_e32 v[218:219], v185
	v_cvt_pk_f32_fp8_sdwa v[220:221], v185 src0_sel:WORD_1
	v_pk_mul_f32 v[222:223], v[112:113], v[214:215]
	v_pk_mul_f32 v[224:225], v[114:115], v[216:217]
	v_cvt_pk_f32_fp8_e32 v[214:215], v186
	v_cvt_pk_f32_fp8_sdwa v[216:217], v186 src0_sel:WORD_1
	v_pk_fma_f32 v[222:223], v[116:117], v[218:219], v[222:223]
	v_pk_fma_f32 v[224:225], v[118:119], v[220:221], v[224:225]
	v_cvt_pk_f32_fp8_e32 v[218:219], v187
	v_cvt_pk_f32_fp8_sdwa v[220:221], v187 src0_sel:WORD_1
	v_pk_fma_f32 v[222:223], v[120:121], v[214:215], v[222:223]
	v_pk_fma_f32 v[224:225], v[122:123], v[216:217], v[224:225]
	v_pk_fma_f32 v[222:223], v[124:125], v[218:219], v[222:223]
	v_pk_fma_f32 v[224:225], v[126:127], v[220:221], v[224:225]
	v_pk_add_f32 v[222:223], v[222:223], v[224:225]
	s_nop 0
	v_add_f32_e32 v228, v222, v223
	v_cvt_pk_f32_fp8_e32 v[214:215], v188
	v_cvt_pk_f32_fp8_sdwa v[216:217], v188 src0_sel:WORD_1
	v_cvt_pk_f32_fp8_e32 v[218:219], v189
	v_cvt_pk_f32_fp8_sdwa v[220:221], v189 src0_sel:WORD_1
	v_pk_mul_f32 v[222:223], v[112:113], v[214:215]
	v_pk_mul_f32 v[224:225], v[114:115], v[216:217]
	v_cvt_pk_f32_fp8_e32 v[214:215], v190
	v_cvt_pk_f32_fp8_sdwa v[216:217], v190 src0_sel:WORD_1
	v_pk_fma_f32 v[222:223], v[116:117], v[218:219], v[222:223]
	v_pk_fma_f32 v[224:225], v[118:119], v[220:221], v[224:225]
	v_cvt_pk_f32_fp8_e32 v[218:219], v191
	v_cvt_pk_f32_fp8_sdwa v[220:221], v191 src0_sel:WORD_1
	v_pk_fma_f32 v[222:223], v[120:121], v[214:215], v[222:223]
	v_pk_fma_f32 v[224:225], v[122:123], v[216:217], v[224:225]
; DI float gelu_exact(float x) { return 0.5f * x * (1.f + erff(x * 0.7071067811865476f)); }
; template <bool STORE>
; DI void peer_item(const Params& p, int item, char* smem) {
;     ...
; #pragma unroll
;       for (int u = 0; u < 8; ++u) {
;         float d = 0.f;
; #pragma unroll
;         for (int i = 0; i < 4; ++i) {
;           f32x2_t lo = __builtin_amdgcn_cvt_pk_f32_fp8((int)uq[u][i], false);
;           f32x2_t hi = __builtin_amdgcn_cvt_pk_f32_fp8((int)uq[u][i], true);
;           d += xf[4 * i] * lo.x + xf[4 * i + 1] * lo.y + xf[4 * i + 2] * hi.x + xf[4 * i + 3] * hi.y;
;         }
;         part[u] = d;
;       }
;       float q4[4], r2[2], h;
; #pragma unroll
;       for (int j = 0; j < 4; ++j) {
;         float mine = b5 ? part[j + 4] : part[j];
;         float other = b5 ? part[j] : part[j + 4];
;         q4[j] = mine + __shfl_xor(other, 32);
;       }
; #pragma unroll
;       for (int j = 0; j < 2; ++j) {
;         float mine = b4 ? q4[j + 2] : q4[j];
;         float other = b4 ? q4[j] : q4[j + 2];
;         r2[j] = mine + __shfl_xor(other, 16);
;       }
;       {
;         float mine = b3 ? r2[1] : r2[0];
;         float other = b3 ? r2[0] : r2[1];
;         h = mine + __shfl_xor(other, 8);
;       }
;       h += __shfl_xor(h, 4);
;       h += __shfl_xor(h, 2);
;       h += __shfl_xor(h, 1);
;       const float amine = gelu_exact(h * su) * gmine * sv;
;       if ((lane & 7) == 0) {
;         EG[tok * 128 + k + (lane >> 3)] = emine;
;         AG[tok * 128 + k + (lane >> 3)] = amine;
;       }
;     }
	v_pk_fma_f32 v[222:223], v[124:125], v[218:219], v[222:223]
	v_pk_fma_f32 v[224:225], v[126:127], v[220:221], v[224:225]
	v_pk_add_f32 v[222:223], v[222:223], v[224:225]
	s_nop 0
	v_add_f32_e32 v229, v222, v223
	v_cvt_pk_f32_fp8_e32 v[214:215], v192
	v_cvt_pk_f32_fp8_sdwa v[216:217], v192 src0_sel:WORD_1
	v_cvt_pk_f32_fp8_e32 v[218:219], v193
	v_cvt_pk_f32_fp8_sdwa v[220:221], v193 src0_sel:WORD_1
	v_pk_mul_f32 v[222:223], v[112:113], v[214:215]
	v_pk_mul_f32 v[224:225], v[114:115], v[216:217]
	v_cvt_pk_f32_fp8_e32 v[214:215], v194
	v_cvt_pk_f32_fp8_sdwa v[216:217], v194 src0_sel:WORD_1
	v_pk_fma_f32 v[222:223], v[116:117], v[218:219], v[222:223]
	v_pk_fma_f32 v[224:225], v[118:119], v[220:221], v[224:225]
	v_cvt_pk_f32_fp8_e32 v[218:219], v195
	v_cvt_pk_f32_fp8_sdwa v[220:221], v195 src0_sel:WORD_1
	v_pk_fma_f32 v[222:223], v[120:121], v[214:215], v[222:223]
	v_pk_fma_f32 v[224:225], v[122:123], v[216:217], v[224:225]
	v_pk_fma_f32 v[222:223], v[124:125], v[218:219], v[222:223]
	v_pk_fma_f32 v[224:225], v[126:127], v[220:221], v[224:225]
	v_pk_add_f32 v[222:223], v[222:223], v[224:225]
	s_nop 0
	v_add_f32_e32 v230, v222, v223
	v_cvt_pk_f32_fp8_e32 v[214:215], v196
	v_cvt_pk_f32_fp8_sdwa v[216:217], v196 src0_sel:WORD_1
	v_cvt_pk_f32_fp8_e32 v[218:219], v197
	v_cvt_pk_f32_fp8_sdwa v[220:221], v197 src0_sel:WORD_1
	v_pk_mul_f32 v[222:223], v[112:113], v[214:215]
	v_pk_mul_f32 v[224:225], v[114:115], v[216:217]
	v_cvt_pk_f32_fp8_e32 v[214:215], v198
	v_cvt_pk_f32_fp8_sdwa v[216:217], v198 src0_sel:WORD_1
	v_pk_fma_f32 v[222:223], v[116:117], v[218:219], v[222:223]
	v_pk_fma_f32 v[224:225], v[118:119], v[220:221], v[224:225]
	v_cvt_pk_f32_fp8_e32 v[218:219], v199
	v_cvt_pk_f32_fp8_sdwa v[220:221], v199 src0_sel:WORD_1
	v_pk_fma_f32 v[222:223], v[120:121], v[214:215], v[222:223]
	v_pk_fma_f32 v[224:225], v[122:123], v[216:217], v[224:225]
	v_pk_fma_f32 v[222:223], v[124:125], v[218:219], v[222:223]
	v_pk_fma_f32 v[224:225], v[126:127], v[220:221], v[224:225]
	v_pk_add_f32 v[222:223], v[222:223], v[224:225]
	s_nop 0
	v_add_f32_e32 v231, v222, v223
	v_cvt_pk_f32_fp8_e32 v[214:215], v200
	v_cvt_pk_f32_fp8_sdwa v[216:217], v200 src0_sel:WORD_1
	v_cvt_pk_f32_fp8_e32 v[218:219], v201
	v_cvt_pk_f32_fp8_sdwa v[220:221], v201 src0_sel:WORD_1
	v_pk_mul_f32 v[222:223], v[112:113], v[214:215]
	v_pk_mul_f32 v[224:225], v[114:115], v[216:217]
	v_cvt_pk_f32_fp8_e32 v[214:215], v202
	v_cvt_pk_f32_fp8_sdwa v[216:217], v202 src0_sel:WORD_1
	v_pk_fma_f32 v[222:223], v[116:117], v[218:219], v[222:223]
	v_pk_fma_f32 v[224:225], v[118:119], v[220:221], v[224:225]
	v_cvt_pk_f32_fp8_e32 v[218:219], v203
	v_cvt_pk_f32_fp8_sdwa v[220:221], v203 src0_sel:WORD_1
	v_pk_fma_f32 v[222:223], v[120:121], v[214:215], v[222:223]
	v_pk_fma_f32 v[224:225], v[122:123], v[216:217], v[224:225]
	v_pk_fma_f32 v[222:223], v[124:125], v[218:219], v[222:223]
	v_pk_fma_f32 v[224:225], v[126:127], v[220:221], v[224:225]
	v_pk_add_f32 v[222:223], v[222:223], v[224:225]
	s_nop 0
	v_add_f32_e32 v232, v222, v223
	v_cvt_pk_f32_fp8_e32 v[214:215], v204
	v_cvt_pk_f32_fp8_sdwa v[216:217], v204 src0_sel:WORD_1
	v_cvt_pk_f32_fp8_e32 v[218:219], v205
	v_cvt_pk_f32_fp8_sdwa v[220:221], v205 src0_sel:WORD_1
	v_pk_mul_f32 v[222:223], v[112:113], v[214:215]
	v_pk_mul_f32 v[224:225], v[114:115], v[216:217]
	v_cvt_pk_f32_fp8_e32 v[214:215], v206
	v_cvt_pk_f32_fp8_sdwa v[216:217], v206 src0_sel:WORD_1
	v_pk_fma_f32 v[222:223], v[116:117], v[218:219], v[222:223]
	v_pk_fma_f32 v[224:225], v[118:119], v[220:221], v[224:225]
	v_cvt_pk_f32_fp8_e32 v[218:219], v207
	v_cvt_pk_f32_fp8_sdwa v[220:221], v207 src0_sel:WORD_1
	v_pk_fma_f32 v[222:223], v[120:121], v[214:215], v[222:223]
	v_pk_fma_f32 v[224:225], v[122:123], v[216:217], v[224:225]
	v_pk_fma_f32 v[222:223], v[124:125], v[218:219], v[222:223]
	v_pk_fma_f32 v[224:225], v[126:127], v[220:221], v[224:225]
	v_pk_add_f32 v[222:223], v[222:223], v[224:225]
	s_nop 0
	v_add_f32_e32 v233, v222, v223
	v_permlane32_swap_b32_e32 v226, v230
	v_permlane32_swap_b32_e32 v227, v231
	v_permlane32_swap_b32_e32 v228, v232
	v_permlane32_swap_b32_e32 v229, v233
	v_add_f32_e32 v226, v226, v230
	v_add_f32_e32 v228, v228, v232
	v_add_f32_e32 v227, v227, v231
	v_add_f32_e32 v229, v229, v233
	s_nop 1
	v_permlane16_swap_b32_e32 v226, v228
	v_permlane16_swap_b32_e32 v227, v229
	v_add_f32_e32 v226, v226, v228
	v_add_f32_e32 v227, v227, v229
	s_nop 0
	v_cndmask_b32_e64 v230, v226, v227, s[24:25]
	v_cndmask_b32_e64 v231, v227, v226, s[24:25]
	s_nop 1
	v_add_f32_dpp v232, v231, v230 row_ror:8 row_mask:0xf bank_mask:0xf
	s_nop 1
	v_add_f32_dpp v233, v232, v232 quad_perm:[1,0,3,2] row_mask:0xf bank_mask:0xf
	s_nop 1
	v_add_f32_dpp v232, v233, v233 quad_perm:[2,3,0,1] row_mask:0xf bank_mask:0xf
	s_nop 1
	v_add_f32_dpp v233, v232, v232 row_half_mirror row_mask:0xf bank_mask:0xf
	ds_write_b32 v235, v233 offset:36384
	v_add_u32_e32 v235, 64, v235
	s_add_u32 s12, s12, 1
	s_cmp_lt_u32 s12, 8
	s_cbranch_scc1 .Lup_k
; template <int NR>
; DI void rms_rows(const float* __restrict__ xr, const float* __restrict__ g, u16* __restrict__ dst, int lane) {
;     ...
;     for (int i = 0; i < 4; ++i) ss += v[r][i].x * v[r][i].x + v[r][i].y * v[r][i].y + v[r][i].z * v[r][i].z + v[r][i].w * v[r][i].w;
;     ss = wave_sum(ss);
;     const float rr = rsqrtf(ss * (1.f / 1024.f) + 1e-6f);
; template <bool STORE>
; DI void peer_item(const Params& p, int item, char* smem) {
;     ...
;       const int emine = e_s[tl * 128 + k + (lane >> 3)];
;       const float gmine = g_s[tl * 128 + k + (lane >> 3)];
;       const float su = SU[emine], sv = SV[emine];
	s_waitcnt vmcnt(0) lgkmcnt(0)
	s_lshl_b32 s13, s14, 9
	s_add_u32 s26, s4, s13
	s_addc_u32 s27, s5, 0
	s_add_u32 s28, s6, s13
	s_addc_u32 s29, s7, 0
	ds_read_b32 v0, v237 offset:32768
	ds_read_b32 v1, v237 offset:33024
	ds_read_b32 v2, v237 offset:0
	ds_read_b32 v3, v237 offset:256
	ds_read_b32 v4, v237 offset:16384
	ds_read_b32 v5, v237 offset:16640
	ds_read_b32 v16, v237 offset:33280
	ds_read_b32 v17, v237 offset:33536
	ds_read_b32 v18, v237 offset:512
	ds_read_b32 v19, v237 offset:768
	ds_read_b32 v20, v237 offset:16896
	ds_read_b32 v21, v237 offset:17152
	ds_read_b32 v32, v237 offset:33792
	ds_read_b32 v33, v237 offset:34048
	ds_read_b32 v34, v237 offset:1024
	ds_read_b32 v35, v237 offset:1280
	ds_read_b32 v36, v237 offset:17408
	ds_read_b32 v37, v237 offset:17664
	ds_read_b32 v48, v237 offset:34304
	ds_read_b32 v49, v237 offset:34560
	ds_read_b32 v50, v237 offset:1536
	ds_read_b32 v51, v237 offset:1792
	ds_read_b32 v52, v237 offset:17920
	ds_read_b32 v53, v237 offset:18176
	ds_read_b32 v64, v237 offset:34816
	ds_read_b32 v65, v237 offset:35072
	ds_read_b32 v66, v237 offset:2048
	ds_read_b32 v67, v237 offset:2304
	ds_read_b32 v68, v237 offset:18432
	ds_read_b32 v69, v237 offset:18688
	ds_read_b32 v80, v237 offset:35328
	ds_read_b32 v81, v237 offset:35584
	ds_read_b32 v82, v237 offset:2560
	ds_read_b32 v83, v237 offset:2816
	ds_read_b32 v84, v237 offset:18944
	ds_read_b32 v85, v237 offset:19200
	ds_read_b32 v96, v237 offset:35840
	ds_read_b32 v97, v237 offset:36096
	ds_read_b32 v98, v237 offset:3072
	ds_read_b32 v99, v237 offset:3328
	ds_read_b32 v100, v237 offset:19456
	ds_read_b32 v101, v237 offset:19712
	ds_read_b32 v112, v237 offset:36352
	ds_read_b32 v113, v237 offset:36608
	ds_read_b32 v114, v237 offset:3584
	ds_read_b32 v115, v237 offset:3840
	ds_read_b32 v116, v237 offset:19968
	ds_read_b32 v117, v237 offset:20224
	s_lshl_b32 s13, s14, 5
	s_add_u32 s32, s56, 0x9a80200
	s_addc_u32 s33, s57, 0
	s_add_u32 s32, s32, s13
	s_addc_u32 s33, s33, 0
	v_mov_b32_e32 v208, 0
	global_load_dwordx4 v[12:15], v208, s[32:33] offset:0
	global_load_dwordx4 v[152:155], v208, s[32:33] offset:16
	global_load_dwordx4 v[28:31], v208, s[32:33] offset:32
	global_load_dwordx4 v[156:159], v208, s[32:33] offset:48
	global_load_dwordx4 v[44:47], v208, s[32:33] offset:64
	global_load_dwordx4 v[160:163], v208, s[32:33] offset:80
	global_load_dwordx4 v[60:63], v208, s[32:33] offset:96
	global_load_dwordx4 v[164:167], v208, s[32:33] offset:112
	global_load_dwordx4 v[76:79], v208, s[32:33] offset:128
	global_load_dwordx4 v[168:171], v208, s[32:33] offset:144
	global_load_dwordx4 v[92:95], v208, s[32:33] offset:160
	global_load_dwordx4 v[172:175], v208, s[32:33] offset:176
	global_load_dwordx4 v[108:111], v208, s[32:33] offset:192
	global_load_dwordx4 v[176:179], v208, s[32:33] offset:208
	global_load_dwordx4 v[124:127], v208, s[32:33] offset:224
	global_load_dwordx4 v[180:183], v208, s[32:33] offset:240
	s_waitcnt lgkmcnt(15)
	v_lshlrev_b32_e32 v10, 2, v2
	v_lshlrev_b32_e32 v11, 2, v3
	global_load_dword v6, v10, s[8:9]
	global_load_dword v7, v11, s[8:9]
	global_load_dword v8, v10, s[10:11]
	global_load_dword v9, v11, s[10:11]
	s_waitcnt lgkmcnt(15)
	v_lshlrev_b32_e32 v26, 2, v18
	v_lshlrev_b32_e32 v27, 2, v19
	global_load_dword v22, v26, s[8:9]
	global_load_dword v23, v27, s[8:9]
	global_load_dword v24, v26, s[10:11]
	global_load_dword v25, v27, s[10:11]
	s_waitcnt lgkmcnt(15)
	v_lshlrev_b32_e32 v42, 2, v34
	v_lshlrev_b32_e32 v43, 2, v35
	global_load_dword v38, v42, s[8:9]
	global_load_dword v39, v43, s[8:9]
	global_load_dword v40, v42, s[10:11]
	global_load_dword v41, v43, s[10:11]
	s_waitcnt lgkmcnt(15)
	v_lshlrev_b32_e32 v58, 2, v50
	v_lshlrev_b32_e32 v59, 2, v51
	global_load_dword v54, v58, s[8:9]
	global_load_dword v55, v59, s[8:9]
	global_load_dword v56, v58, s[10:11]
	global_load_dword v57, v59, s[10:11]
	s_waitcnt lgkmcnt(15)
	v_lshlrev_b32_e32 v74, 2, v66
	v_lshlrev_b32_e32 v75, 2, v67
	global_load_dword v70, v74, s[8:9]
	global_load_dword v71, v75, s[8:9]
	global_load_dword v72, v74, s[10:11]
	global_load_dword v73, v75, s[10:11]
	s_waitcnt lgkmcnt(12)
	v_lshlrev_b32_e32 v90, 2, v82
	v_lshlrev_b32_e32 v91, 2, v83
	global_load_dword v86, v90, s[8:9]
	global_load_dword v87, v91, s[8:9]
	global_load_dword v88, v90, s[10:11]
	global_load_dword v89, v91, s[10:11]
	s_waitcnt lgkmcnt(6)
	v_lshlrev_b32_e32 v106, 2, v98
	v_lshlrev_b32_e32 v107, 2, v99
	global_load_dword v102, v106, s[8:9]
	global_load_dword v103, v107, s[8:9]
	global_load_dword v104, v106, s[10:11]
	global_load_dword v105, v107, s[10:11]
	s_waitcnt lgkmcnt(0)
	v_lshlrev_b32_e32 v122, 2, v114
	v_lshlrev_b32_e32 v123, 2, v115
	global_load_dword v118, v122, s[8:9]
	global_load_dword v119, v123, s[8:9]
	global_load_dword v120, v122, s[10:11]
	global_load_dword v121, v123, s[10:11]
	s_waitcnt vmcnt(28)
; DI float gelu_exact(float x) { return 0.5f * x * (1.f + erff(x * 0.7071067811865476f)); }
; template <int NR>
; DI void rms_rows(const float* __restrict__ xr, const float* __restrict__ g, u16* __restrict__ dst, int lane) {
;     ...
;     for (int i = 0; i < 4; ++i) ss += v[r][i].x * v[r][i].x + v[r][i].y * v[r][i].y + v[r][i].z * v[r][i].z + v[r][i].w * v[r][i].w;
;     ss = wave_sum(ss);
;     const float rr = rsqrtf(ss * (1.f / 1024.f) + 1e-6f);
; template <bool STORE>
; DI void peer_item(const Params& p, int item, char* smem) {
;     ...
;       const float amine = gelu_exact(h * su) * gmine * sv;
;       if ((lane & 7) == 0) {
;         EG[tok * 128 + k + (lane >> 3)] = emine;
;         AG[tok * 128 + k + (lane >> 3)] = amine;
;       }
	v_pk_add_f32 v[12:13], v[12:13], v[14:15]
	v_pk_add_f32 v[152:153], v[152:153], v[154:155]
	v_mov_b32_e32 v14, 0x358637bd
	v_pk_add_f32 v[12:13], v[12:13], v[152:153]
	s_nop 0
	v_add_f32_e32 v12, v12, v13
	s_nop 0
	v_fmamk_f32 v12, v12, 0x3a800000, v14
	s_nop 0
	v_rsq_f32_e32 v12, v12
	s_nop 1
	v_mul_f32_e32 v6, v6, v12
	v_mul_f32_e32 v7, v7, v12
	v_mul_f32_e32 v144, v6, v0
	v_mul_f32_e32 v145, 0x3f3504f3, v144
	v_mov_b32_e32 v146, 0xb9c68948
	v_fma_f32 v146, |v145|, s80, v146
	v_fma_f32 v146, |v145|, v146, s81
	v_fma_f32 v146, |v145|, v146, s82
	v_fma_f32 v146, |v145|, v146, s83
	v_fma_f32 v146, |v145|, v146, s84
	v_fma_f32 v146, |v145|, v146, s85
	v_fma_f32 v146, |v145|, v146, |v145|
	v_mul_f32_e32 v147, 0xbfb8aa3b, v146
	v_fma_f32 v148, v146, s86, -v147
	v_rndne_f32_e32 v149, v147
	v_fmac_f32_e32 v148, 0xb2a5705f, v146
	v_sub_f32_e32 v147, v147, v149
	v_add_f32_e32 v147, v147, v148
	v_cvt_i32_f32_e32 v148, v149
	v_exp_f32_e32 v147, v147
	v_cmp_nlt_f32_e32 vcc, s87, v146
	v_ldexp_f32 v147, v147, v148
	s_nop 0
	v_cndmask_b32_e32 v147, 0, v147, vcc
	v_cmp_ngt_f32_e32 vcc, s88, v146
	v_mov_b32_e32 v148, 0x7f800000
	s_nop 0
	v_cndmask_b32_e32 v147, v148, v147, vcc
	v_sub_f32_e32 v147, 1.0, v147
	v_mul_f32_e32 v148, v145, v145
	v_mov_b32_e32 v149, 0x3ba10414
	v_fmamk_f32 v149, v148, 0xba1345e1, v149
	v_fmaak_f32 v149, v148, v149, 0xbcdac9b8
	v_fmaak_f32 v149, v148, v149, 0x3de703be
	v_fmaak_f32 v149, v148, v149, 0xbec09330
	v_fmaak_f32 v149, v148, v149, 0x3e0375d0
	v_fma_f32 v149, |v145|, v149, |v145|
	v_cmp_nlt_f32_e64 vcc, |v145|, 1.0
	s_nop 1
	v_cndmask_b32_e32 v147, v149, v147, vcc
	v_bfi_b32 v147, s89, v147, v145
	v_mul_f32_e32 v144, 0.5, v144
	v_add_f32_e32 v147, 1.0, v147
	v_mul_f32_e32 v144, v144, v147
	v_mul_f32_e32 v144, v4, v144
	v_mul_f32_e32 v0, v8, v144
	v_mul_f32_e32 v144, v7, v1
	v_mul_f32_e32 v145, 0x3f3504f3, v144
	v_mov_b32_e32 v146, 0xb9c68948
	v_fma_f32 v146, |v145|, s80, v146
	v_fma_f32 v146, |v145|, v146, s81
	v_fma_f32 v146, |v145|, v146, s82
	v_fma_f32 v146, |v145|, v146, s83
	v_fma_f32 v146, |v145|, v146, s84
	v_fma_f32 v146, |v145|, v146, s85
	v_fma_f32 v146, |v145|, v146, |v145|
	v_mul_f32_e32 v147, 0xbfb8aa3b, v146
	v_fma_f32 v148, v146, s86, -v147
	v_rndne_f32_e32 v149, v147
	v_fmac_f32_e32 v148, 0xb2a5705f, v146
	v_sub_f32_e32 v147, v147, v149
	v_add_f32_e32 v147, v147, v148
	v_cvt_i32_f32_e32 v148, v149
	v_exp_f32_e32 v147, v147
	v_cmp_nlt_f32_e32 vcc, s87, v146
	v_ldexp_f32 v147, v147, v148
	s_nop 0
	v_cndmask_b32_e32 v147, 0, v147, vcc
	v_cmp_ngt_f32_e32 vcc, s88, v146
	v_mov_b32_e32 v148, 0x7f800000
	s_nop 0
	v_cndmask_b32_e32 v147, v148, v147, vcc
	v_sub_f32_e32 v147, 1.0, v147
	v_mul_f32_e32 v148, v145, v145
	v_mov_b32_e32 v149, 0x3ba10414
	v_fmamk_f32 v149, v148, 0xba1345e1, v149
	v_fmaak_f32 v149, v148, v149, 0xbcdac9b8
	v_fmaak_f32 v149, v148, v149, 0x3de703be
	v_fmaak_f32 v149, v148, v149, 0xbec09330
	v_fmaak_f32 v149, v148, v149, 0x3e0375d0
	v_fma_f32 v149, |v145|, v149, |v145|
	v_cmp_nlt_f32_e64 vcc, |v145|, 1.0
	s_nop 1
	v_cndmask_b32_e32 v147, v149, v147, vcc
	v_bfi_b32 v147, s89, v147, v145
	v_mul_f32_e32 v144, 0.5, v144
	v_add_f32_e32 v147, 1.0, v147
	v_mul_f32_e32 v144, v144, v147
	v_mul_f32_e32 v144, v5, v144
	v_mul_f32_e32 v1, v9, v144
	global_store_dword v238, v2, s[26:27] offset:0
	global_store_dword v238, v3, s[26:27] offset:256
	global_store_dword v238, v0, s[28:29] offset:0
	global_store_dword v238, v1, s[28:29] offset:256
	s_waitcnt vmcnt(28)
	v_pk_add_f32 v[28:29], v[28:29], v[30:31]
	v_pk_add_f32 v[156:157], v[156:157], v[158:159]
	v_mov_b32_e32 v30, 0x358637bd
	v_pk_add_f32 v[28:29], v[28:29], v[156:157]
	s_nop 0
	v_add_f32_e32 v28, v28, v29
	s_nop 0
	v_fmamk_f32 v28, v28, 0x3a800000, v30
	s_nop 0
	v_rsq_f32_e32 v28, v28
	s_nop 1
	v_mul_f32_e32 v22, v22, v28
	v_mul_f32_e32 v23, v23, v28
	v_mul_f32_e32 v144, v22, v16
	v_mul_f32_e32 v145, 0x3f3504f3, v144
	v_mov_b32_e32 v146, 0xb9c68948
	v_fma_f32 v146, |v145|, s80, v146
	v_fma_f32 v146, |v145|, v146, s81
	v_fma_f32 v146, |v145|, v146, s82
	v_fma_f32 v146, |v145|, v146, s83
	v_fma_f32 v146, |v145|, v146, s84
	v_fma_f32 v146, |v145|, v146, s85
	v_fma_f32 v146, |v145|, v146, |v145|
	v_mul_f32_e32 v147, 0xbfb8aa3b, v146
	v_fma_f32 v148, v146, s86, -v147
	v_rndne_f32_e32 v149, v147
	v_fmac_f32_e32 v148, 0xb2a5705f, v146
	v_sub_f32_e32 v147, v147, v149
	v_add_f32_e32 v147, v147, v148
	v_cvt_i32_f32_e32 v148, v149
	v_exp_f32_e32 v147, v147
	v_cmp_nlt_f32_e32 vcc, s87, v146
	v_ldexp_f32 v147, v147, v148
	s_nop 0
	v_cndmask_b32_e32 v147, 0, v147, vcc
	v_cmp_ngt_f32_e32 vcc, s88, v146
	v_mov_b32_e32 v148, 0x7f800000
	s_nop 0
	v_cndmask_b32_e32 v147, v148, v147, vcc
	v_sub_f32_e32 v147, 1.0, v147
	v_mul_f32_e32 v148, v145, v145
	v_mov_b32_e32 v149, 0x3ba10414
	v_fmamk_f32 v149, v148, 0xba1345e1, v149
	v_fmaak_f32 v149, v148, v149, 0xbcdac9b8
	v_fmaak_f32 v149, v148, v149, 0x3de703be
	v_fmaak_f32 v149, v148, v149, 0xbec09330
	v_fmaak_f32 v149, v148, v149, 0x3e0375d0
	v_fma_f32 v149, |v145|, v149, |v145|
	v_cmp_nlt_f32_e64 vcc, |v145|, 1.0
	s_nop 1
	v_cndmask_b32_e32 v147, v149, v147, vcc
	v_bfi_b32 v147, s89, v147, v145
	v_mul_f32_e32 v144, 0.5, v144
	v_add_f32_e32 v147, 1.0, v147
	v_mul_f32_e32 v144, v144, v147
	v_mul_f32_e32 v144, v20, v144
	v_mul_f32_e32 v16, v24, v144
	v_mul_f32_e32 v144, v23, v17
	v_mul_f32_e32 v145, 0x3f3504f3, v144
	v_mov_b32_e32 v146, 0xb9c68948
	v_fma_f32 v146, |v145|, s80, v146
	v_fma_f32 v146, |v145|, v146, s81
	v_fma_f32 v146, |v145|, v146, s82
	v_fma_f32 v146, |v145|, v146, s83
	v_fma_f32 v146, |v145|, v146, s84
	v_fma_f32 v146, |v145|, v146, s85
	v_fma_f32 v146, |v145|, v146, |v145|
	v_mul_f32_e32 v147, 0xbfb8aa3b, v146
	v_fma_f32 v148, v146, s86, -v147
	v_rndne_f32_e32 v149, v147
	v_fmac_f32_e32 v148, 0xb2a5705f, v146
	v_sub_f32_e32 v147, v147, v149
	v_add_f32_e32 v147, v147, v148
	v_cvt_i32_f32_e32 v148, v149
	v_exp_f32_e32 v147, v147
	v_cmp_nlt_f32_e32 vcc, s87, v146
	v_ldexp_f32 v147, v147, v148
	s_nop 0
	v_cndmask_b32_e32 v147, 0, v147, vcc
	v_cmp_ngt_f32_e32 vcc, s88, v146
	v_mov_b32_e32 v148, 0x7f800000
	s_nop 0
	v_cndmask_b32_e32 v147, v148, v147, vcc
	v_sub_f32_e32 v147, 1.0, v147
	v_mul_f32_e32 v148, v145, v145
	v_mov_b32_e32 v149, 0x3ba10414
	v_fmamk_f32 v149, v148, 0xba1345e1, v149
	v_fmaak_f32 v149, v148, v149, 0xbcdac9b8
	v_fmaak_f32 v149, v148, v149, 0x3de703be
	v_fmaak_f32 v149, v148, v149, 0xbec09330
	v_fmaak_f32 v149, v148, v149, 0x3e0375d0
	v_fma_f32 v149, |v145|, v149, |v145|
	v_cmp_nlt_f32_e64 vcc, |v145|, 1.0
	s_nop 1
	v_cndmask_b32_e32 v147, v149, v147, vcc
	v_bfi_b32 v147, s89, v147, v145
	v_mul_f32_e32 v144, 0.5, v144
	v_add_f32_e32 v147, 1.0, v147
	v_mul_f32_e32 v144, v144, v147
	v_mul_f32_e32 v144, v21, v144
	v_mul_f32_e32 v17, v25, v144
	global_store_dword v238, v18, s[26:27] offset:512
	global_store_dword v238, v19, s[26:27] offset:768
	global_store_dword v238, v16, s[28:29] offset:512
	global_store_dword v238, v17, s[28:29] offset:768
	s_waitcnt vmcnt(28)
; DI float gelu_exact(float x) { return 0.5f * x * (1.f + erff(x * 0.7071067811865476f)); }
; template <int NR>
; DI void rms_rows(const float* __restrict__ xr, const float* __restrict__ g, u16* __restrict__ dst, int lane) {
;     ...
;     for (int i = 0; i < 4; ++i) ss += v[r][i].x * v[r][i].x + v[r][i].y * v[r][i].y + v[r][i].z * v[r][i].z + v[r][i].w * v[r][i].w;
;     ss = wave_sum(ss);
;     const float rr = rsqrtf(ss * (1.f / 1024.f) + 1e-6f);
; template <bool STORE>
; DI void peer_item(const Params& p, int item, char* smem) {
;     ...
;       const float amine = gelu_exact(h * su) * gmine * sv;
;       if ((lane & 7) == 0) {
;         EG[tok * 128 + k + (lane >> 3)] = emine;
;         AG[tok * 128 + k + (lane >> 3)] = amine;
;       }
	v_pk_add_f32 v[44:45], v[44:45], v[46:47]
	v_pk_add_f32 v[160:161], v[160:161], v[162:163]
	v_mov_b32_e32 v46, 0x358637bd
	v_pk_add_f32 v[44:45], v[44:45], v[160:161]
	s_nop 0
	v_add_f32_e32 v44, v44, v45
	s_nop 0
	v_fmamk_f32 v44, v44, 0x3a800000, v46
	s_nop 0
	v_rsq_f32_e32 v44, v44
	s_nop 1
	v_mul_f32_e32 v38, v38, v44
	v_mul_f32_e32 v39, v39, v44
	v_mul_f32_e32 v144, v38, v32
	v_mul_f32_e32 v145, 0x3f3504f3, v144
	v_mov_b32_e32 v146, 0xb9c68948
	v_fma_f32 v146, |v145|, s80, v146
	v_fma_f32 v146, |v145|, v146, s81
	v_fma_f32 v146, |v145|, v146, s82
	v_fma_f32 v146, |v145|, v146, s83
	v_fma_f32 v146, |v145|, v146, s84
	v_fma_f32 v146, |v145|, v146, s85
	v_fma_f32 v146, |v145|, v146, |v145|
	v_mul_f32_e32 v147, 0xbfb8aa3b, v146
	v_fma_f32 v148, v146, s86, -v147
	v_rndne_f32_e32 v149, v147
	v_fmac_f32_e32 v148, 0xb2a5705f, v146
	v_sub_f32_e32 v147, v147, v149
	v_add_f32_e32 v147, v147, v148
	v_cvt_i32_f32_e32 v148, v149
	v_exp_f32_e32 v147, v147
	v_cmp_nlt_f32_e32 vcc, s87, v146
	v_ldexp_f32 v147, v147, v148
	s_nop 0
	v_cndmask_b32_e32 v147, 0, v147, vcc
	v_cmp_ngt_f32_e32 vcc, s88, v146
	v_mov_b32_e32 v148, 0x7f800000
	s_nop 0
	v_cndmask_b32_e32 v147, v148, v147, vcc
	v_sub_f32_e32 v147, 1.0, v147
	v_mul_f32_e32 v148, v145, v145
	v_mov_b32_e32 v149, 0x3ba10414
	v_fmamk_f32 v149, v148, 0xba1345e1, v149
	v_fmaak_f32 v149, v148, v149, 0xbcdac9b8
	v_fmaak_f32 v149, v148, v149, 0x3de703be
	v_fmaak_f32 v149, v148, v149, 0xbec09330
	v_fmaak_f32 v149, v148, v149, 0x3e0375d0
	v_fma_f32 v149, |v145|, v149, |v145|
	v_cmp_nlt_f32_e64 vcc, |v145|, 1.0
	s_nop 1
	v_cndmask_b32_e32 v147, v149, v147, vcc
	v_bfi_b32 v147, s89, v147, v145
	v_mul_f32_e32 v144, 0.5, v144
	v_add_f32_e32 v147, 1.0, v147
	v_mul_f32_e32 v144, v144, v147
	v_mul_f32_e32 v144, v36, v144
	v_mul_f32_e32 v32, v40, v144
	v_mul_f32_e32 v144, v39, v33
	v_mul_f32_e32 v145, 0x3f3504f3, v144
	v_mov_b32_e32 v146, 0xb9c68948
	v_fma_f32 v146, |v145|, s80, v146
	v_fma_f32 v146, |v145|, v146, s81
	v_fma_f32 v146, |v145|, v146, s82
	v_fma_f32 v146, |v145|, v146, s83
	v_fma_f32 v146, |v145|, v146, s84
	v_fma_f32 v146, |v145|, v146, s85
	v_fma_f32 v146, |v145|, v146, |v145|
	v_mul_f32_e32 v147, 0xbfb8aa3b, v146
	v_fma_f32 v148, v146, s86, -v147
	v_rndne_f32_e32 v149, v147
	v_fmac_f32_e32 v148, 0xb2a5705f, v146
	v_sub_f32_e32 v147, v147, v149
	v_add_f32_e32 v147, v147, v148
	v_cvt_i32_f32_e32 v148, v149
	v_exp_f32_e32 v147, v147
	v_cmp_nlt_f32_e32 vcc, s87, v146
	v_ldexp_f32 v147, v147, v148
	s_nop 0
	v_cndmask_b32_e32 v147, 0, v147, vcc
	v_cmp_ngt_f32_e32 vcc, s88, v146
	v_mov_b32_e32 v148, 0x7f800000
	s_nop 0
	v_cndmask_b32_e32 v147, v148, v147, vcc
	v_sub_f32_e32 v147, 1.0, v147
	v_mul_f32_e32 v148, v145, v145
	v_mov_b32_e32 v149, 0x3ba10414
	v_fmamk_f32 v149, v148, 0xba1345e1, v149
	v_fmaak_f32 v149, v148, v149, 0xbcdac9b8
	v_fmaak_f32 v149, v148, v149, 0x3de703be
	v_fmaak_f32 v149, v148, v149, 0xbec09330
	v_fmaak_f32 v149, v148, v149, 0x3e0375d0
	v_fma_f32 v149, |v145|, v149, |v145|
	v_cmp_nlt_f32_e64 vcc, |v145|, 1.0
	s_nop 1
	v_cndmask_b32_e32 v147, v149, v147, vcc
	v_bfi_b32 v147, s89, v147, v145
	v_mul_f32_e32 v144, 0.5, v144
	v_add_f32_e32 v147, 1.0, v147
	v_mul_f32_e32 v144, v144, v147
	v_mul_f32_e32 v144, v37, v144
	v_mul_f32_e32 v33, v41, v144
	global_store_dword v238, v34, s[26:27] offset:1024
	global_store_dword v238, v35, s[26:27] offset:1280
	global_store_dword v238, v32, s[28:29] offset:1024
	global_store_dword v238, v33, s[28:29] offset:1280
	s_waitcnt vmcnt(28)
	v_pk_add_f32 v[60:61], v[60:61], v[62:63]
	v_pk_add_f32 v[164:165], v[164:165], v[166:167]
	v_mov_b32_e32 v62, 0x358637bd
	v_pk_add_f32 v[60:61], v[60:61], v[164:165]
	s_nop 0
	v_add_f32_e32 v60, v60, v61
	s_nop 0
	v_fmamk_f32 v60, v60, 0x3a800000, v62
	s_nop 0
	v_rsq_f32_e32 v60, v60
	s_nop 1
	v_mul_f32_e32 v54, v54, v60
	v_mul_f32_e32 v55, v55, v60
	v_mul_f32_e32 v144, v54, v48
	v_mul_f32_e32 v145, 0x3f3504f3, v144
	v_mov_b32_e32 v146, 0xb9c68948
	v_fma_f32 v146, |v145|, s80, v146
	v_fma_f32 v146, |v145|, v146, s81
	v_fma_f32 v146, |v145|, v146, s82
	v_fma_f32 v146, |v145|, v146, s83
	v_fma_f32 v146, |v145|, v146, s84
	v_fma_f32 v146, |v145|, v146, s85
	v_fma_f32 v146, |v145|, v146, |v145|
	v_mul_f32_e32 v147, 0xbfb8aa3b, v146
	v_fma_f32 v148, v146, s86, -v147
	v_rndne_f32_e32 v149, v147
	v_fmac_f32_e32 v148, 0xb2a5705f, v146
	v_sub_f32_e32 v147, v147, v149
	v_add_f32_e32 v147, v147, v148
	v_cvt_i32_f32_e32 v148, v149
	v_exp_f32_e32 v147, v147
	v_cmp_nlt_f32_e32 vcc, s87, v146
	v_ldexp_f32 v147, v147, v148
	s_nop 0
	v_cndmask_b32_e32 v147, 0, v147, vcc
	v_cmp_ngt_f32_e32 vcc, s88, v146
	v_mov_b32_e32 v148, 0x7f800000
	s_nop 0
	v_cndmask_b32_e32 v147, v148, v147, vcc
	v_sub_f32_e32 v147, 1.0, v147
	v_mul_f32_e32 v148, v145, v145
	v_mov_b32_e32 v149, 0x3ba10414
	v_fmamk_f32 v149, v148, 0xba1345e1, v149
	v_fmaak_f32 v149, v148, v149, 0xbcdac9b8
	v_fmaak_f32 v149, v148, v149, 0x3de703be
	v_fmaak_f32 v149, v148, v149, 0xbec09330
	v_fmaak_f32 v149, v148, v149, 0x3e0375d0
	v_fma_f32 v149, |v145|, v149, |v145|
	v_cmp_nlt_f32_e64 vcc, |v145|, 1.0
	s_nop 1
	v_cndmask_b32_e32 v147, v149, v147, vcc
	v_bfi_b32 v147, s89, v147, v145
	v_mul_f32_e32 v144, 0.5, v144
	v_add_f32_e32 v147, 1.0, v147
	v_mul_f32_e32 v144, v144, v147
	v_mul_f32_e32 v144, v52, v144
	v_mul_f32_e32 v48, v56, v144
	v_mul_f32_e32 v144, v55, v49
	v_mul_f32_e32 v145, 0x3f3504f3, v144
	v_mov_b32_e32 v146, 0xb9c68948
	v_fma_f32 v146, |v145|, s80, v146
	v_fma_f32 v146, |v145|, v146, s81
	v_fma_f32 v146, |v145|, v146, s82
	v_fma_f32 v146, |v145|, v146, s83
	v_fma_f32 v146, |v145|, v146, s84
	v_fma_f32 v146, |v145|, v146, s85
	v_fma_f32 v146, |v145|, v146, |v145|
	v_mul_f32_e32 v147, 0xbfb8aa3b, v146
	v_fma_f32 v148, v146, s86, -v147
	v_rndne_f32_e32 v149, v147
	v_fmac_f32_e32 v148, 0xb2a5705f, v146
	v_sub_f32_e32 v147, v147, v149
	v_add_f32_e32 v147, v147, v148
	v_cvt_i32_f32_e32 v148, v149
	v_exp_f32_e32 v147, v147
	v_cmp_nlt_f32_e32 vcc, s87, v146
	v_ldexp_f32 v147, v147, v148
	s_nop 0
	v_cndmask_b32_e32 v147, 0, v147, vcc
	v_cmp_ngt_f32_e32 vcc, s88, v146
	v_mov_b32_e32 v148, 0x7f800000
	s_nop 0
	v_cndmask_b32_e32 v147, v148, v147, vcc
	v_sub_f32_e32 v147, 1.0, v147
	v_mul_f32_e32 v148, v145, v145
	v_mov_b32_e32 v149, 0x3ba10414
	v_fmamk_f32 v149, v148, 0xba1345e1, v149
	v_fmaak_f32 v149, v148, v149, 0xbcdac9b8
	v_fmaak_f32 v149, v148, v149, 0x3de703be
	v_fmaak_f32 v149, v148, v149, 0xbec09330
	v_fmaak_f32 v149, v148, v149, 0x3e0375d0
	v_fma_f32 v149, |v145|, v149, |v145|
	v_cmp_nlt_f32_e64 vcc, |v145|, 1.0
	s_nop 1
	v_cndmask_b32_e32 v147, v149, v147, vcc
	v_bfi_b32 v147, s89, v147, v145
	v_mul_f32_e32 v144, 0.5, v144
	v_add_f32_e32 v147, 1.0, v147
	v_mul_f32_e32 v144, v144, v147
	v_mul_f32_e32 v144, v53, v144
	v_mul_f32_e32 v49, v57, v144
	global_store_dword v238, v50, s[26:27] offset:1536
	global_store_dword v238, v51, s[26:27] offset:1792
	global_store_dword v238, v48, s[28:29] offset:1536
	global_store_dword v238, v49, s[28:29] offset:1792
	s_waitcnt vmcnt(28)
; DI float gelu_exact(float x) { return 0.5f * x * (1.f + erff(x * 0.7071067811865476f)); }
; template <int NR>
; DI void rms_rows(const float* __restrict__ xr, const float* __restrict__ g, u16* __restrict__ dst, int lane) {
;     ...
;     for (int i = 0; i < 4; ++i) ss += v[r][i].x * v[r][i].x + v[r][i].y * v[r][i].y + v[r][i].z * v[r][i].z + v[r][i].w * v[r][i].w;
;     ss = wave_sum(ss);
;     const float rr = rsqrtf(ss * (1.f / 1024.f) + 1e-6f);
; template <bool STORE>
; DI void peer_item(const Params& p, int item, char* smem) {
;     ...
;       const float amine = gelu_exact(h * su) * gmine * sv;
;       if ((lane & 7) == 0) {
;         EG[tok * 128 + k + (lane >> 3)] = emine;
;         AG[tok * 128 + k + (lane >> 3)] = amine;
;       }
	v_pk_add_f32 v[76:77], v[76:77], v[78:79]
	v_pk_add_f32 v[168:169], v[168:169], v[170:171]
	v_mov_b32_e32 v78, 0x358637bd
	v_pk_add_f32 v[76:77], v[76:77], v[168:169]
	s_nop 0
	v_add_f32_e32 v76, v76, v77
	s_nop 0
	v_fmamk_f32 v76, v76, 0x3a800000, v78
	s_nop 0
	v_rsq_f32_e32 v76, v76
	s_nop 1
	v_mul_f32_e32 v70, v70, v76
	v_mul_f32_e32 v71, v71, v76
	v_mul_f32_e32 v144, v70, v64
	v_mul_f32_e32 v145, 0x3f3504f3, v144
	v_mov_b32_e32 v146, 0xb9c68948
	v_fma_f32 v146, |v145|, s80, v146
	v_fma_f32 v146, |v145|, v146, s81
	v_fma_f32 v146, |v145|, v146, s82
	v_fma_f32 v146, |v145|, v146, s83
	v_fma_f32 v146, |v145|, v146, s84
	v_fma_f32 v146, |v145|, v146, s85
	v_fma_f32 v146, |v145|, v146, |v145|
	v_mul_f32_e32 v147, 0xbfb8aa3b, v146
	v_fma_f32 v148, v146, s86, -v147
	v_rndne_f32_e32 v149, v147
	v_fmac_f32_e32 v148, 0xb2a5705f, v146
	v_sub_f32_e32 v147, v147, v149
	v_add_f32_e32 v147, v147, v148
	v_cvt_i32_f32_e32 v148, v149
	v_exp_f32_e32 v147, v147
	v_cmp_nlt_f32_e32 vcc, s87, v146
	v_ldexp_f32 v147, v147, v148
	s_nop 0
	v_cndmask_b32_e32 v147, 0, v147, vcc
	v_cmp_ngt_f32_e32 vcc, s88, v146
	v_mov_b32_e32 v148, 0x7f800000
	s_nop 0
	v_cndmask_b32_e32 v147, v148, v147, vcc
	v_sub_f32_e32 v147, 1.0, v147
	v_mul_f32_e32 v148, v145, v145
	v_mov_b32_e32 v149, 0x3ba10414
	v_fmamk_f32 v149, v148, 0xba1345e1, v149
	v_fmaak_f32 v149, v148, v149, 0xbcdac9b8
	v_fmaak_f32 v149, v148, v149, 0x3de703be
	v_fmaak_f32 v149, v148, v149, 0xbec09330
	v_fmaak_f32 v149, v148, v149, 0x3e0375d0
	v_fma_f32 v149, |v145|, v149, |v145|
	v_cmp_nlt_f32_e64 vcc, |v145|, 1.0
	s_nop 1
	v_cndmask_b32_e32 v147, v149, v147, vcc
	v_bfi_b32 v147, s89, v147, v145
	v_mul_f32_e32 v144, 0.5, v144
	v_add_f32_e32 v147, 1.0, v147
	v_mul_f32_e32 v144, v144, v147
	v_mul_f32_e32 v144, v68, v144
	v_mul_f32_e32 v64, v72, v144
	v_mul_f32_e32 v144, v71, v65
	v_mul_f32_e32 v145, 0x3f3504f3, v144
	v_mov_b32_e32 v146, 0xb9c68948
	v_fma_f32 v146, |v145|, s80, v146
	v_fma_f32 v146, |v145|, v146, s81
	v_fma_f32 v146, |v145|, v146, s82
	v_fma_f32 v146, |v145|, v146, s83
	v_fma_f32 v146, |v145|, v146, s84
	v_fma_f32 v146, |v145|, v146, s85
	v_fma_f32 v146, |v145|, v146, |v145|
	v_mul_f32_e32 v147, 0xbfb8aa3b, v146
	v_fma_f32 v148, v146, s86, -v147
	v_rndne_f32_e32 v149, v147
	v_fmac_f32_e32 v148, 0xb2a5705f, v146
	v_sub_f32_e32 v147, v147, v149
	v_add_f32_e32 v147, v147, v148
	v_cvt_i32_f32_e32 v148, v149
	v_exp_f32_e32 v147, v147
	v_cmp_nlt_f32_e32 vcc, s87, v146
	v_ldexp_f32 v147, v147, v148
	s_nop 0
	v_cndmask_b32_e32 v147, 0, v147, vcc
	v_cmp_ngt_f32_e32 vcc, s88, v146
	v_mov_b32_e32 v148, 0x7f800000
	s_nop 0
	v_cndmask_b32_e32 v147, v148, v147, vcc
	v_sub_f32_e32 v147, 1.0, v147
	v_mul_f32_e32 v148, v145, v145
	v_mov_b32_e32 v149, 0x3ba10414
	v_fmamk_f32 v149, v148, 0xba1345e1, v149
	v_fmaak_f32 v149, v148, v149, 0xbcdac9b8
	v_fmaak_f32 v149, v148, v149, 0x3de703be
	v_fmaak_f32 v149, v148, v149, 0xbec09330
	v_fmaak_f32 v149, v148, v149, 0x3e0375d0
	v_fma_f32 v149, |v145|, v149, |v145|
	v_cmp_nlt_f32_e64 vcc, |v145|, 1.0
	s_nop 1
	v_cndmask_b32_e32 v147, v149, v147, vcc
	v_bfi_b32 v147, s89, v147, v145
	v_mul_f32_e32 v144, 0.5, v144
	v_add_f32_e32 v147, 1.0, v147
	v_mul_f32_e32 v144, v144, v147
	v_mul_f32_e32 v144, v69, v144
	v_mul_f32_e32 v65, v73, v144
	global_store_dword v238, v66, s[26:27] offset:2048
	global_store_dword v238, v67, s[26:27] offset:2304
	global_store_dword v238, v64, s[28:29] offset:2048
	global_store_dword v238, v65, s[28:29] offset:2304
	s_waitcnt vmcnt(28)
	v_pk_add_f32 v[92:93], v[92:93], v[94:95]
	v_pk_add_f32 v[172:173], v[172:173], v[174:175]
	v_mov_b32_e32 v94, 0x358637bd
	v_pk_add_f32 v[92:93], v[92:93], v[172:173]
	s_nop 0
	v_add_f32_e32 v92, v92, v93
	s_nop 0
	v_fmamk_f32 v92, v92, 0x3a800000, v94
	s_nop 0
	v_rsq_f32_e32 v92, v92
	s_nop 1
	v_mul_f32_e32 v86, v86, v92
	v_mul_f32_e32 v87, v87, v92
	v_mul_f32_e32 v144, v86, v80
	v_mul_f32_e32 v145, 0x3f3504f3, v144
	v_mov_b32_e32 v146, 0xb9c68948
	v_fma_f32 v146, |v145|, s80, v146
	v_fma_f32 v146, |v145|, v146, s81
	v_fma_f32 v146, |v145|, v146, s82
	v_fma_f32 v146, |v145|, v146, s83
	v_fma_f32 v146, |v145|, v146, s84
	v_fma_f32 v146, |v145|, v146, s85
	v_fma_f32 v146, |v145|, v146, |v145|
	v_mul_f32_e32 v147, 0xbfb8aa3b, v146
	v_fma_f32 v148, v146, s86, -v147
	v_rndne_f32_e32 v149, v147
	v_fmac_f32_e32 v148, 0xb2a5705f, v146
	v_sub_f32_e32 v147, v147, v149
	v_add_f32_e32 v147, v147, v148
	v_cvt_i32_f32_e32 v148, v149
	v_exp_f32_e32 v147, v147
	v_cmp_nlt_f32_e32 vcc, s87, v146
	v_ldexp_f32 v147, v147, v148
	s_nop 0
	v_cndmask_b32_e32 v147, 0, v147, vcc
	v_cmp_ngt_f32_e32 vcc, s88, v146
	v_mov_b32_e32 v148, 0x7f800000
	s_nop 0
	v_cndmask_b32_e32 v147, v148, v147, vcc
	v_sub_f32_e32 v147, 1.0, v147
	v_mul_f32_e32 v148, v145, v145
	v_mov_b32_e32 v149, 0x3ba10414
	v_fmamk_f32 v149, v148, 0xba1345e1, v149
	v_fmaak_f32 v149, v148, v149, 0xbcdac9b8
	v_fmaak_f32 v149, v148, v149, 0x3de703be
	v_fmaak_f32 v149, v148, v149, 0xbec09330
	v_fmaak_f32 v149, v148, v149, 0x3e0375d0
	v_fma_f32 v149, |v145|, v149, |v145|
	v_cmp_nlt_f32_e64 vcc, |v145|, 1.0
	s_nop 1
	v_cndmask_b32_e32 v147, v149, v147, vcc
	v_bfi_b32 v147, s89, v147, v145
	v_mul_f32_e32 v144, 0.5, v144
	v_add_f32_e32 v147, 1.0, v147
	v_mul_f32_e32 v144, v144, v147
	v_mul_f32_e32 v144, v84, v144
	v_mul_f32_e32 v80, v88, v144
	v_mul_f32_e32 v144, v87, v81
	v_mul_f32_e32 v145, 0x3f3504f3, v144
	v_mov_b32_e32 v146, 0xb9c68948
	v_fma_f32 v146, |v145|, s80, v146
	v_fma_f32 v146, |v145|, v146, s81
	v_fma_f32 v146, |v145|, v146, s82
	v_fma_f32 v146, |v145|, v146, s83
	v_fma_f32 v146, |v145|, v146, s84
	v_fma_f32 v146, |v145|, v146, s85
	v_fma_f32 v146, |v145|, v146, |v145|
	v_mul_f32_e32 v147, 0xbfb8aa3b, v146
	v_fma_f32 v148, v146, s86, -v147
	v_rndne_f32_e32 v149, v147
	v_fmac_f32_e32 v148, 0xb2a5705f, v146
	v_sub_f32_e32 v147, v147, v149
	v_add_f32_e32 v147, v147, v148
	v_cvt_i32_f32_e32 v148, v149
	v_exp_f32_e32 v147, v147
	v_cmp_nlt_f32_e32 vcc, s87, v146
	v_ldexp_f32 v147, v147, v148
	s_nop 0
	v_cndmask_b32_e32 v147, 0, v147, vcc
	v_cmp_ngt_f32_e32 vcc, s88, v146
	v_mov_b32_e32 v148, 0x7f800000
	s_nop 0
	v_cndmask_b32_e32 v147, v148, v147, vcc
	v_sub_f32_e32 v147, 1.0, v147
	v_mul_f32_e32 v148, v145, v145
	v_mov_b32_e32 v149, 0x3ba10414
	v_fmamk_f32 v149, v148, 0xba1345e1, v149
	v_fmaak_f32 v149, v148, v149, 0xbcdac9b8
	v_fmaak_f32 v149, v148, v149, 0x3de703be
	v_fmaak_f32 v149, v148, v149, 0xbec09330
	v_fmaak_f32 v149, v148, v149, 0x3e0375d0
	v_fma_f32 v149, |v145|, v149, |v145|
	v_cmp_nlt_f32_e64 vcc, |v145|, 1.0
	s_nop 1
	v_cndmask_b32_e32 v147, v149, v147, vcc
	v_bfi_b32 v147, s89, v147, v145
	v_mul_f32_e32 v144, 0.5, v144
	v_add_f32_e32 v147, 1.0, v147
	v_mul_f32_e32 v144, v144, v147
	v_mul_f32_e32 v144, v85, v144
	v_mul_f32_e32 v81, v89, v144
	global_store_dword v238, v82, s[26:27] offset:2560
	global_store_dword v238, v83, s[26:27] offset:2816
	global_store_dword v238, v80, s[28:29] offset:2560
	global_store_dword v238, v81, s[28:29] offset:2816
	s_waitcnt vmcnt(28)
; DI float gelu_exact(float x) { return 0.5f * x * (1.f + erff(x * 0.7071067811865476f)); }
; template <int NR>
; DI void rms_rows(const float* __restrict__ xr, const float* __restrict__ g, u16* __restrict__ dst, int lane) {
;     ...
;     for (int i = 0; i < 4; ++i) ss += v[r][i].x * v[r][i].x + v[r][i].y * v[r][i].y + v[r][i].z * v[r][i].z + v[r][i].w * v[r][i].w;
;     ss = wave_sum(ss);
;     const float rr = rsqrtf(ss * (1.f / 1024.f) + 1e-6f);
; template <bool STORE>
; DI void peer_item(const Params& p, int item, char* smem) {
;     ...
;       const float amine = gelu_exact(h * su) * gmine * sv;
;       if ((lane & 7) == 0) {
;         EG[tok * 128 + k + (lane >> 3)] = emine;
;         AG[tok * 128 + k + (lane >> 3)] = amine;
;       }
	v_pk_add_f32 v[108:109], v[108:109], v[110:111]
	v_pk_add_f32 v[176:177], v[176:177], v[178:179]
	v_mov_b32_e32 v110, 0x358637bd
	v_pk_add_f32 v[108:109], v[108:109], v[176:177]
	s_nop 0
	v_add_f32_e32 v108, v108, v109
	s_nop 0
	v_fmamk_f32 v108, v108, 0x3a800000, v110
	s_nop 0
	v_rsq_f32_e32 v108, v108
	s_nop 1
	v_mul_f32_e32 v102, v102, v108
	v_mul_f32_e32 v103, v103, v108
	v_mul_f32_e32 v144, v102, v96
	v_mul_f32_e32 v145, 0x3f3504f3, v144
	v_mov_b32_e32 v146, 0xb9c68948
	v_fma_f32 v146, |v145|, s80, v146
	v_fma_f32 v146, |v145|, v146, s81
	v_fma_f32 v146, |v145|, v146, s82
	v_fma_f32 v146, |v145|, v146, s83
	v_fma_f32 v146, |v145|, v146, s84
	v_fma_f32 v146, |v145|, v146, s85
	v_fma_f32 v146, |v145|, v146, |v145|
	v_mul_f32_e32 v147, 0xbfb8aa3b, v146
	v_fma_f32 v148, v146, s86, -v147
	v_rndne_f32_e32 v149, v147
	v_fmac_f32_e32 v148, 0xb2a5705f, v146
	v_sub_f32_e32 v147, v147, v149
	v_add_f32_e32 v147, v147, v148
	v_cvt_i32_f32_e32 v148, v149
	v_exp_f32_e32 v147, v147
	v_cmp_nlt_f32_e32 vcc, s87, v146
	v_ldexp_f32 v147, v147, v148
	s_nop 0
	v_cndmask_b32_e32 v147, 0, v147, vcc
	v_cmp_ngt_f32_e32 vcc, s88, v146
	v_mov_b32_e32 v148, 0x7f800000
	s_nop 0
	v_cndmask_b32_e32 v147, v148, v147, vcc
	v_sub_f32_e32 v147, 1.0, v147
	v_mul_f32_e32 v148, v145, v145
	v_mov_b32_e32 v149, 0x3ba10414
	v_fmamk_f32 v149, v148, 0xba1345e1, v149
	v_fmaak_f32 v149, v148, v149, 0xbcdac9b8
	v_fmaak_f32 v149, v148, v149, 0x3de703be
	v_fmaak_f32 v149, v148, v149, 0xbec09330
	v_fmaak_f32 v149, v148, v149, 0x3e0375d0
	v_fma_f32 v149, |v145|, v149, |v145|
	v_cmp_nlt_f32_e64 vcc, |v145|, 1.0
	s_nop 1
	v_cndmask_b32_e32 v147, v149, v147, vcc
	v_bfi_b32 v147, s89, v147, v145
	v_mul_f32_e32 v144, 0.5, v144
	v_add_f32_e32 v147, 1.0, v147
	v_mul_f32_e32 v144, v144, v147
	v_mul_f32_e32 v144, v100, v144
	v_mul_f32_e32 v96, v104, v144
	v_mul_f32_e32 v144, v103, v97
	v_mul_f32_e32 v145, 0x3f3504f3, v144
	v_mov_b32_e32 v146, 0xb9c68948
	v_fma_f32 v146, |v145|, s80, v146
	v_fma_f32 v146, |v145|, v146, s81
	v_fma_f32 v146, |v145|, v146, s82
	v_fma_f32 v146, |v145|, v146, s83
	v_fma_f32 v146, |v145|, v146, s84
	v_fma_f32 v146, |v145|, v146, s85
	v_fma_f32 v146, |v145|, v146, |v145|
	v_mul_f32_e32 v147, 0xbfb8aa3b, v146
	v_fma_f32 v148, v146, s86, -v147
	v_rndne_f32_e32 v149, v147
	v_fmac_f32_e32 v148, 0xb2a5705f, v146
	v_sub_f32_e32 v147, v147, v149
	v_add_f32_e32 v147, v147, v148
	v_cvt_i32_f32_e32 v148, v149
	v_exp_f32_e32 v147, v147
	v_cmp_nlt_f32_e32 vcc, s87, v146
	v_ldexp_f32 v147, v147, v148
	s_nop 0
	v_cndmask_b32_e32 v147, 0, v147, vcc
	v_cmp_ngt_f32_e32 vcc, s88, v146
	v_mov_b32_e32 v148, 0x7f800000
	s_nop 0
	v_cndmask_b32_e32 v147, v148, v147, vcc
	v_sub_f32_e32 v147, 1.0, v147
	v_mul_f32_e32 v148, v145, v145
	v_mov_b32_e32 v149, 0x3ba10414
	v_fmamk_f32 v149, v148, 0xba1345e1, v149
	v_fmaak_f32 v149, v148, v149, 0xbcdac9b8
	v_fmaak_f32 v149, v148, v149, 0x3de703be
	v_fmaak_f32 v149, v148, v149, 0xbec09330
	v_fmaak_f32 v149, v148, v149, 0x3e0375d0
	v_fma_f32 v149, |v145|, v149, |v145|
	v_cmp_nlt_f32_e64 vcc, |v145|, 1.0
	s_nop 1
	v_cndmask_b32_e32 v147, v149, v147, vcc
	v_bfi_b32 v147, s89, v147, v145
	v_mul_f32_e32 v144, 0.5, v144
	v_add_f32_e32 v147, 1.0, v147
	v_mul_f32_e32 v144, v144, v147
	v_mul_f32_e32 v144, v101, v144
	v_mul_f32_e32 v97, v105, v144
	global_store_dword v238, v98, s[26:27] offset:3072
	global_store_dword v238, v99, s[26:27] offset:3328
	global_store_dword v238, v96, s[28:29] offset:3072
	global_store_dword v238, v97, s[28:29] offset:3328
	s_waitcnt vmcnt(28)
; DI float gelu_exact(float x) { return 0.5f * x * (1.f + erff(x * 0.7071067811865476f)); }
; template <int NR>
; DI void rms_rows(const float* __restrict__ xr, const float* __restrict__ g, u16* __restrict__ dst, int lane) {
;     ...
;     for (int i = 0; i < 4; ++i) ss += v[r][i].x * v[r][i].x + v[r][i].y * v[r][i].y + v[r][i].z * v[r][i].z + v[r][i].w * v[r][i].w;
;     ss = wave_sum(ss);
;     const float rr = rsqrtf(ss * (1.f / 1024.f) + 1e-6f);
; template <bool STORE>
; DI void peer_item(const Params& p, int item, char* smem) {
;     ...
;       const float amine = gelu_exact(h * su) * gmine * sv;
;       if ((lane & 7) == 0) {
;         EG[tok * 128 + k + (lane >> 3)] = emine;
;         AG[tok * 128 + k + (lane >> 3)] = amine;
;       }
	v_pk_add_f32 v[124:125], v[124:125], v[126:127]
	v_pk_add_f32 v[180:181], v[180:181], v[182:183]
	v_mov_b32_e32 v126, 0x358637bd
	v_pk_add_f32 v[124:125], v[124:125], v[180:181]
	s_nop 0
	v_add_f32_e32 v124, v124, v125
	s_nop 0
	v_fmamk_f32 v124, v124, 0x3a800000, v126
	s_nop 0
	v_rsq_f32_e32 v124, v124
	s_nop 1
	v_mul_f32_e32 v118, v118, v124
	v_mul_f32_e32 v119, v119, v124
	v_mul_f32_e32 v144, v118, v112
	v_mul_f32_e32 v145, 0x3f3504f3, v144
	v_mov_b32_e32 v146, 0xb9c68948
	v_fma_f32 v146, |v145|, s80, v146
	v_fma_f32 v146, |v145|, v146, s81
	v_fma_f32 v146, |v145|, v146, s82
	v_fma_f32 v146, |v145|, v146, s83
	v_fma_f32 v146, |v145|, v146, s84
	v_fma_f32 v146, |v145|, v146, s85
	v_fma_f32 v146, |v145|, v146, |v145|
	v_mul_f32_e32 v147, 0xbfb8aa3b, v146
	v_fma_f32 v148, v146, s86, -v147
	v_rndne_f32_e32 v149, v147
	v_fmac_f32_e32 v148, 0xb2a5705f, v146
	v_sub_f32_e32 v147, v147, v149
	v_add_f32_e32 v147, v147, v148
	v_cvt_i32_f32_e32 v148, v149
	v_exp_f32_e32 v147, v147
	v_cmp_nlt_f32_e32 vcc, s87, v146
	v_ldexp_f32 v147, v147, v148
	s_nop 0
	v_cndmask_b32_e32 v147, 0, v147, vcc
	v_cmp_ngt_f32_e32 vcc, s88, v146
	v_mov_b32_e32 v148, 0x7f800000
	s_nop 0
	v_cndmask_b32_e32 v147, v148, v147, vcc
	v_sub_f32_e32 v147, 1.0, v147
	v_mul_f32_e32 v148, v145, v145
	v_mov_b32_e32 v149, 0x3ba10414
	v_fmamk_f32 v149, v148, 0xba1345e1, v149
	v_fmaak_f32 v149, v148, v149, 0xbcdac9b8
	v_fmaak_f32 v149, v148, v149, 0x3de703be
	v_fmaak_f32 v149, v148, v149, 0xbec09330
	v_fmaak_f32 v149, v148, v149, 0x3e0375d0
	v_fma_f32 v149, |v145|, v149, |v145|
	v_cmp_nlt_f32_e64 vcc, |v145|, 1.0
	s_nop 1
	v_cndmask_b32_e32 v147, v149, v147, vcc
	v_bfi_b32 v147, s89, v147, v145
	v_mul_f32_e32 v144, 0.5, v144
	v_add_f32_e32 v147, 1.0, v147
	v_mul_f32_e32 v144, v144, v147
	v_mul_f32_e32 v144, v116, v144
	v_mul_f32_e32 v112, v120, v144
	v_mul_f32_e32 v144, v119, v113
	v_mul_f32_e32 v145, 0x3f3504f3, v144
	v_mov_b32_e32 v146, 0xb9c68948
	v_fma_f32 v146, |v145|, s80, v146
	v_fma_f32 v146, |v145|, v146, s81
	v_fma_f32 v146, |v145|, v146, s82
	v_fma_f32 v146, |v145|, v146, s83
	v_fma_f32 v146, |v145|, v146, s84
	v_fma_f32 v146, |v145|, v146, s85
	v_fma_f32 v146, |v145|, v146, |v145|
	v_mul_f32_e32 v147, 0xbfb8aa3b, v146
	v_fma_f32 v148, v146, s86, -v147
	v_rndne_f32_e32 v149, v147
	v_fmac_f32_e32 v148, 0xb2a5705f, v146
	v_sub_f32_e32 v147, v147, v149
	v_add_f32_e32 v147, v147, v148
	v_cvt_i32_f32_e32 v148, v149
	v_exp_f32_e32 v147, v147
	v_cmp_nlt_f32_e32 vcc, s87, v146
	v_ldexp_f32 v147, v147, v148
	s_nop 0
	v_cndmask_b32_e32 v147, 0, v147, vcc
	v_cmp_ngt_f32_e32 vcc, s88, v146
	v_mov_b32_e32 v148, 0x7f800000
	s_nop 0
	v_cndmask_b32_e32 v147, v148, v147, vcc
	v_sub_f32_e32 v147, 1.0, v147
	v_mul_f32_e32 v148, v145, v145
	v_mov_b32_e32 v149, 0x3ba10414
	v_fmamk_f32 v149, v148, 0xba1345e1, v149
	v_fmaak_f32 v149, v148, v149, 0xbcdac9b8
	v_fmaak_f32 v149, v148, v149, 0x3de703be
	v_fmaak_f32 v149, v148, v149, 0xbec09330
	v_fmaak_f32 v149, v148, v149, 0x3e0375d0
	v_fma_f32 v149, |v145|, v149, |v145|
	v_cmp_nlt_f32_e64 vcc, |v145|, 1.0
	s_nop 1
	v_cndmask_b32_e32 v147, v149, v147, vcc
	v_bfi_b32 v147, s89, v147, v145
	v_mul_f32_e32 v144, 0.5, v144
	v_add_f32_e32 v147, 1.0, v147
	v_mul_f32_e32 v144, v144, v147
	v_mul_f32_e32 v144, v117, v144
	v_mul_f32_e32 v113, v121, v144
	global_store_dword v238, v114, s[26:27] offset:3584
	global_store_dword v238, v115, s[26:27] offset:3840
	global_store_dword v238, v112, s[28:29] offset:3584
	global_store_dword v238, v113, s[28:29] offset:3840
	ds_read_b32 v3, v236 offset:512
	ds_read_b32 v53, v236 offset:768
	ds_read_b32 v64, v236 offset:1024
	ds_read_b32 v65, v236 offset:1280
	ds_read_b32 v66, v236 offset:1536
	ds_read_b32 v67, v236 offset:1792
	ds_read_b32 v68, v236 offset:2048
	ds_read_b32 v69, v236 offset:2304
	ds_read_b32 v70, v236 offset:2560
	ds_read_b32 v71, v236 offset:2816
	ds_read_b32 v72, v236 offset:3072
	ds_read_b32 v73, v236 offset:3328
	ds_read_b32 v74, v236 offset:3584
	ds_read_b32 v75, v236 offset:3840
	ds_read_b32 v76, v236 offset:4096
	ds_read_b32 v77, v236 offset:4352
	ds_read_b32 v78, v236 offset:4608
	ds_read_b32 v79, v236 offset:4864
	ds_read_b32 v80, v236 offset:5120
	ds_read_b32 v81, v236 offset:5376
	ds_read_b32 v82, v236 offset:5632
	ds_read_b32 v83, v236 offset:5888
	ds_read_b32 v96, v236 offset:6144
	ds_read_b32 v210, v236 offset:6400
	ds_read_b32 v211, v236 offset:6656
	ds_read_b32 v212, v236 offset:6912
	v_readlane_b32 s6, v254, 0
	v_readlane_b32 s7, v254, 1
	v_readlane_b32 s12, v254, 2
	v_readlane_b32 s13, v254, 3
	v_readlane_b32 s14, v254, 4
	v_readlane_b32 s15, v254, 5
	v_readlane_b32 s16, v254, 6
	v_readlane_b32 s17, v254, 7
	v_readlane_b32 s18, v254, 8
	v_readlane_b32 s19, v254, 9
	v_readlane_b32 s20, v254, 10
	v_readlane_b32 s21, v254, 11
	v_readlane_b32 s22, v254, 12
	v_readlane_b32 s23, v254, 13
	v_readlane_b32 s24, v254, 14
	v_readlane_b32 s25, v254, 15
	v_readlane_b32 s26, v254, 16
	v_readlane_b32 s27, v254, 17
	v_readlane_b32 s28, v254, 18
	v_readlane_b32 s29, v254, 19
	v_readlane_b32 s30, v254, 20
	v_readlane_b32 s31, v254, 21
	v_readlane_b32 s33, v254, 22
	v_readlane_b32 s34, v254, 23
	v_readlane_b32 s35, v254, 24
	v_readlane_b32 s36, v254, 25
	v_readlane_b32 s37, v254, 26
	v_readlane_b32 s38, v254, 27
	v_readlane_b32 s39, v254, 28
	v_readlane_b32 s40, v254, 29
	v_readlane_b32 s41, v254, 30
	v_readlane_b32 s42, v254, 31
	v_readlane_b32 s44, v254, 32
	v_readlane_b32 s45, v254, 33
	v_readlane_b32 s48, v254, 34
	v_readlane_b32 s49, v254, 35
	v_readlane_b32 s50, v254, 36
	v_readlane_b32 s51, v254, 37
	v_readlane_b32 s52, v254, 38
	v_readlane_b32 s53, v254, 39
	v_readlane_b32 s55, v254, 40
	v_readlane_b32 s60, v254, 41
	v_readlane_b32 s61, v254, 42
	v_readlane_b32 s62, v254, 43
	v_readlane_b32 s63, v254, 44
	v_readlane_b32 s66, v254, 45
	v_readlane_b32 s67, v254, 46
	v_readlane_b32 s68, v254, 47
	v_readlane_b32 s69, v254, 48
	v_readlane_b32 s74, v254, 49
	v_readlane_b32 s75, v254, 50
	v_readlane_b32 s76, v254, 51
	v_readlane_b32 s77, v254, 52
	v_readlane_b32 s78, v254, 53
	v_readlane_b32 s79, v254, 54
	v_readlane_b32 s88, v254, 55
	s_waitcnt lgkmcnt(0)
	s_nop 3
